# GEMM K-loop: two write-slot variants by SIMD parity (LDS store path halves) + PEER group-wise load reissue at loop back-edge
# speedup vs baseline: 1.0828x; 1.0074x over previous
.LBB0_272:
	s_and_b32 s2, s8, 0xff
	s_mul_i32 s2, s2, 27
	s_lshr_b32 s2, s2, 9
	s_add_i32 s97, s22, s2
	s_lshl_b32 s14, s97, 19
	v_lshl_add_u64 v[2:3], v[84:85], 0, s[14:15]
	v_add_co_u32_e32 v4, vcc, 0x10000, v2
	s_mul_i32 s2, s2, 19
	s_nop 0
	v_addc_co_u32_e32 v5, vcc, 0, v3, vcc
	v_add_co_u32_e32 v12, vcc, 0x20000, v2
	s_sub_i32 s2, s8, s2
	s_nop 0
	v_addc_co_u32_e32 v13, vcc, 0, v3, vcc
	v_add_co_u32_e32 v14, vcc, 0x30000, v2
	s_and_b32 s9, s2, 0xff
	s_nop 0
	v_addc_co_u32_e32 v15, vcc, 0, v3, vcc
	v_add_co_u32_e32 v24, vcc, 0x40000, v2
	global_load_dwordx4 v[48:51], v[2:3], off
	s_nop 0
	v_addc_co_u32_e32 v25, vcc, 0, v3, vcc
	v_add_co_u32_e32 v26, vcc, 0x50000, v2
	s_lshl_b32 s2, s9, 18
	s_mov_b32 s3, s15
	global_load_dwordx4 v[52:55], v[4:5], off
	global_load_dwordx4 v[56:59], v[12:13], off
	v_addc_co_u32_e32 v27, vcc, 0, v3, vcc
	v_lshl_add_u64 v[0:1], v[82:83], 0, s[2:3]
	v_add_co_u32_e32 v32, vcc, 0x60000, v2
	global_load_dwordx4 v[104:107], v[0:1], off
	s_nop 0
	v_addc_co_u32_e32 v33, vcc, 0, v3, vcc
	global_load_dwordx4 v[60:63], v[14:15], off
	global_load_dwordx4 v[64:67], v[24:25], off
	v_add_co_u32_e32 v34, vcc, 0x70000, v2
	global_load_dwordx4 v[68:71], v[26:27], off
	global_load_dwordx4 v[72:75], v[32:33], off
	v_addc_co_u32_e32 v35, vcc, 0, v3, vcc
	v_add_co_u32_e32 v36, vcc, s33, v0
	global_load_dwordx4 v[76:79], v[34:35], off
	s_nop 0
	v_addc_co_u32_e32 v37, vcc, 0, v1, vcc
	v_add_co_u32_e32 v120, vcc, s57, v0
	global_load_dwordx4 v[108:111], v[36:37], off
	s_nop 0
	v_addc_co_u32_e32 v121, vcc, 0, v1, vcc
	global_load_dwordx4 v[112:115], v[120:121], off
	v_add_co_u32_e32 v122, vcc, s69, v0
	s_mov_b32 s6, 0
	s_nop 0
	v_addc_co_u32_e32 v123, vcc, 0, v1, vcc
	global_load_dwordx4 v[116:119], v[122:123], off
	global_load_dwordx4 v[250:253], v[2:3], off offset:128
	s_nop 0
	global_load_dwordx4 v[246:249], v[4:5], off offset:128
	s_nop 0
	global_load_dwordx4 v[218:221], v[0:1], off offset:128
	global_load_dwordx4 v[242:245], v[12:13], off offset:128
	global_load_dwordx4 v[238:241], v[14:15], off offset:128
	s_nop 0
	global_load_dwordx4 v[234:237], v[24:25], off offset:128
	global_load_dwordx4 v[230:233], v[26:27], off offset:128
	s_nop 0
	global_load_dwordx4 v[226:229], v[32:33], off offset:128
	global_load_dwordx4 v[222:225], v[34:35], off offset:128
	s_nop 0
	global_load_dwordx4 v[214:217], v[36:37], off offset:128
	s_nop 0
	global_load_dwordx4 v[210:213], v[120:121], off offset:128
	v_lshl_add_u64 v[2:3], v[102:103], 0, s[14:15]
	v_accvgpr_write_b32 a47, 0
	v_accvgpr_write_b32 a46, 0
	v_accvgpr_write_b32 a45, 0
	v_accvgpr_write_b32 a44, 0
	v_accvgpr_write_b32 a43, 0
	v_accvgpr_write_b32 a42, 0
	v_accvgpr_write_b32 a41, 0
	v_accvgpr_write_b32 a40, 0
	v_accvgpr_write_b32 a39, 0
	v_accvgpr_write_b32 a38, 0
	v_accvgpr_write_b32 a37, 0
	v_accvgpr_write_b32 a36, 0
	v_accvgpr_write_b32 a35, 0
	v_accvgpr_write_b32 a34, 0
	v_accvgpr_write_b32 a33, 0
	v_accvgpr_write_b32 a32, 0
	v_accvgpr_write_b32 a63, 0
	v_accvgpr_write_b32 a62, 0
	v_accvgpr_write_b32 a61, 0
	v_accvgpr_write_b32 a60, 0
	v_accvgpr_write_b32 a59, 0
	v_accvgpr_write_b32 a58, 0
	v_accvgpr_write_b32 a57, 0
	v_accvgpr_write_b32 a56, 0
	v_accvgpr_write_b32 a55, 0
	v_accvgpr_write_b32 a54, 0
	v_accvgpr_write_b32 a53, 0
	s_waitcnt vmcnt(22)
	ds_write_b128 v146, v[48:51]
	s_waitcnt vmcnt(21)
	ds_write_b128 v146, v[52:55] offset:4608
	s_waitcnt vmcnt(19)
	ds_write_b128 v146, v[104:107] offset:36864
	ds_write_b128 v146, v[56:59] offset:9216
	s_waitcnt vmcnt(18)
	ds_write_b128 v146, v[60:63] offset:13824
	s_waitcnt vmcnt(17)
	ds_write_b128 v146, v[64:67] offset:18432
	s_waitcnt vmcnt(16)
	ds_write_b128 v146, v[68:71] offset:23040
	s_waitcnt vmcnt(15)
	ds_write_b128 v146, v[72:75] offset:27648
	s_waitcnt vmcnt(14)
	ds_write_b128 v146, v[76:79] offset:32256
	s_waitcnt vmcnt(13)
	ds_write_b128 v146, v[108:111] offset:41472
	s_waitcnt vmcnt(12)
	ds_write_b128 v146, v[112:115] offset:46080
	global_load_dwordx4 v[206:209], v[122:123], off offset:128
	v_accvgpr_write_b32 a52, 0
	v_accvgpr_write_b32 a51, 0
	v_accvgpr_write_b32 a50, 0
	v_accvgpr_write_b32 a49, 0
	v_accvgpr_write_b32 a48, 0
	v_accvgpr_write_b32 a79, 0
	v_accvgpr_write_b32 a78, 0
	v_accvgpr_write_b32 a77, 0
	v_accvgpr_write_b32 a76, 0
	v_accvgpr_write_b32 a75, 0
	v_accvgpr_write_b32 a74, 0
	v_accvgpr_write_b32 a73, 0
	v_accvgpr_write_b32 a72, 0
	v_accvgpr_write_b32 a71, 0
	v_accvgpr_write_b32 a70, 0
	v_accvgpr_write_b32 a69, 0
	v_accvgpr_write_b32 a68, 0
	v_accvgpr_write_b32 a67, 0
	v_accvgpr_write_b32 a66, 0
	v_accvgpr_write_b32 a65, 0
	v_accvgpr_write_b32 a64, 0
	v_accvgpr_write_b32 a111, 0
	v_accvgpr_write_b32 a110, 0
	v_accvgpr_write_b32 a109, 0
	v_accvgpr_write_b32 a108, 0
	v_accvgpr_write_b32 a107, 0
	v_accvgpr_write_b32 a106, 0
	v_accvgpr_write_b32 a105, 0
	v_accvgpr_write_b32 a104, 0
	v_accvgpr_write_b32 a103, 0
	v_accvgpr_write_b32 a102, 0
	v_accvgpr_write_b32 a101, 0
	v_accvgpr_write_b32 a100, 0
	v_accvgpr_write_b32 a99, 0
	v_accvgpr_write_b32 a98, 0
	v_accvgpr_write_b32 a97, 0
	v_accvgpr_write_b32 a96, 0
	v_accvgpr_write_b32 a95, 0
	v_accvgpr_write_b32 a94, 0
	v_accvgpr_write_b32 a93, 0
	v_accvgpr_write_b32 a92, 0
	v_accvgpr_write_b32 a91, 0
	v_accvgpr_write_b32 a90, 0
	v_accvgpr_write_b32 a89, 0
	v_accvgpr_write_b32 a88, 0
	v_accvgpr_write_b32 a87, 0
	v_accvgpr_write_b32 a86, 0
	v_accvgpr_write_b32 a85, 0
	v_accvgpr_write_b32 a84, 0
	v_accvgpr_write_b32 a83, 0
	v_accvgpr_write_b32 a82, 0
	v_accvgpr_write_b32 a81, 0
	v_accvgpr_write_b32 a80, 0
	v_accvgpr_write_b32 a127, 0
	v_accvgpr_write_b32 a126, 0
	v_accvgpr_write_b32 a125, 0
	v_accvgpr_write_b32 a124, 0
	v_accvgpr_write_b32 a123, 0
	v_accvgpr_write_b32 a122, 0
	v_accvgpr_write_b32 a121, 0
	v_accvgpr_write_b32 a120, 0
	v_accvgpr_write_b32 a119, 0
	v_accvgpr_write_b32 a118, 0
	v_accvgpr_write_b32 a117, 0
	v_accvgpr_write_b32 a116, 0
	v_accvgpr_write_b32 a115, 0
	v_accvgpr_write_b32 a114, 0
	v_accvgpr_write_b32 a113, 0
	v_accvgpr_write_b32 a112, 0
	v_accvgpr_write_b32 a31, 0
	v_accvgpr_write_b32 a30, 0
	v_accvgpr_write_b32 a29, 0
	v_accvgpr_write_b32 a28, 0
	v_accvgpr_write_b32 a27, 0
	v_accvgpr_write_b32 a26, 0
	v_accvgpr_write_b32 a25, 0
	v_accvgpr_write_b32 a24, 0
	v_accvgpr_write_b32 a23, 0
	v_accvgpr_write_b32 a22, 0
	v_accvgpr_write_b32 a21, 0
	v_accvgpr_write_b32 a20, 0
	v_accvgpr_write_b32 a19, 0
	v_accvgpr_write_b32 a18, 0
	v_accvgpr_write_b32 a17, 0
	v_accvgpr_write_b32 a16, 0
	v_accvgpr_write_b32 a15, 0
	v_accvgpr_write_b32 a14, 0
	v_accvgpr_write_b32 a13, 0
	v_accvgpr_write_b32 a12, 0
	v_accvgpr_write_b32 a11, 0
	v_accvgpr_write_b32 a10, 0
	v_accvgpr_write_b32 a9, 0
	v_accvgpr_write_b32 a8, 0
	v_accvgpr_write_b32 a7, 0
	v_accvgpr_write_b32 a6, 0
	v_accvgpr_write_b32 a5, 0
	v_accvgpr_write_b32 a4, 0
	v_accvgpr_write_b32 a3, 0
	v_accvgpr_write_b32 a2, 0
	v_accvgpr_write_b32 a1, 0
	v_accvgpr_write_b32 a0, 0
	s_mov_b64 s[2:3], 0
	s_waitcnt vmcnt(12)
	ds_write_b128 v146, v[116:119] offset:50688
	s_waitcnt lgkmcnt(0)
	s_barrier
	s_waitcnt vmcnt(0)
	v_readfirstlane_b32 s100, v2
	v_readfirstlane_b32 s101, v3
	v_readfirstlane_b32 s98, v0
	v_readfirstlane_b32 s99, v1
	s_nop 1
	v_subrev_u32_e32 v194, s100, v2
	v_subrev_u32_e32 v193, s98, v0
	v_add_u32_e32 v254, 0x126fa000, v194
	v_add_u32_e32 v205, 0x1270a000, v194
	v_add_u32_e32 v204, 0x1271a000, v194
	v_add_u32_e32 v203, 0x1272a000, v194
	v_add_u32_e32 v202, 0x1273a000, v194
	v_add_u32_e32 v201, 0x1274a000, v194
	v_add_u32_e32 v200, 0x1275a000, v194
	v_add_u32_e32 v199, 0x1276a000, v194
	v_mov_b32_e32 v198, v193
	v_add_u32_e32 v197, s33, v193
	v_add_u32_e32 v196, s57, v193
	v_add_u32_e32 v195, s69, v193
	s_add_u32 s100, s100, s2
	s_addc_u32 s101, s101, s3
	s_add_u32 s98, s98, s2
	s_addc_u32 s99, s99, s3
	v_add_u32_e32 v192, v148, v147
	v_add_u32_e32 v191, v148, v150
	v_add_u32_e32 v190, v148, v151
	s_and_b32 s7, s6, 1
	s_mul_i32 s14, s7, 0xd800
	v_add_u32_e32 v189, s14, v192
	v_add_u32_e32 v188, s14, v191
	v_add_u32_e32 v187, s14, v190
	ds_read_b128 v[52:55], v189
	ds_read_b128 v[4:7], v187 offset:36864
	ds_read_b128 v[56:59], v189 offset:4608
	ds_read_b128 v[8:11], v187 offset:41472
	ds_read_b128 v[60:63], v189 offset:9216
	ds_read_b128 v[64:67], v188
	s_getreg_b32 s7, hwreg(HW_REG_HW_ID, 4, 1)
	s_cmp_lg_u32 s7, 0
	s_cbranch_scc1 xg5_varB_1
.LBB0_273:
	s_and_b32 s7, s6, 1
	s_mul_i32 s14, s7, 0xd800
	s_xor_b32 s7, s7, 1
	s_mul_i32 s7, s7, 0xd800
	s_add_i32 s6, s6, 1
	v_add_u32_e32 v186, s7, v146
	ds_read_b128 v[12:15], v189 offset:32
	ds_read_b128 v[24:27], v187 offset:36896
	ds_read_b128 v[16:19], v189 offset:4640
	ds_read_b128 v[28:31], v187 offset:41504
	ds_read_b128 v[20:23], v189 offset:9248
	ds_read_b128 v[48:51], v188 offset:32
	s_waitcnt lgkmcnt(10)
	v_mfma_f32_32x32x16_bf16 a[32:47], v[52:55], v[4:7], a[32:47]
	s_waitcnt vmcnt(11)
	ds_write_b128 v186, v[250:253]
	s_waitcnt lgkmcnt(9)
	v_mfma_f32_32x32x16_bf16 a[48:63], v[52:55], v[8:11], a[48:63]
	s_waitcnt vmcnt(10)
	ds_write_b128 v186, v[246:249] offset:4608
	global_load_dwordx4 v[250:253], v254, s[100:101] offset:512
	v_mfma_f32_32x32x16_bf16 a[64:79], v[56:59], v[4:7], a[64:79]
	s_waitcnt vmcnt(10)
	ds_write_b128 v186, v[242:245] offset:9216
	global_load_dwordx4 v[246:249], v205, s[100:101] offset:512
	v_mfma_f32_32x32x16_bf16 a[96:111], v[56:59], v[8:11], a[96:111]
	s_waitcnt vmcnt(10)
	ds_write_b128 v186, v[238:241] offset:13824
	global_load_dwordx4 v[242:245], v204, s[100:101] offset:512
	s_waitcnt lgkmcnt(11)
	v_mfma_f32_32x32x16_bf16 a[80:95], v[60:63], v[4:7], a[80:95]
	s_waitcnt vmcnt(10)
	ds_write_b128 v186, v[234:237] offset:18432
	global_load_dwordx4 v[238:241], v203, s[100:101] offset:512
	v_mfma_f32_32x32x16_bf16 a[112:127], v[60:63], v[8:11], a[112:127]
	s_waitcnt vmcnt(10)
	ds_write_b128 v186, v[230:233] offset:23040
	global_load_dwordx4 v[234:237], v202, s[100:101] offset:512
	s_waitcnt lgkmcnt(12)
	v_mfma_f32_32x32x16_bf16 a[16:31], v[64:67], v[4:7], a[16:31]
	s_waitcnt vmcnt(10)
	ds_write_b128 v186, v[226:229] offset:27648
	global_load_dwordx4 v[230:233], v201, s[100:101] offset:512
	v_mfma_f32_32x32x16_bf16 a[0:15], v[64:67], v[8:11], a[0:15]
	s_waitcnt vmcnt(10)
	ds_write_b128 v186, v[222:225] offset:32256
	global_load_dwordx4 v[226:229], v200, s[100:101] offset:512
	ds_read_b128 v[52:55], v189 offset:64
	ds_read_b128 v[4:7], v187 offset:36928
	ds_read_b128 v[56:59], v189 offset:4672
	ds_read_b128 v[8:11], v187 offset:41536
	ds_read_b128 v[60:63], v189 offset:9280
	ds_read_b128 v[64:67], v188 offset:64
	s_waitcnt lgkmcnt(15)
	v_mfma_f32_32x32x16_bf16 a[32:47], v[12:15], v[24:27], a[32:47]
	s_waitcnt vmcnt(10)
	ds_write_b128 v186, v[218:221] offset:36864
	global_load_dwordx4 v[222:225], v199, s[100:101] offset:512
	v_mfma_f32_32x32x16_bf16 a[48:63], v[12:15], v[28:31], a[48:63]
	s_waitcnt vmcnt(10)
	ds_write_b128 v186, v[214:217] offset:41472
	global_load_dwordx4 v[218:221], v198, s[98:99] offset:256
	v_mfma_f32_32x32x16_bf16 a[64:79], v[16:19], v[24:27], a[64:79]
	s_waitcnt vmcnt(10)
	ds_write_b128 v186, v[210:213] offset:46080
	global_load_dwordx4 v[214:217], v197, s[98:99] offset:256
	v_mfma_f32_32x32x16_bf16 a[96:111], v[16:19], v[28:31], a[96:111]
	s_waitcnt vmcnt(10)
	ds_write_b128 v186, v[206:209] offset:50688
	global_load_dwordx4 v[210:213], v196, s[98:99] offset:256
	v_mfma_f32_32x32x16_bf16 a[80:95], v[20:23], v[24:27], a[80:95]
	global_load_dwordx4 v[206:209], v195, s[98:99] offset:256
	s_add_u32 s100, s100, 0x80
	s_addc_u32 s101, s101, 0
	s_add_u32 s98, s98, 0x80
	s_addc_u32 s99, s99, 0
	v_mfma_f32_32x32x16_bf16 a[112:127], v[20:23], v[28:31], a[112:127]
	s_waitcnt lgkmcnt(15)
	v_mfma_f32_32x32x16_bf16 a[16:31], v[48:51], v[24:27], a[16:31]
	v_mfma_f32_32x32x16_bf16 a[0:15], v[48:51], v[28:31], a[0:15]
	ds_read_b128 v[12:15], v189 offset:96
	ds_read_b128 v[24:27], v187 offset:36960
	ds_read_b128 v[16:19], v189 offset:4704
	ds_read_b128 v[28:31], v187 offset:41568
	ds_read_b128 v[20:23], v189 offset:9312
	ds_read_b128 v[48:51], v188 offset:96
	s_waitcnt lgkmcnt(14)
	v_mfma_f32_32x32x16_bf16 a[32:47], v[52:55], v[4:7], a[32:47]
	s_waitcnt lgkmcnt(12)
	v_mfma_f32_32x32x16_bf16 a[48:63], v[52:55], v[8:11], a[48:63]
	v_mfma_f32_32x32x16_bf16 a[64:79], v[56:59], v[4:7], a[64:79]
	v_mfma_f32_32x32x16_bf16 a[96:111], v[56:59], v[8:11], a[96:111]
	s_waitcnt lgkmcnt(11)
	v_mfma_f32_32x32x16_bf16 a[80:95], v[60:63], v[4:7], a[80:95]
	v_mfma_f32_32x32x16_bf16 a[112:127], v[60:63], v[8:11], a[112:127]
	s_waitcnt lgkmcnt(10)
	v_mfma_f32_32x32x16_bf16 a[16:31], v[64:67], v[4:7], a[16:31]
	v_mfma_f32_32x32x16_bf16 a[0:15], v[64:67], v[8:11], a[0:15]
	s_waitcnt lgkmcnt(0)
	v_mfma_f32_32x32x16_bf16 a[32:47], v[12:15], v[24:27], a[32:47]
	v_mfma_f32_32x32x16_bf16 a[48:63], v[12:15], v[28:31], a[48:63]
	v_mfma_f32_32x32x16_bf16 a[64:79], v[16:19], v[24:27], a[64:79]
	v_mfma_f32_32x32x16_bf16 a[96:111], v[16:19], v[28:31], a[96:111]
	s_barrier
	v_add_u32_e32 v189, s7, v192
	v_add_u32_e32 v188, s7, v191
	v_add_u32_e32 v187, s7, v190
	ds_read_b128 v[52:55], v189
	ds_read_b128 v[4:7], v187 offset:36864
	ds_read_b128 v[56:59], v189 offset:4608
	ds_read_b128 v[8:11], v187 offset:41472
	ds_read_b128 v[60:63], v189 offset:9216
	ds_read_b128 v[64:67], v188
	v_mfma_f32_32x32x16_bf16 a[80:95], v[20:23], v[24:27], a[80:95]
	v_mfma_f32_32x32x16_bf16 a[112:127], v[20:23], v[28:31], a[112:127]
	v_mfma_f32_32x32x16_bf16 a[16:31], v[48:51], v[24:27], a[16:31]
	v_mfma_f32_32x32x16_bf16 a[0:15], v[48:51], v[28:31], a[0:15]
	s_add_u32 s2, s2, 0x80
	s_addc_u32 s3, s3, 0
	s_cmpk_lg_i32 s2, 0x700
	s_cbranch_scc1 .LBB0_273
	s_branch xg5_tail_1
xg5_varB_1:
	s_and_b32 s7, s6, 1
	s_mul_i32 s14, s7, 0xd800
	s_xor_b32 s7, s7, 1
	s_mul_i32 s7, s7, 0xd800
	s_add_i32 s6, s6, 1
	v_add_u32_e32 v186, s7, v146
	ds_read_b128 v[12:15], v189 offset:32
	ds_read_b128 v[24:27], v187 offset:36896
	ds_read_b128 v[16:19], v189 offset:4640
	ds_read_b128 v[28:31], v187 offset:41504
	ds_read_b128 v[20:23], v189 offset:9248
	ds_read_b128 v[48:51], v188 offset:32
	s_waitcnt lgkmcnt(10)
	v_mfma_f32_32x32x16_bf16 a[32:47], v[52:55], v[4:7], a[32:47]
	s_waitcnt lgkmcnt(8)
	v_mfma_f32_32x32x16_bf16 a[48:63], v[52:55], v[8:11], a[48:63]
	v_mfma_f32_32x32x16_bf16 a[64:79], v[56:59], v[4:7], a[64:79]
	v_mfma_f32_32x32x16_bf16 a[96:111], v[56:59], v[8:11], a[96:111]
	s_waitcnt lgkmcnt(7)
	v_mfma_f32_32x32x16_bf16 a[80:95], v[60:63], v[4:7], a[80:95]
	v_mfma_f32_32x32x16_bf16 a[112:127], v[60:63], v[8:11], a[112:127]
	s_waitcnt lgkmcnt(6)
	v_mfma_f32_32x32x16_bf16 a[16:31], v[64:67], v[4:7], a[16:31]
	v_mfma_f32_32x32x16_bf16 a[0:15], v[64:67], v[8:11], a[0:15]
	ds_read_b128 v[52:55], v189 offset:64
	ds_read_b128 v[4:7], v187 offset:36928
	ds_read_b128 v[56:59], v189 offset:4672
	ds_read_b128 v[8:11], v187 offset:41536
	ds_read_b128 v[60:63], v189 offset:9280
	ds_read_b128 v[64:67], v188 offset:64
	s_waitcnt lgkmcnt(10)
	v_mfma_f32_32x32x16_bf16 a[32:47], v[12:15], v[24:27], a[32:47]
	s_waitcnt lgkmcnt(8)
	v_mfma_f32_32x32x16_bf16 a[48:63], v[12:15], v[28:31], a[48:63]
	v_mfma_f32_32x32x16_bf16 a[64:79], v[16:19], v[24:27], a[64:79]
	v_mfma_f32_32x32x16_bf16 a[96:111], v[16:19], v[28:31], a[96:111]
	s_waitcnt lgkmcnt(7)
	v_mfma_f32_32x32x16_bf16 a[80:95], v[20:23], v[24:27], a[80:95]
	s_waitcnt vmcnt(11)
	ds_write_b128 v186, v[250:253]
	v_mfma_f32_32x32x16_bf16 a[112:127], v[20:23], v[28:31], a[112:127]
	s_waitcnt vmcnt(10)
	ds_write_b128 v186, v[246:249] offset:4608
	global_load_dwordx4 v[250:253], v254, s[100:101] offset:512
	s_waitcnt lgkmcnt(8)
	v_mfma_f32_32x32x16_bf16 a[16:31], v[48:51], v[24:27], a[16:31]
	s_waitcnt vmcnt(10)
	ds_write_b128 v186, v[242:245] offset:9216
	global_load_dwordx4 v[246:249], v205, s[100:101] offset:512
	v_mfma_f32_32x32x16_bf16 a[0:15], v[48:51], v[28:31], a[0:15]
	s_waitcnt vmcnt(10)
	ds_write_b128 v186, v[238:241] offset:13824
	global_load_dwordx4 v[242:245], v204, s[100:101] offset:512
	ds_read_b128 v[12:15], v189 offset:96
	ds_read_b128 v[24:27], v187 offset:36960
	ds_read_b128 v[16:19], v189 offset:4704
	ds_read_b128 v[28:31], v187 offset:41568
	ds_read_b128 v[20:23], v189 offset:9312
	ds_read_b128 v[48:51], v188 offset:96
	s_waitcnt lgkmcnt(14)
	v_mfma_f32_32x32x16_bf16 a[32:47], v[52:55], v[4:7], a[32:47]
	s_waitcnt vmcnt(10)
	ds_write_b128 v186, v[234:237] offset:18432
	global_load_dwordx4 v[238:241], v203, s[100:101] offset:512
	s_waitcnt lgkmcnt(13)
	v_mfma_f32_32x32x16_bf16 a[48:63], v[52:55], v[8:11], a[48:63]
	s_waitcnt vmcnt(10)
	ds_write_b128 v186, v[230:233] offset:23040
	global_load_dwordx4 v[234:237], v202, s[100:101] offset:512
	v_mfma_f32_32x32x16_bf16 a[64:79], v[56:59], v[4:7], a[64:79]
	s_waitcnt vmcnt(10)
	ds_write_b128 v186, v[226:229] offset:27648
	global_load_dwordx4 v[230:233], v201, s[100:101] offset:512
	v_mfma_f32_32x32x16_bf16 a[96:111], v[56:59], v[8:11], a[96:111]
	s_waitcnt vmcnt(10)
	ds_write_b128 v186, v[222:225] offset:32256
	global_load_dwordx4 v[226:229], v200, s[100:101] offset:512
	s_waitcnt lgkmcnt(15)
	v_mfma_f32_32x32x16_bf16 a[80:95], v[60:63], v[4:7], a[80:95]
	s_waitcnt vmcnt(10)
	ds_write_b128 v186, v[218:221] offset:36864
	global_load_dwordx4 v[222:225], v199, s[100:101] offset:512
	v_mfma_f32_32x32x16_bf16 a[112:127], v[60:63], v[8:11], a[112:127]
	s_waitcnt vmcnt(10)
	ds_write_b128 v186, v[214:217] offset:41472
	global_load_dwordx4 v[218:221], v198, s[98:99] offset:256
	s_waitcnt lgkmcnt(15)
	v_mfma_f32_32x32x16_bf16 a[16:31], v[64:67], v[4:7], a[16:31]
	s_waitcnt vmcnt(10)
	ds_write_b128 v186, v[210:213] offset:46080
	global_load_dwordx4 v[214:217], v197, s[98:99] offset:256
	v_mfma_f32_32x32x16_bf16 a[0:15], v[64:67], v[8:11], a[0:15]
	s_waitcnt vmcnt(10)
	ds_write_b128 v186, v[206:209] offset:50688
	global_load_dwordx4 v[210:213], v196, s[98:99] offset:256
	s_waitcnt lgkmcnt(0)
	v_mfma_f32_32x32x16_bf16 a[32:47], v[12:15], v[24:27], a[32:47]
	global_load_dwordx4 v[206:209], v195, s[98:99] offset:256
	s_add_u32 s100, s100, 0x80
	s_addc_u32 s101, s101, 0
	s_add_u32 s98, s98, 0x80
	s_addc_u32 s99, s99, 0
	v_mfma_f32_32x32x16_bf16 a[48:63], v[12:15], v[28:31], a[48:63]
	v_mfma_f32_32x32x16_bf16 a[64:79], v[16:19], v[24:27], a[64:79]
	v_mfma_f32_32x32x16_bf16 a[96:111], v[16:19], v[28:31], a[96:111]
	s_barrier
	v_add_u32_e32 v189, s7, v192
	v_add_u32_e32 v188, s7, v191
	v_add_u32_e32 v187, s7, v190
	ds_read_b128 v[52:55], v189
	ds_read_b128 v[4:7], v187 offset:36864
	ds_read_b128 v[56:59], v189 offset:4608
	ds_read_b128 v[8:11], v187 offset:41472
	ds_read_b128 v[60:63], v189 offset:9216
	ds_read_b128 v[64:67], v188
	v_mfma_f32_32x32x16_bf16 a[80:95], v[20:23], v[24:27], a[80:95]
	v_mfma_f32_32x32x16_bf16 a[112:127], v[20:23], v[28:31], a[112:127]
	v_mfma_f32_32x32x16_bf16 a[16:31], v[48:51], v[24:27], a[16:31]
	v_mfma_f32_32x32x16_bf16 a[0:15], v[48:51], v[28:31], a[0:15]
	s_add_u32 s2, s2, 0x80
	s_addc_u32 s3, s3, 0
	s_cmpk_lg_i32 s2, 0x700
	s_cbranch_scc1 xg5_varB_1
xg5_tail_1:
	ds_read_b128 v[0:3], v164
	ds_read_b128 v[52:55], v164 offset:4608
	ds_read_b128 v[56:59], v164 offset:9216
	ds_read_b128 v[60:63], v165
	ds_read_b128 v[64:67], v166 offset:36864
	ds_read_b128 v[68:71], v166 offset:41472
	s_waitcnt vmcnt(5)
	s_waitcnt vmcnt(0)
	ds_write_b128 v167, v[250:253] offset:55296
	ds_write_b128 v167, v[246:249] offset:59904
	ds_write_b128 v167, v[242:245] offset:64512
	ds_write_b128 v153, v[238:241] offset:55296
	ds_write_b128 v154, v[234:237] offset:55296
	ds_write_b128 v155, v[230:233] offset:55296
	ds_write_b128 v156, v[226:229] offset:55296
	s_waitcnt vmcnt(3)
	ds_write_b128 v157, v[222:225] offset:55296
	ds_write_b128 v158, v[218:221]
	s_waitcnt vmcnt(2)
	ds_write_b128 v158, v[214:217] offset:4608
	s_waitcnt vmcnt(1)
	ds_write_b128 v158, v[210:213] offset:9216
	s_waitcnt vmcnt(0)
	ds_write_b128 v158, v[206:209] offset:13824
	s_lshl_b32 s23, s97, 8
	s_cmp_gt_u32 s97, 31
	s_waitcnt lgkmcnt(13)
	v_mfma_f32_32x32x16_bf16 a[144:159], v[52:55], v[64:67], a[64:79]
	s_cselect_b64 s[2:3], -1, 0
	s_add_i32 s6, s23, 0xffffe000
	s_lshr_b32 s14, s6, 12
	s_cmp_lt_u32 s97, 32
	s_cselect_b64 s[72:73], -1, 0
	s_and_b64 s[6:7], s[72:73], exec
	s_cselect_b32 s6, 32, 0xf00
	s_waitcnt lgkmcnt(12)
	v_mfma_f32_32x32x16_bf16 a[160:175], v[0:3], v[68:71], a[48:63]
	s_cselect_b32 s25, s97, s14
	s_and_b32 s24, s6, s23
	s_cmp_lg_u32 s9, 5
	s_cselect_b64 s[74:75], -1, 0
	s_mov_b64 s[6:7], -1
	s_and_b64 vcc, exec, s[74:75]
	v_mfma_f32_32x32x16_bf16 a[128:143], v[52:55], v[68:71], a[96:111]
	v_mfma_f32_32x32x16_bf16 a[64:79], v[56:59], v[64:67], a[80:95]
	v_mfma_f32_32x32x16_bf16 a[48:63], v[56:59], v[68:71], a[112:127]
	v_mfma_f32_32x32x16_bf16 a[176:191], v[0:3], v[64:67], a[32:47]
	ds_read_b128 v[0:3], v164 offset:4640
	ds_read_b128 v[4:7], v164 offset:9248
	ds_read_b128 v[8:11], v166 offset:41504
	ds_read_b128 v[12:15], v166 offset:36896
	ds_read_b128 v[16:19], v166 offset:36928
	ds_read_b128 v[20:23], v164 offset:32
	ds_read_b128 v[24:27], v164 offset:64
	v_mfma_f32_32x32x16_bf16 a[32:47], v[60:63], v[64:67], a[16:31]
	v_mfma_f32_32x32x16_bf16 a[16:31], v[60:63], v[68:71], a[0:15]
	s_waitcnt lgkmcnt(3)
	v_mfma_f32_32x32x16_bf16 a[144:159], v[0:3], v[12:15], a[144:159]
	v_mfma_f32_32x32x16_bf16 a[128:143], v[0:3], v[8:11], a[128:143]
	v_mfma_f32_32x32x16_bf16 a[64:79], v[4:7], v[12:15], a[64:79]
	v_mfma_f32_32x32x16_bf16 a[48:63], v[4:7], v[8:11], a[48:63]
	ds_read_b128 v[0:3], v165 offset:32
	ds_read_b128 v[4:7], v165 offset:64
	s_waitcnt lgkmcnt(3)
	v_mfma_f32_32x32x16_bf16 a[176:191], v[20:23], v[12:15], a[176:191]
	v_mfma_f32_32x32x16_bf16 a[160:175], v[20:23], v[8:11], a[160:175]
	s_waitcnt lgkmcnt(1)
	v_mfma_f32_32x32x16_bf16 a[32:47], v[0:3], v[12:15], a[32:47]
	v_mfma_f32_32x32x16_bf16 a[16:31], v[0:3], v[8:11], a[16:31]
	ds_read_b128 v[0:3], v166 offset:41536
	ds_read_b128 v[8:11], v164 offset:9280
	ds_read_b128 v[12:15], v164 offset:4672
	v_mfma_f32_32x32x16_bf16 a[176:191], v[24:27], v[16:19], a[176:191]
	s_waitcnt lgkmcnt(0)
	v_mfma_f32_32x32x16_bf16 a[144:159], v[12:15], v[16:19], a[144:159]
	v_mfma_f32_32x32x16_bf16 a[128:143], v[12:15], v[0:3], a[128:143]
	v_mfma_f32_32x32x16_bf16 a[64:79], v[8:11], v[16:19], a[64:79]
	v_mfma_f32_32x32x16_bf16 a[48:63], v[8:11], v[0:3], a[48:63]
	v_mfma_f32_32x32x16_bf16 a[160:175], v[24:27], v[0:3], a[160:175]
	v_mfma_f32_32x32x16_bf16 a[32:47], v[4:7], v[16:19], a[32:47]
	v_mfma_f32_32x32x16_bf16 a[16:31], v[4:7], v[0:3], a[16:31]
	ds_read_b128 v[0:3], v166 offset:41568
	ds_read_b128 v[4:7], v166 offset:36960
	ds_read_b128 v[8:11], v165 offset:96
	ds_read_b128 v[12:15], v164 offset:9312
	ds_read_b128 v[16:19], v164 offset:4704
	ds_read_b128 v[20:23], v164 offset:96
	s_waitcnt lgkmcnt(0)
	s_barrier
	v_mfma_f32_32x32x16_bf16 a[176:191], v[20:23], v[4:7], a[176:191]
	v_mfma_f32_32x32x16_bf16 a[144:159], v[16:19], v[4:7], a[144:159]
	v_mfma_f32_32x32x16_bf16 a[128:143], v[16:19], v[0:3], a[128:143]
	v_mfma_f32_32x32x16_bf16 a[64:79], v[12:15], v[4:7], a[64:79]
	v_mfma_f32_32x32x16_bf16 a[48:63], v[12:15], v[0:3], a[48:63]
	v_mfma_f32_32x32x16_bf16 a[160:175], v[20:23], v[0:3], a[160:175]
	v_mfma_f32_32x32x16_bf16 a[32:47], v[8:11], v[4:7], a[32:47]
	v_mfma_f32_32x32x16_bf16 a[16:31], v[8:11], v[0:3], a[16:31]
	ds_read_b128 v[0:3], v164 offset:59904
	ds_read_b128 v[4:7], v164 offset:64512
	ds_read_b128 v[8:11], v159 offset:4608
	ds_read_b128 v[12:15], v164 offset:55296
	ds_read_b128 v[16:19], v164 offset:55328
	ds_read_b128 v[20:23], v159
	ds_read_b128 v[24:27], v159 offset:32
	s_waitcnt lgkmcnt(1)
	v_mfma_f32_32x32x16_bf16 a[176:191], v[12:15], v[20:23], a[176:191]
	v_mfma_f32_32x32x16_bf16 a[144:159], v[0:3], v[20:23], a[144:159]
	v_mfma_f32_32x32x16_bf16 a[128:143], v[0:3], v[8:11], a[128:143]
	v_mfma_f32_32x32x16_bf16 a[64:79], v[4:7], v[20:23], a[64:79]
	v_mfma_f32_32x32x16_bf16 a[48:63], v[4:7], v[8:11], a[48:63]
	ds_read_b128 v[0:3], v165 offset:55296
	ds_read_b128 v[4:7], v165 offset:55328
	v_mfma_f32_32x32x16_bf16 a[160:175], v[12:15], v[8:11], a[160:175]
	s_waitcnt lgkmcnt(1)
	v_mfma_f32_32x32x16_bf16 a[32:47], v[0:3], v[20:23], a[32:47]
	v_mfma_f32_32x32x16_bf16 a[16:31], v[0:3], v[8:11], a[16:31]
	ds_read_b128 v[0:3], v164 offset:64544
	ds_read_b128 v[8:11], v164 offset:59936
	ds_read_b128 v[12:15], v159 offset:4640
	v_mfma_f32_32x32x16_bf16 a[176:191], v[16:19], v[24:27], a[176:191]
	s_waitcnt lgkmcnt(0)
	v_mfma_f32_32x32x16_bf16 a[160:175], v[16:19], v[12:15], a[160:175]
	v_mfma_f32_32x32x16_bf16 a[144:159], v[8:11], v[24:27], a[144:159]
	v_mfma_f32_32x32x16_bf16 a[128:143], v[8:11], v[12:15], a[128:143]
	v_mfma_f32_32x32x16_bf16 a[64:79], v[0:3], v[24:27], a[64:79]
	v_mfma_f32_32x32x16_bf16 a[48:63], v[0:3], v[12:15], a[48:63]
	v_mfma_f32_32x32x16_bf16 a[32:47], v[4:7], v[24:27], a[32:47]
	v_mfma_f32_32x32x16_bf16 a[16:31], v[4:7], v[12:15], a[16:31]
	ds_read_b128 v[0:3], v165 offset:55360
	ds_read_b128 v[4:7], v164 offset:64576
	ds_read_b128 v[8:11], v164 offset:59968
	ds_read_b128 v[12:15], v164 offset:55360
	ds_read_b128 v[16:19], v159 offset:64
	ds_read_b128 v[20:23], v159 offset:4672
	s_waitcnt lgkmcnt(1)
	v_mfma_f32_32x32x16_bf16 a[176:191], v[12:15], v[16:19], a[176:191]
	s_waitcnt lgkmcnt(0)
	v_mfma_f32_32x32x16_bf16 a[160:175], v[12:15], v[20:23], a[160:175]
	v_mfma_f32_32x32x16_bf16 a[144:159], v[8:11], v[16:19], a[144:159]
	v_mfma_f32_32x32x16_bf16 a[128:143], v[8:11], v[20:23], a[128:143]
	v_mfma_f32_32x32x16_bf16 a[64:79], v[4:7], v[16:19], a[64:79]
	v_mfma_f32_32x32x16_bf16 a[48:63], v[4:7], v[20:23], a[48:63]
	v_mfma_f32_32x32x16_bf16 a[32:47], v[0:3], v[16:19], a[32:47]
	v_mfma_f32_32x32x16_bf16 a[16:31], v[0:3], v[20:23], a[16:31]
	ds_read_b128 v[0:3], v165 offset:55392
	ds_read_b128 v[4:7], v164 offset:64608
	ds_read_b128 v[8:11], v164 offset:60000
	ds_read_b128 v[12:15], v164 offset:55392
	ds_read_b128 v[16:19], v159 offset:96
	ds_read_b128 v[20:23], v159 offset:4704
	s_waitcnt lgkmcnt(0)
	s_barrier
	v_mfma_f32_32x32x16_bf16 a[176:191], v[12:15], v[16:19], a[176:191]
	v_mfma_f32_32x32x16_bf16 a[32:47], v[0:3], v[16:19], a[32:47]
	v_mfma_f32_32x32x16_bf16 a[16:31], v[0:3], v[20:23], a[16:31]
	v_accvgpr_read_b32 v0, a212
	v_lshlrev_b32_e32 v0, 5, v0
	v_lshlrev_b32_e32 v104, 1, v0
	v_mfma_f32_32x32x16_bf16 a[160:175], v[12:15], v[20:23], a[160:175]
	v_mfma_f32_32x32x16_bf16 a[144:159], v[8:11], v[16:19], a[144:159]
	v_mfma_f32_32x32x16_bf16 a[128:143], v[8:11], v[20:23], a[128:143]
	v_mfma_f32_32x32x16_bf16 a[64:79], v[4:7], v[16:19], a[64:79]
	v_mfma_f32_32x32x16_bf16 a[48:63], v[4:7], v[20:23], a[48:63]
	s_nop 1
	ds_write_b32 v152, a176
	ds_write_b32 v152, a177 offset:516
	ds_write_b32 v152, a178 offset:1032
	ds_write_b32 v152, a179 offset:1548
	ds_write_b32 v152, a180 offset:4128
	ds_write_b32 v152, a181 offset:4644
	ds_write_b32 v152, a182 offset:5160
	ds_write_b32 v152, a183 offset:5676
	ds_write_b32 v152, a184 offset:8256
	ds_write_b32 v152, a185 offset:8772
	ds_write_b32 v152, a186 offset:9288
	ds_write_b32 v152, a187 offset:9804
	ds_write_b32 v152, a188 offset:12384
	ds_write_b32 v152, a189 offset:12900
	ds_write_b32 v152, a190 offset:13416
	ds_write_b32 v152, a191 offset:13932
	ds_write_b32 v152, a160 offset:128
	ds_write_b32 v152, a161 offset:644
	ds_write_b32 v152, a162 offset:1160
	ds_write_b32 v152, a163 offset:1676
	ds_write_b32 v152, a164 offset:4256
	ds_write_b32 v152, a165 offset:4772
	ds_write_b32 v152, a166 offset:5288
	ds_write_b32 v152, a167 offset:5804
	ds_write_b32 v152, a168 offset:8384
	ds_write_b32 v152, a169 offset:8900
	ds_write_b32 v152, a170 offset:9416
	ds_write_b32 v152, a171 offset:9932
	ds_write_b32 v152, a172 offset:12512
	ds_write_b32 v152, a173 offset:13028
	ds_write_b32 v152, a174 offset:13544
	ds_write_b32 v152, a175 offset:14060
	ds_write_b32 v152, a144 offset:16512
	ds_write_b32 v152, a145 offset:17028
	ds_write_b32 v152, a146 offset:17544
	ds_write_b32 v152, a147 offset:18060
	ds_write_b32 v152, a148 offset:20640
	ds_write_b32 v152, a149 offset:21156
	ds_write_b32 v152, a150 offset:21672
	ds_write_b32 v152, a151 offset:22188
	ds_write_b32 v152, a152 offset:24768
	ds_write_b32 v152, a153 offset:25284
	ds_write_b32 v152, a154 offset:25800
	ds_write_b32 v152, a155 offset:26316
	ds_write_b32 v152, a156 offset:28896
	ds_write_b32 v152, a157 offset:29412
	ds_write_b32 v152, a158 offset:29928
	ds_write_b32 v152, a159 offset:30444
	ds_write_b32 v152, a128 offset:16640
	ds_write_b32 v152, a129 offset:17156
	ds_write_b32 v152, a130 offset:17672
	ds_write_b32 v152, a131 offset:18188
	ds_write_b32 v152, a132 offset:20768
	ds_write_b32 v152, a133 offset:21284
	ds_write_b32 v152, a134 offset:21800
	ds_write_b32 v152, a135 offset:22316
	ds_write_b32 v152, a136 offset:24896
	ds_write_b32 v152, a137 offset:25412
	ds_write_b32 v152, a138 offset:25928
	ds_write_b32 v152, a139 offset:26444
	ds_write_b32 v152, a140 offset:29024
	ds_write_b32 v152, a141 offset:29540
	ds_write_b32 v152, a142 offset:30056
	ds_write_b32 v152, a143 offset:30572
	ds_write_b32 v152, a64 offset:33024
	ds_write_b32 v152, a65 offset:33540
	ds_write_b32 v152, a66 offset:34056
	ds_write_b32 v152, a67 offset:34572
	ds_write_b32 v152, a68 offset:37152
	ds_write_b32 v152, a69 offset:37668
	ds_write_b32 v152, a70 offset:38184
	ds_write_b32 v152, a71 offset:38700
	ds_write_b32 v152, a72 offset:41280
	ds_write_b32 v152, a73 offset:41796
	ds_write_b32 v152, a74 offset:42312
	ds_write_b32 v152, a75 offset:42828
	ds_write_b32 v152, a76 offset:45408
	ds_write_b32 v152, a77 offset:45924
	ds_write_b32 v152, a78 offset:46440
	ds_write_b32 v152, a79 offset:46956
	ds_write_b32 v152, a48 offset:33152
	ds_write_b32 v152, a49 offset:33668
	ds_write_b32 v152, a50 offset:34184
	ds_write_b32 v152, a51 offset:34700
	ds_write_b32 v152, a52 offset:37280
	ds_write_b32 v152, a53 offset:37796
	ds_write_b32 v152, a54 offset:38312
	ds_write_b32 v152, a55 offset:38828
	ds_write_b32 v152, a56 offset:41408
	ds_write_b32 v152, a57 offset:41924
	ds_write_b32 v152, a58 offset:42440
	ds_write_b32 v152, a59 offset:42956
	ds_write_b32 v152, a60 offset:45536
	ds_write_b32 v152, a61 offset:46052
	ds_write_b32 v152, a62 offset:46568
	ds_write_b32 v152, a63 offset:47084
	ds_write_b32 v152, a32 offset:49536
	ds_write_b32 v152, a33 offset:50052
	ds_write_b32 v152, a34 offset:50568
	ds_write_b32 v152, a35 offset:51084
	ds_write_b32 v152, a36 offset:53664
	ds_write_b32 v152, a37 offset:54180
	ds_write_b32 v152, a38 offset:54696
	ds_write_b32 v152, a39 offset:55212
	ds_write_b32 v152, a40 offset:57792
	ds_write_b32 v152, a41 offset:58308
	ds_write_b32 v152, a42 offset:58824
	ds_write_b32 v152, a43 offset:59340
	ds_write_b32 v152, a44 offset:61920
	ds_write_b32 v152, a45 offset:62436
	ds_write_b32 v152, a46 offset:62952
	ds_write_b32 v152, a47 offset:63468
	ds_write_b32 v152, a16 offset:49664
	ds_write_b32 v152, a17 offset:50180
	ds_write_b32 v152, a18 offset:50696
	ds_write_b32 v152, a19 offset:51212
	ds_write_b32 v152, a20 offset:53792
	ds_write_b32 v152, a21 offset:54308
	ds_write_b32 v152, a22 offset:54824
	ds_write_b32 v152, a23 offset:55340
	ds_write_b32 v152, a24 offset:57920
	ds_write_b32 v152, a25 offset:58436
	ds_write_b32 v152, a26 offset:58952
	ds_write_b32 v152, a27 offset:59468
	ds_write_b32 v152, a28 offset:62048
	ds_write_b32 v152, a29 offset:62564
	ds_write_b32 v152, a30 offset:63080
	ds_write_b32 v152, a31 offset:63596
	s_waitcnt lgkmcnt(0)
	s_barrier
	s_cbranch_vccz .LBB0_313
	s_cmp_eq_u32 s9, 18
	s_cselect_b64 s[76:77], -1, 0
	s_cmp_gt_u32 s9, 3
	s_cselect_b64 s[78:79], -1, 0
	s_cmp_lg_u32 s9, 4
	v_accvgpr_read_b32 v0, a210
	s_cselect_b64 s[80:81], -1, 0
	s_cmp_gt_u32 s9, 7
	v_add_u32_e32 v4, s23, v0
	s_cselect_b64 s[82:83], -1, 0
	s_cmp_gt_u32 s9, 9
	s_cselect_b64 s[84:85], -1, 0
	s_cmp_gt_u32 s9, 13
	v_lshlrev_b32_e32 v80, 7, v4
	s_cselect_b64 s[86:87], -1, 0
	s_cmp_gt_u32 s9, 17
	v_lshl_add_u64 v[106:107], s[18:19], 0, v[80:81]
	v_lshlrev_b32_e32 v80, 10, v4
	v_add_u32_e32 v5, s24, v0
	s_cselect_b64 s[88:89], -1, 0
	v_lshl_add_u64 v[0:1], s[10:11], 0, v[80:81]
	s_lshl_b32 s14, s9, 8
	v_lshl_add_u64 v[2:3], v[0:1], 0, s[14:15]
	v_mov_b32_e32 v105, v81
	v_lshl_add_u64 v[2:3], v[2:3], 0, v[104:105]
	v_lshl_add_u64 v[108:109], v[2:3], 0, s[60:61]
	v_lshl_add_u64 v[110:111], v[2:3], 0, s[62:63]
	v_lshlrev_b32_e32 v2, 9, v4
	v_sub_co_u32_e32 v2, vcc, 0, v2
	s_lshl_b32 s26, s9, 7
	s_nop 0
	v_subb_co_u32_e64 v3, s[6:7], 0, 0, vcc
	v_lshl_add_u64 v[0:1], v[0:1], 0, v[2:3]
	v_lshl_add_u64 v[0:1], v[0:1], 0, s[14:15]
	v_lshl_add_u64 v[0:1], v[0:1], 0, v[104:105]
	v_lshl_add_u64 v[112:113], v[0:1], 0, s[64:65]
	v_lshl_add_u64 v[114:115], v[0:1], 0, s[66:67]
	v_lshrrev_b32_e32 v0, 6, v5
	v_accvgpr_read_b32 v1, a211
	v_cndmask_b32_e64 v0, v1, v0, s[4:5]
	v_lshlrev_b32_e32 v80, 7, v0
	v_lshlrev_b32_e32 v0, 7, v5
	v_mov_b32_e32 v1, v81
	v_lshl_add_u64 v[118:119], v[88:89], 0, v[0:1]
	v_lshl_add_u32 v0, s25, 9, v5
	v_lshlrev_b64 v[0:1], 9, v[0:1]
	v_lshlrev_b32_e32 v2, 11, v4
	v_mov_b32_e32 v3, v81
	v_lshl_add_u64 v[116:117], s[16:17], 0, v[80:81]
	s_lshl_b32 s27, s25, 1
	v_mov_b32_e32 v80, v5
	v_lshl_add_u64 v[120:121], v[90:91], 0, v[2:3]
	v_lshl_add_u64 v[122:123], v[94:95], 0, v[0:1]
	s_mov_b32 s94, 0
	s_mov_b64 s[92:93], -1
	s_mov_b64 s[90:91], 0
	s_branch .LBB0_278

.LBB0_777:
	s_lshr_b32 s50, s49, 3
	s_lshl_b32 s44, s50, 18
	s_add_i32 s44, s70, s44
	v_lshl_add_u64 v[10:11], s[44:45], 1, v[8:9]
	s_and_b32 s44, s48, 7
	s_lshl_b32 s44, s44, 18
	s_add_i32 s50, s50, s67
	v_lshl_add_u64 v[12:13], v[8:9], 0, s[44:45]
	s_lshl_b32 s44, s50, 19
	v_lshl_add_u64 v[14:15], v[2:3], 0, s[44:45]
	v_add_co_u32_e32 v16, vcc, s71, v14
	s_mov_b32 s44, 0x40000
	s_nop 0
	v_addc_co_u32_e32 v17, vcc, 0, v15, vcc
	v_add_co_u32_e32 v18, vcc, s72, v14
	s_and_b32 s51, s49, 7
	s_nop 0
	v_addc_co_u32_e32 v19, vcc, 0, v15, vcc
	v_add_co_u32_e32 v76, vcc, s73, v14
	global_load_dwordx4 v[108:111], v[14:15], off
	global_load_dwordx4 v[112:115], v[16:17], off
	v_addc_co_u32_e32 v77, vcc, 0, v15, vcc
	v_add_co_u32_e32 v78, vcc, s44, v14
	s_lshl_b32 s44, s51, 18
	s_nop 0
	v_addc_co_u32_e32 v79, vcc, 0, v15, vcc
	v_add_co_u32_e32 v80, vcc, s74, v14
	v_lshl_add_u64 v[90:91], v[4:5], 0, s[44:45]
	s_nop 0
	v_addc_co_u32_e32 v81, vcc, 0, v15, vcc
	v_add_co_u32_e32 v82, vcc, s75, v14
	global_load_dwordx4 v[116:119], v[18:19], off
	global_load_dwordx4 v[120:123], v[76:77], off
	v_addc_co_u32_e32 v83, vcc, 0, v15, vcc
	v_add_co_u32_e32 v88, vcc, s76, v14
	global_load_dwordx4 v[124:127], v[78:79], off
	global_load_dwordx4 v[128:131], v[80:81], off
	v_addc_co_u32_e32 v89, vcc, 0, v15, vcc
	v_add_co_u32_e32 v92, vcc, s71, v90
	global_load_dwordx4 v[136:139], v[82:83], off
	global_load_dwordx4 v[140:143], v[88:89], off
	v_addc_co_u32_e32 v93, vcc, 0, v91, vcc
	v_add_co_u32_e32 v104, vcc, s72, v90
	global_load_dwordx4 v[144:147], v[90:91], off
	global_load_dwordx4 v[148:151], v[92:93], off
	v_addc_co_u32_e32 v105, vcc, 0, v91, vcc
	v_add_co_u32_e32 v106, vcc, s73, v90
	global_load_dwordx4 v[152:155], v[104:105], off
	s_nop 0
	v_addc_co_u32_e32 v107, vcc, 0, v91, vcc
	global_load_dwordx4 v[156:159], v[106:107], off
	global_load_dwordx4 v[250:253], v[14:15], off offset:128
	global_load_dwordx4 v[246:249], v[16:17], off offset:128
	global_load_dwordx4 v[242:245], v[18:19], off offset:128
	s_nop 0
	global_load_dwordx4 v[238:241], v[76:77], off offset:128
	global_load_dwordx4 v[234:237], v[78:79], off offset:128
	global_load_dwordx4 v[230:233], v[80:81], off offset:128
	s_nop 0
	global_load_dwordx4 v[226:229], v[82:83], off offset:128
	s_nop 0
	global_load_dwordx4 v[222:225], v[88:89], off offset:128
	global_load_dwordx4 v[218:221], v[90:91], off offset:128
	s_nop 0
	global_load_dwordx4 v[214:217], v[92:93], off offset:128
	s_nop 0
	global_load_dwordx4 v[210:213], v[104:105], off offset:128
	s_nop 0
	global_load_dwordx4 v[206:209], v[106:107], off offset:128
	s_mov_b32 s44, 0
	v_accvgpr_write_b32 a47, 0
	v_accvgpr_write_b32 a46, 0
	v_accvgpr_write_b32 a45, 0
	v_accvgpr_write_b32 a44, 0
	v_accvgpr_write_b32 a43, 0
	v_accvgpr_write_b32 a42, 0
	v_accvgpr_write_b32 a41, 0
	v_accvgpr_write_b32 a40, 0
	v_accvgpr_write_b32 a39, 0
	v_accvgpr_write_b32 a38, 0
	v_accvgpr_write_b32 a37, 0
	v_accvgpr_write_b32 a36, 0
	v_accvgpr_write_b32 a35, 0
	v_accvgpr_write_b32 a34, 0
	v_accvgpr_write_b32 a33, 0
	v_accvgpr_write_b32 a32, 0
	v_accvgpr_write_b32 a63, 0
	v_accvgpr_write_b32 a62, 0
	v_accvgpr_write_b32 a61, 0
	v_accvgpr_write_b32 a60, 0
	v_accvgpr_write_b32 a59, 0
	v_accvgpr_write_b32 a58, 0
	v_accvgpr_write_b32 a57, 0
	v_accvgpr_write_b32 a56, 0
	v_accvgpr_write_b32 a55, 0
	v_accvgpr_write_b32 a54, 0
	v_accvgpr_write_b32 a53, 0
	v_accvgpr_write_b32 a52, 0
	v_accvgpr_write_b32 a51, 0
	v_accvgpr_write_b32 a50, 0
	v_accvgpr_write_b32 a49, 0
	v_accvgpr_write_b32 a48, 0
	v_accvgpr_write_b32 a79, 0
	v_accvgpr_write_b32 a78, 0
	v_accvgpr_write_b32 a77, 0
	v_accvgpr_write_b32 a76, 0
	v_accvgpr_write_b32 a75, 0
	v_accvgpr_write_b32 a74, 0
	v_accvgpr_write_b32 a73, 0
	v_accvgpr_write_b32 a72, 0
	v_accvgpr_write_b32 a71, 0
	v_accvgpr_write_b32 a70, 0
	v_accvgpr_write_b32 a69, 0
	v_accvgpr_write_b32 a68, 0
	v_accvgpr_write_b32 a67, 0
	v_accvgpr_write_b32 a66, 0
	v_accvgpr_write_b32 a65, 0
	v_accvgpr_write_b32 a64, 0
	v_accvgpr_write_b32 a111, 0
	v_accvgpr_write_b32 a110, 0
	v_accvgpr_write_b32 a109, 0
	v_accvgpr_write_b32 a108, 0
	v_accvgpr_write_b32 a107, 0
	v_accvgpr_write_b32 a106, 0
	v_accvgpr_write_b32 a105, 0
	v_accvgpr_write_b32 a104, 0
	v_accvgpr_write_b32 a103, 0
	v_accvgpr_write_b32 a102, 0
	v_accvgpr_write_b32 a101, 0
	v_accvgpr_write_b32 a100, 0
	v_accvgpr_write_b32 a99, 0
	v_accvgpr_write_b32 a98, 0
	v_accvgpr_write_b32 a97, 0
	v_accvgpr_write_b32 a96, 0
	v_accvgpr_write_b32 a95, 0
	v_accvgpr_write_b32 a94, 0
	v_accvgpr_write_b32 a93, 0
	v_accvgpr_write_b32 a92, 0
	v_accvgpr_write_b32 a91, 0
	v_accvgpr_write_b32 a90, 0
	v_accvgpr_write_b32 a89, 0
	v_accvgpr_write_b32 a88, 0
	v_accvgpr_write_b32 a87, 0
	v_accvgpr_write_b32 a86, 0
	v_accvgpr_write_b32 a85, 0
	v_accvgpr_write_b32 a84, 0
	v_accvgpr_write_b32 a83, 0
	v_accvgpr_write_b32 a82, 0
	v_accvgpr_write_b32 a81, 0
	v_accvgpr_write_b32 a80, 0
	v_accvgpr_write_b32 a127, 0
	v_accvgpr_write_b32 a126, 0
	v_accvgpr_write_b32 a125, 0
	v_accvgpr_write_b32 a124, 0
	v_accvgpr_write_b32 a123, 0
	v_accvgpr_write_b32 a122, 0
	v_accvgpr_write_b32 a121, 0
	v_accvgpr_write_b32 a120, 0
	v_accvgpr_write_b32 a119, 0
	v_accvgpr_write_b32 a118, 0
	v_accvgpr_write_b32 a117, 0
	v_accvgpr_write_b32 a116, 0
	v_accvgpr_write_b32 a115, 0
	v_accvgpr_write_b32 a114, 0
	v_accvgpr_write_b32 a113, 0
	v_accvgpr_write_b32 a112, 0
	v_accvgpr_write_b32 a31, 0
	v_accvgpr_write_b32 a30, 0
	v_accvgpr_write_b32 a29, 0
	v_accvgpr_write_b32 a28, 0
	v_accvgpr_write_b32 a27, 0
	v_accvgpr_write_b32 a26, 0
	v_accvgpr_write_b32 a25, 0
	v_accvgpr_write_b32 a24, 0
	v_accvgpr_write_b32 a23, 0
	v_accvgpr_write_b32 a22, 0
	v_accvgpr_write_b32 a21, 0
	v_accvgpr_write_b32 a20, 0
	v_accvgpr_write_b32 a19, 0
	v_accvgpr_write_b32 a18, 0
	v_accvgpr_write_b32 a17, 0
	v_accvgpr_write_b32 a16, 0
	v_accvgpr_write_b32 a15, 0
	v_accvgpr_write_b32 a14, 0
	v_accvgpr_write_b32 a13, 0
	v_accvgpr_write_b32 a12, 0
	v_accvgpr_write_b32 a11, 0
	v_accvgpr_write_b32 a10, 0
	v_accvgpr_write_b32 a9, 0
	v_accvgpr_write_b32 a8, 0
	v_accvgpr_write_b32 a7, 0
	v_accvgpr_write_b32 a6, 0
	v_accvgpr_write_b32 a5, 0
	v_accvgpr_write_b32 a4, 0
	v_accvgpr_write_b32 a3, 0
	v_accvgpr_write_b32 a2, 0
	v_accvgpr_write_b32 a1, 0
	v_accvgpr_write_b32 a0, 0
	s_mov_b64 s[46:47], 0
	s_waitcnt vmcnt(23)
	ds_write_b128 v45, v[108:111]
	s_waitcnt vmcnt(22)
	ds_write_b128 v45, v[112:115] offset:4608
	s_waitcnt vmcnt(21)
	ds_write_b128 v45, v[116:119] offset:9216
	s_waitcnt vmcnt(20)
	ds_write_b128 v45, v[120:123] offset:13824
	s_waitcnt vmcnt(19)
	ds_write_b128 v45, v[124:127] offset:18432
	s_waitcnt vmcnt(18)
	ds_write_b128 v45, v[128:131] offset:23040
	s_waitcnt vmcnt(17)
	ds_write_b128 v45, v[136:139] offset:27648
	s_waitcnt vmcnt(16)
	ds_write_b128 v45, v[140:143] offset:32256
	s_waitcnt vmcnt(15)
	ds_write_b128 v45, v[144:147] offset:36864
	s_waitcnt vmcnt(14)
	ds_write_b128 v45, v[148:151] offset:41472
	s_waitcnt vmcnt(13)
	ds_write_b128 v45, v[152:155] offset:46080
	s_waitcnt vmcnt(12)
	ds_write_b128 v45, v[156:159] offset:50688
	s_waitcnt lgkmcnt(0)
	s_barrier
	s_waitcnt vmcnt(0)
	v_readfirstlane_b32 s100, v10
	v_readfirstlane_b32 s101, v11
	v_readfirstlane_b32 s98, v12
	v_readfirstlane_b32 s99, v13
	s_nop 1
	v_subrev_u32_e32 v194, s100, v10
	v_subrev_u32_e32 v193, s98, v12
	v_add_u32_e32 v254, s77, v194
	v_add_u32_e32 v205, s80, v194
	v_add_u32_e32 v204, s81, v194
	v_add_u32_e32 v203, s82, v194
	v_add_u32_e32 v202, s83, v194
	v_add_u32_e32 v201, s84, v194
	v_add_u32_e32 v200, s85, v194
	v_add_u32_e32 v199, s86, v194
	v_add_u32_e32 v198, s87, v193
	v_add_u32_e32 v197, s88, v193
	v_add_u32_e32 v196, s89, v193
	v_add_u32_e32 v195, s90, v193
	s_add_u32 s100, s100, s46
	s_addc_u32 s101, s101, s47
	s_add_u32 s98, s98, s46
	s_addc_u32 s99, s99, s47
	v_add_u32_e32 v192, v20, v46
	v_add_u32_e32 v191, v20, v47
	v_add_u32_e32 v190, v20, v48
	s_and_b32 s52, s44, 1
	s_mul_i32 s53, s52, 0xd800
	v_add_u32_e32 v189, s53, v192
	v_add_u32_e32 v188, s53, v191
	v_add_u32_e32 v187, s53, v190
	ds_read_b128 v[108:111], v189
	ds_read_b128 v[14:17], v187 offset:36864
	ds_read_b128 v[112:115], v189 offset:4608
	ds_read_b128 v[64:67], v187 offset:41472
	ds_read_b128 v[116:119], v189 offset:9216
	ds_read_b128 v[120:123], v188
	s_getreg_b32 s52, hwreg(HW_REG_HW_ID, 4, 1)
	s_cmp_lg_u32 s52, 0
	s_cbranch_scc1 xg5_varB_2
.LBB0_778:
	s_and_b32 s52, s44, 1
	s_mul_i32 s53, s52, 0xd800
	s_xor_b32 s52, s52, 1
	s_mul_i32 s52, s52, 0xd800
	s_add_i32 s44, s44, 1
	v_add_u32_e32 v186, s52, v45
	ds_read_b128 v[68:71], v189 offset:32
	ds_read_b128 v[80:83], v187 offset:36896
	ds_read_b128 v[72:75], v189 offset:4640
	ds_read_b128 v[84:87], v187 offset:41504
	ds_read_b128 v[76:79], v189 offset:9248
	ds_read_b128 v[104:107], v188 offset:32
	s_waitcnt lgkmcnt(10)
	v_mfma_f32_32x32x16_bf16 a[32:47], v[108:111], v[14:17], a[32:47]
	s_waitcnt vmcnt(11)
	ds_write_b128 v186, v[250:253]
	s_waitcnt lgkmcnt(9)
	v_mfma_f32_32x32x16_bf16 a[48:63], v[108:111], v[64:67], a[48:63]
	s_waitcnt vmcnt(10)
	ds_write_b128 v186, v[246:249] offset:4608
	global_load_dwordx4 v[250:253], v254, s[100:101] offset:512
	v_mfma_f32_32x32x16_bf16 a[64:79], v[112:115], v[14:17], a[64:79]
	s_waitcnt vmcnt(10)
	ds_write_b128 v186, v[242:245] offset:9216
	global_load_dwordx4 v[246:249], v205, s[100:101] offset:512
	v_mfma_f32_32x32x16_bf16 a[96:111], v[112:115], v[64:67], a[96:111]
	s_waitcnt vmcnt(10)
	ds_write_b128 v186, v[238:241] offset:13824
	global_load_dwordx4 v[242:245], v204, s[100:101] offset:512
	s_waitcnt lgkmcnt(11)
	v_mfma_f32_32x32x16_bf16 a[80:95], v[116:119], v[14:17], a[80:95]
	s_waitcnt vmcnt(10)
	ds_write_b128 v186, v[234:237] offset:18432
	global_load_dwordx4 v[238:241], v203, s[100:101] offset:512
	v_mfma_f32_32x32x16_bf16 a[112:127], v[116:119], v[64:67], a[112:127]
	s_waitcnt vmcnt(10)
	ds_write_b128 v186, v[230:233] offset:23040
	global_load_dwordx4 v[234:237], v202, s[100:101] offset:512
	s_waitcnt lgkmcnt(12)
	v_mfma_f32_32x32x16_bf16 a[16:31], v[120:123], v[14:17], a[16:31]
	s_waitcnt vmcnt(10)
	ds_write_b128 v186, v[226:229] offset:27648
	global_load_dwordx4 v[230:233], v201, s[100:101] offset:512
	v_mfma_f32_32x32x16_bf16 a[0:15], v[120:123], v[64:67], a[0:15]
	s_waitcnt vmcnt(10)
	ds_write_b128 v186, v[222:225] offset:32256
	global_load_dwordx4 v[226:229], v200, s[100:101] offset:512
	ds_read_b128 v[108:111], v189 offset:64
	ds_read_b128 v[14:17], v187 offset:36928
	ds_read_b128 v[112:115], v189 offset:4672
	ds_read_b128 v[64:67], v187 offset:41536
	ds_read_b128 v[116:119], v189 offset:9280
	ds_read_b128 v[120:123], v188 offset:64
	s_waitcnt lgkmcnt(15)
	v_mfma_f32_32x32x16_bf16 a[32:47], v[68:71], v[80:83], a[32:47]
	s_waitcnt vmcnt(10)
	ds_write_b128 v186, v[218:221] offset:36864
	global_load_dwordx4 v[222:225], v199, s[100:101] offset:512
	v_mfma_f32_32x32x16_bf16 a[48:63], v[68:71], v[84:87], a[48:63]
	s_waitcnt vmcnt(10)
	ds_write_b128 v186, v[214:217] offset:41472
	global_load_dwordx4 v[218:221], v198, s[98:99] offset:256
	v_mfma_f32_32x32x16_bf16 a[64:79], v[72:75], v[80:83], a[64:79]
	s_waitcnt vmcnt(10)
	ds_write_b128 v186, v[210:213] offset:46080
	global_load_dwordx4 v[214:217], v197, s[98:99] offset:256
	v_mfma_f32_32x32x16_bf16 a[96:111], v[72:75], v[84:87], a[96:111]
	s_waitcnt vmcnt(10)
	ds_write_b128 v186, v[206:209] offset:50688
	global_load_dwordx4 v[210:213], v196, s[98:99] offset:256
	v_mfma_f32_32x32x16_bf16 a[80:95], v[76:79], v[80:83], a[80:95]
	global_load_dwordx4 v[206:209], v195, s[98:99] offset:256
	s_add_u32 s100, s100, 0x80
	s_addc_u32 s101, s101, 0
	s_add_u32 s98, s98, 0x80
	s_addc_u32 s99, s99, 0
	v_mfma_f32_32x32x16_bf16 a[112:127], v[76:79], v[84:87], a[112:127]
	s_waitcnt lgkmcnt(15)
	v_mfma_f32_32x32x16_bf16 a[16:31], v[104:107], v[80:83], a[16:31]
	v_mfma_f32_32x32x16_bf16 a[0:15], v[104:107], v[84:87], a[0:15]
	ds_read_b128 v[68:71], v189 offset:96
	ds_read_b128 v[80:83], v187 offset:36960
	ds_read_b128 v[72:75], v189 offset:4704
	ds_read_b128 v[84:87], v187 offset:41568
	ds_read_b128 v[76:79], v189 offset:9312
	ds_read_b128 v[104:107], v188 offset:96
	s_waitcnt lgkmcnt(14)
	v_mfma_f32_32x32x16_bf16 a[32:47], v[108:111], v[14:17], a[32:47]
	s_waitcnt lgkmcnt(12)
	v_mfma_f32_32x32x16_bf16 a[48:63], v[108:111], v[64:67], a[48:63]
	v_mfma_f32_32x32x16_bf16 a[64:79], v[112:115], v[14:17], a[64:79]
	v_mfma_f32_32x32x16_bf16 a[96:111], v[112:115], v[64:67], a[96:111]
	s_waitcnt lgkmcnt(11)
	v_mfma_f32_32x32x16_bf16 a[80:95], v[116:119], v[14:17], a[80:95]
	v_mfma_f32_32x32x16_bf16 a[112:127], v[116:119], v[64:67], a[112:127]
	s_waitcnt lgkmcnt(10)
	v_mfma_f32_32x32x16_bf16 a[16:31], v[120:123], v[14:17], a[16:31]
	v_mfma_f32_32x32x16_bf16 a[0:15], v[120:123], v[64:67], a[0:15]
	s_waitcnt lgkmcnt(0)
	v_mfma_f32_32x32x16_bf16 a[32:47], v[68:71], v[80:83], a[32:47]
	v_mfma_f32_32x32x16_bf16 a[48:63], v[68:71], v[84:87], a[48:63]
	v_mfma_f32_32x32x16_bf16 a[64:79], v[72:75], v[80:83], a[64:79]
	v_mfma_f32_32x32x16_bf16 a[96:111], v[72:75], v[84:87], a[96:111]
	s_barrier
	v_add_u32_e32 v189, s52, v192
	v_add_u32_e32 v188, s52, v191
	v_add_u32_e32 v187, s52, v190
	ds_read_b128 v[108:111], v189
	ds_read_b128 v[14:17], v187 offset:36864
	ds_read_b128 v[112:115], v189 offset:4608
	ds_read_b128 v[64:67], v187 offset:41472
	ds_read_b128 v[116:119], v189 offset:9216
	ds_read_b128 v[120:123], v188
	v_mfma_f32_32x32x16_bf16 a[80:95], v[76:79], v[80:83], a[80:95]
	v_mfma_f32_32x32x16_bf16 a[112:127], v[76:79], v[84:87], a[112:127]
	v_mfma_f32_32x32x16_bf16 a[16:31], v[104:107], v[80:83], a[16:31]
	v_mfma_f32_32x32x16_bf16 a[0:15], v[104:107], v[84:87], a[0:15]
	s_add_u32 s46, s46, 0x80
	s_addc_u32 s47, s47, 0
	s_cmpk_lg_i32 s46, 0x700
	s_cbranch_scc1 .LBB0_778
	s_branch xg5_tail_2
xg5_varB_2:
	s_and_b32 s52, s44, 1
	s_mul_i32 s53, s52, 0xd800
	s_xor_b32 s52, s52, 1
	s_mul_i32 s52, s52, 0xd800
	s_add_i32 s44, s44, 1
	v_add_u32_e32 v186, s52, v45
	ds_read_b128 v[68:71], v189 offset:32
	ds_read_b128 v[80:83], v187 offset:36896
	ds_read_b128 v[72:75], v189 offset:4640
	ds_read_b128 v[84:87], v187 offset:41504
	ds_read_b128 v[76:79], v189 offset:9248
	ds_read_b128 v[104:107], v188 offset:32
	s_waitcnt lgkmcnt(10)
	v_mfma_f32_32x32x16_bf16 a[32:47], v[108:111], v[14:17], a[32:47]
	s_waitcnt lgkmcnt(8)
	v_mfma_f32_32x32x16_bf16 a[48:63], v[108:111], v[64:67], a[48:63]
	v_mfma_f32_32x32x16_bf16 a[64:79], v[112:115], v[14:17], a[64:79]
	v_mfma_f32_32x32x16_bf16 a[96:111], v[112:115], v[64:67], a[96:111]
	s_waitcnt lgkmcnt(7)
	v_mfma_f32_32x32x16_bf16 a[80:95], v[116:119], v[14:17], a[80:95]
	v_mfma_f32_32x32x16_bf16 a[112:127], v[116:119], v[64:67], a[112:127]
	s_waitcnt lgkmcnt(6)
	v_mfma_f32_32x32x16_bf16 a[16:31], v[120:123], v[14:17], a[16:31]
	v_mfma_f32_32x32x16_bf16 a[0:15], v[120:123], v[64:67], a[0:15]
	ds_read_b128 v[108:111], v189 offset:64
	ds_read_b128 v[14:17], v187 offset:36928
	ds_read_b128 v[112:115], v189 offset:4672
	ds_read_b128 v[64:67], v187 offset:41536
	ds_read_b128 v[116:119], v189 offset:9280
	ds_read_b128 v[120:123], v188 offset:64
	s_waitcnt lgkmcnt(10)
	v_mfma_f32_32x32x16_bf16 a[32:47], v[68:71], v[80:83], a[32:47]
	s_waitcnt lgkmcnt(8)
	v_mfma_f32_32x32x16_bf16 a[48:63], v[68:71], v[84:87], a[48:63]
	v_mfma_f32_32x32x16_bf16 a[64:79], v[72:75], v[80:83], a[64:79]
	v_mfma_f32_32x32x16_bf16 a[96:111], v[72:75], v[84:87], a[96:111]
	s_waitcnt lgkmcnt(7)
	v_mfma_f32_32x32x16_bf16 a[80:95], v[76:79], v[80:83], a[80:95]
	s_waitcnt vmcnt(11)
	ds_write_b128 v186, v[250:253]
	v_mfma_f32_32x32x16_bf16 a[112:127], v[76:79], v[84:87], a[112:127]
	s_waitcnt vmcnt(10)
	ds_write_b128 v186, v[246:249] offset:4608
	global_load_dwordx4 v[250:253], v254, s[100:101] offset:512
	s_waitcnt lgkmcnt(8)
	v_mfma_f32_32x32x16_bf16 a[16:31], v[104:107], v[80:83], a[16:31]
	s_waitcnt vmcnt(10)
	ds_write_b128 v186, v[242:245] offset:9216
	global_load_dwordx4 v[246:249], v205, s[100:101] offset:512
	v_mfma_f32_32x32x16_bf16 a[0:15], v[104:107], v[84:87], a[0:15]
	s_waitcnt vmcnt(10)
	ds_write_b128 v186, v[238:241] offset:13824
	global_load_dwordx4 v[242:245], v204, s[100:101] offset:512
	ds_read_b128 v[68:71], v189 offset:96
	ds_read_b128 v[80:83], v187 offset:36960
	ds_read_b128 v[72:75], v189 offset:4704
	ds_read_b128 v[84:87], v187 offset:41568
	ds_read_b128 v[76:79], v189 offset:9312
	ds_read_b128 v[104:107], v188 offset:96
	s_waitcnt lgkmcnt(14)
	v_mfma_f32_32x32x16_bf16 a[32:47], v[108:111], v[14:17], a[32:47]
	s_waitcnt vmcnt(10)
	ds_write_b128 v186, v[234:237] offset:18432
	global_load_dwordx4 v[238:241], v203, s[100:101] offset:512
	s_waitcnt lgkmcnt(13)
	v_mfma_f32_32x32x16_bf16 a[48:63], v[108:111], v[64:67], a[48:63]
	s_waitcnt vmcnt(10)
	ds_write_b128 v186, v[230:233] offset:23040
	global_load_dwordx4 v[234:237], v202, s[100:101] offset:512
	v_mfma_f32_32x32x16_bf16 a[64:79], v[112:115], v[14:17], a[64:79]
	s_waitcnt vmcnt(10)
	ds_write_b128 v186, v[226:229] offset:27648
	global_load_dwordx4 v[230:233], v201, s[100:101] offset:512
	v_mfma_f32_32x32x16_bf16 a[96:111], v[112:115], v[64:67], a[96:111]
	s_waitcnt vmcnt(10)
	ds_write_b128 v186, v[222:225] offset:32256
	global_load_dwordx4 v[226:229], v200, s[100:101] offset:512
	s_waitcnt lgkmcnt(15)
	v_mfma_f32_32x32x16_bf16 a[80:95], v[116:119], v[14:17], a[80:95]
	s_waitcnt vmcnt(10)
	ds_write_b128 v186, v[218:221] offset:36864
	global_load_dwordx4 v[222:225], v199, s[100:101] offset:512
	v_mfma_f32_32x32x16_bf16 a[112:127], v[116:119], v[64:67], a[112:127]
	s_waitcnt vmcnt(10)
	ds_write_b128 v186, v[214:217] offset:41472
	global_load_dwordx4 v[218:221], v198, s[98:99] offset:256
	s_waitcnt lgkmcnt(15)
	v_mfma_f32_32x32x16_bf16 a[16:31], v[120:123], v[14:17], a[16:31]
	s_waitcnt vmcnt(10)
	ds_write_b128 v186, v[210:213] offset:46080
	global_load_dwordx4 v[214:217], v197, s[98:99] offset:256
	v_mfma_f32_32x32x16_bf16 a[0:15], v[120:123], v[64:67], a[0:15]
	s_waitcnt vmcnt(10)
	ds_write_b128 v186, v[206:209] offset:50688
	global_load_dwordx4 v[210:213], v196, s[98:99] offset:256
	s_waitcnt lgkmcnt(0)
	v_mfma_f32_32x32x16_bf16 a[32:47], v[68:71], v[80:83], a[32:47]
	global_load_dwordx4 v[206:209], v195, s[98:99] offset:256
	s_add_u32 s100, s100, 0x80
	s_addc_u32 s101, s101, 0
	s_add_u32 s98, s98, 0x80
	s_addc_u32 s99, s99, 0
	v_mfma_f32_32x32x16_bf16 a[48:63], v[68:71], v[84:87], a[48:63]
	v_mfma_f32_32x32x16_bf16 a[64:79], v[72:75], v[80:83], a[64:79]
	v_mfma_f32_32x32x16_bf16 a[96:111], v[72:75], v[84:87], a[96:111]
	s_barrier
	v_add_u32_e32 v189, s52, v192
	v_add_u32_e32 v188, s52, v191
	v_add_u32_e32 v187, s52, v190
	ds_read_b128 v[108:111], v189
	ds_read_b128 v[14:17], v187 offset:36864
	ds_read_b128 v[112:115], v189 offset:4608
	ds_read_b128 v[64:67], v187 offset:41472
	ds_read_b128 v[116:119], v189 offset:9216
	ds_read_b128 v[120:123], v188
	v_mfma_f32_32x32x16_bf16 a[80:95], v[76:79], v[80:83], a[80:95]
	v_mfma_f32_32x32x16_bf16 a[112:127], v[76:79], v[84:87], a[112:127]
	v_mfma_f32_32x32x16_bf16 a[16:31], v[104:107], v[80:83], a[16:31]
	v_mfma_f32_32x32x16_bf16 a[0:15], v[104:107], v[84:87], a[0:15]
	s_add_u32 s46, s46, 0x80
	s_addc_u32 s47, s47, 0
	s_cmpk_lg_i32 s46, 0x700
	s_cbranch_scc1 xg5_varB_2
xg5_tail_2:
	ds_read_b128 v[10:13], v60
	ds_read_b128 v[108:111], v62 offset:36864
	ds_read_b128 v[112:115], v60 offset:4608
	ds_read_b128 v[116:119], v62 offset:41472
	s_lshl_b32 s46, s50, 8
	s_lshl_b32 s44, s51, 8
	s_waitcnt lgkmcnt(2)
	v_mfma_f32_32x32x16_bf16 a[176:191], v[10:13], v[108:111], a[32:47]
	s_add_i32 s49, s49, s79
	s_add_i32 s48, s48, s79
	s_waitcnt lgkmcnt(0)
	v_mfma_f32_32x32x16_bf16 a[160:175], v[10:13], v[116:119], a[48:63]
	v_mfma_f32_32x32x16_bf16 a[144:159], v[112:115], v[108:111], a[64:79]
	v_mfma_f32_32x32x16_bf16 a[128:143], v[112:115], v[116:119], a[96:111]
	ds_read_b128 v[10:13], v60 offset:9216
	ds_read_b128 v[112:115], v61
	s_waitcnt vmcnt(11)
	s_waitcnt vmcnt(0)
	ds_write_b128 v63, v[250:253] offset:55296
	s_waitcnt vmcnt(10)
	ds_write_b128 v63, v[246:249] offset:59904
	s_waitcnt vmcnt(9)
	ds_write_b128 v63, v[242:245] offset:64512
	s_waitcnt vmcnt(8)
	ds_write_b128 v50, v[238:241] offset:55296
	s_waitcnt vmcnt(7)
	ds_write_b128 v51, v[234:237] offset:55296
	s_waitcnt vmcnt(6)
	ds_write_b128 v52, v[230:233] offset:55296
	s_waitcnt vmcnt(5)
	ds_write_b128 v53, v[226:229] offset:55296
	s_waitcnt vmcnt(4)
	ds_write_b128 v54, v[222:225] offset:55296
	s_waitcnt vmcnt(3)
	ds_write_b128 v55, v[218:221]
	s_waitcnt vmcnt(2)
	ds_write_b128 v55, v[214:217] offset:4608
	s_waitcnt vmcnt(1)
	ds_write_b128 v55, v[210:213] offset:9216
	s_waitcnt vmcnt(0)
	ds_write_b128 v55, v[206:209] offset:13824
	s_waitcnt lgkmcnt(13)
	v_mfma_f32_32x32x16_bf16 a[64:79], v[10:13], v[108:111], a[80:95]
	v_mfma_f32_32x32x16_bf16 a[48:63], v[10:13], v[116:119], a[112:127]
	ds_read_b128 v[10:13], v60 offset:32
	ds_read_b128 v[14:17], v62 offset:36896
	ds_read_b128 v[64:67], v62 offset:36928
	ds_read_b128 v[68:71], v60 offset:64
	ds_read_b128 v[72:75], v62 offset:41504
	ds_read_b128 v[76:79], v62 offset:36960
	s_waitcnt lgkmcnt(4)
	v_mfma_f32_32x32x16_bf16 a[176:191], v[10:13], v[14:17], a[176:191]
	s_waitcnt lgkmcnt(1)
	v_mfma_f32_32x32x16_bf16 a[160:175], v[10:13], v[72:75], a[160:175]
	ds_read_b128 v[10:13], v60 offset:4640
	ds_read_b128 v[80:83], v60 offset:96
	v_mfma_f32_32x32x16_bf16 a[32:47], v[112:115], v[108:111], a[16:31]
	v_mfma_f32_32x32x16_bf16 a[16:31], v[112:115], v[116:119], a[0:15]
	s_waitcnt lgkmcnt(1)
	v_mfma_f32_32x32x16_bf16 a[144:159], v[10:13], v[14:17], a[144:159]
	v_mfma_f32_32x32x16_bf16 a[128:143], v[10:13], v[72:75], a[128:143]
	ds_read_b128 v[10:13], v60 offset:9248
	ds_read_b128 v[84:87], v60 offset:9280
	s_waitcnt lgkmcnt(1)
	v_mfma_f32_32x32x16_bf16 a[64:79], v[10:13], v[14:17], a[64:79]
	v_mfma_f32_32x32x16_bf16 a[48:63], v[10:13], v[72:75], a[48:63]
	ds_read_b128 v[10:13], v61 offset:32
	ds_read_b128 v[88:91], v60 offset:9312
	s_waitcnt lgkmcnt(1)
	v_mfma_f32_32x32x16_bf16 a[32:47], v[10:13], v[14:17], a[32:47]
	v_mfma_f32_32x32x16_bf16 a[16:31], v[10:13], v[72:75], a[16:31]
	ds_read_b128 v[10:13], v62 offset:41536
	ds_read_b128 v[14:17], v62 offset:41568
	v_mfma_f32_32x32x16_bf16 a[176:191], v[68:71], v[64:67], a[176:191]
	s_waitcnt lgkmcnt(1)
	v_mfma_f32_32x32x16_bf16 a[160:175], v[68:71], v[10:13], a[160:175]
	ds_read_b128 v[68:71], v60 offset:4672
	ds_read_b128 v[72:75], v60 offset:4704
	s_waitcnt lgkmcnt(1)
	v_mfma_f32_32x32x16_bf16 a[144:159], v[68:71], v[64:67], a[144:159]
	v_mfma_f32_32x32x16_bf16 a[128:143], v[68:71], v[10:13], a[128:143]
	v_mfma_f32_32x32x16_bf16 a[64:79], v[84:87], v[64:67], a[64:79]
	v_mfma_f32_32x32x16_bf16 a[48:63], v[84:87], v[10:13], a[48:63]
	ds_read_b128 v[68:71], v61 offset:64
	ds_read_b128 v[84:87], v61 offset:96
	s_waitcnt lgkmcnt(0)
	s_barrier
	v_mfma_f32_32x32x16_bf16 a[32:47], v[68:71], v[64:67], a[32:47]
	v_mfma_f32_32x32x16_bf16 a[16:31], v[68:71], v[10:13], a[16:31]
	v_mfma_f32_32x32x16_bf16 a[176:191], v[80:83], v[76:79], a[176:191]
	v_mfma_f32_32x32x16_bf16 a[160:175], v[80:83], v[14:17], a[160:175]
	v_mfma_f32_32x32x16_bf16 a[144:159], v[72:75], v[76:79], a[144:159]
	v_mfma_f32_32x32x16_bf16 a[128:143], v[72:75], v[14:17], a[128:143]
	v_mfma_f32_32x32x16_bf16 a[64:79], v[88:91], v[76:79], a[64:79]
	v_mfma_f32_32x32x16_bf16 a[48:63], v[88:91], v[14:17], a[48:63]
	v_mfma_f32_32x32x16_bf16 a[32:47], v[84:87], v[76:79], a[32:47]
	v_mfma_f32_32x32x16_bf16 a[16:31], v[84:87], v[14:17], a[16:31]
	ds_read_b128 v[10:13], v60 offset:55296
	ds_read_b128 v[14:17], v56
	ds_read_b128 v[64:67], v60 offset:55328
	ds_read_b128 v[68:71], v56 offset:32
	ds_read_b128 v[72:75], v56 offset:4608
	ds_read_b128 v[76:79], v56 offset:4640
	s_waitcnt lgkmcnt(4)
	v_mfma_f32_32x32x16_bf16 a[176:191], v[10:13], v[14:17], a[176:191]
	s_waitcnt lgkmcnt(1)
	v_mfma_f32_32x32x16_bf16 a[160:175], v[10:13], v[72:75], a[160:175]
	ds_read_b128 v[10:13], v60 offset:59904
	ds_read_b128 v[80:83], v60 offset:59936
	s_waitcnt lgkmcnt(1)
	v_mfma_f32_32x32x16_bf16 a[144:159], v[10:13], v[14:17], a[144:159]
	v_mfma_f32_32x32x16_bf16 a[128:143], v[10:13], v[72:75], a[128:143]
	ds_read_b128 v[10:13], v60 offset:64512
	ds_read_b128 v[84:87], v60 offset:64544
	s_waitcnt lgkmcnt(1)
	v_mfma_f32_32x32x16_bf16 a[64:79], v[10:13], v[14:17], a[64:79]
	v_mfma_f32_32x32x16_bf16 a[48:63], v[10:13], v[72:75], a[48:63]
	ds_read_b128 v[10:13], v61 offset:55296
	ds_read_b128 v[88:91], v61 offset:55328
	s_waitcnt lgkmcnt(1)
	v_mfma_f32_32x32x16_bf16 a[32:47], v[10:13], v[14:17], a[32:47]
	v_mfma_f32_32x32x16_bf16 a[16:31], v[10:13], v[72:75], a[16:31]
	ds_read_b128 v[10:13], v60 offset:55360
	v_mfma_f32_32x32x16_bf16 a[176:191], v[64:67], v[68:71], a[176:191]
	v_mfma_f32_32x32x16_bf16 a[160:175], v[64:67], v[76:79], a[160:175]
	v_mfma_f32_32x32x16_bf16 a[144:159], v[80:83], v[68:71], a[144:159]
	v_mfma_f32_32x32x16_bf16 a[128:143], v[80:83], v[76:79], a[128:143]
	v_mfma_f32_32x32x16_bf16 a[64:79], v[84:87], v[68:71], a[64:79]
	v_mfma_f32_32x32x16_bf16 a[48:63], v[84:87], v[76:79], a[48:63]
	ds_read_b128 v[14:17], v56 offset:64
	ds_read_b128 v[64:67], v61 offset:55360
	ds_read_b128 v[72:75], v61 offset:55392
	ds_read_b128 v[80:83], v60 offset:64576
	ds_read_b128 v[84:87], v60 offset:64608
	ds_read_b128 v[92:95], v60 offset:55392
	ds_read_b128 v[96:99], v56 offset:96
	ds_read_b128 v[100:103], v60 offset:59968
	ds_read_b128 v[104:107], v60 offset:60000
	ds_read_b128 v[108:111], v56 offset:4672
	ds_read_b128 v[112:115], v56 offset:4704
	s_waitcnt lgkmcnt(0)
	s_barrier
	v_mfma_f32_32x32x16_bf16 a[32:47], v[88:91], v[68:71], a[32:47]
	v_add_u32_e32 v70, 0x2048, v21
	v_mfma_f32_32x32x16_bf16 a[16:31], v[88:91], v[76:79], a[16:31]
	v_accvgpr_read_b32 v76, a222
	v_accvgpr_read_b32 v77, a223
	v_accvgpr_read_b32 v78, a224
	v_accvgpr_read_b32 v79, a225
	v_mfma_f32_32x32x16_bf16 a[176:191], v[10:13], v[14:17], a[176:191]
	v_mfma_f32_32x32x16_bf16 a[160:175], v[10:13], v[108:111], a[160:175]
	v_lshl_add_u64 v[10:11], v[6:7], 0, s[44:45]
	v_mfma_f32_32x32x16_bf16 a[144:159], v[100:103], v[14:17], a[144:159]
	v_mfma_f32_32x32x16_bf16 a[128:143], v[100:103], v[108:111], a[128:143]
	v_mfma_f32_32x32x16_bf16 a[64:79], v[80:83], v[14:17], a[64:79]
	v_mfma_f32_32x32x16_bf16 a[48:63], v[80:83], v[108:111], a[48:63]
	v_accvgpr_read_b32 v80, a226
	v_mfma_f32_32x32x16_bf16 a[32:47], v[64:67], v[14:17], a[32:47]
	v_mfma_f32_32x32x16_bf16 a[16:31], v[64:67], v[108:111], a[16:31]
	v_add_u32_e32 v66, 0x1028, v21
	v_mfma_f32_32x32x16_bf16 a[176:191], v[92:95], v[96:99], a[176:191]
	s_nop 11
	ds_write_b32 v49, a176
	ds_write_b32 v49, a177 offset:516
	ds_write_b32 v49, a178 offset:1032
	ds_write_b32 v49, a179 offset:1548
	ds_write_b32 v49, a180 offset:4128
	ds_write_b32 v49, a181 offset:4644
	ds_write_b32 v49, a182 offset:5160
	v_mfma_f32_32x32x16_bf16 a[160:175], v[92:95], v[112:115], a[160:175]
	ds_write_b32 v49, a183 offset:5676
	ds_write_b32 v49, a184 offset:8256
	ds_write_b32 v49, a185 offset:8772
	ds_write_b32 v49, a186 offset:9288
	ds_write_b32 v49, a187 offset:9804
	ds_write_b32 v49, a188 offset:12384
	ds_write_b32 v49, a189 offset:12900
	ds_write_b32 v49, a190 offset:13416
	ds_write_b32 v49, a191 offset:13932
	s_nop 2
	ds_write_b32 v49, a160 offset:128
	ds_write_b32 v49, a161 offset:644
	ds_write_b32 v49, a162 offset:1160
	ds_write_b32 v49, a163 offset:1676
	ds_write_b32 v49, a164 offset:4256
	ds_write_b32 v49, a165 offset:4772
	ds_write_b32 v49, a166 offset:5288
	ds_write_b32 v49, a167 offset:5804
	ds_write_b32 v49, a168 offset:8384
	ds_write_b32 v49, a169 offset:8900
	ds_write_b32 v49, a170 offset:9416
	ds_write_b32 v49, a171 offset:9932
	v_mfma_f32_32x32x16_bf16 a[144:159], v[104:107], v[96:99], a[144:159]
	ds_write_b32 v49, a172 offset:12512
	ds_write_b32 v49, a173 offset:13028
	ds_write_b32 v49, a174 offset:13544
	ds_write_b32 v49, a175 offset:14060
	s_nop 7
	ds_write_b32 v49, a144 offset:16512
	ds_write_b32 v49, a145 offset:17028
	ds_write_b32 v49, a146 offset:17544
	ds_write_b32 v49, a147 offset:18060
	ds_write_b32 v49, a148 offset:20640
	ds_write_b32 v49, a149 offset:21156
	ds_write_b32 v49, a150 offset:21672
	ds_write_b32 v49, a151 offset:22188
	ds_write_b32 v49, a152 offset:24768
	ds_write_b32 v49, a153 offset:25284
	v_mfma_f32_32x32x16_bf16 a[128:143], v[104:107], v[112:115], a[128:143]
	ds_write_b32 v49, a154 offset:25800
	ds_write_b32 v49, a155 offset:26316
	ds_write_b32 v49, a156 offset:28896
	ds_write_b32 v49, a157 offset:29412
	ds_write_b32 v49, a158 offset:29928
	ds_write_b32 v49, a159 offset:30444
	s_nop 5
	ds_write_b32 v49, a128 offset:16640
	ds_write_b32 v49, a129 offset:17156
	ds_write_b32 v49, a130 offset:17672
	ds_write_b32 v49, a131 offset:18188
	ds_write_b32 v49, a132 offset:20768
	ds_write_b32 v49, a133 offset:21284
	ds_write_b32 v49, a134 offset:21800
	ds_write_b32 v49, a135 offset:22316
	v_mfma_f32_32x32x16_bf16 a[64:79], v[84:87], v[96:99], a[64:79]
	ds_write_b32 v49, a136 offset:24896
	ds_write_b32 v49, a137 offset:25412
	ds_write_b32 v49, a138 offset:25928
	ds_write_b32 v49, a139 offset:26444
	ds_write_b32 v49, a140 offset:29024
	ds_write_b32 v49, a141 offset:29540
	ds_write_b32 v49, a142 offset:30056
	ds_write_b32 v49, a143 offset:30572
	s_nop 3
	ds_write_b32 v49, a64 offset:33024
	ds_write_b32 v49, a65 offset:33540
	ds_write_b32 v49, a66 offset:34056
	ds_write_b32 v49, a67 offset:34572
	ds_write_b32 v49, a68 offset:37152
	ds_write_b32 v49, a69 offset:37668
	v_mfma_f32_32x32x16_bf16 a[48:63], v[84:87], v[112:115], a[48:63]
	ds_write_b32 v49, a70 offset:38184
	ds_write_b32 v49, a71 offset:38700
	ds_write_b32 v49, a72 offset:41280
	ds_write_b32 v49, a73 offset:41796
	ds_write_b32 v49, a74 offset:42312
	ds_write_b32 v49, a75 offset:42828
	ds_write_b32 v49, a76 offset:45408
	ds_write_b32 v49, a77 offset:45924
	ds_write_b32 v49, a78 offset:46440
	ds_write_b32 v49, a79 offset:46956
	s_nop 1
	ds_write_b32 v49, a48 offset:33152
	ds_write_b32 v49, a49 offset:33668
	ds_write_b32 v49, a50 offset:34184
	ds_write_b32 v49, a51 offset:34700
	ds_write_b32 v49, a52 offset:37280
	ds_write_b32 v49, a53 offset:37796
	ds_write_b32 v49, a54 offset:38312
	ds_write_b32 v49, a55 offset:38828
	ds_write_b32 v49, a56 offset:41408
	ds_write_b32 v49, a57 offset:41924
	ds_write_b32 v49, a58 offset:42440
	v_mfma_f32_32x32x16_bf16 a[32:47], v[72:75], v[96:99], a[32:47]
	ds_write_b32 v49, a59 offset:42956
	ds_write_b32 v49, a60 offset:45536
	ds_write_b32 v49, a61 offset:46052
	ds_write_b32 v49, a62 offset:46568
	ds_write_b32 v49, a63 offset:47084
	s_nop 6
	ds_write_b32 v49, a32 offset:49536
	ds_write_b32 v49, a33 offset:50052
	ds_write_b32 v49, a34 offset:50568
	ds_write_b32 v49, a35 offset:51084
	ds_write_b32 v49, a36 offset:53664
	ds_write_b32 v49, a37 offset:54180
	ds_write_b32 v49, a38 offset:54696
	ds_write_b32 v49, a39 offset:55212
	ds_write_b32 v49, a40 offset:57792
	v_mfma_f32_32x32x16_bf16 a[16:31], v[72:75], v[112:115], a[16:31]
	ds_write_b32 v49, a41 offset:58308
	ds_write_b32 v49, a42 offset:58824
	ds_write_b32 v49, a43 offset:59340
	ds_write_b32 v49, a44 offset:61920
	ds_write_b32 v49, a45 offset:62436
	ds_write_b32 v49, a46 offset:62952
	ds_write_b32 v49, a47 offset:63468
	s_nop 4
	ds_write_b32 v49, a16 offset:49664
	ds_write_b32 v49, a17 offset:50180
	ds_write_b32 v49, a18 offset:50696
	ds_write_b32 v49, a19 offset:51212
	ds_write_b32 v49, a20 offset:53792
	ds_write_b32 v49, a21 offset:54308
	ds_write_b32 v49, a22 offset:54824
	ds_write_b32 v49, a23 offset:55340
	ds_write_b32 v49, a24 offset:57920
	ds_write_b32 v49, a25 offset:58436
	ds_write_b32 v49, a26 offset:58952
	ds_write_b32 v49, a27 offset:59468
	ds_write_b32 v49, a28 offset:62048
	ds_write_b32 v49, a29 offset:62564
	ds_write_b32 v49, a30 offset:63080
	ds_write_b32 v49, a31 offset:63596
	s_waitcnt lgkmcnt(0)
	s_barrier
	ds_read2_b32 v[16:17], v21 offset1:1
	ds_read2_b32 v[18:19], v21 offset0:2 offset1:3
	v_accvgpr_read_b32 v72, a218
	v_or_b32_e32 v0, s46, v72
	v_lshlrev_b32_e32 v0, 11, v0
	s_waitcnt lgkmcnt(1)
	v_cvt_pk_bf16_f32 v16, v16, v17
	s_waitcnt lgkmcnt(0)
	v_cvt_pk_bf16_f32 v17, v18, v19
	v_lshl_add_u64 v[18:19], v[10:11], 0, v[0:1]
	v_add_u32_e32 v0, 0x1020, v21
	ds_read2_b32 v[12:13], v29 offset1:1
	ds_read2_b32 v[14:15], v29 offset0:2 offset1:3
	ds_read2_b32 v[64:65], v0 offset1:1
	ds_read2_b32 v[66:67], v66 offset1:1
	v_accvgpr_read_b32 v73, a219
	v_or_b32_e32 v0, s46, v73
	v_lshlrev_b32_e32 v0, 11, v0
	global_store_dwordx2 v[18:19], v[16:17], off
	s_waitcnt lgkmcnt(1)
	v_cvt_pk_bf16_f32 v64, v64, v65
	s_waitcnt lgkmcnt(0)
	v_cvt_pk_bf16_f32 v65, v66, v67
	v_lshl_add_u64 v[66:67], v[10:11], 0, v[0:1]
	v_add_u32_e32 v0, 0x2040, v21
	ds_read2_b32 v[16:17], v44 offset1:1
	ds_read2_b32 v[18:19], v44 offset0:2 offset1:3
	ds_read2_b32 v[68:69], v0 offset1:1
	ds_read2_b32 v[70:71], v70 offset1:1
	global_store_dwordx2 v[66:67], v[64:65], off
	v_add_u32_e32 v0, 0x3060, v21
	v_add_u32_e32 v66, 0x3068, v21
	ds_read2_b32 v[64:65], v0 offset1:1
	ds_read2_b32 v[66:67], v66 offset1:1
	v_accvgpr_read_b32 v74, a220
	v_or_b32_e32 v0, s46, v74
	v_lshlrev_b32_e32 v0, 11, v0
	v_accvgpr_read_b32 v75, a221
	s_waitcnt lgkmcnt(3)
	v_cvt_pk_bf16_f32 v68, v68, v69
	s_waitcnt lgkmcnt(2)
	v_cvt_pk_bf16_f32 v69, v70, v71
	v_lshl_add_u64 v[70:71], v[10:11], 0, v[0:1]
	v_or_b32_e32 v0, s46, v75
	v_lshlrev_b32_e32 v0, 11, v0
	global_store_dwordx2 v[70:71], v[68:69], off
	s_waitcnt lgkmcnt(1)
	v_cvt_pk_bf16_f32 v64, v64, v65
	s_waitcnt lgkmcnt(0)
	v_cvt_pk_bf16_f32 v65, v66, v67
	v_lshl_add_u64 v[66:67], v[10:11], 0, v[0:1]
	v_add_u32_e32 v0, 0x4080, v21
	v_add_u32_e32 v70, 0x4088, v21
	ds_read2_b32 v[68:69], v0 offset1:1
	ds_read2_b32 v[70:71], v70 offset1:1
	global_store_dwordx2 v[66:67], v[64:65], off
	v_add_u32_e32 v0, 0x50a0, v21
	v_add_u32_e32 v66, 0x50a8, v21
	ds_read2_b32 v[64:65], v0 offset1:1
	ds_read2_b32 v[66:67], v66 offset1:1
	v_or_b32_e32 v0, s46, v76
	v_lshlrev_b32_e32 v0, 11, v0
	s_waitcnt lgkmcnt(3)
	v_cvt_pk_bf16_f32 v68, v68, v69
	s_waitcnt lgkmcnt(2)
	v_cvt_pk_bf16_f32 v69, v70, v71
	v_lshl_add_u64 v[70:71], v[10:11], 0, v[0:1]
	v_or_b32_e32 v0, s46, v77
	v_lshlrev_b32_e32 v0, 11, v0
	global_store_dwordx2 v[70:71], v[68:69], off
	s_waitcnt lgkmcnt(1)
	v_cvt_pk_bf16_f32 v64, v64, v65
	s_waitcnt lgkmcnt(0)
	v_cvt_pk_bf16_f32 v65, v66, v67
	v_lshl_add_u64 v[66:67], v[10:11], 0, v[0:1]
	v_add_u32_e32 v0, 0x60c0, v21
	v_add_u32_e32 v70, 0x60c8, v21
	ds_read2_b32 v[68:69], v0 offset1:1
	ds_read2_b32 v[70:71], v70 offset1:1
	global_store_dwordx2 v[66:67], v[64:65], off
	v_add_u32_e32 v0, 0x70e0, v21
	v_add_u32_e32 v66, 0x70e8, v21
	ds_read2_b32 v[64:65], v0 offset1:1
	ds_read2_b32 v[66:67], v66 offset1:1
	v_or_b32_e32 v0, s46, v78
	v_lshlrev_b32_e32 v0, 11, v0
	s_waitcnt lgkmcnt(3)
	v_cvt_pk_bf16_f32 v68, v68, v69
	s_waitcnt lgkmcnt(2)
	v_cvt_pk_bf16_f32 v69, v70, v71
	v_lshl_add_u64 v[70:71], v[10:11], 0, v[0:1]
	v_or_b32_e32 v0, s46, v79
	v_lshlrev_b32_e32 v0, 11, v0
	global_store_dwordx2 v[70:71], v[68:69], off
	s_waitcnt lgkmcnt(1)
	v_cvt_pk_bf16_f32 v64, v64, v65
	s_waitcnt lgkmcnt(0)
	v_cvt_pk_bf16_f32 v65, v66, v67
	v_lshl_add_u64 v[66:67], v[10:11], 0, v[0:1]
	v_add_u32_e32 v0, 0x8100, v21
	v_add_u32_e32 v70, 0x8108, v21
	ds_read2_b32 v[68:69], v0 offset1:1
	ds_read2_b32 v[70:71], v70 offset1:1
	global_store_dwordx2 v[66:67], v[64:65], off
	v_add_u32_e32 v0, 0x9120, v21
	v_add_u32_e32 v66, 0x9128, v21
	ds_read2_b32 v[64:65], v0 offset1:1
	ds_read2_b32 v[66:67], v66 offset1:1
	v_or_b32_e32 v0, s46, v80
	v_lshlrev_b32_e32 v0, 11, v0
	s_waitcnt lgkmcnt(3)
	v_cvt_pk_bf16_f32 v68, v68, v69
	s_waitcnt lgkmcnt(2)
	v_cvt_pk_bf16_f32 v69, v70, v71
	v_lshl_add_u64 v[70:71], v[10:11], 0, v[0:1]
	v_or_b32_e32 v0, s46, v22
	v_lshlrev_b32_e32 v0, 11, v0
	global_store_dwordx2 v[70:71], v[68:69], off
	s_waitcnt lgkmcnt(1)
	v_cvt_pk_bf16_f32 v64, v64, v65
	s_waitcnt lgkmcnt(0)
	v_cvt_pk_bf16_f32 v65, v66, v67
	v_lshl_add_u64 v[66:67], v[10:11], 0, v[0:1]
	v_add_u32_e32 v0, 0xa140, v21
	v_add_u32_e32 v70, 0xa148, v21
	ds_read2_b32 v[68:69], v0 offset1:1
	ds_read2_b32 v[70:71], v70 offset1:1
	global_store_dwordx2 v[66:67], v[64:65], off
	v_add_u32_e32 v0, 0xb160, v21
	v_add_u32_e32 v66, 0xb168, v21
	ds_read2_b32 v[64:65], v0 offset1:1
	ds_read2_b32 v[66:67], v66 offset1:1
	v_or_b32_e32 v0, s46, v23
	v_lshlrev_b32_e32 v0, 11, v0
	s_waitcnt lgkmcnt(3)
	v_cvt_pk_bf16_f32 v68, v68, v69
	s_waitcnt lgkmcnt(2)
	v_cvt_pk_bf16_f32 v69, v70, v71
	v_lshl_add_u64 v[70:71], v[10:11], 0, v[0:1]
	v_or_b32_e32 v0, s46, v24
	v_lshlrev_b32_e32 v0, 11, v0
	global_store_dwordx2 v[70:71], v[68:69], off
	s_waitcnt lgkmcnt(1)
	v_cvt_pk_bf16_f32 v64, v64, v65
	s_waitcnt lgkmcnt(0)
	v_cvt_pk_bf16_f32 v65, v66, v67
	v_lshl_add_u64 v[66:67], v[10:11], 0, v[0:1]
	v_add_u32_e32 v0, 0xc180, v21
	v_add_u32_e32 v70, 0xc188, v21
	ds_read2_b32 v[68:69], v0 offset1:1
	ds_read2_b32 v[70:71], v70 offset1:1
	global_store_dwordx2 v[66:67], v[64:65], off
	v_add_u32_e32 v0, 0xd1a0, v21
	v_add_u32_e32 v66, 0xd1a8, v21
	ds_read2_b32 v[64:65], v0 offset1:1
	ds_read2_b32 v[66:67], v66 offset1:1
	v_or_b32_e32 v0, s46, v25
	v_lshlrev_b32_e32 v0, 11, v0
	s_waitcnt lgkmcnt(3)
	v_cvt_pk_bf16_f32 v68, v68, v69
	s_waitcnt lgkmcnt(2)
	v_cvt_pk_bf16_f32 v69, v70, v71
	v_lshl_add_u64 v[70:71], v[10:11], 0, v[0:1]
	v_or_b32_e32 v0, s46, v26
	v_lshlrev_b32_e32 v0, 11, v0
	global_store_dwordx2 v[70:71], v[68:69], off
	s_waitcnt lgkmcnt(1)
	v_cvt_pk_bf16_f32 v64, v64, v65
	s_waitcnt lgkmcnt(0)
	v_cvt_pk_bf16_f32 v65, v66, v67
	v_lshl_add_u64 v[66:67], v[10:11], 0, v[0:1]
	v_add_u32_e32 v0, 0xe1c0, v21
	v_add_u32_e32 v70, 0xe1c8, v21
	ds_read2_b32 v[68:69], v0 offset1:1
	ds_read2_b32 v[70:71], v70 offset1:1
	global_store_dwordx2 v[66:67], v[64:65], off
	v_add_u32_e32 v0, 0xf1e0, v21
	v_add_u32_e32 v66, 0xf1e8, v21
	ds_read2_b32 v[64:65], v0 offset1:1
	ds_read2_b32 v[66:67], v66 offset1:1
	v_or_b32_e32 v0, s46, v27
	v_lshlrev_b32_e32 v0, 11, v0
	s_waitcnt lgkmcnt(3)
	v_cvt_pk_bf16_f32 v68, v68, v69
	s_waitcnt lgkmcnt(2)
	v_cvt_pk_bf16_f32 v69, v70, v71
	v_lshl_add_u64 v[70:71], v[10:11], 0, v[0:1]
	v_or_b32_e32 v0, s46, v28
	v_lshlrev_b32_e32 v0, 11, v0
	s_bitset1_b32 s46, 7
	s_waitcnt lgkmcnt(1)
	v_cvt_pk_bf16_f32 v64, v64, v65
	s_waitcnt lgkmcnt(0)
	v_cvt_pk_bf16_f32 v65, v66, v67
	v_lshl_add_u64 v[66:67], v[10:11], 0, v[0:1]
	v_or_b32_e32 v0, s46, v72
	global_store_dwordx2 v[70:71], v[68:69], off
	global_store_dwordx2 v[66:67], v[64:65], off
	v_lshlrev_b32_e32 v0, 11, v0
	v_cvt_pk_bf16_f32 v12, v12, v13
	v_cvt_pk_bf16_f32 v13, v14, v15
	v_lshl_add_u64 v[14:15], v[10:11], 0, v[0:1]
	ds_read2_b32 v[64:65], v30 offset1:1
	ds_read2_b32 v[66:67], v30 offset0:2 offset1:3
	global_store_dwordx2 v[14:15], v[12:13], off
	ds_read2_b32 v[12:13], v31 offset1:1
	ds_read2_b32 v[14:15], v31 offset0:2 offset1:3
	v_or_b32_e32 v0, s46, v73
	v_lshlrev_b32_e32 v0, 11, v0
	s_waitcnt lgkmcnt(3)
	v_cvt_pk_bf16_f32 v64, v64, v65
	s_waitcnt lgkmcnt(2)
	v_cvt_pk_bf16_f32 v65, v66, v67
	v_lshl_add_u64 v[66:67], v[10:11], 0, v[0:1]
	v_or_b32_e32 v0, s46, v74
	global_store_dwordx2 v[66:67], v[64:65], off
	v_lshlrev_b32_e32 v0, 11, v0
	s_waitcnt lgkmcnt(1)
	v_cvt_pk_bf16_f32 v12, v12, v13
	s_waitcnt lgkmcnt(0)
	v_cvt_pk_bf16_f32 v13, v14, v15
	v_lshl_add_u64 v[14:15], v[10:11], 0, v[0:1]
	ds_read2_b32 v[64:65], v32 offset1:1
	ds_read2_b32 v[66:67], v32 offset0:2 offset1:3
	global_store_dwordx2 v[14:15], v[12:13], off
	ds_read2_b32 v[12:13], v33 offset1:1
	ds_read2_b32 v[14:15], v33 offset0:2 offset1:3
	v_or_b32_e32 v0, s46, v75
	v_lshlrev_b32_e32 v0, 11, v0
	s_waitcnt lgkmcnt(3)
	v_cvt_pk_bf16_f32 v64, v64, v65
	s_waitcnt lgkmcnt(2)
	v_cvt_pk_bf16_f32 v65, v66, v67
	v_lshl_add_u64 v[66:67], v[10:11], 0, v[0:1]
	v_or_b32_e32 v0, s46, v76
	global_store_dwordx2 v[66:67], v[64:65], off
	v_lshlrev_b32_e32 v0, 11, v0
	s_waitcnt lgkmcnt(1)
	v_cvt_pk_bf16_f32 v12, v12, v13
	s_waitcnt lgkmcnt(0)
	v_cvt_pk_bf16_f32 v13, v14, v15
	v_lshl_add_u64 v[14:15], v[10:11], 0, v[0:1]
	ds_read2_b32 v[64:65], v34 offset1:1
	ds_read2_b32 v[66:67], v34 offset0:2 offset1:3
	global_store_dwordx2 v[14:15], v[12:13], off
	ds_read2_b32 v[12:13], v35 offset1:1
	ds_read2_b32 v[14:15], v35 offset0:2 offset1:3
	v_or_b32_e32 v0, s46, v77
	v_lshlrev_b32_e32 v0, 11, v0
	s_waitcnt lgkmcnt(3)
	v_cvt_pk_bf16_f32 v64, v64, v65
	s_waitcnt lgkmcnt(2)
	v_cvt_pk_bf16_f32 v65, v66, v67
	v_lshl_add_u64 v[66:67], v[10:11], 0, v[0:1]
	v_or_b32_e32 v0, s46, v78
	global_store_dwordx2 v[66:67], v[64:65], off
	v_lshlrev_b32_e32 v0, 11, v0
	s_waitcnt lgkmcnt(1)
	v_cvt_pk_bf16_f32 v12, v12, v13
	s_waitcnt lgkmcnt(0)
	v_cvt_pk_bf16_f32 v13, v14, v15
	v_lshl_add_u64 v[14:15], v[10:11], 0, v[0:1]
	ds_read2_b32 v[64:65], v36 offset1:1
	ds_read2_b32 v[66:67], v36 offset0:2 offset1:3
	global_store_dwordx2 v[14:15], v[12:13], off
	ds_read2_b32 v[12:13], v37 offset1:1
	ds_read2_b32 v[14:15], v37 offset0:2 offset1:3
	v_or_b32_e32 v0, s46, v79
	v_lshlrev_b32_e32 v0, 11, v0
	s_waitcnt lgkmcnt(3)
	v_cvt_pk_bf16_f32 v64, v64, v65
	s_waitcnt lgkmcnt(2)
	v_cvt_pk_bf16_f32 v65, v66, v67
	v_lshl_add_u64 v[66:67], v[10:11], 0, v[0:1]
	v_or_b32_e32 v0, s46, v80
	global_store_dwordx2 v[66:67], v[64:65], off
	v_lshlrev_b32_e32 v0, 11, v0
	s_waitcnt lgkmcnt(1)
	v_cvt_pk_bf16_f32 v12, v12, v13
	s_waitcnt lgkmcnt(0)
	v_cvt_pk_bf16_f32 v13, v14, v15
	v_lshl_add_u64 v[14:15], v[10:11], 0, v[0:1]
	ds_read2_b32 v[64:65], v38 offset1:1
	ds_read2_b32 v[66:67], v38 offset0:2 offset1:3
	global_store_dwordx2 v[14:15], v[12:13], off
	ds_read2_b32 v[12:13], v39 offset1:1
	ds_read2_b32 v[14:15], v39 offset0:2 offset1:3
	v_or_b32_e32 v0, s46, v22
	v_lshlrev_b32_e32 v0, 11, v0
	s_waitcnt lgkmcnt(3)
	v_cvt_pk_bf16_f32 v64, v64, v65
	s_waitcnt lgkmcnt(2)
	v_cvt_pk_bf16_f32 v65, v66, v67
	v_lshl_add_u64 v[66:67], v[10:11], 0, v[0:1]
	v_or_b32_e32 v0, s46, v23
	global_store_dwordx2 v[66:67], v[64:65], off
	v_lshlrev_b32_e32 v0, 11, v0
	s_waitcnt lgkmcnt(1)
	v_cvt_pk_bf16_f32 v12, v12, v13
	s_waitcnt lgkmcnt(0)
	v_cvt_pk_bf16_f32 v13, v14, v15
	v_lshl_add_u64 v[14:15], v[10:11], 0, v[0:1]
	ds_read2_b32 v[64:65], v40 offset1:1
	ds_read2_b32 v[66:67], v40 offset0:2 offset1:3
	global_store_dwordx2 v[14:15], v[12:13], off
	ds_read2_b32 v[12:13], v41 offset1:1
	ds_read2_b32 v[14:15], v41 offset0:2 offset1:3
	v_or_b32_e32 v0, s46, v24
	v_lshlrev_b32_e32 v0, 11, v0
	s_waitcnt lgkmcnt(3)
	v_cvt_pk_bf16_f32 v64, v64, v65
	s_waitcnt lgkmcnt(2)
	v_cvt_pk_bf16_f32 v65, v66, v67
	v_lshl_add_u64 v[66:67], v[10:11], 0, v[0:1]
	v_or_b32_e32 v0, s46, v25
	v_lshlrev_b32_e32 v0, 11, v0
	global_store_dwordx2 v[66:67], v[64:65], off
	s_waitcnt lgkmcnt(1)
	v_cvt_pk_bf16_f32 v12, v12, v13
	s_waitcnt lgkmcnt(0)
	v_cvt_pk_bf16_f32 v13, v14, v15
	v_lshl_add_u64 v[14:15], v[10:11], 0, v[0:1]
	ds_read2_b32 v[64:65], v42 offset1:1
	ds_read2_b32 v[66:67], v42 offset0:2 offset1:3
	global_store_dwordx2 v[14:15], v[12:13], off
	ds_read2_b32 v[12:13], v43 offset1:1
	ds_read2_b32 v[14:15], v43 offset0:2 offset1:3
	v_add_lshl_u32 v0, s46, v26, 11
	s_waitcnt lgkmcnt(3)
	v_cvt_pk_bf16_f32 v64, v64, v65
	s_waitcnt lgkmcnt(2)
	v_cvt_pk_bf16_f32 v65, v66, v67
	v_lshl_add_u64 v[66:67], v[10:11], 0, v[0:1]
	v_add_lshl_u32 v0, s46, v27, 11
	s_waitcnt lgkmcnt(1)
	v_cvt_pk_bf16_f32 v12, v12, v13
	s_waitcnt lgkmcnt(0)
	v_cvt_pk_bf16_f32 v13, v14, v15
	v_lshl_add_u64 v[14:15], v[10:11], 0, v[0:1]
	v_add_lshl_u32 v0, s46, v28, 11
	global_store_dwordx2 v[14:15], v[12:13], off
	v_cvt_pk_bf16_f32 v12, v16, v17
	v_cvt_pk_bf16_f32 v13, v18, v19
	v_lshl_add_u64 v[10:11], v[10:11], 0, v[0:1]
	s_cmpk_lt_u32 s49, 0x60
	global_store_dwordx2 v[66:67], v[64:65], off
	global_store_dwordx2 v[10:11], v[12:13], off
	s_barrier
	s_cbranch_scc1 .LBB0_777

.LBB0_918:
	s_andn2_saveexec_b64 s[50:51], s[50:51]
	v_mul_f32_e32 v34, v33, v33
	v_fmamk_f32 v35, v34, 0xba1345e1, v139
	v_fmaak_f32 v35, v34, v35, 0xbcdac9b8
	v_fmaak_f32 v35, v34, v35, 0x3de703be
	v_fmaak_f32 v35, v34, v35, 0xbec09330
	v_fmaak_f32 v34, v34, v35, 0x3e0375d0
	v_fma_f32 v34, |v33|, v34, |v33|
	s_or_b64 exec, exec, s[50:51]
	v_cvt_scalef32_pk_f32_fp4 v[36:37], v204, 1.0
	v_pk_fma_f32 v[36:37], s[30:31], v[36:37], v[200:201] op_sel_hi:[0,1,1]
	v_cvt_scalef32_pk_f32_fp4 v[38:39], v204, 1.0 op_sel:[1,0,0]
	v_cvt_scalef32_pk_f32_fp4 v[52:53], v202, 1.0
	v_pk_fma_f32 v[38:39], s[30:31], v[38:39], v[218:219] op_sel_hi:[0,1,1]
	v_cvt_scalef32_pk_f32_fp4 v[40:41], v204, 1.0 op_sel:[0,1,0]
	v_pk_fma_f32 v[36:37], s[28:29], v[52:53], v[36:37] op_sel_hi:[0,1,1]
	v_cvt_scalef32_pk_f32_fp4 v[52:53], v202, 1.0 op_sel:[1,0,0]
	v_pk_fma_f32 v[40:41], s[30:31], v[40:41], v[216:217] op_sel_hi:[0,1,1]
	v_cvt_scalef32_pk_f32_fp4 v[42:43], v204, 1.0 op_sel:[1,1,0]
	v_pk_fma_f32 v[38:39], s[28:29], v[52:53], v[38:39] op_sel_hi:[0,1,1]
	v_cvt_scalef32_pk_f32_fp4 v[52:53], v202, 1.0 op_sel:[0,1,0]
	v_pk_fma_f32 v[42:43], s[30:31], v[42:43], v[214:215] op_sel_hi:[0,1,1]
	v_cvt_scalef32_pk_f32_fp4 v[44:45], v205, 1.0
	v_pk_fma_f32 v[40:41], s[28:29], v[52:53], v[40:41] op_sel_hi:[0,1,1]
	v_cvt_scalef32_pk_f32_fp4 v[52:53], v202, 1.0 op_sel:[1,1,0]
	v_pk_fma_f32 v[44:45], s[30:31], v[44:45], v[212:213] op_sel_hi:[0,1,1]
	v_cvt_scalef32_pk_f32_fp4 v[46:47], v205, 1.0 op_sel:[1,0,0]
	v_pk_fma_f32 v[42:43], s[28:29], v[52:53], v[42:43] op_sel_hi:[0,1,1]
	v_cvt_scalef32_pk_f32_fp4 v[52:53], v203, 1.0
	v_pk_fma_f32 v[46:47], s[30:31], v[46:47], v[210:211] op_sel_hi:[0,1,1]
	v_cvt_scalef32_pk_f32_fp4 v[48:49], v205, 1.0 op_sel:[0,1,0]
	v_pk_fma_f32 v[44:45], s[28:29], v[52:53], v[44:45] op_sel_hi:[0,1,1]
	v_cvt_scalef32_pk_f32_fp4 v[52:53], v203, 1.0 op_sel:[1,0,0]
	v_pk_fma_f32 v[48:49], s[30:31], v[48:49], v[208:209] op_sel_hi:[0,1,1]
	v_cvt_scalef32_pk_f32_fp4 v[50:51], v205, 1.0 op_sel:[1,1,0]
	v_pk_fma_f32 v[46:47], s[28:29], v[52:53], v[46:47] op_sel_hi:[0,1,1]
	v_cvt_scalef32_pk_f32_fp4 v[52:53], v203, 1.0 op_sel:[0,1,0]
	v_pk_fma_f32 v[50:51], s[30:31], v[50:51], v[206:207] op_sel_hi:[0,1,1]
	v_pk_fma_f32 v[48:49], s[28:29], v[52:53], v[48:49] op_sel_hi:[0,1,1]
	v_cvt_scalef32_pk_f32_fp4 v[52:53], v203, 1.0 op_sel:[1,1,0]
	v_pk_fma_f32 v[50:51], s[28:29], v[52:53], v[50:51] op_sel_hi:[0,1,1]
	v_cvt_scalef32_pk_f32_fp4 v[52:53], v198, 1.0
	v_pk_fma_f32 v[36:37], s[26:27], v[52:53], v[36:37] op_sel_hi:[0,1,1]
	v_cvt_scalef32_pk_f32_fp4 v[52:53], v198, 1.0 op_sel:[1,0,0]
	v_pk_fma_f32 v[38:39], s[26:27], v[52:53], v[38:39] op_sel_hi:[0,1,1]
	v_cvt_scalef32_pk_f32_fp4 v[52:53], v198, 1.0 op_sel:[0,1,0]
	v_pk_fma_f32 v[40:41], s[26:27], v[52:53], v[40:41] op_sel_hi:[0,1,1]
	v_cvt_scalef32_pk_f32_fp4 v[52:53], v198, 1.0 op_sel:[1,1,0]
	v_pk_fma_f32 v[42:43], s[26:27], v[52:53], v[42:43] op_sel_hi:[0,1,1]
	v_cvt_scalef32_pk_f32_fp4 v[52:53], v199, 1.0
	v_pk_fma_f32 v[44:45], s[26:27], v[52:53], v[44:45] op_sel_hi:[0,1,1]
	v_cvt_scalef32_pk_f32_fp4 v[52:53], v199, 1.0 op_sel:[1,0,0]
	v_pk_fma_f32 v[46:47], s[26:27], v[52:53], v[46:47] op_sel_hi:[0,1,1]
	v_cvt_scalef32_pk_f32_fp4 v[52:53], v199, 1.0 op_sel:[0,1,0]
	v_pk_fma_f32 v[48:49], s[26:27], v[52:53], v[48:49] op_sel_hi:[0,1,1]
	v_cvt_scalef32_pk_f32_fp4 v[52:53], v199, 1.0 op_sel:[1,1,0]
	v_pk_fma_f32 v[50:51], s[26:27], v[52:53], v[50:51] op_sel_hi:[0,1,1]
	v_cvt_scalef32_pk_f32_fp4 v[52:53], v196, 1.0
	v_pk_fma_f32 v[36:37], s[10:11], v[52:53], v[36:37] op_sel_hi:[0,1,1]
	v_cvt_scalef32_pk_f32_fp4 v[52:53], v196, 1.0 op_sel:[1,0,0]
	v_pk_fma_f32 v[38:39], s[10:11], v[52:53], v[38:39] op_sel_hi:[0,1,1]
	v_cvt_scalef32_pk_f32_fp4 v[52:53], v196, 1.0 op_sel:[0,1,0]
	v_pk_fma_f32 v[40:41], s[10:11], v[52:53], v[40:41] op_sel_hi:[0,1,1]
	v_cvt_scalef32_pk_f32_fp4 v[52:53], v196, 1.0 op_sel:[1,1,0]
	v_pk_fma_f32 v[42:43], s[10:11], v[52:53], v[42:43] op_sel_hi:[0,1,1]
	v_cvt_scalef32_pk_f32_fp4 v[52:53], v197, 1.0
	v_pk_fma_f32 v[44:45], s[10:11], v[52:53], v[44:45] op_sel_hi:[0,1,1]
	v_cvt_scalef32_pk_f32_fp4 v[52:53], v197, 1.0 op_sel:[1,0,0]
	v_pk_fma_f32 v[46:47], s[10:11], v[52:53], v[46:47] op_sel_hi:[0,1,1]
	v_cvt_scalef32_pk_f32_fp4 v[52:53], v197, 1.0 op_sel:[0,1,0]
	v_pk_fma_f32 v[48:49], s[10:11], v[52:53], v[48:49] op_sel_hi:[0,1,1]
	v_cvt_scalef32_pk_f32_fp4 v[52:53], v197, 1.0 op_sel:[1,1,0]
	v_pk_fma_f32 v[50:51], s[10:11], v[52:53], v[50:51] op_sel_hi:[0,1,1]
	v_cvt_scalef32_pk_f32_fp4 v[52:53], v194, 1.0
	v_pk_fma_f32 v[36:37], s[40:41], v[52:53], v[36:37] op_sel_hi:[0,1,1]
	v_cvt_scalef32_pk_f32_fp4 v[52:53], v194, 1.0 op_sel:[1,0,0]
	v_pk_fma_f32 v[38:39], s[40:41], v[52:53], v[38:39] op_sel_hi:[0,1,1]
	v_cvt_scalef32_pk_f32_fp4 v[52:53], v194, 1.0 op_sel:[0,1,0]
	v_pk_fma_f32 v[40:41], s[40:41], v[52:53], v[40:41] op_sel_hi:[0,1,1]
	v_cvt_scalef32_pk_f32_fp4 v[52:53], v194, 1.0 op_sel:[1,1,0]
	v_pk_fma_f32 v[42:43], s[40:41], v[52:53], v[42:43] op_sel_hi:[0,1,1]
	v_cvt_scalef32_pk_f32_fp4 v[52:53], v195, 1.0
	v_pk_fma_f32 v[44:45], s[40:41], v[52:53], v[44:45] op_sel_hi:[0,1,1]
	v_cvt_scalef32_pk_f32_fp4 v[52:53], v195, 1.0 op_sel:[1,0,0]
	v_pk_fma_f32 v[46:47], s[40:41], v[52:53], v[46:47] op_sel_hi:[0,1,1]
	v_cvt_scalef32_pk_f32_fp4 v[52:53], v195, 1.0 op_sel:[0,1,0]
	v_pk_fma_f32 v[48:49], s[40:41], v[52:53], v[48:49] op_sel_hi:[0,1,1]
	v_cvt_scalef32_pk_f32_fp4 v[52:53], v195, 1.0 op_sel:[1,1,0]
	v_pk_fma_f32 v[50:51], s[40:41], v[52:53], v[50:51] op_sel_hi:[0,1,1]
	v_cvt_scalef32_pk_f32_fp4 v[52:53], v192, 1.0
	v_pk_fma_f32 v[36:37], s[38:39], v[52:53], v[36:37] op_sel_hi:[0,1,1]
	v_cvt_scalef32_pk_f32_fp4 v[52:53], v192, 1.0 op_sel:[1,0,0]
	v_pk_fma_f32 v[38:39], s[38:39], v[52:53], v[38:39] op_sel_hi:[0,1,1]
	v_cvt_scalef32_pk_f32_fp4 v[52:53], v192, 1.0 op_sel:[0,1,0]
	v_pk_fma_f32 v[40:41], s[38:39], v[52:53], v[40:41] op_sel_hi:[0,1,1]
	v_cvt_scalef32_pk_f32_fp4 v[52:53], v192, 1.0 op_sel:[1,1,0]
	v_pk_fma_f32 v[42:43], s[38:39], v[52:53], v[42:43] op_sel_hi:[0,1,1]
	v_cvt_scalef32_pk_f32_fp4 v[52:53], v193, 1.0
	v_pk_fma_f32 v[44:45], s[38:39], v[52:53], v[44:45] op_sel_hi:[0,1,1]
	v_cvt_scalef32_pk_f32_fp4 v[52:53], v193, 1.0 op_sel:[1,0,0]
	v_pk_fma_f32 v[46:47], s[38:39], v[52:53], v[46:47] op_sel_hi:[0,1,1]
	v_cvt_scalef32_pk_f32_fp4 v[52:53], v193, 1.0 op_sel:[0,1,0]
	v_pk_fma_f32 v[48:49], s[38:39], v[52:53], v[48:49] op_sel_hi:[0,1,1]
	v_cvt_scalef32_pk_f32_fp4 v[52:53], v193, 1.0 op_sel:[1,1,0]
	v_pk_fma_f32 v[50:51], s[38:39], v[52:53], v[50:51] op_sel_hi:[0,1,1]
	v_cvt_scalef32_pk_f32_fp4 v[52:53], v190, 1.0
	v_pk_fma_f32 v[36:37], s[36:37], v[52:53], v[36:37] op_sel_hi:[0,1,1]
	v_cvt_scalef32_pk_f32_fp4 v[52:53], v190, 1.0 op_sel:[1,0,0]
	v_pk_fma_f32 v[38:39], s[36:37], v[52:53], v[38:39] op_sel_hi:[0,1,1]
	v_cvt_scalef32_pk_f32_fp4 v[52:53], v190, 1.0 op_sel:[0,1,0]
	v_pk_fma_f32 v[40:41], s[36:37], v[52:53], v[40:41] op_sel_hi:[0,1,1]
	v_cvt_scalef32_pk_f32_fp4 v[52:53], v190, 1.0 op_sel:[1,1,0]
	v_pk_fma_f32 v[42:43], s[36:37], v[52:53], v[42:43] op_sel_hi:[0,1,1]
	v_cvt_scalef32_pk_f32_fp4 v[52:53], v191, 1.0
	v_pk_fma_f32 v[44:45], s[36:37], v[52:53], v[44:45] op_sel_hi:[0,1,1]
	v_cvt_scalef32_pk_f32_fp4 v[52:53], v191, 1.0 op_sel:[1,0,0]
	v_pk_fma_f32 v[46:47], s[36:37], v[52:53], v[46:47] op_sel_hi:[0,1,1]
	v_cvt_scalef32_pk_f32_fp4 v[52:53], v191, 1.0 op_sel:[0,1,0]
	v_pk_fma_f32 v[48:49], s[36:37], v[52:53], v[48:49] op_sel_hi:[0,1,1]
	v_cvt_scalef32_pk_f32_fp4 v[52:53], v191, 1.0 op_sel:[1,1,0]
	v_pk_fma_f32 v[50:51], s[36:37], v[52:53], v[50:51] op_sel_hi:[0,1,1]
	v_cvt_scalef32_pk_f32_fp4 v[52:53], v188, 1.0
	v_pk_fma_f32 v[36:37], s[34:35], v[52:53], v[36:37] op_sel_hi:[0,1,1]
	v_cvt_scalef32_pk_f32_fp4 v[52:53], v188, 1.0 op_sel:[1,0,0]
	v_pk_fma_f32 v[38:39], s[34:35], v[52:53], v[38:39] op_sel_hi:[0,1,1]
	v_cvt_scalef32_pk_f32_fp4 v[52:53], v188, 1.0 op_sel:[0,1,0]
	v_pk_fma_f32 v[40:41], s[34:35], v[52:53], v[40:41] op_sel_hi:[0,1,1]
	v_cvt_scalef32_pk_f32_fp4 v[52:53], v188, 1.0 op_sel:[1,1,0]
	v_pk_fma_f32 v[42:43], s[34:35], v[52:53], v[42:43] op_sel_hi:[0,1,1]
	v_cvt_scalef32_pk_f32_fp4 v[52:53], v189, 1.0
	v_pk_fma_f32 v[44:45], s[34:35], v[52:53], v[44:45] op_sel_hi:[0,1,1]
	v_cvt_scalef32_pk_f32_fp4 v[52:53], v189, 1.0 op_sel:[1,0,0]
	v_pk_fma_f32 v[46:47], s[34:35], v[52:53], v[46:47] op_sel_hi:[0,1,1]
	v_cvt_scalef32_pk_f32_fp4 v[52:53], v189, 1.0 op_sel:[0,1,0]
	v_pk_fma_f32 v[48:49], s[34:35], v[52:53], v[48:49] op_sel_hi:[0,1,1]
	v_cvt_scalef32_pk_f32_fp4 v[52:53], v189, 1.0 op_sel:[1,1,0]
	v_pk_fma_f32 v[50:51], s[34:35], v[52:53], v[50:51] op_sel_hi:[0,1,1]
	v_cvt_scalef32_pk_f32_fp4 v[52:53], v186, 1.0
	v_pk_fma_f32 v[36:37], s[48:49], v[52:53], v[36:37] op_sel_hi:[0,1,1]
	v_cvt_scalef32_pk_f32_fp4 v[52:53], v186, 1.0 op_sel:[1,0,0]
	v_pk_fma_f32 v[38:39], s[48:49], v[52:53], v[38:39] op_sel_hi:[0,1,1]
	v_cvt_scalef32_pk_f32_fp4 v[52:53], v186, 1.0 op_sel:[0,1,0]
	v_pk_fma_f32 v[40:41], s[48:49], v[52:53], v[40:41] op_sel_hi:[0,1,1]
	v_cvt_scalef32_pk_f32_fp4 v[52:53], v186, 1.0 op_sel:[1,1,0]
	v_pk_fma_f32 v[42:43], s[48:49], v[52:53], v[42:43] op_sel_hi:[0,1,1]
	v_cvt_scalef32_pk_f32_fp4 v[52:53], v187, 1.0
	v_pk_fma_f32 v[44:45], s[48:49], v[52:53], v[44:45] op_sel_hi:[0,1,1]
	v_cvt_scalef32_pk_f32_fp4 v[52:53], v187, 1.0 op_sel:[1,0,0]
	v_pk_fma_f32 v[46:47], s[48:49], v[52:53], v[46:47] op_sel_hi:[0,1,1]
	v_cvt_scalef32_pk_f32_fp4 v[52:53], v187, 1.0 op_sel:[0,1,0]
	v_pk_fma_f32 v[48:49], s[48:49], v[52:53], v[48:49] op_sel_hi:[0,1,1]
	v_cvt_scalef32_pk_f32_fp4 v[52:53], v187, 1.0 op_sel:[1,1,0]
	v_pk_fma_f32 v[50:51], s[48:49], v[52:53], v[50:51] op_sel_hi:[0,1,1]
	v_cvt_scalef32_pk_f32_fp4 v[52:53], v184, 1.0
	v_pk_fma_f32 v[36:37], s[46:47], v[52:53], v[36:37] op_sel_hi:[0,1,1]
	v_cvt_scalef32_pk_f32_fp4 v[52:53], v184, 1.0 op_sel:[1,0,0]
	v_pk_fma_f32 v[38:39], s[46:47], v[52:53], v[38:39] op_sel_hi:[0,1,1]
	v_cvt_scalef32_pk_f32_fp4 v[52:53], v184, 1.0 op_sel:[0,1,0]
	v_pk_fma_f32 v[40:41], s[46:47], v[52:53], v[40:41] op_sel_hi:[0,1,1]
	v_cvt_scalef32_pk_f32_fp4 v[52:53], v184, 1.0 op_sel:[1,1,0]
	v_pk_fma_f32 v[42:43], s[46:47], v[52:53], v[42:43] op_sel_hi:[0,1,1]
	v_cvt_scalef32_pk_f32_fp4 v[52:53], v185, 1.0
	v_pk_fma_f32 v[44:45], s[46:47], v[52:53], v[44:45] op_sel_hi:[0,1,1]
	v_cvt_scalef32_pk_f32_fp4 v[52:53], v185, 1.0 op_sel:[1,0,0]
	v_pk_fma_f32 v[46:47], s[46:47], v[52:53], v[46:47] op_sel_hi:[0,1,1]
	v_cvt_scalef32_pk_f32_fp4 v[52:53], v185, 1.0 op_sel:[0,1,0]
	v_pk_fma_f32 v[48:49], s[46:47], v[52:53], v[48:49] op_sel_hi:[0,1,1]
	v_cvt_scalef32_pk_f32_fp4 v[52:53], v185, 1.0 op_sel:[1,1,0]
	v_pk_fma_f32 v[50:51], s[46:47], v[52:53], v[50:51] op_sel_hi:[0,1,1]
	v_cvt_scalef32_pk_f32_fp4 v[52:53], v182, 1.0
	v_pk_fma_f32 v[36:37], s[44:45], v[52:53], v[36:37] op_sel_hi:[0,1,1]
	v_cvt_scalef32_pk_f32_fp4 v[52:53], v182, 1.0 op_sel:[1,0,0]
	v_pk_fma_f32 v[38:39], s[44:45], v[52:53], v[38:39] op_sel_hi:[0,1,1]
	v_cvt_scalef32_pk_f32_fp4 v[52:53], v182, 1.0 op_sel:[0,1,0]
	v_pk_fma_f32 v[40:41], s[44:45], v[52:53], v[40:41] op_sel_hi:[0,1,1]
	v_cvt_scalef32_pk_f32_fp4 v[52:53], v182, 1.0 op_sel:[1,1,0]
	v_pk_fma_f32 v[42:43], s[44:45], v[52:53], v[42:43] op_sel_hi:[0,1,1]
	v_cvt_scalef32_pk_f32_fp4 v[52:53], v183, 1.0
	v_pk_fma_f32 v[44:45], s[44:45], v[52:53], v[44:45] op_sel_hi:[0,1,1]
	v_cvt_scalef32_pk_f32_fp4 v[52:53], v183, 1.0 op_sel:[1,0,0]
	v_pk_fma_f32 v[46:47], s[44:45], v[52:53], v[46:47] op_sel_hi:[0,1,1]
	v_cvt_scalef32_pk_f32_fp4 v[52:53], v183, 1.0 op_sel:[0,1,0]
	v_pk_fma_f32 v[48:49], s[44:45], v[52:53], v[48:49] op_sel_hi:[0,1,1]
	v_cvt_scalef32_pk_f32_fp4 v[52:53], v183, 1.0 op_sel:[1,1,0]
	v_pk_fma_f32 v[50:51], s[44:45], v[52:53], v[50:51] op_sel_hi:[0,1,1]
	v_cvt_scalef32_pk_f32_fp4 v[52:53], v180, 1.0
	v_pk_fma_f32 v[36:37], s[42:43], v[52:53], v[36:37] op_sel_hi:[0,1,1]
	v_cvt_scalef32_pk_f32_fp4 v[52:53], v180, 1.0 op_sel:[1,0,0]
	v_pk_fma_f32 v[38:39], s[42:43], v[52:53], v[38:39] op_sel_hi:[0,1,1]
	v_cvt_scalef32_pk_f32_fp4 v[52:53], v180, 1.0 op_sel:[0,1,0]
	v_pk_fma_f32 v[40:41], s[42:43], v[52:53], v[40:41] op_sel_hi:[0,1,1]
	v_cvt_scalef32_pk_f32_fp4 v[52:53], v180, 1.0 op_sel:[1,1,0]
	v_pk_fma_f32 v[42:43], s[42:43], v[52:53], v[42:43] op_sel_hi:[0,1,1]
	v_cvt_scalef32_pk_f32_fp4 v[52:53], v181, 1.0
	v_pk_fma_f32 v[44:45], s[42:43], v[52:53], v[44:45] op_sel_hi:[0,1,1]
	v_cvt_scalef32_pk_f32_fp4 v[52:53], v181, 1.0 op_sel:[1,0,0]
	v_pk_fma_f32 v[46:47], s[42:43], v[52:53], v[46:47] op_sel_hi:[0,1,1]
	v_cvt_scalef32_pk_f32_fp4 v[52:53], v181, 1.0 op_sel:[0,1,0]
	v_pk_fma_f32 v[48:49], s[42:43], v[52:53], v[48:49] op_sel_hi:[0,1,1]
	v_cvt_scalef32_pk_f32_fp4 v[52:53], v181, 1.0 op_sel:[1,1,0]
	v_pk_fma_f32 v[50:51], s[42:43], v[52:53], v[50:51] op_sel_hi:[0,1,1]
	v_mov_b32_e32 v35, s59
	v_mov_b32_e32 v52, s35
	v_cndmask_b32_e64 v35, v35, v52, s[8:9]
	v_mov_b32_e32 v52, s43
	v_bfi_b32 v33, s55, v34, v33
	v_cndmask_b32_e64 v35, v35, v52, s[6:7]
	v_mov_b32_e32 v52, s11
	v_mul_f32_e32 v32, 0.5, v32
	v_add_f32_e32 v33, 1.0, v33
	v_cndmask_b32_e64 v35, v35, v52, s[4:5]
	v_mul_f32_e32 v32, v32, v33
	v_mul_f32_e32 v32, v35, v32
	v_cvt_scalef32_pk_f32_fp4 v[34:35], v178, 1.0 op_sel:[1,0,0]
	v_readlane_b32 s10, v32, 0
	v_readlane_b32 s26, v32, 32
	v_readlane_b32 s28, v32, 16
	v_readlane_b32 s30, v32, 48
	v_cvt_scalef32_pk_f32_fp4 v[32:33], v178, 1.0
	v_pk_fma_f32 v[32:33], s[10:11], v[32:33], v[36:37] op_sel_hi:[0,1,1]
	v_cvt_scalef32_pk_f32_fp4 v[36:37], v178, 1.0 op_sel:[0,1,0]
	v_pk_fma_f32 v[36:37], s[10:11], v[36:37], v[40:41] op_sel_hi:[0,1,1]
	v_cvt_scalef32_pk_f32_fp4 v[40:41], v179, 1.0
	v_pk_fma_f32 v[40:41], s[10:11], v[40:41], v[44:45] op_sel_hi:[0,1,1]
	v_cvt_scalef32_pk_f32_fp4 v[44:45], v179, 1.0 op_sel:[0,1,0]
	v_pk_fma_f32 v[44:45], s[10:11], v[44:45], v[48:49] op_sel_hi:[0,1,1]
	v_cvt_scalef32_pk_f32_fp4 v[48:49], v176, 1.0
	v_pk_fma_f32 v[34:35], s[10:11], v[34:35], v[38:39] op_sel_hi:[0,1,1]
	v_pk_fma_f32 v[32:33], s[26:27], v[48:49], v[32:33] op_sel_hi:[0,1,1]
	v_cvt_scalef32_pk_f32_fp4 v[48:49], v176, 1.0 op_sel:[1,0,0]
	v_cvt_scalef32_pk_f32_fp4 v[38:39], v178, 1.0 op_sel:[1,1,0]
	v_pk_fma_f32 v[34:35], s[26:27], v[48:49], v[34:35] op_sel_hi:[0,1,1]
	v_cvt_scalef32_pk_f32_fp4 v[48:49], v176, 1.0 op_sel:[0,1,0]
	v_pk_fma_f32 v[38:39], s[10:11], v[38:39], v[42:43] op_sel_hi:[0,1,1]
	v_pk_fma_f32 v[36:37], s[26:27], v[48:49], v[36:37] op_sel_hi:[0,1,1]
	v_cvt_scalef32_pk_f32_fp4 v[48:49], v176, 1.0 op_sel:[1,1,0]
	v_cvt_scalef32_pk_f32_fp4 v[42:43], v179, 1.0 op_sel:[1,0,0]
	v_pk_fma_f32 v[38:39], s[26:27], v[48:49], v[38:39] op_sel_hi:[0,1,1]
	v_cvt_scalef32_pk_f32_fp4 v[48:49], v177, 1.0
	v_pk_fma_f32 v[42:43], s[10:11], v[42:43], v[46:47] op_sel_hi:[0,1,1]
	v_pk_fma_f32 v[40:41], s[26:27], v[48:49], v[40:41] op_sel_hi:[0,1,1]
	v_cvt_scalef32_pk_f32_fp4 v[48:49], v177, 1.0 op_sel:[1,0,0]
	v_cvt_scalef32_pk_f32_fp4 v[46:47], v179, 1.0 op_sel:[1,1,0]
	v_pk_fma_f32 v[42:43], s[26:27], v[48:49], v[42:43] op_sel_hi:[0,1,1]
	v_cvt_scalef32_pk_f32_fp4 v[48:49], v177, 1.0 op_sel:[0,1,0]
	v_pk_fma_f32 v[46:47], s[10:11], v[46:47], v[50:51] op_sel_hi:[0,1,1]
	v_pk_fma_f32 v[44:45], s[26:27], v[48:49], v[44:45] op_sel_hi:[0,1,1]
	v_cvt_scalef32_pk_f32_fp4 v[48:49], v177, 1.0 op_sel:[1,1,0]
	v_pk_fma_f32 v[46:47], s[26:27], v[48:49], v[46:47] op_sel_hi:[0,1,1]
	v_cvt_scalef32_pk_f32_fp4 v[48:49], v174, 1.0
	v_pk_fma_f32 v[32:33], s[28:29], v[48:49], v[32:33] op_sel_hi:[0,1,1]
	v_cvt_scalef32_pk_f32_fp4 v[48:49], v174, 1.0 op_sel:[1,0,0]
	v_pk_fma_f32 v[34:35], s[28:29], v[48:49], v[34:35] op_sel_hi:[0,1,1]
	v_cvt_scalef32_pk_f32_fp4 v[48:49], v174, 1.0 op_sel:[0,1,0]
	v_pk_fma_f32 v[36:37], s[28:29], v[48:49], v[36:37] op_sel_hi:[0,1,1]
	v_cvt_scalef32_pk_f32_fp4 v[48:49], v174, 1.0 op_sel:[1,1,0]
	v_pk_fma_f32 v[38:39], s[28:29], v[48:49], v[38:39] op_sel_hi:[0,1,1]
	v_cvt_scalef32_pk_f32_fp4 v[48:49], v175, 1.0
	v_pk_fma_f32 v[40:41], s[28:29], v[48:49], v[40:41] op_sel_hi:[0,1,1]
	v_cvt_scalef32_pk_f32_fp4 v[48:49], v175, 1.0 op_sel:[1,0,0]
	v_pk_fma_f32 v[42:43], s[28:29], v[48:49], v[42:43] op_sel_hi:[0,1,1]
	v_cvt_scalef32_pk_f32_fp4 v[48:49], v175, 1.0 op_sel:[0,1,0]
	v_pk_fma_f32 v[44:45], s[28:29], v[48:49], v[44:45] op_sel_hi:[0,1,1]
	v_cvt_scalef32_pk_f32_fp4 v[48:49], v175, 1.0 op_sel:[1,1,0]
	v_pk_fma_f32 v[46:47], s[28:29], v[48:49], v[46:47] op_sel_hi:[0,1,1]
	v_cvt_scalef32_pk_f32_fp4 v[48:49], v172, 1.0
	v_pk_fma_f32 v[200:201], s[30:31], v[48:49], v[32:33] op_sel_hi:[0,1,1]
	v_cvt_scalef32_pk_f32_fp4 v[32:33], v172, 1.0 op_sel:[1,0,0]
	v_pk_fma_f32 v[218:219], s[30:31], v[32:33], v[34:35] op_sel_hi:[0,1,1]
	v_cvt_scalef32_pk_f32_fp4 v[32:33], v172, 1.0 op_sel:[0,1,0]
	v_pk_fma_f32 v[216:217], s[30:31], v[32:33], v[36:37] op_sel_hi:[0,1,1]
	v_cvt_scalef32_pk_f32_fp4 v[32:33], v172, 1.0 op_sel:[1,1,0]
	v_pk_fma_f32 v[214:215], s[30:31], v[32:33], v[38:39] op_sel_hi:[0,1,1]
	v_cvt_scalef32_pk_f32_fp4 v[32:33], v173, 1.0
	v_pk_fma_f32 v[212:213], s[30:31], v[32:33], v[40:41] op_sel_hi:[0,1,1]
	v_cvt_scalef32_pk_f32_fp4 v[32:33], v173, 1.0 op_sel:[1,0,0]
	v_pk_fma_f32 v[210:211], s[30:31], v[32:33], v[42:43] op_sel_hi:[0,1,1]
	v_cvt_scalef32_pk_f32_fp4 v[32:33], v173, 1.0 op_sel:[0,1,0]
	v_pk_fma_f32 v[208:209], s[30:31], v[32:33], v[44:45] op_sel_hi:[0,1,1]
	v_cvt_scalef32_pk_f32_fp4 v[32:33], v173, 1.0 op_sel:[1,1,0]
	v_pk_fma_f32 v[206:207], s[30:31], v[32:33], v[46:47] op_sel_hi:[0,1,1]
	s_and_b64 vcc, exec, s[24:25]
	s_cbranch_vccnz .LBB0_900
	s_mov_b32 s26, s58
	s_add_i32 s58, s26, 16
	s_cmpk_gt_u32 s26, 0x6f
	s_cselect_b64 s[24:25], -1, 0
	s_cmpk_lt_u32 s26, 0x70
	s_cselect_b64 vcc, -1, 0
	s_bitcmp0_b32 s58, 6
	s_cselect_b64 s[10:11], -1, 0
	v_cndmask_b32_e64 v100, v116, v102, s[10:11]
	v_cndmask_b32_e32 v100, v118, v100, vcc
	s_nop 0
	s_waitcnt vmcnt(24)
	v_accvgpr_read_b32 v205, a43
	v_accvgpr_read_b32 v203, a45
	v_accvgpr_read_b32 v199, a47
	v_accvgpr_read_b32 v197, a49
	v_accvgpr_read_b32 v95, a23
	v_accvgpr_read_b32 v91, a27
	v_accvgpr_read_b32 v87, a31
	v_mov_b64_e32 v[80:81], v[232:233]
	v_accvgpr_read_b32 v204, a42
	v_accvgpr_read_b32 v202, a44
	v_accvgpr_read_b32 v198, a46
	v_accvgpr_read_b32 v196, a48
	v_accvgpr_read_b32 v94, a22
	v_accvgpr_read_b32 v93, a21
	v_accvgpr_read_b32 v92, a20
	v_accvgpr_read_b32 v90, a26
	v_accvgpr_read_b32 v89, a25
	v_accvgpr_read_b32 v88, a24
	v_accvgpr_read_b32 v86, a30
	v_accvgpr_read_b32 v85, a29
	v_accvgpr_read_b32 v84, a28
	v_mov_b64_e32 v[82:83], v[234:235]
	s_add_i32 s30, s26, 16
	v_readlane_b32 s28, v100, s30
	s_nop 1
	v_mad_i64_i32 v[136:137], s[10:11], s28, v130, v[96:97]
	global_load_dwordx4 a[20:23], v[136:137], off
	v_mad_i64_i32 v[136:137], s[10:11], s28, v130, v[98:99]
	global_load_dwordx2 a[42:43], v[136:137], off
	s_add_i32 s30, s26, 17
	v_readlane_b32 s28, v100, s30
	s_nop 1
	v_mad_i64_i32 v[136:137], s[10:11], s28, v130, v[96:97]
	global_load_dwordx4 a[24:27], v[136:137], off
	v_mad_i64_i32 v[136:137], s[10:11], s28, v130, v[98:99]
	global_load_dwordx2 a[44:45], v[136:137], off
	s_add_i32 s30, s26, 18
	v_readlane_b32 s28, v100, s30
	s_nop 1
	v_mad_i64_i32 v[136:137], s[10:11], s28, v130, v[96:97]
	global_load_dwordx4 a[28:31], v[136:137], off
	v_mad_i64_i32 v[136:137], s[10:11], s28, v130, v[98:99]
	global_load_dwordx2 a[46:47], v[136:137], off
	s_add_i32 s30, s26, 19
	v_readlane_b32 s28, v100, s30
	s_nop 1
	v_mad_i64_i32 v[136:137], s[10:11], s28, v130, v[96:97]
	global_load_dwordx4 v[232:235], v[136:137], off
	v_mad_i64_i32 v[136:137], s[10:11], s28, v130, v[98:99]
	global_load_dwordx2 a[48:49], v[136:137], off
	s_waitcnt vmcnt(24)
	v_accvgpr_read_b32 v195, a51
	v_accvgpr_read_b32 v193, a53
	v_accvgpr_read_b32 v191, a55
	v_accvgpr_read_b32 v189, a57
	v_mov_b64_e32 v[76:77], v[236:237]
	v_mov_b64_e32 v[72:73], v[240:241]
	v_mov_b64_e32 v[68:69], v[244:245]
	v_mov_b64_e32 v[64:65], v[248:249]
	v_accvgpr_read_b32 v194, a50
	v_accvgpr_read_b32 v192, a52
	v_accvgpr_read_b32 v190, a54
	v_accvgpr_read_b32 v188, a56
	v_mov_b64_e32 v[78:79], v[238:239]
	v_mov_b64_e32 v[74:75], v[242:243]
	v_mov_b64_e32 v[70:71], v[246:247]
	v_mov_b64_e32 v[66:67], v[250:251]
	s_add_i32 s30, s26, 20
	v_readlane_b32 s28, v100, s30
	s_nop 1
	v_mad_i64_i32 v[136:137], s[10:11], s28, v130, v[96:97]
	global_load_dwordx4 v[236:239], v[136:137], off
	v_mad_i64_i32 v[136:137], s[10:11], s28, v130, v[98:99]
	global_load_dwordx2 a[50:51], v[136:137], off
	s_add_i32 s30, s26, 21
	v_readlane_b32 s28, v100, s30
	s_nop 1
	v_mad_i64_i32 v[136:137], s[10:11], s28, v130, v[96:97]
	global_load_dwordx4 v[240:243], v[136:137], off
	v_mad_i64_i32 v[136:137], s[10:11], s28, v130, v[98:99]
	global_load_dwordx2 a[52:53], v[136:137], off
	s_add_i32 s30, s26, 22
	v_readlane_b32 s28, v100, s30
	s_nop 1
	v_mad_i64_i32 v[136:137], s[10:11], s28, v130, v[96:97]
	global_load_dwordx4 v[244:247], v[136:137], off
	v_mad_i64_i32 v[136:137], s[10:11], s28, v130, v[98:99]
	global_load_dwordx2 a[54:55], v[136:137], off
	s_add_i32 s30, s26, 23
	v_readlane_b32 s28, v100, s30
	s_nop 1
	v_mad_i64_i32 v[136:137], s[10:11], s28, v130, v[96:97]
	global_load_dwordx4 v[248:251], v[136:137], off
	v_mad_i64_i32 v[136:137], s[10:11], s28, v130, v[98:99]
	global_load_dwordx2 a[56:57], v[136:137], off
	s_waitcnt vmcnt(24)
	v_accvgpr_read_b32 v187, a59
	v_accvgpr_read_b32 v185, a61
	v_accvgpr_read_b32 v183, a63
	v_accvgpr_read_b32 v181, a65
	v_accvgpr_read_b32 v63, a3
	v_accvgpr_read_b32 v59, a7
	v_accvgpr_read_b32 v55, a11
	v_accvgpr_read_b32 v51, a15
	v_accvgpr_read_b32 v186, a58
	v_accvgpr_read_b32 v184, a60
	v_accvgpr_read_b32 v182, a62
	v_accvgpr_read_b32 v180, a64
	v_accvgpr_read_b32 v62, a2
	v_accvgpr_read_b32 v61, a1
	v_accvgpr_read_b32 v60, a0
	v_accvgpr_read_b32 v58, a6
	v_accvgpr_read_b32 v57, a5
	v_accvgpr_read_b32 v56, a4
	v_accvgpr_read_b32 v54, a10
	v_accvgpr_read_b32 v53, a9
	v_accvgpr_read_b32 v52, a8
	v_accvgpr_read_b32 v50, a14
	v_accvgpr_read_b32 v49, a13
	v_accvgpr_read_b32 v48, a12
	s_add_i32 s30, s26, 24
	v_readlane_b32 s28, v100, s30
	s_nop 1
	v_mad_i64_i32 v[136:137], s[10:11], s28, v130, v[96:97]
	global_load_dwordx4 a[0:3], v[136:137], off
	v_mad_i64_i32 v[136:137], s[10:11], s28, v130, v[98:99]
	global_load_dwordx2 a[58:59], v[136:137], off
	s_add_i32 s30, s26, 25
	v_readlane_b32 s28, v100, s30
	s_nop 1
	v_mad_i64_i32 v[136:137], s[10:11], s28, v130, v[96:97]
	global_load_dwordx4 a[4:7], v[136:137], off
	v_mad_i64_i32 v[136:137], s[10:11], s28, v130, v[98:99]
	global_load_dwordx2 a[60:61], v[136:137], off
	s_add_i32 s30, s26, 26
	v_readlane_b32 s28, v100, s30
	s_nop 1
	v_mad_i64_i32 v[136:137], s[10:11], s28, v130, v[96:97]
	global_load_dwordx4 a[8:11], v[136:137], off
	v_mad_i64_i32 v[136:137], s[10:11], s28, v130, v[98:99]
	global_load_dwordx2 a[62:63], v[136:137], off
	s_add_i32 s30, s26, 27
	v_readlane_b32 s28, v100, s30
	s_nop 1
	v_mad_i64_i32 v[136:137], s[10:11], s28, v130, v[96:97]
	global_load_dwordx4 a[12:15], v[136:137], off
	v_mad_i64_i32 v[136:137], s[10:11], s28, v130, v[98:99]
	global_load_dwordx2 a[64:65], v[136:137], off
	s_waitcnt vmcnt(24)
	v_accvgpr_read_b32 v179, a67
	v_accvgpr_read_b32 v173, a41
	v_accvgpr_read_b32 v47, a19
	v_mov_b64_e32 v[40:41], v[220:221]
	v_mov_b64_e32 v[36:37], v[224:225]
	v_mov_b64_e32 v[32:33], v[228:229]
	v_accvgpr_read_b32 v178, a66
	v_mov_b64_e32 v[176:177], v[148:149]
	v_mov_b64_e32 v[174:175], v[252:253]
	v_accvgpr_read_b32 v172, a40
	v_accvgpr_read_b32 v46, a18
	v_accvgpr_read_b32 v45, a17
	v_accvgpr_read_b32 v44, a16
	v_mov_b64_e32 v[42:43], v[222:223]
	v_mov_b64_e32 v[38:39], v[226:227]
	v_mov_b64_e32 v[34:35], v[230:231]
	s_add_i32 s30, s26, 28
	v_readlane_b32 s28, v100, s30
	s_nop 1
	v_mad_i64_i32 v[136:137], s[10:11], s28, v130, v[96:97]
	global_load_dwordx4 a[16:19], v[136:137], off
	v_mad_i64_i32 v[136:137], s[10:11], s28, v130, v[98:99]
	global_load_dwordx2 a[66:67], v[136:137], off
	s_add_i32 s30, s26, 29
	v_readlane_b32 s28, v100, s30
	s_nop 1
	v_mad_i64_i32 v[136:137], s[10:11], s28, v130, v[96:97]
	global_load_dwordx4 v[220:223], v[136:137], off
	v_mad_i64_i32 v[136:137], s[10:11], s28, v130, v[98:99]
	global_load_dwordx2 v[148:149], v[136:137], off
	s_add_i32 s30, s26, 30
	v_readlane_b32 s28, v100, s30
	s_nop 1
	v_mad_i64_i32 v[136:137], s[10:11], s28, v130, v[96:97]
	global_load_dwordx4 v[224:227], v[136:137], off
	v_mad_i64_i32 v[136:137], s[10:11], s28, v130, v[98:99]
	global_load_dwordx2 v[252:253], v[136:137], off
	s_add_i32 s30, s26, 31
	v_readlane_b32 s28, v100, s30
	s_nop 1
	v_mad_i64_i32 v[136:137], s[10:11], s28, v130, v[96:97]
	global_load_dwordx4 v[228:231], v[136:137], off
	v_mad_i64_i32 v[136:137], s[10:11], s28, v130, v[98:99]
	global_load_dwordx2 a[40:41], v[136:137], off
	s_cmp_lg_u32 s26, 64
	s_cbranch_scc1 .LBB0_904
	global_load_dword a68, v[170:171], off
	global_load_dword a69, v[168:169], off
	global_load_dword v117, v[166:167], off
	global_load_dword v103, v[164:165], off
	s_branch .LBB0_904

.LBB0_976:
	s_and_b32 s6, s72, 0xffff
	s_mul_i32 s6, s6, 0xaaab
	s_lshr_b32 s6, s6, 20
	s_add_i32 s74, s78, s6
	s_lshl_b32 s12, s74, 19
	v_lshl_add_u64 v[4:5], v[54:55], 0, s[12:13]
	v_add_co_u32_e32 v12, vcc, 0x10000, v4
	s_mul_i32 s6, s6, 24
	s_nop 0
	v_addc_co_u32_e32 v13, vcc, 0, v5, vcc
	v_add_co_u32_e32 v14, vcc, 0x20000, v4
	s_sub_i32 s9, s72, s6
	s_nop 0
	v_addc_co_u32_e32 v15, vcc, 0, v5, vcc
	v_add_co_u32_e32 v24, vcc, 0x30000, v4
	s_lshl_b32 s6, s9, 18
	s_nop 0
	v_addc_co_u32_e32 v25, vcc, 0, v5, vcc
	v_add_co_u32_e32 v26, vcc, 0x40000, v4
	s_mov_b32 s7, s13
	s_nop 0
	v_addc_co_u32_e32 v27, vcc, 0, v5, vcc
	global_load_dwordx4 v[0:3], v[4:5], off
	v_add_co_u32_e32 v28, vcc, 0x50000, v4
	v_lshl_add_u64 v[8:9], v[56:57], 0, s[6:7]
	s_nop 0
	v_addc_co_u32_e32 v29, vcc, 0, v5, vcc
	global_load_dwordx4 v[102:105], v[8:9], off
	global_load_dwordx4 v[74:77], v[12:13], off
	global_load_dwordx4 v[78:81], v[14:15], off
	v_add_co_u32_e32 v30, vcc, 0x60000, v4
	global_load_dwordx4 v[82:85], v[24:25], off
	global_load_dwordx4 v[86:89], v[26:27], off
	v_addc_co_u32_e32 v31, vcc, 0, v5, vcc
	v_add_co_u32_e32 v32, vcc, 0x70000, v4
	global_load_dwordx4 v[90:93], v[28:29], off
	global_load_dwordx4 v[94:97], v[30:31], off
	v_addc_co_u32_e32 v33, vcc, 0, v5, vcc
	v_add_co_u32_e32 v118, vcc, s11, v8
	s_mov_b32 s8, 0x20000
	s_nop 0
	v_addc_co_u32_e32 v119, vcc, 0, v9, vcc
	global_load_dwordx4 v[98:101], v[32:33], off
	global_load_dwordx4 v[106:109], v[118:119], off
	v_add_co_u32_e32 v120, vcc, s8, v8
	s_mov_b32 s8, 0x30000
	s_nop 0
	v_addc_co_u32_e32 v121, vcc, 0, v9, vcc
	global_load_dwordx4 v[110:113], v[120:121], off
	v_add_co_u32_e32 v122, vcc, s8, v8
	s_mov_b32 s8, 0
	s_nop 0
	v_addc_co_u32_e32 v123, vcc, 0, v9, vcc
	global_load_dwordx4 v[114:117], v[122:123], off
	s_nop 0
	global_load_dwordx4 v[250:253], v[4:5], off offset:128
	s_nop 0
	global_load_dwordx4 v[218:221], v[8:9], off offset:128
	s_nop 0
	global_load_dwordx4 v[246:249], v[12:13], off offset:128
	global_load_dwordx4 v[242:245], v[14:15], off offset:128
	s_nop 0
	global_load_dwordx4 v[238:241], v[24:25], off offset:128
	global_load_dwordx4 v[234:237], v[26:27], off offset:128
	global_load_dwordx4 v[230:233], v[28:29], off offset:128
	global_load_dwordx4 v[226:229], v[30:31], off offset:128
	s_nop 0
	global_load_dwordx4 v[222:225], v[32:33], off offset:128
	s_nop 0
	global_load_dwordx4 v[214:217], v[118:119], off offset:128
	global_load_dwordx4 v[210:213], v[120:121], off offset:128
	s_and_b32 s73, s9, 0xffff
	v_accvgpr_write_b32 a47, 0
	v_accvgpr_write_b32 a46, 0
	v_accvgpr_write_b32 a45, 0
	v_accvgpr_write_b32 a44, 0
	v_accvgpr_write_b32 a43, 0
	v_accvgpr_write_b32 a42, 0
	v_accvgpr_write_b32 a41, 0
	v_accvgpr_write_b32 a40, 0
	v_accvgpr_write_b32 a39, 0
	v_accvgpr_write_b32 a38, 0
	v_accvgpr_write_b32 a37, 0
	v_accvgpr_write_b32 a36, 0
	v_accvgpr_write_b32 a35, 0
	v_accvgpr_write_b32 a34, 0
	v_accvgpr_write_b32 a33, 0
	v_accvgpr_write_b32 a32, 0
	v_accvgpr_write_b32 a63, 0
	v_accvgpr_write_b32 a62, 0
	v_accvgpr_write_b32 a61, 0
	v_accvgpr_write_b32 a60, 0
	v_accvgpr_write_b32 a59, 0
	v_accvgpr_write_b32 a58, 0
	v_accvgpr_write_b32 a57, 0
	v_accvgpr_write_b32 a56, 0
	v_accvgpr_write_b32 a55, 0
	v_accvgpr_write_b32 a54, 0
	s_waitcnt vmcnt(22)
	ds_write_b128 v131, v[0:3]
	s_waitcnt vmcnt(21)
	ds_write_b128 v131, v[102:105] offset:36864
	s_waitcnt vmcnt(20)
	ds_write_b128 v131, v[74:77] offset:4608
	s_waitcnt vmcnt(19)
	ds_write_b128 v131, v[78:81] offset:9216
	s_waitcnt vmcnt(18)
	ds_write_b128 v131, v[82:85] offset:13824
	s_waitcnt vmcnt(17)
	ds_write_b128 v131, v[86:89] offset:18432
	s_waitcnt vmcnt(16)
	ds_write_b128 v131, v[90:93] offset:23040
	s_waitcnt vmcnt(15)
	ds_write_b128 v131, v[94:97] offset:27648
	s_waitcnt vmcnt(14)
	ds_write_b128 v131, v[98:101] offset:32256
	s_waitcnt vmcnt(13)
	ds_write_b128 v131, v[106:109] offset:41472
	s_waitcnt vmcnt(12)
	ds_write_b128 v131, v[110:113] offset:46080
	global_load_dwordx4 v[206:209], v[122:123], off offset:128
	v_lshl_add_u64 v[0:1], v[72:73], 0, s[12:13]
	v_lshl_add_u64 v[2:3], v[72:73], 0, s[6:7]
	v_accvgpr_write_b32 a53, 0
	v_accvgpr_write_b32 a52, 0
	v_accvgpr_write_b32 a51, 0
	v_accvgpr_write_b32 a50, 0
	v_accvgpr_write_b32 a49, 0
	v_accvgpr_write_b32 a48, 0
	v_accvgpr_write_b32 a79, 0
	v_accvgpr_write_b32 a78, 0
	v_accvgpr_write_b32 a77, 0
	v_accvgpr_write_b32 a76, 0
	v_accvgpr_write_b32 a75, 0
	v_accvgpr_write_b32 a74, 0
	v_accvgpr_write_b32 a73, 0
	v_accvgpr_write_b32 a72, 0
	v_accvgpr_write_b32 a71, 0
	v_accvgpr_write_b32 a70, 0
	v_accvgpr_write_b32 a69, 0
	v_accvgpr_write_b32 a68, 0
	v_accvgpr_write_b32 a67, 0
	v_accvgpr_write_b32 a66, 0
	v_accvgpr_write_b32 a65, 0
	v_accvgpr_write_b32 a64, 0
	v_accvgpr_write_b32 a111, 0
	v_accvgpr_write_b32 a110, 0
	v_accvgpr_write_b32 a109, 0
	v_accvgpr_write_b32 a108, 0
	v_accvgpr_write_b32 a107, 0
	v_accvgpr_write_b32 a106, 0
	v_accvgpr_write_b32 a105, 0
	v_accvgpr_write_b32 a104, 0
	v_accvgpr_write_b32 a103, 0
	v_accvgpr_write_b32 a102, 0
	v_accvgpr_write_b32 a101, 0
	v_accvgpr_write_b32 a100, 0
	v_accvgpr_write_b32 a99, 0
	v_accvgpr_write_b32 a98, 0
	v_accvgpr_write_b32 a97, 0
	v_accvgpr_write_b32 a96, 0
	v_accvgpr_write_b32 a95, 0
	v_accvgpr_write_b32 a94, 0
	v_accvgpr_write_b32 a93, 0
	v_accvgpr_write_b32 a92, 0
	v_accvgpr_write_b32 a91, 0
	v_accvgpr_write_b32 a90, 0
	v_accvgpr_write_b32 a89, 0
	v_accvgpr_write_b32 a88, 0
	v_accvgpr_write_b32 a87, 0
	v_accvgpr_write_b32 a86, 0
	v_accvgpr_write_b32 a85, 0
	v_accvgpr_write_b32 a84, 0
	v_accvgpr_write_b32 a83, 0
	v_accvgpr_write_b32 a82, 0
	v_accvgpr_write_b32 a81, 0
	v_accvgpr_write_b32 a80, 0
	v_accvgpr_write_b32 a127, 0
	v_accvgpr_write_b32 a126, 0
	v_accvgpr_write_b32 a125, 0
	v_accvgpr_write_b32 a124, 0
	v_accvgpr_write_b32 a123, 0
	v_accvgpr_write_b32 a122, 0
	v_accvgpr_write_b32 a121, 0
	v_accvgpr_write_b32 a120, 0
	v_accvgpr_write_b32 a119, 0
	v_accvgpr_write_b32 a118, 0
	v_accvgpr_write_b32 a117, 0
	v_accvgpr_write_b32 a116, 0
	v_accvgpr_write_b32 a115, 0
	v_accvgpr_write_b32 a114, 0
	v_accvgpr_write_b32 a113, 0
	v_accvgpr_write_b32 a112, 0
	v_accvgpr_write_b32 a31, 0
	v_accvgpr_write_b32 a30, 0
	v_accvgpr_write_b32 a29, 0
	v_accvgpr_write_b32 a28, 0
	v_accvgpr_write_b32 a27, 0
	v_accvgpr_write_b32 a26, 0
	v_accvgpr_write_b32 a25, 0
	v_accvgpr_write_b32 a24, 0
	v_accvgpr_write_b32 a23, 0
	v_accvgpr_write_b32 a22, 0
	v_accvgpr_write_b32 a21, 0
	v_accvgpr_write_b32 a20, 0
	v_accvgpr_write_b32 a19, 0
	v_accvgpr_write_b32 a18, 0
	v_accvgpr_write_b32 a17, 0
	v_accvgpr_write_b32 a16, 0
	v_accvgpr_write_b32 a15, 0
	v_accvgpr_write_b32 a14, 0
	v_accvgpr_write_b32 a13, 0
	v_accvgpr_write_b32 a12, 0
	v_accvgpr_write_b32 a11, 0
	v_accvgpr_write_b32 a10, 0
	v_accvgpr_write_b32 a9, 0
	v_accvgpr_write_b32 a8, 0
	v_accvgpr_write_b32 a7, 0
	v_accvgpr_write_b32 a6, 0
	v_accvgpr_write_b32 a5, 0
	v_accvgpr_write_b32 a4, 0
	v_accvgpr_write_b32 a3, 0
	v_accvgpr_write_b32 a2, 0
	v_accvgpr_write_b32 a1, 0
	v_accvgpr_write_b32 a0, 0
	s_mov_b64 s[6:7], 0
	s_waitcnt vmcnt(12)
	ds_write_b128 v131, v[114:117] offset:50688
	s_waitcnt lgkmcnt(0)
	s_barrier
	s_waitcnt vmcnt(0)
	v_readfirstlane_b32 s100, v0
	v_readfirstlane_b32 s101, v1
	v_readfirstlane_b32 s98, v2
	v_readfirstlane_b32 s99, v3
	s_nop 1
	v_subrev_u32_e32 v194, s100, v0
	v_subrev_u32_e32 v193, s98, v2
	v_add_u32_e32 v254, 0x126fa000, v194
	v_add_u32_e32 v205, 0x1270a000, v194
	v_add_u32_e32 v204, 0x1271a000, v194
	v_add_u32_e32 v203, 0x1272a000, v194
	v_add_u32_e32 v202, 0x1273a000, v194
	v_add_u32_e32 v201, 0x1274a000, v194
	v_add_u32_e32 v200, s82, v194
	v_add_u32_e32 v199, s83, v194
	v_add_u32_e32 v198, s84, v193
	v_add_u32_e32 v197, s85, v193
	v_add_u32_e32 v196, s86, v193
	v_add_u32_e32 v195, s87, v193
	s_add_u32 s100, s100, s6
	s_addc_u32 s101, s101, s7
	s_add_u32 s98, s98, s6
	s_addc_u32 s99, s99, s7
	v_add_u32_e32 v192, v51, v132
	v_add_u32_e32 v191, v51, v133
	v_add_u32_e32 v190, v51, v136
	s_and_b32 s9, s8, 1
	s_mul_i32 s12, s9, 0xd800
	v_add_u32_e32 v189, s12, v192
	v_add_u32_e32 v188, s12, v191
	v_add_u32_e32 v187, s12, v190
	ds_read_b128 v[78:81], v189
	ds_read_b128 v[4:7], v187 offset:36864
	ds_read_b128 v[82:85], v189 offset:4608
	ds_read_b128 v[8:11], v187 offset:41472
	ds_read_b128 v[86:89], v189 offset:9216
	ds_read_b128 v[90:93], v188
	s_getreg_b32 s9, hwreg(HW_REG_HW_ID, 4, 1)
	s_cmp_lg_u32 s9, 0
	s_cbranch_scc1 xg5_varB_3
.LBB0_977:
	s_and_b32 s9, s8, 1
	s_mul_i32 s12, s9, 0xd800
	s_xor_b32 s9, s9, 1
	s_mul_i32 s9, s9, 0xd800
	s_add_i32 s8, s8, 1
	v_add_u32_e32 v186, s9, v131
	ds_read_b128 v[12:15], v189 offset:32
	ds_read_b128 v[24:27], v187 offset:36896
	ds_read_b128 v[16:19], v189 offset:4640
	ds_read_b128 v[28:31], v187 offset:41504
	ds_read_b128 v[20:23], v189 offset:9248
	ds_read_b128 v[74:77], v188 offset:32
	s_waitcnt lgkmcnt(10)
	v_mfma_f32_32x32x16_bf16 a[32:47], v[78:81], v[4:7], a[32:47]
	s_waitcnt vmcnt(11)
	ds_write_b128 v186, v[250:253]
	s_waitcnt lgkmcnt(9)
	v_mfma_f32_32x32x16_bf16 a[48:63], v[78:81], v[8:11], a[48:63]
	s_waitcnt vmcnt(10)
	ds_write_b128 v186, v[246:249] offset:4608
	global_load_dwordx4 v[250:253], v254, s[100:101] offset:512
	v_mfma_f32_32x32x16_bf16 a[64:79], v[82:85], v[4:7], a[64:79]
	s_waitcnt vmcnt(10)
	ds_write_b128 v186, v[242:245] offset:9216
	global_load_dwordx4 v[246:249], v205, s[100:101] offset:512
	v_mfma_f32_32x32x16_bf16 a[96:111], v[82:85], v[8:11], a[96:111]
	s_waitcnt vmcnt(10)
	ds_write_b128 v186, v[238:241] offset:13824
	global_load_dwordx4 v[242:245], v204, s[100:101] offset:512
	s_waitcnt lgkmcnt(11)
	v_mfma_f32_32x32x16_bf16 a[80:95], v[86:89], v[4:7], a[80:95]
	s_waitcnt vmcnt(10)
	ds_write_b128 v186, v[234:237] offset:18432
	global_load_dwordx4 v[238:241], v203, s[100:101] offset:512
	v_mfma_f32_32x32x16_bf16 a[112:127], v[86:89], v[8:11], a[112:127]
	s_waitcnt vmcnt(10)
	ds_write_b128 v186, v[230:233] offset:23040
	global_load_dwordx4 v[234:237], v202, s[100:101] offset:512
	s_waitcnt lgkmcnt(12)
	v_mfma_f32_32x32x16_bf16 a[16:31], v[90:93], v[4:7], a[16:31]
	s_waitcnt vmcnt(10)
	ds_write_b128 v186, v[226:229] offset:27648
	global_load_dwordx4 v[230:233], v201, s[100:101] offset:512
	v_mfma_f32_32x32x16_bf16 a[0:15], v[90:93], v[8:11], a[0:15]
	s_waitcnt vmcnt(10)
	ds_write_b128 v186, v[222:225] offset:32256
	global_load_dwordx4 v[226:229], v200, s[100:101] offset:512
	ds_read_b128 v[78:81], v189 offset:64
	ds_read_b128 v[4:7], v187 offset:36928
	ds_read_b128 v[82:85], v189 offset:4672
	ds_read_b128 v[8:11], v187 offset:41536
	ds_read_b128 v[86:89], v189 offset:9280
	ds_read_b128 v[90:93], v188 offset:64
	s_waitcnt lgkmcnt(15)
	v_mfma_f32_32x32x16_bf16 a[32:47], v[12:15], v[24:27], a[32:47]
	s_waitcnt vmcnt(10)
	ds_write_b128 v186, v[218:221] offset:36864
	global_load_dwordx4 v[222:225], v199, s[100:101] offset:512
	v_mfma_f32_32x32x16_bf16 a[48:63], v[12:15], v[28:31], a[48:63]
	s_waitcnt vmcnt(10)
	ds_write_b128 v186, v[214:217] offset:41472
	global_load_dwordx4 v[218:221], v198, s[98:99] offset:256
	v_mfma_f32_32x32x16_bf16 a[64:79], v[16:19], v[24:27], a[64:79]
	s_waitcnt vmcnt(10)
	ds_write_b128 v186, v[210:213] offset:46080
	global_load_dwordx4 v[214:217], v197, s[98:99] offset:256
	v_mfma_f32_32x32x16_bf16 a[96:111], v[16:19], v[28:31], a[96:111]
	s_waitcnt vmcnt(10)
	ds_write_b128 v186, v[206:209] offset:50688
	global_load_dwordx4 v[210:213], v196, s[98:99] offset:256
	v_mfma_f32_32x32x16_bf16 a[80:95], v[20:23], v[24:27], a[80:95]
	global_load_dwordx4 v[206:209], v195, s[98:99] offset:256
	s_add_u32 s100, s100, 0x80
	s_addc_u32 s101, s101, 0
	s_add_u32 s98, s98, 0x80
	s_addc_u32 s99, s99, 0
	v_mfma_f32_32x32x16_bf16 a[112:127], v[20:23], v[28:31], a[112:127]
	s_waitcnt lgkmcnt(15)
	v_mfma_f32_32x32x16_bf16 a[16:31], v[74:77], v[24:27], a[16:31]
	v_mfma_f32_32x32x16_bf16 a[0:15], v[74:77], v[28:31], a[0:15]
	ds_read_b128 v[12:15], v189 offset:96
	ds_read_b128 v[24:27], v187 offset:36960
	ds_read_b128 v[16:19], v189 offset:4704
	ds_read_b128 v[28:31], v187 offset:41568
	ds_read_b128 v[20:23], v189 offset:9312
	ds_read_b128 v[74:77], v188 offset:96
	s_waitcnt lgkmcnt(14)
	v_mfma_f32_32x32x16_bf16 a[32:47], v[78:81], v[4:7], a[32:47]
	s_waitcnt lgkmcnt(12)
	v_mfma_f32_32x32x16_bf16 a[48:63], v[78:81], v[8:11], a[48:63]
	v_mfma_f32_32x32x16_bf16 a[64:79], v[82:85], v[4:7], a[64:79]
	v_mfma_f32_32x32x16_bf16 a[96:111], v[82:85], v[8:11], a[96:111]
	s_waitcnt lgkmcnt(11)
	v_mfma_f32_32x32x16_bf16 a[80:95], v[86:89], v[4:7], a[80:95]
	v_mfma_f32_32x32x16_bf16 a[112:127], v[86:89], v[8:11], a[112:127]
	s_waitcnt lgkmcnt(10)
	v_mfma_f32_32x32x16_bf16 a[16:31], v[90:93], v[4:7], a[16:31]
	v_mfma_f32_32x32x16_bf16 a[0:15], v[90:93], v[8:11], a[0:15]
	s_waitcnt lgkmcnt(0)
	v_mfma_f32_32x32x16_bf16 a[32:47], v[12:15], v[24:27], a[32:47]
	v_mfma_f32_32x32x16_bf16 a[48:63], v[12:15], v[28:31], a[48:63]
	v_mfma_f32_32x32x16_bf16 a[64:79], v[16:19], v[24:27], a[64:79]
	v_mfma_f32_32x32x16_bf16 a[96:111], v[16:19], v[28:31], a[96:111]
	s_barrier
	v_add_u32_e32 v189, s9, v192
	v_add_u32_e32 v188, s9, v191
	v_add_u32_e32 v187, s9, v190
	ds_read_b128 v[78:81], v189
	ds_read_b128 v[4:7], v187 offset:36864
	ds_read_b128 v[82:85], v189 offset:4608
	ds_read_b128 v[8:11], v187 offset:41472
	ds_read_b128 v[86:89], v189 offset:9216
	ds_read_b128 v[90:93], v188
	v_mfma_f32_32x32x16_bf16 a[80:95], v[20:23], v[24:27], a[80:95]
	v_mfma_f32_32x32x16_bf16 a[112:127], v[20:23], v[28:31], a[112:127]
	v_mfma_f32_32x32x16_bf16 a[16:31], v[74:77], v[24:27], a[16:31]
	v_mfma_f32_32x32x16_bf16 a[0:15], v[74:77], v[28:31], a[0:15]
	s_add_u32 s6, s6, 0x80
	s_addc_u32 s7, s7, 0
	s_cmpk_lg_i32 s6, 0x700
	s_cbranch_scc1 .LBB0_977
	s_branch xg5_tail_3
xg5_varB_3:
	s_and_b32 s9, s8, 1
	s_mul_i32 s12, s9, 0xd800
	s_xor_b32 s9, s9, 1
	s_mul_i32 s9, s9, 0xd800
	s_add_i32 s8, s8, 1
	v_add_u32_e32 v186, s9, v131
	ds_read_b128 v[12:15], v189 offset:32
	ds_read_b128 v[24:27], v187 offset:36896
	ds_read_b128 v[16:19], v189 offset:4640
	ds_read_b128 v[28:31], v187 offset:41504
	ds_read_b128 v[20:23], v189 offset:9248
	ds_read_b128 v[74:77], v188 offset:32
	s_waitcnt lgkmcnt(10)
	v_mfma_f32_32x32x16_bf16 a[32:47], v[78:81], v[4:7], a[32:47]
	s_waitcnt lgkmcnt(8)
	v_mfma_f32_32x32x16_bf16 a[48:63], v[78:81], v[8:11], a[48:63]
	v_mfma_f32_32x32x16_bf16 a[64:79], v[82:85], v[4:7], a[64:79]
	v_mfma_f32_32x32x16_bf16 a[96:111], v[82:85], v[8:11], a[96:111]
	s_waitcnt lgkmcnt(7)
	v_mfma_f32_32x32x16_bf16 a[80:95], v[86:89], v[4:7], a[80:95]
	v_mfma_f32_32x32x16_bf16 a[112:127], v[86:89], v[8:11], a[112:127]
	s_waitcnt lgkmcnt(6)
	v_mfma_f32_32x32x16_bf16 a[16:31], v[90:93], v[4:7], a[16:31]
	v_mfma_f32_32x32x16_bf16 a[0:15], v[90:93], v[8:11], a[0:15]
	ds_read_b128 v[78:81], v189 offset:64
	ds_read_b128 v[4:7], v187 offset:36928
	ds_read_b128 v[82:85], v189 offset:4672
	ds_read_b128 v[8:11], v187 offset:41536
	ds_read_b128 v[86:89], v189 offset:9280
	ds_read_b128 v[90:93], v188 offset:64
	s_waitcnt lgkmcnt(10)
	v_mfma_f32_32x32x16_bf16 a[32:47], v[12:15], v[24:27], a[32:47]
	s_waitcnt lgkmcnt(8)
	v_mfma_f32_32x32x16_bf16 a[48:63], v[12:15], v[28:31], a[48:63]
	v_mfma_f32_32x32x16_bf16 a[64:79], v[16:19], v[24:27], a[64:79]
	v_mfma_f32_32x32x16_bf16 a[96:111], v[16:19], v[28:31], a[96:111]
	s_waitcnt lgkmcnt(7)
	v_mfma_f32_32x32x16_bf16 a[80:95], v[20:23], v[24:27], a[80:95]
	s_waitcnt vmcnt(11)
	ds_write_b128 v186, v[250:253]
	v_mfma_f32_32x32x16_bf16 a[112:127], v[20:23], v[28:31], a[112:127]
	s_waitcnt vmcnt(10)
	ds_write_b128 v186, v[246:249] offset:4608
	global_load_dwordx4 v[250:253], v254, s[100:101] offset:512
	s_waitcnt lgkmcnt(8)
	v_mfma_f32_32x32x16_bf16 a[16:31], v[74:77], v[24:27], a[16:31]
	s_waitcnt vmcnt(10)
	ds_write_b128 v186, v[242:245] offset:9216
	global_load_dwordx4 v[246:249], v205, s[100:101] offset:512
	v_mfma_f32_32x32x16_bf16 a[0:15], v[74:77], v[28:31], a[0:15]
	s_waitcnt vmcnt(10)
	ds_write_b128 v186, v[238:241] offset:13824
	global_load_dwordx4 v[242:245], v204, s[100:101] offset:512
	ds_read_b128 v[12:15], v189 offset:96
	ds_read_b128 v[24:27], v187 offset:36960
	ds_read_b128 v[16:19], v189 offset:4704
	ds_read_b128 v[28:31], v187 offset:41568
	ds_read_b128 v[20:23], v189 offset:9312
	ds_read_b128 v[74:77], v188 offset:96
	s_waitcnt lgkmcnt(14)
	v_mfma_f32_32x32x16_bf16 a[32:47], v[78:81], v[4:7], a[32:47]
	s_waitcnt vmcnt(10)
	ds_write_b128 v186, v[234:237] offset:18432
	global_load_dwordx4 v[238:241], v203, s[100:101] offset:512
	s_waitcnt lgkmcnt(13)
	v_mfma_f32_32x32x16_bf16 a[48:63], v[78:81], v[8:11], a[48:63]
	s_waitcnt vmcnt(10)
	ds_write_b128 v186, v[230:233] offset:23040
	global_load_dwordx4 v[234:237], v202, s[100:101] offset:512
	v_mfma_f32_32x32x16_bf16 a[64:79], v[82:85], v[4:7], a[64:79]
	s_waitcnt vmcnt(10)
	ds_write_b128 v186, v[226:229] offset:27648
	global_load_dwordx4 v[230:233], v201, s[100:101] offset:512
	v_mfma_f32_32x32x16_bf16 a[96:111], v[82:85], v[8:11], a[96:111]
	s_waitcnt vmcnt(10)
	ds_write_b128 v186, v[222:225] offset:32256
	global_load_dwordx4 v[226:229], v200, s[100:101] offset:512
	s_waitcnt lgkmcnt(15)
	v_mfma_f32_32x32x16_bf16 a[80:95], v[86:89], v[4:7], a[80:95]
	s_waitcnt vmcnt(10)
	ds_write_b128 v186, v[218:221] offset:36864
	global_load_dwordx4 v[222:225], v199, s[100:101] offset:512
	v_mfma_f32_32x32x16_bf16 a[112:127], v[86:89], v[8:11], a[112:127]
	s_waitcnt vmcnt(10)
	ds_write_b128 v186, v[214:217] offset:41472
	global_load_dwordx4 v[218:221], v198, s[98:99] offset:256
	s_waitcnt lgkmcnt(15)
	v_mfma_f32_32x32x16_bf16 a[16:31], v[90:93], v[4:7], a[16:31]
	s_waitcnt vmcnt(10)
	ds_write_b128 v186, v[210:213] offset:46080
	global_load_dwordx4 v[214:217], v197, s[98:99] offset:256
	v_mfma_f32_32x32x16_bf16 a[0:15], v[90:93], v[8:11], a[0:15]
	s_waitcnt vmcnt(10)
	ds_write_b128 v186, v[206:209] offset:50688
	global_load_dwordx4 v[210:213], v196, s[98:99] offset:256
	s_waitcnt lgkmcnt(0)
	v_mfma_f32_32x32x16_bf16 a[32:47], v[12:15], v[24:27], a[32:47]
	global_load_dwordx4 v[206:209], v195, s[98:99] offset:256
	s_add_u32 s100, s100, 0x80
	s_addc_u32 s101, s101, 0
	s_add_u32 s98, s98, 0x80
	s_addc_u32 s99, s99, 0
	v_mfma_f32_32x32x16_bf16 a[48:63], v[12:15], v[28:31], a[48:63]
	v_mfma_f32_32x32x16_bf16 a[64:79], v[16:19], v[24:27], a[64:79]
	v_mfma_f32_32x32x16_bf16 a[96:111], v[16:19], v[28:31], a[96:111]
	s_barrier
	v_add_u32_e32 v189, s9, v192
	v_add_u32_e32 v188, s9, v191
	v_add_u32_e32 v187, s9, v190
	ds_read_b128 v[78:81], v189
	ds_read_b128 v[4:7], v187 offset:36864
	ds_read_b128 v[82:85], v189 offset:4608
	ds_read_b128 v[8:11], v187 offset:41472
	ds_read_b128 v[86:89], v189 offset:9216
	ds_read_b128 v[90:93], v188
	v_mfma_f32_32x32x16_bf16 a[80:95], v[20:23], v[24:27], a[80:95]
	v_mfma_f32_32x32x16_bf16 a[112:127], v[20:23], v[28:31], a[112:127]
	v_mfma_f32_32x32x16_bf16 a[16:31], v[74:77], v[24:27], a[16:31]
	v_mfma_f32_32x32x16_bf16 a[0:15], v[74:77], v[28:31], a[0:15]
	s_add_u32 s6, s6, 0x80
	s_addc_u32 s7, s7, 0
	s_cmpk_lg_i32 s6, 0x700
	s_cbranch_scc1 xg5_varB_3
xg5_tail_3:
	ds_read_b128 v[0:3], v152
	ds_read_b128 v[78:81], v152 offset:4608
	ds_read_b128 v[82:85], v152 offset:9216
	ds_read_b128 v[86:89], v153
	ds_read_b128 v[90:93], v154 offset:36864
	ds_read_b128 v[94:97], v154 offset:41472
	s_waitcnt vmcnt(11)
	s_waitcnt vmcnt(0)
	ds_write_b128 v155, v[250:253] offset:55296
	s_waitcnt vmcnt(10)
	ds_write_b128 v155, v[246:249] offset:59904
	s_waitcnt vmcnt(9)
	ds_write_b128 v155, v[242:245] offset:64512
	s_waitcnt vmcnt(8)
	ds_write_b128 v53, v[238:241] offset:55296
	s_waitcnt vmcnt(7)
	ds_write_b128 v135, v[234:237] offset:55296
	s_waitcnt vmcnt(6)
	ds_write_b128 v139, v[230:233] offset:55296
	s_waitcnt vmcnt(5)
	ds_write_b128 v144, v[226:229] offset:55296
	s_waitcnt vmcnt(4)
	ds_write_b128 v145, v[222:225] offset:55296
	s_waitcnt vmcnt(3)
	ds_write_b128 v146, v[218:221]
	s_waitcnt vmcnt(2)
	ds_write_b128 v146, v[214:217] offset:4608
	s_waitcnt vmcnt(1)
	ds_write_b128 v146, v[210:213] offset:9216
	s_waitcnt vmcnt(0)
	ds_write_b128 v146, v[206:209] offset:13824
	s_lshl_b32 s75, s74, 8
	s_cmp_gt_u32 s74, 31
	s_waitcnt lgkmcnt(13)
	v_mfma_f32_32x32x16_bf16 a[144:159], v[78:81], v[90:93], a[64:79]
	s_cselect_b64 s[60:61], -1, 0
	s_add_i32 s6, s75, 0xffffe000
	s_lshr_b32 s12, s6, 12
	s_cmp_lt_u32 s74, 32
	s_cselect_b64 s[8:9], -1, 0
	s_and_b64 s[6:7], s[8:9], exec
	s_cselect_b32 s6, 32, 0xf00
	s_waitcnt lgkmcnt(12)
	v_mfma_f32_32x32x16_bf16 a[160:175], v[0:3], v[94:97], a[48:63]
	s_cselect_b32 s93, s74, s12
	s_and_b32 s92, s6, s75
	s_cmp_lt_u32 s73, 16
	s_cselect_b64 s[62:63], -1, 0
	s_mov_b64 s[6:7], -1
	s_and_b64 vcc, exec, s[62:63]
	v_mfma_f32_32x32x16_bf16 a[128:143], v[78:81], v[94:97], a[96:111]
	v_mfma_f32_32x32x16_bf16 a[64:79], v[82:85], v[90:93], a[80:95]
	v_mfma_f32_32x32x16_bf16 a[48:63], v[82:85], v[94:97], a[112:127]
	v_mfma_f32_32x32x16_bf16 a[176:191], v[0:3], v[90:93], a[32:47]
	ds_read_b128 v[0:3], v152 offset:4640
	ds_read_b128 v[4:7], v152 offset:9248
	ds_read_b128 v[8:11], v154 offset:41504
	ds_read_b128 v[12:15], v154 offset:36896
	ds_read_b128 v[16:19], v154 offset:36928
	ds_read_b128 v[20:23], v152 offset:32
	ds_read_b128 v[24:27], v152 offset:64
	v_mfma_f32_32x32x16_bf16 a[32:47], v[86:89], v[90:93], a[16:31]
	v_mfma_f32_32x32x16_bf16 a[16:31], v[86:89], v[94:97], a[0:15]
	s_waitcnt lgkmcnt(3)
	v_mfma_f32_32x32x16_bf16 a[144:159], v[0:3], v[12:15], a[144:159]
	v_mfma_f32_32x32x16_bf16 a[128:143], v[0:3], v[8:11], a[128:143]
	v_mfma_f32_32x32x16_bf16 a[64:79], v[4:7], v[12:15], a[64:79]
	v_mfma_f32_32x32x16_bf16 a[48:63], v[4:7], v[8:11], a[48:63]
	ds_read_b128 v[0:3], v153 offset:32
	ds_read_b128 v[4:7], v153 offset:64
	s_waitcnt lgkmcnt(3)
	v_mfma_f32_32x32x16_bf16 a[176:191], v[20:23], v[12:15], a[176:191]
	v_mfma_f32_32x32x16_bf16 a[160:175], v[20:23], v[8:11], a[160:175]
	s_waitcnt lgkmcnt(1)
	v_mfma_f32_32x32x16_bf16 a[32:47], v[0:3], v[12:15], a[32:47]
	v_mfma_f32_32x32x16_bf16 a[16:31], v[0:3], v[8:11], a[16:31]
	ds_read_b128 v[0:3], v154 offset:41536
	ds_read_b128 v[8:11], v152 offset:9280
	ds_read_b128 v[12:15], v152 offset:4672
	v_mfma_f32_32x32x16_bf16 a[176:191], v[24:27], v[16:19], a[176:191]
	s_waitcnt lgkmcnt(0)
	v_mfma_f32_32x32x16_bf16 a[144:159], v[12:15], v[16:19], a[144:159]
	v_mfma_f32_32x32x16_bf16 a[128:143], v[12:15], v[0:3], a[128:143]
	v_mfma_f32_32x32x16_bf16 a[64:79], v[8:11], v[16:19], a[64:79]
	v_mfma_f32_32x32x16_bf16 a[48:63], v[8:11], v[0:3], a[48:63]
	v_mfma_f32_32x32x16_bf16 a[160:175], v[24:27], v[0:3], a[160:175]
	v_mfma_f32_32x32x16_bf16 a[32:47], v[4:7], v[16:19], a[32:47]
	v_mfma_f32_32x32x16_bf16 a[16:31], v[4:7], v[0:3], a[16:31]
	ds_read_b128 v[0:3], v154 offset:41568
	ds_read_b128 v[4:7], v154 offset:36960
	ds_read_b128 v[8:11], v153 offset:96
	ds_read_b128 v[12:15], v152 offset:9312
	ds_read_b128 v[16:19], v152 offset:4704
	ds_read_b128 v[20:23], v152 offset:96
	s_waitcnt lgkmcnt(0)
	s_barrier
	v_mfma_f32_32x32x16_bf16 a[176:191], v[20:23], v[4:7], a[176:191]
	v_mfma_f32_32x32x16_bf16 a[144:159], v[16:19], v[4:7], a[144:159]
	v_mfma_f32_32x32x16_bf16 a[128:143], v[16:19], v[0:3], a[128:143]
	v_mfma_f32_32x32x16_bf16 a[64:79], v[12:15], v[4:7], a[64:79]
	v_mfma_f32_32x32x16_bf16 a[48:63], v[12:15], v[0:3], a[48:63]
	v_mfma_f32_32x32x16_bf16 a[160:175], v[20:23], v[0:3], a[160:175]
	v_mfma_f32_32x32x16_bf16 a[32:47], v[8:11], v[4:7], a[32:47]
	v_mfma_f32_32x32x16_bf16 a[16:31], v[8:11], v[0:3], a[16:31]
	ds_read_b128 v[0:3], v152 offset:59904
	ds_read_b128 v[4:7], v152 offset:64512
	ds_read_b128 v[8:11], v147 offset:4608
	ds_read_b128 v[12:15], v152 offset:55296
	ds_read_b128 v[16:19], v152 offset:55328
	ds_read_b128 v[20:23], v147
	ds_read_b128 v[24:27], v147 offset:32
	s_waitcnt lgkmcnt(1)
	v_mfma_f32_32x32x16_bf16 a[176:191], v[12:15], v[20:23], a[176:191]
	v_mfma_f32_32x32x16_bf16 a[144:159], v[0:3], v[20:23], a[144:159]
	v_mfma_f32_32x32x16_bf16 a[128:143], v[0:3], v[8:11], a[128:143]
	v_mfma_f32_32x32x16_bf16 a[64:79], v[4:7], v[20:23], a[64:79]
	v_mfma_f32_32x32x16_bf16 a[48:63], v[4:7], v[8:11], a[48:63]
	ds_read_b128 v[0:3], v153 offset:55296
	ds_read_b128 v[4:7], v153 offset:55328
	v_mfma_f32_32x32x16_bf16 a[160:175], v[12:15], v[8:11], a[160:175]
	s_waitcnt lgkmcnt(1)
	v_mfma_f32_32x32x16_bf16 a[32:47], v[0:3], v[20:23], a[32:47]
	v_mfma_f32_32x32x16_bf16 a[16:31], v[0:3], v[8:11], a[16:31]
	ds_read_b128 v[0:3], v152 offset:64544
	ds_read_b128 v[8:11], v152 offset:59936
	ds_read_b128 v[12:15], v147 offset:4640
	v_mfma_f32_32x32x16_bf16 a[176:191], v[16:19], v[24:27], a[176:191]
	s_waitcnt lgkmcnt(0)
	v_mfma_f32_32x32x16_bf16 a[160:175], v[16:19], v[12:15], a[160:175]
	v_mfma_f32_32x32x16_bf16 a[144:159], v[8:11], v[24:27], a[144:159]
	v_mfma_f32_32x32x16_bf16 a[128:143], v[8:11], v[12:15], a[128:143]
	v_mfma_f32_32x32x16_bf16 a[64:79], v[0:3], v[24:27], a[64:79]
	v_mfma_f32_32x32x16_bf16 a[48:63], v[0:3], v[12:15], a[48:63]
	v_mfma_f32_32x32x16_bf16 a[32:47], v[4:7], v[24:27], a[32:47]
	v_mfma_f32_32x32x16_bf16 a[16:31], v[4:7], v[12:15], a[16:31]
	ds_read_b128 v[0:3], v153 offset:55360
	ds_read_b128 v[4:7], v152 offset:64576
	ds_read_b128 v[8:11], v152 offset:59968
	ds_read_b128 v[12:15], v152 offset:55360
	ds_read_b128 v[16:19], v147 offset:64
	ds_read_b128 v[20:23], v147 offset:4672
	s_waitcnt lgkmcnt(1)
	v_mfma_f32_32x32x16_bf16 a[176:191], v[12:15], v[16:19], a[176:191]
	s_waitcnt lgkmcnt(0)
	v_mfma_f32_32x32x16_bf16 a[160:175], v[12:15], v[20:23], a[160:175]
	v_mfma_f32_32x32x16_bf16 a[144:159], v[8:11], v[16:19], a[144:159]
	v_mfma_f32_32x32x16_bf16 a[128:143], v[8:11], v[20:23], a[128:143]
	v_mfma_f32_32x32x16_bf16 a[64:79], v[4:7], v[16:19], a[64:79]
	v_mfma_f32_32x32x16_bf16 a[48:63], v[4:7], v[20:23], a[48:63]
	v_mfma_f32_32x32x16_bf16 a[32:47], v[0:3], v[16:19], a[32:47]
	v_mfma_f32_32x32x16_bf16 a[16:31], v[0:3], v[20:23], a[16:31]
	ds_read_b128 v[0:3], v153 offset:55392
	ds_read_b128 v[4:7], v152 offset:64608
	ds_read_b128 v[8:11], v152 offset:60000
	ds_read_b128 v[12:15], v152 offset:55392
	ds_read_b128 v[16:19], v147 offset:96
	ds_read_b128 v[20:23], v147 offset:4704
	s_waitcnt lgkmcnt(0)
	s_barrier
	v_mfma_f32_32x32x16_bf16 a[176:191], v[12:15], v[16:19], a[176:191]
	v_mfma_f32_32x32x16_bf16 a[32:47], v[0:3], v[16:19], a[32:47]
	v_mfma_f32_32x32x16_bf16 a[16:31], v[0:3], v[20:23], a[16:31]
	v_accvgpr_read_b32 v0, a212
	v_lshlrev_b32_e32 v0, 5, v0
	v_lshlrev_b32_e32 v74, 1, v0
	v_mfma_f32_32x32x16_bf16 a[160:175], v[12:15], v[20:23], a[160:175]
	v_mfma_f32_32x32x16_bf16 a[144:159], v[8:11], v[16:19], a[144:159]
	v_mfma_f32_32x32x16_bf16 a[128:143], v[8:11], v[20:23], a[128:143]
	v_mfma_f32_32x32x16_bf16 a[64:79], v[4:7], v[16:19], a[64:79]
	v_mfma_f32_32x32x16_bf16 a[48:63], v[4:7], v[20:23], a[48:63]
	s_nop 1
	ds_write_b32 v137, a176
	ds_write_b32 v137, a177 offset:516
	ds_write_b32 v137, a178 offset:1032
	ds_write_b32 v137, a179 offset:1548
	ds_write_b32 v137, a180 offset:4128
	ds_write_b32 v137, a181 offset:4644
	ds_write_b32 v137, a182 offset:5160
	ds_write_b32 v137, a183 offset:5676
	ds_write_b32 v137, a184 offset:8256
	ds_write_b32 v137, a185 offset:8772
	ds_write_b32 v137, a186 offset:9288
	ds_write_b32 v137, a187 offset:9804
	ds_write_b32 v137, a188 offset:12384
	ds_write_b32 v137, a189 offset:12900
	ds_write_b32 v137, a190 offset:13416
	ds_write_b32 v137, a191 offset:13932
	ds_write_b32 v137, a160 offset:128
	ds_write_b32 v137, a161 offset:644
	ds_write_b32 v137, a162 offset:1160
	ds_write_b32 v137, a163 offset:1676
	ds_write_b32 v137, a164 offset:4256
	ds_write_b32 v137, a165 offset:4772
	ds_write_b32 v137, a166 offset:5288
	ds_write_b32 v137, a167 offset:5804
	ds_write_b32 v137, a168 offset:8384
	ds_write_b32 v137, a169 offset:8900
	ds_write_b32 v137, a170 offset:9416
	ds_write_b32 v137, a171 offset:9932
	ds_write_b32 v137, a172 offset:12512
	ds_write_b32 v137, a173 offset:13028
	ds_write_b32 v137, a174 offset:13544
	ds_write_b32 v137, a175 offset:14060
	ds_write_b32 v137, a144 offset:16512
	ds_write_b32 v137, a145 offset:17028
	ds_write_b32 v137, a146 offset:17544
	ds_write_b32 v137, a147 offset:18060
	ds_write_b32 v137, a148 offset:20640
	ds_write_b32 v137, a149 offset:21156
	ds_write_b32 v137, a150 offset:21672
	ds_write_b32 v137, a151 offset:22188
	ds_write_b32 v137, a152 offset:24768
	ds_write_b32 v137, a153 offset:25284
	ds_write_b32 v137, a154 offset:25800
	ds_write_b32 v137, a155 offset:26316
	ds_write_b32 v137, a156 offset:28896
	ds_write_b32 v137, a157 offset:29412
	ds_write_b32 v137, a158 offset:29928
	ds_write_b32 v137, a159 offset:30444
	ds_write_b32 v137, a128 offset:16640
	ds_write_b32 v137, a129 offset:17156
	ds_write_b32 v137, a130 offset:17672
	ds_write_b32 v137, a131 offset:18188
	ds_write_b32 v137, a132 offset:20768
	ds_write_b32 v137, a133 offset:21284
	ds_write_b32 v137, a134 offset:21800
	ds_write_b32 v137, a135 offset:22316
	ds_write_b32 v137, a136 offset:24896
	ds_write_b32 v137, a137 offset:25412
	ds_write_b32 v137, a138 offset:25928
	ds_write_b32 v137, a139 offset:26444
	ds_write_b32 v137, a140 offset:29024
	ds_write_b32 v137, a141 offset:29540
	ds_write_b32 v137, a142 offset:30056
	ds_write_b32 v137, a143 offset:30572
	ds_write_b32 v137, a64 offset:33024
	ds_write_b32 v137, a65 offset:33540
	ds_write_b32 v137, a66 offset:34056
	ds_write_b32 v137, a67 offset:34572
	ds_write_b32 v137, a68 offset:37152
	ds_write_b32 v137, a69 offset:37668
	ds_write_b32 v137, a70 offset:38184
	ds_write_b32 v137, a71 offset:38700
	ds_write_b32 v137, a72 offset:41280
	ds_write_b32 v137, a73 offset:41796
	ds_write_b32 v137, a74 offset:42312
	ds_write_b32 v137, a75 offset:42828
	ds_write_b32 v137, a76 offset:45408
	ds_write_b32 v137, a77 offset:45924
	ds_write_b32 v137, a78 offset:46440
	ds_write_b32 v137, a79 offset:46956
	ds_write_b32 v137, a48 offset:33152
	ds_write_b32 v137, a49 offset:33668
	ds_write_b32 v137, a50 offset:34184
	ds_write_b32 v137, a51 offset:34700
	ds_write_b32 v137, a52 offset:37280
	ds_write_b32 v137, a53 offset:37796
	ds_write_b32 v137, a54 offset:38312
	ds_write_b32 v137, a55 offset:38828
	ds_write_b32 v137, a56 offset:41408
	ds_write_b32 v137, a57 offset:41924
	ds_write_b32 v137, a58 offset:42440
	ds_write_b32 v137, a59 offset:42956
	ds_write_b32 v137, a60 offset:45536
	ds_write_b32 v137, a61 offset:46052
	ds_write_b32 v137, a62 offset:46568
	ds_write_b32 v137, a63 offset:47084
	ds_write_b32 v137, a32 offset:49536
	ds_write_b32 v137, a33 offset:50052
	ds_write_b32 v137, a34 offset:50568
	ds_write_b32 v137, a35 offset:51084
	ds_write_b32 v137, a36 offset:53664
	ds_write_b32 v137, a37 offset:54180
	ds_write_b32 v137, a38 offset:54696
	ds_write_b32 v137, a39 offset:55212
	ds_write_b32 v137, a40 offset:57792
	ds_write_b32 v137, a41 offset:58308
	ds_write_b32 v137, a42 offset:58824
	ds_write_b32 v137, a43 offset:59340
	ds_write_b32 v137, a44 offset:61920
	ds_write_b32 v137, a45 offset:62436
	ds_write_b32 v137, a46 offset:62952
	ds_write_b32 v137, a47 offset:63468
	ds_write_b32 v137, a16 offset:49664
	ds_write_b32 v137, a17 offset:50180
	ds_write_b32 v137, a18 offset:50696
	ds_write_b32 v137, a19 offset:51212
	ds_write_b32 v137, a20 offset:53792
	ds_write_b32 v137, a21 offset:54308
	ds_write_b32 v137, a22 offset:54824
	ds_write_b32 v137, a23 offset:55340
	ds_write_b32 v137, a24 offset:57920
	ds_write_b32 v137, a25 offset:58436
	ds_write_b32 v137, a26 offset:58952
	ds_write_b32 v137, a27 offset:59468
	ds_write_b32 v137, a28 offset:62048
	ds_write_b32 v137, a29 offset:62564
	ds_write_b32 v137, a30 offset:63080
	ds_write_b32 v137, a31 offset:63596
	s_waitcnt lgkmcnt(0)
	s_barrier
	s_cbranch_vccz .LBB0_995
	v_accvgpr_read_b32 v1, a210
	v_add_u32_e32 v4, s92, v1
	v_add_u32_e32 v0, s75, v1
	v_lshrrev_b32_e32 v1, 6, v4
	v_accvgpr_read_b32 v2, a211
	s_cmp_gt_u32 s73, 7
	v_cndmask_b32_e64 v1, v2, v1, s[4:5]
	s_cselect_b64 s[64:65], -1, 0
	s_add_i32 s12, s73, -8
	v_lshlrev_b32_e32 v48, 7, v1
	s_lshl_b32 s6, s93, 3
	v_mov_b32_e32 v1, v49
	s_add_i32 s6, s6, s12
	v_lshlrev_b64 v[0:1], 11, v[0:1]
	s_ashr_i32 s7, s6, 31
	s_lshl_b64 s[68:69], s[12:13], 1
	v_lshl_add_u64 v[0:1], s[16:17], 0, v[0:1]
	s_lshl_b32 s12, s73, 8
	s_lshl_b64 s[66:67], s[6:7], 1
	v_lshl_add_u32 v2, s93, 9, v4
	v_mov_b32_e32 v3, v49
	v_lshl_add_u64 v[0:1], v[0:1], 0, s[12:13]
	v_mov_b32_e32 v75, v49
	s_lshl_b64 s[6:7], s[6:7], 16
	v_lshl_add_u64 v[78:79], v[2:3], 4, s[68:69]
	v_lshl_add_u64 v[80:81], v[0:1], 0, v[74:75]
	v_lshlrev_b32_e32 v0, 7, v4
	v_mov_b32_e32 v1, v49
	v_lshl_add_u64 v[2:3], v[60:61], 0, s[6:7]
	v_lshl_add_u64 v[82:83], v[2:3], 0, v[0:1]
	v_and_b32_e32 v1, 64, v156
	v_xor_b32_e32 v0, 1, v156
	v_add_u32_e32 v1, 64, v1
	v_cmp_lt_i32_e32 vcc, v0, v1
	v_lshl_add_u64 v[76:77], s[14:15], 0, v[48:49]
	v_mov_b32_e32 v48, v4
	v_cndmask_b32_e32 v0, v156, v0, vcc
	s_mov_b32 s12, 0
	v_lshlrev_b32_e32 v75, 2, v0
	s_mov_b64 s[68:69], -1
	s_branch .LBB0_982

.LBB0_1264:
	s_lshr_b32 s48, s47, 3
	s_lshl_b32 s42, s48, 18
	s_add_i32 s42, s68, s42
	v_lshl_add_u64 v[10:11], s[42:43], 1, v[8:9]
	s_and_b32 s42, s46, 7
	s_lshl_b32 s42, s42, 18
	s_add_i32 s48, s48, s65
	v_lshl_add_u64 v[12:13], v[8:9], 0, s[42:43]
	s_lshl_b32 s42, s48, 19
	v_lshl_add_u64 v[14:15], v[2:3], 0, s[42:43]
	v_add_co_u32_e32 v16, vcc, s69, v14
	s_mov_b32 s42, 0x40000
	s_nop 0
	v_addc_co_u32_e32 v17, vcc, 0, v15, vcc
	v_add_co_u32_e32 v18, vcc, s70, v14
	s_and_b32 s49, s47, 7
	s_nop 0
	v_addc_co_u32_e32 v19, vcc, 0, v15, vcc
	v_add_co_u32_e32 v76, vcc, s71, v14
	global_load_dwordx4 v[108:111], v[14:15], off
	global_load_dwordx4 v[112:115], v[16:17], off
	v_addc_co_u32_e32 v77, vcc, 0, v15, vcc
	v_add_co_u32_e32 v78, vcc, s42, v14
	s_mov_b32 s42, 0x50000
	s_nop 0
	v_addc_co_u32_e32 v79, vcc, 0, v15, vcc
	v_add_co_u32_e32 v80, vcc, s42, v14
	s_mov_b32 s42, 0x60000
	s_nop 0
	v_addc_co_u32_e32 v81, vcc, 0, v15, vcc
	v_add_co_u32_e32 v82, vcc, s42, v14
	s_lshl_b32 s42, s49, 18
	s_nop 0
	v_addc_co_u32_e32 v83, vcc, 0, v15, vcc
	v_add_co_u32_e32 v88, vcc, s72, v14
	v_lshl_add_u64 v[90:91], v[4:5], 0, s[42:43]
	s_nop 0
	v_addc_co_u32_e32 v89, vcc, 0, v15, vcc
	v_add_co_u32_e32 v92, vcc, s69, v90
	global_load_dwordx4 v[116:119], v[18:19], off
	global_load_dwordx4 v[120:123], v[76:77], off
	v_addc_co_u32_e32 v93, vcc, 0, v91, vcc
	v_add_co_u32_e32 v104, vcc, s70, v90
	global_load_dwordx4 v[124:127], v[78:79], off
	global_load_dwordx4 v[128:131], v[80:81], off
	v_addc_co_u32_e32 v105, vcc, 0, v91, vcc
	v_add_co_u32_e32 v106, vcc, s71, v90
	global_load_dwordx4 v[140:143], v[82:83], off
	global_load_dwordx4 v[144:147], v[88:89], off
	v_addc_co_u32_e32 v107, vcc, 0, v91, vcc
	global_load_dwordx4 v[148:151], v[90:91], off
	global_load_dwordx4 v[152:155], v[92:93], off
	global_load_dwordx4 v[156:159], v[104:105], off
	global_load_dwordx4 v[160:163], v[106:107], off
	global_load_dwordx4 v[250:253], v[14:15], off offset:128
	global_load_dwordx4 v[246:249], v[16:17], off offset:128
	global_load_dwordx4 v[242:245], v[18:19], off offset:128
	s_nop 0
	global_load_dwordx4 v[238:241], v[76:77], off offset:128
	global_load_dwordx4 v[234:237], v[78:79], off offset:128
	global_load_dwordx4 v[230:233], v[80:81], off offset:128
	s_nop 0
	global_load_dwordx4 v[226:229], v[82:83], off offset:128
	s_nop 0
	global_load_dwordx4 v[222:225], v[88:89], off offset:128
	global_load_dwordx4 v[218:221], v[90:91], off offset:128
	s_nop 0
	global_load_dwordx4 v[214:217], v[92:93], off offset:128
	s_nop 0
	global_load_dwordx4 v[210:213], v[104:105], off offset:128
	s_nop 0
	global_load_dwordx4 v[206:209], v[106:107], off offset:128
	s_mov_b32 s42, 0
	v_accvgpr_write_b32 a47, 0
	v_accvgpr_write_b32 a46, 0
	v_accvgpr_write_b32 a45, 0
	v_accvgpr_write_b32 a44, 0
	v_accvgpr_write_b32 a43, 0
	v_accvgpr_write_b32 a42, 0
	v_accvgpr_write_b32 a41, 0
	v_accvgpr_write_b32 a40, 0
	v_accvgpr_write_b32 a39, 0
	v_accvgpr_write_b32 a38, 0
	v_accvgpr_write_b32 a37, 0
	v_accvgpr_write_b32 a36, 0
	v_accvgpr_write_b32 a35, 0
	v_accvgpr_write_b32 a34, 0
	v_accvgpr_write_b32 a33, 0
	v_accvgpr_write_b32 a32, 0
	v_accvgpr_write_b32 a63, 0
	v_accvgpr_write_b32 a62, 0
	v_accvgpr_write_b32 a61, 0
	v_accvgpr_write_b32 a60, 0
	v_accvgpr_write_b32 a59, 0
	v_accvgpr_write_b32 a58, 0
	v_accvgpr_write_b32 a57, 0
	v_accvgpr_write_b32 a56, 0
	v_accvgpr_write_b32 a55, 0
	v_accvgpr_write_b32 a54, 0
	v_accvgpr_write_b32 a53, 0
	v_accvgpr_write_b32 a52, 0
	v_accvgpr_write_b32 a51, 0
	v_accvgpr_write_b32 a50, 0
	v_accvgpr_write_b32 a49, 0
	v_accvgpr_write_b32 a48, 0
	v_accvgpr_write_b32 a79, 0
	v_accvgpr_write_b32 a78, 0
	v_accvgpr_write_b32 a77, 0
	v_accvgpr_write_b32 a76, 0
	v_accvgpr_write_b32 a75, 0
	v_accvgpr_write_b32 a74, 0
	v_accvgpr_write_b32 a73, 0
	v_accvgpr_write_b32 a72, 0
	v_accvgpr_write_b32 a71, 0
	v_accvgpr_write_b32 a70, 0
	v_accvgpr_write_b32 a69, 0
	v_accvgpr_write_b32 a68, 0
	v_accvgpr_write_b32 a67, 0
	v_accvgpr_write_b32 a66, 0
	v_accvgpr_write_b32 a65, 0
	v_accvgpr_write_b32 a64, 0
	v_accvgpr_write_b32 a111, 0
	v_accvgpr_write_b32 a110, 0
	v_accvgpr_write_b32 a109, 0
	v_accvgpr_write_b32 a108, 0
	v_accvgpr_write_b32 a107, 0
	v_accvgpr_write_b32 a106, 0
	v_accvgpr_write_b32 a105, 0
	v_accvgpr_write_b32 a104, 0
	v_accvgpr_write_b32 a103, 0
	v_accvgpr_write_b32 a102, 0
	v_accvgpr_write_b32 a101, 0
	v_accvgpr_write_b32 a100, 0
	v_accvgpr_write_b32 a99, 0
	v_accvgpr_write_b32 a98, 0
	v_accvgpr_write_b32 a97, 0
	v_accvgpr_write_b32 a96, 0
	v_accvgpr_write_b32 a95, 0
	v_accvgpr_write_b32 a94, 0
	v_accvgpr_write_b32 a93, 0
	v_accvgpr_write_b32 a92, 0
	v_accvgpr_write_b32 a91, 0
	v_accvgpr_write_b32 a90, 0
	v_accvgpr_write_b32 a89, 0
	v_accvgpr_write_b32 a88, 0
	v_accvgpr_write_b32 a87, 0
	v_accvgpr_write_b32 a86, 0
	v_accvgpr_write_b32 a85, 0
	v_accvgpr_write_b32 a84, 0
	v_accvgpr_write_b32 a83, 0
	v_accvgpr_write_b32 a82, 0
	v_accvgpr_write_b32 a81, 0
	v_accvgpr_write_b32 a80, 0
	v_accvgpr_write_b32 a127, 0
	v_accvgpr_write_b32 a126, 0
	v_accvgpr_write_b32 a125, 0
	v_accvgpr_write_b32 a124, 0
	v_accvgpr_write_b32 a123, 0
	v_accvgpr_write_b32 a122, 0
	v_accvgpr_write_b32 a121, 0
	v_accvgpr_write_b32 a120, 0
	v_accvgpr_write_b32 a119, 0
	v_accvgpr_write_b32 a118, 0
	v_accvgpr_write_b32 a117, 0
	v_accvgpr_write_b32 a116, 0
	v_accvgpr_write_b32 a115, 0
	v_accvgpr_write_b32 a114, 0
	v_accvgpr_write_b32 a113, 0
	v_accvgpr_write_b32 a112, 0
	v_accvgpr_write_b32 a31, 0
	v_accvgpr_write_b32 a30, 0
	v_accvgpr_write_b32 a29, 0
	v_accvgpr_write_b32 a28, 0
	v_accvgpr_write_b32 a27, 0
	v_accvgpr_write_b32 a26, 0
	v_accvgpr_write_b32 a25, 0
	v_accvgpr_write_b32 a24, 0
	v_accvgpr_write_b32 a23, 0
	v_accvgpr_write_b32 a22, 0
	v_accvgpr_write_b32 a21, 0
	v_accvgpr_write_b32 a20, 0
	v_accvgpr_write_b32 a19, 0
	v_accvgpr_write_b32 a18, 0
	v_accvgpr_write_b32 a17, 0
	v_accvgpr_write_b32 a16, 0
	v_accvgpr_write_b32 a15, 0
	v_accvgpr_write_b32 a14, 0
	v_accvgpr_write_b32 a13, 0
	v_accvgpr_write_b32 a12, 0
	v_accvgpr_write_b32 a11, 0
	v_accvgpr_write_b32 a10, 0
	v_accvgpr_write_b32 a9, 0
	v_accvgpr_write_b32 a8, 0
	v_accvgpr_write_b32 a7, 0
	v_accvgpr_write_b32 a6, 0
	v_accvgpr_write_b32 a5, 0
	v_accvgpr_write_b32 a4, 0
	v_accvgpr_write_b32 a3, 0
	v_accvgpr_write_b32 a2, 0
	v_accvgpr_write_b32 a1, 0
	v_accvgpr_write_b32 a0, 0
	s_mov_b64 s[44:45], 0
	s_waitcnt vmcnt(23)
	ds_write_b128 v45, v[108:111]
	s_waitcnt vmcnt(22)
	ds_write_b128 v45, v[112:115] offset:4608
	s_waitcnt vmcnt(21)
	ds_write_b128 v45, v[116:119] offset:9216
	s_waitcnt vmcnt(20)
	ds_write_b128 v45, v[120:123] offset:13824
	s_waitcnt vmcnt(19)
	ds_write_b128 v45, v[124:127] offset:18432
	s_waitcnt vmcnt(18)
	ds_write_b128 v45, v[128:131] offset:23040
	s_waitcnt vmcnt(17)
	ds_write_b128 v45, v[140:143] offset:27648
	s_waitcnt vmcnt(16)
	ds_write_b128 v45, v[144:147] offset:32256
	s_waitcnt vmcnt(15)
	ds_write_b128 v45, v[148:151] offset:36864
	s_waitcnt vmcnt(14)
	ds_write_b128 v45, v[152:155] offset:41472
	s_waitcnt vmcnt(13)
	ds_write_b128 v45, v[156:159] offset:46080
	s_waitcnt vmcnt(12)
	ds_write_b128 v45, v[160:163] offset:50688
	s_waitcnt lgkmcnt(0)
	s_barrier
	s_waitcnt vmcnt(0)
	v_readfirstlane_b32 s100, v10
	v_readfirstlane_b32 s101, v11
	v_readfirstlane_b32 s98, v12
	v_readfirstlane_b32 s99, v13
	s_nop 1
	v_subrev_u32_e32 v194, s100, v10
	v_subrev_u32_e32 v193, s98, v12
	v_add_u32_e32 v254, s73, v194
	v_add_u32_e32 v205, s74, v194
	v_add_u32_e32 v204, s75, v194
	v_add_u32_e32 v203, s78, v194
	v_add_u32_e32 v202, s79, v194
	v_add_u32_e32 v201, s80, v194
	v_add_u32_e32 v200, s81, v194
	v_add_u32_e32 v199, s82, v194
	v_add_u32_e32 v198, s83, v193
	v_add_u32_e32 v197, s84, v193
	v_add_u32_e32 v196, s85, v193
	v_add_u32_e32 v195, s86, v193
	s_add_u32 s100, s100, s44
	s_addc_u32 s101, s101, s45
	s_add_u32 s98, s98, s44
	s_addc_u32 s99, s99, s45
	v_add_u32_e32 v192, v20, v46
	v_add_u32_e32 v191, v20, v47
	v_add_u32_e32 v190, v20, v48
	s_and_b32 s50, s42, 1
	s_mul_i32 s51, s50, 0xd800
	v_add_u32_e32 v189, s51, v192
	v_add_u32_e32 v188, s51, v191
	v_add_u32_e32 v187, s51, v190
	ds_read_b128 v[108:111], v189
	ds_read_b128 v[14:17], v187 offset:36864
	ds_read_b128 v[112:115], v189 offset:4608
	ds_read_b128 v[64:67], v187 offset:41472
	ds_read_b128 v[116:119], v189 offset:9216
	ds_read_b128 v[120:123], v188
	s_getreg_b32 s50, hwreg(HW_REG_HW_ID, 4, 1)
	s_cmp_lg_u32 s50, 0
	s_cbranch_scc1 xg5_varB_4
.LBB0_1265:
	s_and_b32 s50, s42, 1
	s_mul_i32 s51, s50, 0xd800
	s_xor_b32 s50, s50, 1
	s_mul_i32 s50, s50, 0xd800
	s_add_i32 s42, s42, 1
	v_add_u32_e32 v186, s50, v45
	ds_read_b128 v[68:71], v189 offset:32
	ds_read_b128 v[80:83], v187 offset:36896
	ds_read_b128 v[72:75], v189 offset:4640
	ds_read_b128 v[84:87], v187 offset:41504
	ds_read_b128 v[76:79], v189 offset:9248
	ds_read_b128 v[104:107], v188 offset:32
	s_waitcnt lgkmcnt(10)
	v_mfma_f32_32x32x16_bf16 a[32:47], v[108:111], v[14:17], a[32:47]
	s_waitcnt vmcnt(11)
	ds_write_b128 v186, v[250:253]
	s_waitcnt lgkmcnt(9)
	v_mfma_f32_32x32x16_bf16 a[48:63], v[108:111], v[64:67], a[48:63]
	s_waitcnt vmcnt(10)
	ds_write_b128 v186, v[246:249] offset:4608
	global_load_dwordx4 v[250:253], v254, s[100:101] offset:512
	v_mfma_f32_32x32x16_bf16 a[64:79], v[112:115], v[14:17], a[64:79]
	s_waitcnt vmcnt(10)
	ds_write_b128 v186, v[242:245] offset:9216
	global_load_dwordx4 v[246:249], v205, s[100:101] offset:512
	v_mfma_f32_32x32x16_bf16 a[96:111], v[112:115], v[64:67], a[96:111]
	s_waitcnt vmcnt(10)
	ds_write_b128 v186, v[238:241] offset:13824
	global_load_dwordx4 v[242:245], v204, s[100:101] offset:512
	s_waitcnt lgkmcnt(11)
	v_mfma_f32_32x32x16_bf16 a[80:95], v[116:119], v[14:17], a[80:95]
	s_waitcnt vmcnt(10)
	ds_write_b128 v186, v[234:237] offset:18432
	global_load_dwordx4 v[238:241], v203, s[100:101] offset:512
	v_mfma_f32_32x32x16_bf16 a[112:127], v[116:119], v[64:67], a[112:127]
	s_waitcnt vmcnt(10)
	ds_write_b128 v186, v[230:233] offset:23040
	global_load_dwordx4 v[234:237], v202, s[100:101] offset:512
	s_waitcnt lgkmcnt(12)
	v_mfma_f32_32x32x16_bf16 a[16:31], v[120:123], v[14:17], a[16:31]
	s_waitcnt vmcnt(10)
	ds_write_b128 v186, v[226:229] offset:27648
	global_load_dwordx4 v[230:233], v201, s[100:101] offset:512
	v_mfma_f32_32x32x16_bf16 a[0:15], v[120:123], v[64:67], a[0:15]
	s_waitcnt vmcnt(10)
	ds_write_b128 v186, v[222:225] offset:32256
	global_load_dwordx4 v[226:229], v200, s[100:101] offset:512
	ds_read_b128 v[108:111], v189 offset:64
	ds_read_b128 v[14:17], v187 offset:36928
	ds_read_b128 v[112:115], v189 offset:4672
	ds_read_b128 v[64:67], v187 offset:41536
	ds_read_b128 v[116:119], v189 offset:9280
	ds_read_b128 v[120:123], v188 offset:64
	s_waitcnt lgkmcnt(15)
	v_mfma_f32_32x32x16_bf16 a[32:47], v[68:71], v[80:83], a[32:47]
	s_waitcnt vmcnt(10)
	ds_write_b128 v186, v[218:221] offset:36864
	global_load_dwordx4 v[222:225], v199, s[100:101] offset:512
	v_mfma_f32_32x32x16_bf16 a[48:63], v[68:71], v[84:87], a[48:63]
	s_waitcnt vmcnt(10)
	ds_write_b128 v186, v[214:217] offset:41472
	global_load_dwordx4 v[218:221], v198, s[98:99] offset:256
	v_mfma_f32_32x32x16_bf16 a[64:79], v[72:75], v[80:83], a[64:79]
	s_waitcnt vmcnt(10)
	ds_write_b128 v186, v[210:213] offset:46080
	global_load_dwordx4 v[214:217], v197, s[98:99] offset:256
	v_mfma_f32_32x32x16_bf16 a[96:111], v[72:75], v[84:87], a[96:111]
	s_waitcnt vmcnt(10)
	ds_write_b128 v186, v[206:209] offset:50688
	global_load_dwordx4 v[210:213], v196, s[98:99] offset:256
	v_mfma_f32_32x32x16_bf16 a[80:95], v[76:79], v[80:83], a[80:95]
	global_load_dwordx4 v[206:209], v195, s[98:99] offset:256
	s_add_u32 s100, s100, 0x80
	s_addc_u32 s101, s101, 0
	s_add_u32 s98, s98, 0x80
	s_addc_u32 s99, s99, 0
	v_mfma_f32_32x32x16_bf16 a[112:127], v[76:79], v[84:87], a[112:127]
	s_waitcnt lgkmcnt(15)
	v_mfma_f32_32x32x16_bf16 a[16:31], v[104:107], v[80:83], a[16:31]
	v_mfma_f32_32x32x16_bf16 a[0:15], v[104:107], v[84:87], a[0:15]
	ds_read_b128 v[68:71], v189 offset:96
	ds_read_b128 v[80:83], v187 offset:36960
	ds_read_b128 v[72:75], v189 offset:4704
	ds_read_b128 v[84:87], v187 offset:41568
	ds_read_b128 v[76:79], v189 offset:9312
	ds_read_b128 v[104:107], v188 offset:96
	s_waitcnt lgkmcnt(14)
	v_mfma_f32_32x32x16_bf16 a[32:47], v[108:111], v[14:17], a[32:47]
	s_waitcnt lgkmcnt(12)
	v_mfma_f32_32x32x16_bf16 a[48:63], v[108:111], v[64:67], a[48:63]
	v_mfma_f32_32x32x16_bf16 a[64:79], v[112:115], v[14:17], a[64:79]
	v_mfma_f32_32x32x16_bf16 a[96:111], v[112:115], v[64:67], a[96:111]
	s_waitcnt lgkmcnt(11)
	v_mfma_f32_32x32x16_bf16 a[80:95], v[116:119], v[14:17], a[80:95]
	v_mfma_f32_32x32x16_bf16 a[112:127], v[116:119], v[64:67], a[112:127]
	s_waitcnt lgkmcnt(10)
	v_mfma_f32_32x32x16_bf16 a[16:31], v[120:123], v[14:17], a[16:31]
	v_mfma_f32_32x32x16_bf16 a[0:15], v[120:123], v[64:67], a[0:15]
	s_waitcnt lgkmcnt(0)
	v_mfma_f32_32x32x16_bf16 a[32:47], v[68:71], v[80:83], a[32:47]
	v_mfma_f32_32x32x16_bf16 a[48:63], v[68:71], v[84:87], a[48:63]
	v_mfma_f32_32x32x16_bf16 a[64:79], v[72:75], v[80:83], a[64:79]
	v_mfma_f32_32x32x16_bf16 a[96:111], v[72:75], v[84:87], a[96:111]
	s_barrier
	v_add_u32_e32 v189, s50, v192
	v_add_u32_e32 v188, s50, v191
	v_add_u32_e32 v187, s50, v190
	ds_read_b128 v[108:111], v189
	ds_read_b128 v[14:17], v187 offset:36864
	ds_read_b128 v[112:115], v189 offset:4608
	ds_read_b128 v[64:67], v187 offset:41472
	ds_read_b128 v[116:119], v189 offset:9216
	ds_read_b128 v[120:123], v188
	v_mfma_f32_32x32x16_bf16 a[80:95], v[76:79], v[80:83], a[80:95]
	v_mfma_f32_32x32x16_bf16 a[112:127], v[76:79], v[84:87], a[112:127]
	v_mfma_f32_32x32x16_bf16 a[16:31], v[104:107], v[80:83], a[16:31]
	v_mfma_f32_32x32x16_bf16 a[0:15], v[104:107], v[84:87], a[0:15]
	s_add_u32 s44, s44, 0x80
	s_addc_u32 s45, s45, 0
	s_cmpk_lg_i32 s44, 0x700
	s_cbranch_scc1 .LBB0_1265
	s_branch xg5_tail_4
xg5_varB_4:
	s_and_b32 s50, s42, 1
	s_mul_i32 s51, s50, 0xd800
	s_xor_b32 s50, s50, 1
	s_mul_i32 s50, s50, 0xd800
	s_add_i32 s42, s42, 1
	v_add_u32_e32 v186, s50, v45
	ds_read_b128 v[68:71], v189 offset:32
	ds_read_b128 v[80:83], v187 offset:36896
	ds_read_b128 v[72:75], v189 offset:4640
	ds_read_b128 v[84:87], v187 offset:41504
	ds_read_b128 v[76:79], v189 offset:9248
	ds_read_b128 v[104:107], v188 offset:32
	s_waitcnt lgkmcnt(10)
	v_mfma_f32_32x32x16_bf16 a[32:47], v[108:111], v[14:17], a[32:47]
	s_waitcnt lgkmcnt(8)
	v_mfma_f32_32x32x16_bf16 a[48:63], v[108:111], v[64:67], a[48:63]
	v_mfma_f32_32x32x16_bf16 a[64:79], v[112:115], v[14:17], a[64:79]
	v_mfma_f32_32x32x16_bf16 a[96:111], v[112:115], v[64:67], a[96:111]
	s_waitcnt lgkmcnt(7)
	v_mfma_f32_32x32x16_bf16 a[80:95], v[116:119], v[14:17], a[80:95]
	v_mfma_f32_32x32x16_bf16 a[112:127], v[116:119], v[64:67], a[112:127]
	s_waitcnt lgkmcnt(6)
	v_mfma_f32_32x32x16_bf16 a[16:31], v[120:123], v[14:17], a[16:31]
	v_mfma_f32_32x32x16_bf16 a[0:15], v[120:123], v[64:67], a[0:15]
	ds_read_b128 v[108:111], v189 offset:64
	ds_read_b128 v[14:17], v187 offset:36928
	ds_read_b128 v[112:115], v189 offset:4672
	ds_read_b128 v[64:67], v187 offset:41536
	ds_read_b128 v[116:119], v189 offset:9280
	ds_read_b128 v[120:123], v188 offset:64
	s_waitcnt lgkmcnt(10)
	v_mfma_f32_32x32x16_bf16 a[32:47], v[68:71], v[80:83], a[32:47]
	s_waitcnt lgkmcnt(8)
	v_mfma_f32_32x32x16_bf16 a[48:63], v[68:71], v[84:87], a[48:63]
	v_mfma_f32_32x32x16_bf16 a[64:79], v[72:75], v[80:83], a[64:79]
	v_mfma_f32_32x32x16_bf16 a[96:111], v[72:75], v[84:87], a[96:111]
	s_waitcnt lgkmcnt(7)
	v_mfma_f32_32x32x16_bf16 a[80:95], v[76:79], v[80:83], a[80:95]
	s_waitcnt vmcnt(11)
	ds_write_b128 v186, v[250:253]
	v_mfma_f32_32x32x16_bf16 a[112:127], v[76:79], v[84:87], a[112:127]
	s_waitcnt vmcnt(10)
	ds_write_b128 v186, v[246:249] offset:4608
	global_load_dwordx4 v[250:253], v254, s[100:101] offset:512
	s_waitcnt lgkmcnt(8)
	v_mfma_f32_32x32x16_bf16 a[16:31], v[104:107], v[80:83], a[16:31]
	s_waitcnt vmcnt(10)
	ds_write_b128 v186, v[242:245] offset:9216
	global_load_dwordx4 v[246:249], v205, s[100:101] offset:512
	v_mfma_f32_32x32x16_bf16 a[0:15], v[104:107], v[84:87], a[0:15]
	s_waitcnt vmcnt(10)
	ds_write_b128 v186, v[238:241] offset:13824
	global_load_dwordx4 v[242:245], v204, s[100:101] offset:512
	ds_read_b128 v[68:71], v189 offset:96
	ds_read_b128 v[80:83], v187 offset:36960
	ds_read_b128 v[72:75], v189 offset:4704
	ds_read_b128 v[84:87], v187 offset:41568
	ds_read_b128 v[76:79], v189 offset:9312
	ds_read_b128 v[104:107], v188 offset:96
	s_waitcnt lgkmcnt(14)
	v_mfma_f32_32x32x16_bf16 a[32:47], v[108:111], v[14:17], a[32:47]
	s_waitcnt vmcnt(10)
	ds_write_b128 v186, v[234:237] offset:18432
	global_load_dwordx4 v[238:241], v203, s[100:101] offset:512
	s_waitcnt lgkmcnt(13)
	v_mfma_f32_32x32x16_bf16 a[48:63], v[108:111], v[64:67], a[48:63]
	s_waitcnt vmcnt(10)
	ds_write_b128 v186, v[230:233] offset:23040
	global_load_dwordx4 v[234:237], v202, s[100:101] offset:512
	v_mfma_f32_32x32x16_bf16 a[64:79], v[112:115], v[14:17], a[64:79]
	s_waitcnt vmcnt(10)
	ds_write_b128 v186, v[226:229] offset:27648
	global_load_dwordx4 v[230:233], v201, s[100:101] offset:512
	v_mfma_f32_32x32x16_bf16 a[96:111], v[112:115], v[64:67], a[96:111]
	s_waitcnt vmcnt(10)
	ds_write_b128 v186, v[222:225] offset:32256
	global_load_dwordx4 v[226:229], v200, s[100:101] offset:512
	s_waitcnt lgkmcnt(15)
	v_mfma_f32_32x32x16_bf16 a[80:95], v[116:119], v[14:17], a[80:95]
	s_waitcnt vmcnt(10)
	ds_write_b128 v186, v[218:221] offset:36864
	global_load_dwordx4 v[222:225], v199, s[100:101] offset:512
	v_mfma_f32_32x32x16_bf16 a[112:127], v[116:119], v[64:67], a[112:127]
	s_waitcnt vmcnt(10)
	ds_write_b128 v186, v[214:217] offset:41472
	global_load_dwordx4 v[218:221], v198, s[98:99] offset:256
	s_waitcnt lgkmcnt(15)
	v_mfma_f32_32x32x16_bf16 a[16:31], v[120:123], v[14:17], a[16:31]
	s_waitcnt vmcnt(10)
	ds_write_b128 v186, v[210:213] offset:46080
	global_load_dwordx4 v[214:217], v197, s[98:99] offset:256
	v_mfma_f32_32x32x16_bf16 a[0:15], v[120:123], v[64:67], a[0:15]
	s_waitcnt vmcnt(10)
	ds_write_b128 v186, v[206:209] offset:50688
	global_load_dwordx4 v[210:213], v196, s[98:99] offset:256
	s_waitcnt lgkmcnt(0)
	v_mfma_f32_32x32x16_bf16 a[32:47], v[68:71], v[80:83], a[32:47]
	global_load_dwordx4 v[206:209], v195, s[98:99] offset:256
	s_add_u32 s100, s100, 0x80
	s_addc_u32 s101, s101, 0
	s_add_u32 s98, s98, 0x80
	s_addc_u32 s99, s99, 0
	v_mfma_f32_32x32x16_bf16 a[48:63], v[68:71], v[84:87], a[48:63]
	v_mfma_f32_32x32x16_bf16 a[64:79], v[72:75], v[80:83], a[64:79]
	v_mfma_f32_32x32x16_bf16 a[96:111], v[72:75], v[84:87], a[96:111]
	s_barrier
	v_add_u32_e32 v189, s50, v192
	v_add_u32_e32 v188, s50, v191
	v_add_u32_e32 v187, s50, v190
	ds_read_b128 v[108:111], v189
	ds_read_b128 v[14:17], v187 offset:36864
	ds_read_b128 v[112:115], v189 offset:4608
	ds_read_b128 v[64:67], v187 offset:41472
	ds_read_b128 v[116:119], v189 offset:9216
	ds_read_b128 v[120:123], v188
	v_mfma_f32_32x32x16_bf16 a[80:95], v[76:79], v[80:83], a[80:95]
	v_mfma_f32_32x32x16_bf16 a[112:127], v[76:79], v[84:87], a[112:127]
	v_mfma_f32_32x32x16_bf16 a[16:31], v[104:107], v[80:83], a[16:31]
	v_mfma_f32_32x32x16_bf16 a[0:15], v[104:107], v[84:87], a[0:15]
	s_add_u32 s44, s44, 0x80
	s_addc_u32 s45, s45, 0
	s_cmpk_lg_i32 s44, 0x700
	s_cbranch_scc1 xg5_varB_4
xg5_tail_4:
	ds_read_b128 v[10:13], v60
	ds_read_b128 v[108:111], v62 offset:36864
	ds_read_b128 v[112:115], v60 offset:4608
	ds_read_b128 v[116:119], v62 offset:41472
	s_lshl_b32 s44, s48, 8
	s_lshl_b32 s42, s49, 8
	s_waitcnt lgkmcnt(2)
	v_mfma_f32_32x32x16_bf16 a[176:191], v[10:13], v[108:111], a[32:47]
	s_add_i32 s47, s47, s77
	s_add_i32 s46, s46, s77
	s_waitcnt lgkmcnt(0)
	v_mfma_f32_32x32x16_bf16 a[160:175], v[10:13], v[116:119], a[48:63]
	v_mfma_f32_32x32x16_bf16 a[144:159], v[112:115], v[108:111], a[64:79]
	v_mfma_f32_32x32x16_bf16 a[128:143], v[112:115], v[116:119], a[96:111]
	ds_read_b128 v[10:13], v60 offset:9216
	ds_read_b128 v[112:115], v61
	s_waitcnt vmcnt(11)
	s_waitcnt vmcnt(0)
	ds_write_b128 v63, v[250:253] offset:55296
	s_waitcnt vmcnt(10)
	ds_write_b128 v63, v[246:249] offset:59904
	s_waitcnt vmcnt(9)
	ds_write_b128 v63, v[242:245] offset:64512
	s_waitcnt vmcnt(8)
	ds_write_b128 v50, v[238:241] offset:55296
	s_waitcnt vmcnt(7)
	ds_write_b128 v51, v[234:237] offset:55296
	s_waitcnt vmcnt(6)
	ds_write_b128 v52, v[230:233] offset:55296
	s_waitcnt vmcnt(5)
	ds_write_b128 v53, v[226:229] offset:55296
	s_waitcnt vmcnt(4)
	ds_write_b128 v54, v[222:225] offset:55296
	s_waitcnt vmcnt(3)
	ds_write_b128 v55, v[218:221]
	s_waitcnt vmcnt(2)
	ds_write_b128 v55, v[214:217] offset:4608
	s_waitcnt vmcnt(1)
	ds_write_b128 v55, v[210:213] offset:9216
	s_waitcnt vmcnt(0)
	ds_write_b128 v55, v[206:209] offset:13824
	s_waitcnt lgkmcnt(13)
	v_mfma_f32_32x32x16_bf16 a[64:79], v[10:13], v[108:111], a[80:95]
	v_mfma_f32_32x32x16_bf16 a[48:63], v[10:13], v[116:119], a[112:127]
	ds_read_b128 v[10:13], v60 offset:32
	ds_read_b128 v[14:17], v62 offset:36896
	ds_read_b128 v[64:67], v62 offset:36928
	ds_read_b128 v[68:71], v60 offset:64
	ds_read_b128 v[72:75], v62 offset:41504
	ds_read_b128 v[76:79], v62 offset:36960
	s_waitcnt lgkmcnt(4)
	v_mfma_f32_32x32x16_bf16 a[176:191], v[10:13], v[14:17], a[176:191]
	s_waitcnt lgkmcnt(1)
	v_mfma_f32_32x32x16_bf16 a[160:175], v[10:13], v[72:75], a[160:175]
	ds_read_b128 v[10:13], v60 offset:4640
	ds_read_b128 v[80:83], v60 offset:96
	v_mfma_f32_32x32x16_bf16 a[32:47], v[112:115], v[108:111], a[16:31]
	v_mfma_f32_32x32x16_bf16 a[16:31], v[112:115], v[116:119], a[0:15]
	s_waitcnt lgkmcnt(1)
	v_mfma_f32_32x32x16_bf16 a[144:159], v[10:13], v[14:17], a[144:159]
	v_mfma_f32_32x32x16_bf16 a[128:143], v[10:13], v[72:75], a[128:143]
	ds_read_b128 v[10:13], v60 offset:9248
	ds_read_b128 v[84:87], v60 offset:9280
	s_waitcnt lgkmcnt(1)
	v_mfma_f32_32x32x16_bf16 a[64:79], v[10:13], v[14:17], a[64:79]
	v_mfma_f32_32x32x16_bf16 a[48:63], v[10:13], v[72:75], a[48:63]
	ds_read_b128 v[10:13], v61 offset:32
	ds_read_b128 v[88:91], v60 offset:9312
	s_waitcnt lgkmcnt(1)
	v_mfma_f32_32x32x16_bf16 a[32:47], v[10:13], v[14:17], a[32:47]
	v_mfma_f32_32x32x16_bf16 a[16:31], v[10:13], v[72:75], a[16:31]
	ds_read_b128 v[10:13], v62 offset:41536
	ds_read_b128 v[14:17], v62 offset:41568
	v_mfma_f32_32x32x16_bf16 a[176:191], v[68:71], v[64:67], a[176:191]
	s_waitcnt lgkmcnt(1)
	v_mfma_f32_32x32x16_bf16 a[160:175], v[68:71], v[10:13], a[160:175]
	ds_read_b128 v[68:71], v60 offset:4672
	ds_read_b128 v[72:75], v60 offset:4704
	s_waitcnt lgkmcnt(1)
	v_mfma_f32_32x32x16_bf16 a[144:159], v[68:71], v[64:67], a[144:159]
	v_mfma_f32_32x32x16_bf16 a[128:143], v[68:71], v[10:13], a[128:143]
	v_mfma_f32_32x32x16_bf16 a[64:79], v[84:87], v[64:67], a[64:79]
	v_mfma_f32_32x32x16_bf16 a[48:63], v[84:87], v[10:13], a[48:63]
	ds_read_b128 v[68:71], v61 offset:64
	ds_read_b128 v[84:87], v61 offset:96
	s_waitcnt lgkmcnt(0)
	s_barrier
	v_mfma_f32_32x32x16_bf16 a[32:47], v[68:71], v[64:67], a[32:47]
	v_mfma_f32_32x32x16_bf16 a[16:31], v[68:71], v[10:13], a[16:31]
	v_mfma_f32_32x32x16_bf16 a[176:191], v[80:83], v[76:79], a[176:191]
	v_mfma_f32_32x32x16_bf16 a[160:175], v[80:83], v[14:17], a[160:175]
	v_mfma_f32_32x32x16_bf16 a[144:159], v[72:75], v[76:79], a[144:159]
	v_mfma_f32_32x32x16_bf16 a[128:143], v[72:75], v[14:17], a[128:143]
	v_mfma_f32_32x32x16_bf16 a[64:79], v[88:91], v[76:79], a[64:79]
	v_mfma_f32_32x32x16_bf16 a[48:63], v[88:91], v[14:17], a[48:63]
	v_mfma_f32_32x32x16_bf16 a[32:47], v[84:87], v[76:79], a[32:47]
	v_mfma_f32_32x32x16_bf16 a[16:31], v[84:87], v[14:17], a[16:31]
	ds_read_b128 v[10:13], v60 offset:55296
	ds_read_b128 v[14:17], v56
	ds_read_b128 v[64:67], v60 offset:55328
	ds_read_b128 v[68:71], v56 offset:32
	ds_read_b128 v[72:75], v56 offset:4608
	ds_read_b128 v[76:79], v56 offset:4640
	s_waitcnt lgkmcnt(4)
	v_mfma_f32_32x32x16_bf16 a[176:191], v[10:13], v[14:17], a[176:191]
	s_waitcnt lgkmcnt(1)
	v_mfma_f32_32x32x16_bf16 a[160:175], v[10:13], v[72:75], a[160:175]
	ds_read_b128 v[10:13], v60 offset:59904
	ds_read_b128 v[80:83], v60 offset:59936
	s_waitcnt lgkmcnt(1)
	v_mfma_f32_32x32x16_bf16 a[144:159], v[10:13], v[14:17], a[144:159]
	v_mfma_f32_32x32x16_bf16 a[128:143], v[10:13], v[72:75], a[128:143]
	ds_read_b128 v[10:13], v60 offset:64512
	ds_read_b128 v[84:87], v60 offset:64544
	s_waitcnt lgkmcnt(1)
	v_mfma_f32_32x32x16_bf16 a[64:79], v[10:13], v[14:17], a[64:79]
	v_mfma_f32_32x32x16_bf16 a[48:63], v[10:13], v[72:75], a[48:63]
	ds_read_b128 v[10:13], v61 offset:55296
	ds_read_b128 v[88:91], v61 offset:55328
	s_waitcnt lgkmcnt(1)
	v_mfma_f32_32x32x16_bf16 a[32:47], v[10:13], v[14:17], a[32:47]
	v_mfma_f32_32x32x16_bf16 a[16:31], v[10:13], v[72:75], a[16:31]
	ds_read_b128 v[10:13], v60 offset:55360
	v_mfma_f32_32x32x16_bf16 a[176:191], v[64:67], v[68:71], a[176:191]
	v_mfma_f32_32x32x16_bf16 a[160:175], v[64:67], v[76:79], a[160:175]
	v_mfma_f32_32x32x16_bf16 a[144:159], v[80:83], v[68:71], a[144:159]
	v_mfma_f32_32x32x16_bf16 a[128:143], v[80:83], v[76:79], a[128:143]
	v_mfma_f32_32x32x16_bf16 a[64:79], v[84:87], v[68:71], a[64:79]
	v_mfma_f32_32x32x16_bf16 a[48:63], v[84:87], v[76:79], a[48:63]
	ds_read_b128 v[14:17], v56 offset:64
	ds_read_b128 v[64:67], v61 offset:55360
	ds_read_b128 v[72:75], v61 offset:55392
	ds_read_b128 v[80:83], v60 offset:64576
	ds_read_b128 v[84:87], v60 offset:64608
	ds_read_b128 v[92:95], v60 offset:55392
	ds_read_b128 v[96:99], v56 offset:96
	ds_read_b128 v[100:103], v60 offset:59968
	ds_read_b128 v[104:107], v60 offset:60000
	ds_read_b128 v[108:111], v56 offset:4672
	ds_read_b128 v[112:115], v56 offset:4704
	s_waitcnt lgkmcnt(0)
	s_barrier
	v_mfma_f32_32x32x16_bf16 a[32:47], v[88:91], v[68:71], a[32:47]
	v_add_u32_e32 v70, 0x2048, v21
	v_mfma_f32_32x32x16_bf16 a[16:31], v[88:91], v[76:79], a[16:31]
	v_mfma_f32_32x32x16_bf16 a[176:191], v[10:13], v[14:17], a[176:191]
	v_mfma_f32_32x32x16_bf16 a[160:175], v[10:13], v[108:111], a[160:175]
	v_lshl_add_u64 v[10:11], v[6:7], 0, s[42:43]
	v_mfma_f32_32x32x16_bf16 a[144:159], v[100:103], v[14:17], a[144:159]
	v_mfma_f32_32x32x16_bf16 a[128:143], v[100:103], v[108:111], a[128:143]
	v_mfma_f32_32x32x16_bf16 a[64:79], v[80:83], v[14:17], a[64:79]
	v_mfma_f32_32x32x16_bf16 a[48:63], v[80:83], v[108:111], a[48:63]
	v_mfma_f32_32x32x16_bf16 a[32:47], v[64:67], v[14:17], a[32:47]
	v_mfma_f32_32x32x16_bf16 a[16:31], v[64:67], v[108:111], a[16:31]
	v_add_u32_e32 v66, 0x1028, v21
	v_mfma_f32_32x32x16_bf16 a[176:191], v[92:95], v[96:99], a[176:191]
	s_nop 11
	ds_write_b32 v49, a176
	ds_write_b32 v49, a177 offset:516
	ds_write_b32 v49, a178 offset:1032
	ds_write_b32 v49, a179 offset:1548
	ds_write_b32 v49, a180 offset:4128
	ds_write_b32 v49, a181 offset:4644
	ds_write_b32 v49, a182 offset:5160
	v_mfma_f32_32x32x16_bf16 a[160:175], v[92:95], v[112:115], a[160:175]
	ds_write_b32 v49, a183 offset:5676
	ds_write_b32 v49, a184 offset:8256
	ds_write_b32 v49, a185 offset:8772
	ds_write_b32 v49, a186 offset:9288
	ds_write_b32 v49, a187 offset:9804
	ds_write_b32 v49, a188 offset:12384
	ds_write_b32 v49, a189 offset:12900
	ds_write_b32 v49, a190 offset:13416
	ds_write_b32 v49, a191 offset:13932
	s_nop 2
	ds_write_b32 v49, a160 offset:128
	ds_write_b32 v49, a161 offset:644
	ds_write_b32 v49, a162 offset:1160
	ds_write_b32 v49, a163 offset:1676
	ds_write_b32 v49, a164 offset:4256
	ds_write_b32 v49, a165 offset:4772
	ds_write_b32 v49, a166 offset:5288
	ds_write_b32 v49, a167 offset:5804
	ds_write_b32 v49, a168 offset:8384
	ds_write_b32 v49, a169 offset:8900
	ds_write_b32 v49, a170 offset:9416
	ds_write_b32 v49, a171 offset:9932
	v_mfma_f32_32x32x16_bf16 a[144:159], v[104:107], v[96:99], a[144:159]
	ds_write_b32 v49, a172 offset:12512
	ds_write_b32 v49, a173 offset:13028
	ds_write_b32 v49, a174 offset:13544
	ds_write_b32 v49, a175 offset:14060
	s_nop 7
	ds_write_b32 v49, a144 offset:16512
	ds_write_b32 v49, a145 offset:17028
	ds_write_b32 v49, a146 offset:17544
	ds_write_b32 v49, a147 offset:18060
	ds_write_b32 v49, a148 offset:20640
	ds_write_b32 v49, a149 offset:21156
	ds_write_b32 v49, a150 offset:21672
	ds_write_b32 v49, a151 offset:22188
	ds_write_b32 v49, a152 offset:24768
	ds_write_b32 v49, a153 offset:25284
	v_mfma_f32_32x32x16_bf16 a[128:143], v[104:107], v[112:115], a[128:143]
	ds_write_b32 v49, a154 offset:25800
	ds_write_b32 v49, a155 offset:26316
	ds_write_b32 v49, a156 offset:28896
	ds_write_b32 v49, a157 offset:29412
	ds_write_b32 v49, a158 offset:29928
	ds_write_b32 v49, a159 offset:30444
	s_nop 5
	ds_write_b32 v49, a128 offset:16640
	ds_write_b32 v49, a129 offset:17156
	ds_write_b32 v49, a130 offset:17672
	ds_write_b32 v49, a131 offset:18188
	ds_write_b32 v49, a132 offset:20768
	ds_write_b32 v49, a133 offset:21284
	ds_write_b32 v49, a134 offset:21800
	ds_write_b32 v49, a135 offset:22316
	v_mfma_f32_32x32x16_bf16 a[64:79], v[84:87], v[96:99], a[64:79]
	ds_write_b32 v49, a136 offset:24896
	ds_write_b32 v49, a137 offset:25412
	ds_write_b32 v49, a138 offset:25928
	ds_write_b32 v49, a139 offset:26444
	ds_write_b32 v49, a140 offset:29024
	ds_write_b32 v49, a141 offset:29540
	ds_write_b32 v49, a142 offset:30056
	ds_write_b32 v49, a143 offset:30572
	s_nop 3
	ds_write_b32 v49, a64 offset:33024
	ds_write_b32 v49, a65 offset:33540
	ds_write_b32 v49, a66 offset:34056
	ds_write_b32 v49, a67 offset:34572
	ds_write_b32 v49, a68 offset:37152
	ds_write_b32 v49, a69 offset:37668
	v_mfma_f32_32x32x16_bf16 a[48:63], v[84:87], v[112:115], a[48:63]
	ds_write_b32 v49, a70 offset:38184
	ds_write_b32 v49, a71 offset:38700
	ds_write_b32 v49, a72 offset:41280
	ds_write_b32 v49, a73 offset:41796
	ds_write_b32 v49, a74 offset:42312
	ds_write_b32 v49, a75 offset:42828
	ds_write_b32 v49, a76 offset:45408
	ds_write_b32 v49, a77 offset:45924
	ds_write_b32 v49, a78 offset:46440
	ds_write_b32 v49, a79 offset:46956
	s_nop 1
	ds_write_b32 v49, a48 offset:33152
	ds_write_b32 v49, a49 offset:33668
	ds_write_b32 v49, a50 offset:34184
	ds_write_b32 v49, a51 offset:34700
	ds_write_b32 v49, a52 offset:37280
	ds_write_b32 v49, a53 offset:37796
	ds_write_b32 v49, a54 offset:38312
	ds_write_b32 v49, a55 offset:38828
	ds_write_b32 v49, a56 offset:41408
	ds_write_b32 v49, a57 offset:41924
	ds_write_b32 v49, a58 offset:42440
	v_mfma_f32_32x32x16_bf16 a[32:47], v[72:75], v[96:99], a[32:47]
	ds_write_b32 v49, a59 offset:42956
	ds_write_b32 v49, a60 offset:45536
	ds_write_b32 v49, a61 offset:46052
	ds_write_b32 v49, a62 offset:46568
	ds_write_b32 v49, a63 offset:47084
	s_nop 6
	ds_write_b32 v49, a32 offset:49536
	ds_write_b32 v49, a33 offset:50052
	ds_write_b32 v49, a34 offset:50568
	ds_write_b32 v49, a35 offset:51084
	ds_write_b32 v49, a36 offset:53664
	ds_write_b32 v49, a37 offset:54180
	ds_write_b32 v49, a38 offset:54696
	ds_write_b32 v49, a39 offset:55212
	ds_write_b32 v49, a40 offset:57792
	v_mfma_f32_32x32x16_bf16 a[16:31], v[72:75], v[112:115], a[16:31]
	ds_write_b32 v49, a41 offset:58308
	ds_write_b32 v49, a42 offset:58824
	ds_write_b32 v49, a43 offset:59340
	ds_write_b32 v49, a44 offset:61920
	ds_write_b32 v49, a45 offset:62436
	ds_write_b32 v49, a46 offset:62952
	ds_write_b32 v49, a47 offset:63468
	s_nop 4
	ds_write_b32 v49, a16 offset:49664
	ds_write_b32 v49, a17 offset:50180
	ds_write_b32 v49, a18 offset:50696
	ds_write_b32 v49, a19 offset:51212
	ds_write_b32 v49, a20 offset:53792
	ds_write_b32 v49, a21 offset:54308
	ds_write_b32 v49, a22 offset:54824
	ds_write_b32 v49, a23 offset:55340
	ds_write_b32 v49, a24 offset:57920
	ds_write_b32 v49, a25 offset:58436
	ds_write_b32 v49, a26 offset:58952
	ds_write_b32 v49, a27 offset:59468
	ds_write_b32 v49, a28 offset:62048
	ds_write_b32 v49, a29 offset:62564
	ds_write_b32 v49, a30 offset:63080
	ds_write_b32 v49, a31 offset:63596
	s_waitcnt lgkmcnt(0)
	s_barrier
	ds_read2_b32 v[16:17], v21 offset1:1
	ds_read2_b32 v[18:19], v21 offset0:2 offset1:3
	v_accvgpr_read_b32 v72, a218
	v_or_b32_e32 v0, s44, v72
	v_lshlrev_b32_e32 v0, 11, v0
	s_waitcnt lgkmcnt(1)
	v_cvt_pk_bf16_f32 v16, v16, v17
	s_waitcnt lgkmcnt(0)
	v_cvt_pk_bf16_f32 v17, v18, v19
	v_lshl_add_u64 v[18:19], v[10:11], 0, v[0:1]
	v_add_u32_e32 v0, 0x1020, v21
	ds_read2_b32 v[12:13], v29 offset1:1
	ds_read2_b32 v[14:15], v29 offset0:2 offset1:3
	ds_read2_b32 v[64:65], v0 offset1:1
	ds_read2_b32 v[66:67], v66 offset1:1
	v_accvgpr_read_b32 v73, a219
	v_or_b32_e32 v0, s44, v73
	v_lshlrev_b32_e32 v0, 11, v0
	global_store_dwordx2 v[18:19], v[16:17], off
	s_waitcnt lgkmcnt(1)
	v_cvt_pk_bf16_f32 v64, v64, v65
	s_waitcnt lgkmcnt(0)
	v_cvt_pk_bf16_f32 v65, v66, v67
	v_lshl_add_u64 v[66:67], v[10:11], 0, v[0:1]
	v_add_u32_e32 v0, 0x2040, v21
	ds_read2_b32 v[16:17], v44 offset1:1
	ds_read2_b32 v[18:19], v44 offset0:2 offset1:3
	ds_read2_b32 v[68:69], v0 offset1:1
	ds_read2_b32 v[70:71], v70 offset1:1
	global_store_dwordx2 v[66:67], v[64:65], off
	v_add_u32_e32 v0, 0x3060, v21
	v_add_u32_e32 v66, 0x3068, v21
	ds_read2_b32 v[64:65], v0 offset1:1
	ds_read2_b32 v[66:67], v66 offset1:1
	v_or_b32_e32 v0, s44, v132
	v_lshlrev_b32_e32 v0, 11, v0
	s_waitcnt lgkmcnt(3)
	v_cvt_pk_bf16_f32 v68, v68, v69
	s_waitcnt lgkmcnt(2)
	v_cvt_pk_bf16_f32 v69, v70, v71
	v_lshl_add_u64 v[70:71], v[10:11], 0, v[0:1]
	v_or_b32_e32 v0, s44, v133
	v_lshlrev_b32_e32 v0, 11, v0
	global_store_dwordx2 v[70:71], v[68:69], off
	s_waitcnt lgkmcnt(1)
	v_cvt_pk_bf16_f32 v64, v64, v65
	s_waitcnt lgkmcnt(0)
	v_cvt_pk_bf16_f32 v65, v66, v67
	v_lshl_add_u64 v[66:67], v[10:11], 0, v[0:1]
	v_add_u32_e32 v0, 0x4080, v21
	v_add_u32_e32 v70, 0x4088, v21
	ds_read2_b32 v[68:69], v0 offset1:1
	ds_read2_b32 v[70:71], v70 offset1:1
	global_store_dwordx2 v[66:67], v[64:65], off
	v_add_u32_e32 v0, 0x50a0, v21
	v_add_u32_e32 v66, 0x50a8, v21
	ds_read2_b32 v[64:65], v0 offset1:1
	ds_read2_b32 v[66:67], v66 offset1:1
	v_or_b32_e32 v0, s44, v136
	v_lshlrev_b32_e32 v0, 11, v0
	s_waitcnt lgkmcnt(3)
	v_cvt_pk_bf16_f32 v68, v68, v69
	s_waitcnt lgkmcnt(2)
	v_cvt_pk_bf16_f32 v69, v70, v71
	v_lshl_add_u64 v[70:71], v[10:11], 0, v[0:1]
	v_or_b32_e32 v0, s44, v137
	v_lshlrev_b32_e32 v0, 11, v0
	global_store_dwordx2 v[70:71], v[68:69], off
	s_waitcnt lgkmcnt(1)
	v_cvt_pk_bf16_f32 v64, v64, v65
	s_waitcnt lgkmcnt(0)
	v_cvt_pk_bf16_f32 v65, v66, v67
	v_lshl_add_u64 v[66:67], v[10:11], 0, v[0:1]
	v_add_u32_e32 v0, 0x60c0, v21
	v_add_u32_e32 v70, 0x60c8, v21
	ds_read2_b32 v[68:69], v0 offset1:1
	ds_read2_b32 v[70:71], v70 offset1:1
	global_store_dwordx2 v[66:67], v[64:65], off
	v_add_u32_e32 v0, 0x70e0, v21
	v_add_u32_e32 v66, 0x70e8, v21
	ds_read2_b32 v[64:65], v0 offset1:1
	ds_read2_b32 v[66:67], v66 offset1:1
	v_or_b32_e32 v0, s44, v139
	v_lshlrev_b32_e32 v0, 11, v0
	v_accvgpr_read_b32 v74, a225
	s_waitcnt lgkmcnt(3)
	v_cvt_pk_bf16_f32 v68, v68, v69
	s_waitcnt lgkmcnt(2)
	v_cvt_pk_bf16_f32 v69, v70, v71
	v_lshl_add_u64 v[70:71], v[10:11], 0, v[0:1]
	v_or_b32_e32 v0, s44, v74
	v_lshlrev_b32_e32 v0, 11, v0
	global_store_dwordx2 v[70:71], v[68:69], off
	s_waitcnt lgkmcnt(1)
	v_cvt_pk_bf16_f32 v64, v64, v65
	s_waitcnt lgkmcnt(0)
	v_cvt_pk_bf16_f32 v65, v66, v67
	v_lshl_add_u64 v[66:67], v[10:11], 0, v[0:1]
	v_add_u32_e32 v0, 0x8100, v21
	v_add_u32_e32 v70, 0x8108, v21
	ds_read2_b32 v[68:69], v0 offset1:1
	ds_read2_b32 v[70:71], v70 offset1:1
	global_store_dwordx2 v[66:67], v[64:65], off
	v_add_u32_e32 v0, 0x9120, v21
	v_add_u32_e32 v66, 0x9128, v21
	ds_read2_b32 v[64:65], v0 offset1:1
	ds_read2_b32 v[66:67], v66 offset1:1
	v_accvgpr_read_b32 v75, a226
	v_or_b32_e32 v0, s44, v75
	v_lshlrev_b32_e32 v0, 11, v0
	s_waitcnt lgkmcnt(3)
	v_cvt_pk_bf16_f32 v68, v68, v69
	s_waitcnt lgkmcnt(2)
	v_cvt_pk_bf16_f32 v69, v70, v71
	v_lshl_add_u64 v[70:71], v[10:11], 0, v[0:1]
	v_or_b32_e32 v0, s44, v22
	v_lshlrev_b32_e32 v0, 11, v0
	global_store_dwordx2 v[70:71], v[68:69], off
	s_waitcnt lgkmcnt(1)
	v_cvt_pk_bf16_f32 v64, v64, v65
	s_waitcnt lgkmcnt(0)
	v_cvt_pk_bf16_f32 v65, v66, v67
	v_lshl_add_u64 v[66:67], v[10:11], 0, v[0:1]
	v_add_u32_e32 v0, 0xa140, v21
	v_add_u32_e32 v70, 0xa148, v21
	ds_read2_b32 v[68:69], v0 offset1:1
	ds_read2_b32 v[70:71], v70 offset1:1
	global_store_dwordx2 v[66:67], v[64:65], off
	v_add_u32_e32 v0, 0xb160, v21
	v_add_u32_e32 v66, 0xb168, v21
	ds_read2_b32 v[64:65], v0 offset1:1
	ds_read2_b32 v[66:67], v66 offset1:1
	v_or_b32_e32 v0, s44, v23
	v_lshlrev_b32_e32 v0, 11, v0
	s_waitcnt lgkmcnt(3)
	v_cvt_pk_bf16_f32 v68, v68, v69
	s_waitcnt lgkmcnt(2)
	v_cvt_pk_bf16_f32 v69, v70, v71
	v_lshl_add_u64 v[70:71], v[10:11], 0, v[0:1]
	v_or_b32_e32 v0, s44, v24
	v_lshlrev_b32_e32 v0, 11, v0
	global_store_dwordx2 v[70:71], v[68:69], off
	s_waitcnt lgkmcnt(1)
	v_cvt_pk_bf16_f32 v64, v64, v65
	s_waitcnt lgkmcnt(0)
	v_cvt_pk_bf16_f32 v65, v66, v67
	v_lshl_add_u64 v[66:67], v[10:11], 0, v[0:1]
	v_add_u32_e32 v0, 0xc180, v21
	v_add_u32_e32 v70, 0xc188, v21
	ds_read2_b32 v[68:69], v0 offset1:1
	ds_read2_b32 v[70:71], v70 offset1:1
	global_store_dwordx2 v[66:67], v[64:65], off
	v_add_u32_e32 v0, 0xd1a0, v21
	v_add_u32_e32 v66, 0xd1a8, v21
	ds_read2_b32 v[64:65], v0 offset1:1
	ds_read2_b32 v[66:67], v66 offset1:1
	v_or_b32_e32 v0, s44, v25
	v_lshlrev_b32_e32 v0, 11, v0
	s_waitcnt lgkmcnt(3)
	v_cvt_pk_bf16_f32 v68, v68, v69
	s_waitcnt lgkmcnt(2)
	v_cvt_pk_bf16_f32 v69, v70, v71
	v_lshl_add_u64 v[70:71], v[10:11], 0, v[0:1]
	v_or_b32_e32 v0, s44, v26
	v_lshlrev_b32_e32 v0, 11, v0
	global_store_dwordx2 v[70:71], v[68:69], off
	s_waitcnt lgkmcnt(1)
	v_cvt_pk_bf16_f32 v64, v64, v65
	s_waitcnt lgkmcnt(0)
	v_cvt_pk_bf16_f32 v65, v66, v67
	v_lshl_add_u64 v[66:67], v[10:11], 0, v[0:1]
	v_add_u32_e32 v0, 0xe1c0, v21
	v_add_u32_e32 v70, 0xe1c8, v21
	ds_read2_b32 v[68:69], v0 offset1:1
	ds_read2_b32 v[70:71], v70 offset1:1
	global_store_dwordx2 v[66:67], v[64:65], off
	v_add_u32_e32 v0, 0xf1e0, v21
	v_add_u32_e32 v66, 0xf1e8, v21
	ds_read2_b32 v[64:65], v0 offset1:1
	ds_read2_b32 v[66:67], v66 offset1:1
	v_or_b32_e32 v0, s44, v27
	v_lshlrev_b32_e32 v0, 11, v0
	s_waitcnt lgkmcnt(3)
	v_cvt_pk_bf16_f32 v68, v68, v69
	s_waitcnt lgkmcnt(2)
	v_cvt_pk_bf16_f32 v69, v70, v71
	v_lshl_add_u64 v[70:71], v[10:11], 0, v[0:1]
	v_or_b32_e32 v0, s44, v28
	v_lshlrev_b32_e32 v0, 11, v0
	s_bitset1_b32 s44, 7
	s_waitcnt lgkmcnt(1)
	v_cvt_pk_bf16_f32 v64, v64, v65
	s_waitcnt lgkmcnt(0)
	v_cvt_pk_bf16_f32 v65, v66, v67
	v_lshl_add_u64 v[66:67], v[10:11], 0, v[0:1]
	v_or_b32_e32 v0, s44, v72
	global_store_dwordx2 v[70:71], v[68:69], off
	global_store_dwordx2 v[66:67], v[64:65], off
	v_lshlrev_b32_e32 v0, 11, v0
	v_cvt_pk_bf16_f32 v12, v12, v13
	v_cvt_pk_bf16_f32 v13, v14, v15
	v_lshl_add_u64 v[14:15], v[10:11], 0, v[0:1]
	ds_read2_b32 v[64:65], v30 offset1:1
	ds_read2_b32 v[66:67], v30 offset0:2 offset1:3
	global_store_dwordx2 v[14:15], v[12:13], off
	ds_read2_b32 v[12:13], v31 offset1:1
	ds_read2_b32 v[14:15], v31 offset0:2 offset1:3
	v_or_b32_e32 v0, s44, v73
	v_lshlrev_b32_e32 v0, 11, v0
	s_waitcnt lgkmcnt(3)
	v_cvt_pk_bf16_f32 v64, v64, v65
	s_waitcnt lgkmcnt(2)
	v_cvt_pk_bf16_f32 v65, v66, v67
	v_lshl_add_u64 v[66:67], v[10:11], 0, v[0:1]
	v_or_b32_e32 v0, s44, v132
	global_store_dwordx2 v[66:67], v[64:65], off
	v_lshlrev_b32_e32 v0, 11, v0
	s_waitcnt lgkmcnt(1)
	v_cvt_pk_bf16_f32 v12, v12, v13
	s_waitcnt lgkmcnt(0)
	v_cvt_pk_bf16_f32 v13, v14, v15
	v_lshl_add_u64 v[14:15], v[10:11], 0, v[0:1]
	ds_read2_b32 v[64:65], v32 offset1:1
	ds_read2_b32 v[66:67], v32 offset0:2 offset1:3
	global_store_dwordx2 v[14:15], v[12:13], off
	ds_read2_b32 v[12:13], v33 offset1:1
	ds_read2_b32 v[14:15], v33 offset0:2 offset1:3
	v_or_b32_e32 v0, s44, v133
	v_lshlrev_b32_e32 v0, 11, v0
	s_waitcnt lgkmcnt(3)
	v_cvt_pk_bf16_f32 v64, v64, v65
	s_waitcnt lgkmcnt(2)
	v_cvt_pk_bf16_f32 v65, v66, v67
	v_lshl_add_u64 v[66:67], v[10:11], 0, v[0:1]
	v_or_b32_e32 v0, s44, v136
	global_store_dwordx2 v[66:67], v[64:65], off
	v_lshlrev_b32_e32 v0, 11, v0
	s_waitcnt lgkmcnt(1)
	v_cvt_pk_bf16_f32 v12, v12, v13
	s_waitcnt lgkmcnt(0)
	v_cvt_pk_bf16_f32 v13, v14, v15
	v_lshl_add_u64 v[14:15], v[10:11], 0, v[0:1]
	ds_read2_b32 v[64:65], v34 offset1:1
	ds_read2_b32 v[66:67], v34 offset0:2 offset1:3
	global_store_dwordx2 v[14:15], v[12:13], off
	ds_read2_b32 v[12:13], v35 offset1:1
	ds_read2_b32 v[14:15], v35 offset0:2 offset1:3
	v_or_b32_e32 v0, s44, v137
	v_lshlrev_b32_e32 v0, 11, v0
	s_waitcnt lgkmcnt(3)
	v_cvt_pk_bf16_f32 v64, v64, v65
	s_waitcnt lgkmcnt(2)
	v_cvt_pk_bf16_f32 v65, v66, v67
	v_lshl_add_u64 v[66:67], v[10:11], 0, v[0:1]
	v_or_b32_e32 v0, s44, v139
	global_store_dwordx2 v[66:67], v[64:65], off
	v_lshlrev_b32_e32 v0, 11, v0
	s_waitcnt lgkmcnt(1)
	v_cvt_pk_bf16_f32 v12, v12, v13
	s_waitcnt lgkmcnt(0)
	v_cvt_pk_bf16_f32 v13, v14, v15
	v_lshl_add_u64 v[14:15], v[10:11], 0, v[0:1]
	ds_read2_b32 v[64:65], v36 offset1:1
	ds_read2_b32 v[66:67], v36 offset0:2 offset1:3
	global_store_dwordx2 v[14:15], v[12:13], off
	ds_read2_b32 v[12:13], v37 offset1:1
	ds_read2_b32 v[14:15], v37 offset0:2 offset1:3
	v_or_b32_e32 v0, s44, v74
	v_lshlrev_b32_e32 v0, 11, v0
	s_waitcnt lgkmcnt(3)
	v_cvt_pk_bf16_f32 v64, v64, v65
	s_waitcnt lgkmcnt(2)
	v_cvt_pk_bf16_f32 v65, v66, v67
	v_lshl_add_u64 v[66:67], v[10:11], 0, v[0:1]
	v_or_b32_e32 v0, s44, v75
	global_store_dwordx2 v[66:67], v[64:65], off
	v_lshlrev_b32_e32 v0, 11, v0
	s_waitcnt lgkmcnt(1)
	v_cvt_pk_bf16_f32 v12, v12, v13
	s_waitcnt lgkmcnt(0)
	v_cvt_pk_bf16_f32 v13, v14, v15
	v_lshl_add_u64 v[14:15], v[10:11], 0, v[0:1]
	ds_read2_b32 v[64:65], v38 offset1:1
	ds_read2_b32 v[66:67], v38 offset0:2 offset1:3
	global_store_dwordx2 v[14:15], v[12:13], off
	ds_read2_b32 v[12:13], v39 offset1:1
	ds_read2_b32 v[14:15], v39 offset0:2 offset1:3
	v_or_b32_e32 v0, s44, v22
	v_lshlrev_b32_e32 v0, 11, v0
	s_waitcnt lgkmcnt(3)
	v_cvt_pk_bf16_f32 v64, v64, v65
	s_waitcnt lgkmcnt(2)
	v_cvt_pk_bf16_f32 v65, v66, v67
	v_lshl_add_u64 v[66:67], v[10:11], 0, v[0:1]
	v_or_b32_e32 v0, s44, v23
	global_store_dwordx2 v[66:67], v[64:65], off
	v_lshlrev_b32_e32 v0, 11, v0
	s_waitcnt lgkmcnt(1)
	v_cvt_pk_bf16_f32 v12, v12, v13
	s_waitcnt lgkmcnt(0)
	v_cvt_pk_bf16_f32 v13, v14, v15
	v_lshl_add_u64 v[14:15], v[10:11], 0, v[0:1]
	ds_read2_b32 v[64:65], v40 offset1:1
	ds_read2_b32 v[66:67], v40 offset0:2 offset1:3
	global_store_dwordx2 v[14:15], v[12:13], off
	ds_read2_b32 v[12:13], v41 offset1:1
	ds_read2_b32 v[14:15], v41 offset0:2 offset1:3
	v_or_b32_e32 v0, s44, v24
	v_lshlrev_b32_e32 v0, 11, v0
	s_waitcnt lgkmcnt(3)
	v_cvt_pk_bf16_f32 v64, v64, v65
	s_waitcnt lgkmcnt(2)
	v_cvt_pk_bf16_f32 v65, v66, v67
	v_lshl_add_u64 v[66:67], v[10:11], 0, v[0:1]
	v_or_b32_e32 v0, s44, v25
	v_lshlrev_b32_e32 v0, 11, v0
	global_store_dwordx2 v[66:67], v[64:65], off
	s_waitcnt lgkmcnt(1)
	v_cvt_pk_bf16_f32 v12, v12, v13
	s_waitcnt lgkmcnt(0)
	v_cvt_pk_bf16_f32 v13, v14, v15
	v_lshl_add_u64 v[14:15], v[10:11], 0, v[0:1]
	ds_read2_b32 v[64:65], v42 offset1:1
	ds_read2_b32 v[66:67], v42 offset0:2 offset1:3
	global_store_dwordx2 v[14:15], v[12:13], off
	ds_read2_b32 v[12:13], v43 offset1:1
	ds_read2_b32 v[14:15], v43 offset0:2 offset1:3
	v_add_lshl_u32 v0, s44, v26, 11
	s_waitcnt lgkmcnt(3)
	v_cvt_pk_bf16_f32 v64, v64, v65
	s_waitcnt lgkmcnt(2)
	v_cvt_pk_bf16_f32 v65, v66, v67
	v_lshl_add_u64 v[66:67], v[10:11], 0, v[0:1]
	v_add_lshl_u32 v0, s44, v27, 11
	s_waitcnt lgkmcnt(1)
	v_cvt_pk_bf16_f32 v12, v12, v13
	s_waitcnt lgkmcnt(0)
	v_cvt_pk_bf16_f32 v13, v14, v15
	v_lshl_add_u64 v[14:15], v[10:11], 0, v[0:1]
	v_add_lshl_u32 v0, s44, v28, 11
	global_store_dwordx2 v[14:15], v[12:13], off
	v_cvt_pk_bf16_f32 v12, v16, v17
	v_cvt_pk_bf16_f32 v13, v18, v19
	v_lshl_add_u64 v[10:11], v[10:11], 0, v[0:1]
	s_cmpk_lt_u32 s47, 0x60
	global_store_dwordx2 v[66:67], v[64:65], off
	global_store_dwordx2 v[10:11], v[12:13], off
	s_barrier
	s_cbranch_scc1 .LBB0_1264

.LBB0_1403:
	s_andn2_saveexec_b64 s[50:51], s[50:51]
	v_mul_f32_e32 v34, v33, v33
	v_fmamk_f32 v35, v34, 0xba1345e1, v139
	v_fmaak_f32 v35, v34, v35, 0xbcdac9b8
	v_fmaak_f32 v35, v34, v35, 0x3de703be
	v_fmaak_f32 v35, v34, v35, 0xbec09330
	v_fmaak_f32 v34, v34, v35, 0x3e0375d0
	v_fma_f32 v34, |v33|, v34, |v33|
	s_or_b64 exec, exec, s[50:51]
	v_cvt_scalef32_pk_f32_fp4 v[36:37], v204, 1.0
	v_pk_fma_f32 v[36:37], s[30:31], v[36:37], v[200:201] op_sel_hi:[0,1,1]
	v_cvt_scalef32_pk_f32_fp4 v[38:39], v204, 1.0 op_sel:[1,0,0]
	v_cvt_scalef32_pk_f32_fp4 v[52:53], v202, 1.0
	v_pk_fma_f32 v[38:39], s[30:31], v[38:39], v[218:219] op_sel_hi:[0,1,1]
	v_cvt_scalef32_pk_f32_fp4 v[40:41], v204, 1.0 op_sel:[0,1,0]
	v_pk_fma_f32 v[36:37], s[28:29], v[52:53], v[36:37] op_sel_hi:[0,1,1]
	v_cvt_scalef32_pk_f32_fp4 v[52:53], v202, 1.0 op_sel:[1,0,0]
	v_pk_fma_f32 v[40:41], s[30:31], v[40:41], v[216:217] op_sel_hi:[0,1,1]
	v_cvt_scalef32_pk_f32_fp4 v[42:43], v204, 1.0 op_sel:[1,1,0]
	v_pk_fma_f32 v[38:39], s[28:29], v[52:53], v[38:39] op_sel_hi:[0,1,1]
	v_cvt_scalef32_pk_f32_fp4 v[52:53], v202, 1.0 op_sel:[0,1,0]
	v_pk_fma_f32 v[42:43], s[30:31], v[42:43], v[214:215] op_sel_hi:[0,1,1]
	v_cvt_scalef32_pk_f32_fp4 v[44:45], v205, 1.0
	v_pk_fma_f32 v[40:41], s[28:29], v[52:53], v[40:41] op_sel_hi:[0,1,1]
	v_cvt_scalef32_pk_f32_fp4 v[52:53], v202, 1.0 op_sel:[1,1,0]
	v_pk_fma_f32 v[44:45], s[30:31], v[44:45], v[212:213] op_sel_hi:[0,1,1]
	v_cvt_scalef32_pk_f32_fp4 v[46:47], v205, 1.0 op_sel:[1,0,0]
	v_pk_fma_f32 v[42:43], s[28:29], v[52:53], v[42:43] op_sel_hi:[0,1,1]
	v_cvt_scalef32_pk_f32_fp4 v[52:53], v203, 1.0
	v_pk_fma_f32 v[46:47], s[30:31], v[46:47], v[210:211] op_sel_hi:[0,1,1]
	v_cvt_scalef32_pk_f32_fp4 v[48:49], v205, 1.0 op_sel:[0,1,0]
	v_pk_fma_f32 v[44:45], s[28:29], v[52:53], v[44:45] op_sel_hi:[0,1,1]
	v_cvt_scalef32_pk_f32_fp4 v[52:53], v203, 1.0 op_sel:[1,0,0]
	v_pk_fma_f32 v[48:49], s[30:31], v[48:49], v[208:209] op_sel_hi:[0,1,1]
	v_cvt_scalef32_pk_f32_fp4 v[50:51], v205, 1.0 op_sel:[1,1,0]
	v_pk_fma_f32 v[46:47], s[28:29], v[52:53], v[46:47] op_sel_hi:[0,1,1]
	v_cvt_scalef32_pk_f32_fp4 v[52:53], v203, 1.0 op_sel:[0,1,0]
	v_pk_fma_f32 v[50:51], s[30:31], v[50:51], v[206:207] op_sel_hi:[0,1,1]
	v_pk_fma_f32 v[48:49], s[28:29], v[52:53], v[48:49] op_sel_hi:[0,1,1]
	v_cvt_scalef32_pk_f32_fp4 v[52:53], v203, 1.0 op_sel:[1,1,0]
	v_pk_fma_f32 v[50:51], s[28:29], v[52:53], v[50:51] op_sel_hi:[0,1,1]
	v_cvt_scalef32_pk_f32_fp4 v[52:53], v198, 1.0
	v_pk_fma_f32 v[36:37], s[26:27], v[52:53], v[36:37] op_sel_hi:[0,1,1]
	v_cvt_scalef32_pk_f32_fp4 v[52:53], v198, 1.0 op_sel:[1,0,0]
	v_pk_fma_f32 v[38:39], s[26:27], v[52:53], v[38:39] op_sel_hi:[0,1,1]
	v_cvt_scalef32_pk_f32_fp4 v[52:53], v198, 1.0 op_sel:[0,1,0]
	v_pk_fma_f32 v[40:41], s[26:27], v[52:53], v[40:41] op_sel_hi:[0,1,1]
	v_cvt_scalef32_pk_f32_fp4 v[52:53], v198, 1.0 op_sel:[1,1,0]
	v_pk_fma_f32 v[42:43], s[26:27], v[52:53], v[42:43] op_sel_hi:[0,1,1]
	v_cvt_scalef32_pk_f32_fp4 v[52:53], v199, 1.0
	v_pk_fma_f32 v[44:45], s[26:27], v[52:53], v[44:45] op_sel_hi:[0,1,1]
	v_cvt_scalef32_pk_f32_fp4 v[52:53], v199, 1.0 op_sel:[1,0,0]
	v_pk_fma_f32 v[46:47], s[26:27], v[52:53], v[46:47] op_sel_hi:[0,1,1]
	v_cvt_scalef32_pk_f32_fp4 v[52:53], v199, 1.0 op_sel:[0,1,0]
	v_pk_fma_f32 v[48:49], s[26:27], v[52:53], v[48:49] op_sel_hi:[0,1,1]
	v_cvt_scalef32_pk_f32_fp4 v[52:53], v199, 1.0 op_sel:[1,1,0]
	v_pk_fma_f32 v[50:51], s[26:27], v[52:53], v[50:51] op_sel_hi:[0,1,1]
	v_cvt_scalef32_pk_f32_fp4 v[52:53], v196, 1.0
	v_pk_fma_f32 v[36:37], s[12:13], v[52:53], v[36:37] op_sel_hi:[0,1,1]
	v_cvt_scalef32_pk_f32_fp4 v[52:53], v196, 1.0 op_sel:[1,0,0]
	v_pk_fma_f32 v[38:39], s[12:13], v[52:53], v[38:39] op_sel_hi:[0,1,1]
	v_cvt_scalef32_pk_f32_fp4 v[52:53], v196, 1.0 op_sel:[0,1,0]
	v_pk_fma_f32 v[40:41], s[12:13], v[52:53], v[40:41] op_sel_hi:[0,1,1]
	v_cvt_scalef32_pk_f32_fp4 v[52:53], v196, 1.0 op_sel:[1,1,0]
	v_pk_fma_f32 v[42:43], s[12:13], v[52:53], v[42:43] op_sel_hi:[0,1,1]
	v_cvt_scalef32_pk_f32_fp4 v[52:53], v197, 1.0
	v_pk_fma_f32 v[44:45], s[12:13], v[52:53], v[44:45] op_sel_hi:[0,1,1]
	v_cvt_scalef32_pk_f32_fp4 v[52:53], v197, 1.0 op_sel:[1,0,0]
	v_pk_fma_f32 v[46:47], s[12:13], v[52:53], v[46:47] op_sel_hi:[0,1,1]
	v_cvt_scalef32_pk_f32_fp4 v[52:53], v197, 1.0 op_sel:[0,1,0]
	v_pk_fma_f32 v[48:49], s[12:13], v[52:53], v[48:49] op_sel_hi:[0,1,1]
	v_cvt_scalef32_pk_f32_fp4 v[52:53], v197, 1.0 op_sel:[1,1,0]
	v_pk_fma_f32 v[50:51], s[12:13], v[52:53], v[50:51] op_sel_hi:[0,1,1]
	v_cvt_scalef32_pk_f32_fp4 v[52:53], v194, 1.0
	v_pk_fma_f32 v[36:37], s[40:41], v[52:53], v[36:37] op_sel_hi:[0,1,1]
	v_cvt_scalef32_pk_f32_fp4 v[52:53], v194, 1.0 op_sel:[1,0,0]
	v_pk_fma_f32 v[38:39], s[40:41], v[52:53], v[38:39] op_sel_hi:[0,1,1]
	v_cvt_scalef32_pk_f32_fp4 v[52:53], v194, 1.0 op_sel:[0,1,0]
	v_pk_fma_f32 v[40:41], s[40:41], v[52:53], v[40:41] op_sel_hi:[0,1,1]
	v_cvt_scalef32_pk_f32_fp4 v[52:53], v194, 1.0 op_sel:[1,1,0]
	v_pk_fma_f32 v[42:43], s[40:41], v[52:53], v[42:43] op_sel_hi:[0,1,1]
	v_cvt_scalef32_pk_f32_fp4 v[52:53], v195, 1.0
	v_pk_fma_f32 v[44:45], s[40:41], v[52:53], v[44:45] op_sel_hi:[0,1,1]
	v_cvt_scalef32_pk_f32_fp4 v[52:53], v195, 1.0 op_sel:[1,0,0]
	v_pk_fma_f32 v[46:47], s[40:41], v[52:53], v[46:47] op_sel_hi:[0,1,1]
	v_cvt_scalef32_pk_f32_fp4 v[52:53], v195, 1.0 op_sel:[0,1,0]
	v_pk_fma_f32 v[48:49], s[40:41], v[52:53], v[48:49] op_sel_hi:[0,1,1]
	v_cvt_scalef32_pk_f32_fp4 v[52:53], v195, 1.0 op_sel:[1,1,0]
	v_pk_fma_f32 v[50:51], s[40:41], v[52:53], v[50:51] op_sel_hi:[0,1,1]
	v_cvt_scalef32_pk_f32_fp4 v[52:53], v192, 1.0
	v_pk_fma_f32 v[36:37], s[38:39], v[52:53], v[36:37] op_sel_hi:[0,1,1]
	v_cvt_scalef32_pk_f32_fp4 v[52:53], v192, 1.0 op_sel:[1,0,0]
	v_pk_fma_f32 v[38:39], s[38:39], v[52:53], v[38:39] op_sel_hi:[0,1,1]
	v_cvt_scalef32_pk_f32_fp4 v[52:53], v192, 1.0 op_sel:[0,1,0]
	v_pk_fma_f32 v[40:41], s[38:39], v[52:53], v[40:41] op_sel_hi:[0,1,1]
	v_cvt_scalef32_pk_f32_fp4 v[52:53], v192, 1.0 op_sel:[1,1,0]
	v_pk_fma_f32 v[42:43], s[38:39], v[52:53], v[42:43] op_sel_hi:[0,1,1]
	v_cvt_scalef32_pk_f32_fp4 v[52:53], v193, 1.0
	v_pk_fma_f32 v[44:45], s[38:39], v[52:53], v[44:45] op_sel_hi:[0,1,1]
	v_cvt_scalef32_pk_f32_fp4 v[52:53], v193, 1.0 op_sel:[1,0,0]
	v_pk_fma_f32 v[46:47], s[38:39], v[52:53], v[46:47] op_sel_hi:[0,1,1]
	v_cvt_scalef32_pk_f32_fp4 v[52:53], v193, 1.0 op_sel:[0,1,0]
	v_pk_fma_f32 v[48:49], s[38:39], v[52:53], v[48:49] op_sel_hi:[0,1,1]
	v_cvt_scalef32_pk_f32_fp4 v[52:53], v193, 1.0 op_sel:[1,1,0]
	v_pk_fma_f32 v[50:51], s[38:39], v[52:53], v[50:51] op_sel_hi:[0,1,1]
	v_cvt_scalef32_pk_f32_fp4 v[52:53], v190, 1.0
	v_pk_fma_f32 v[36:37], s[36:37], v[52:53], v[36:37] op_sel_hi:[0,1,1]
	v_cvt_scalef32_pk_f32_fp4 v[52:53], v190, 1.0 op_sel:[1,0,0]
	v_pk_fma_f32 v[38:39], s[36:37], v[52:53], v[38:39] op_sel_hi:[0,1,1]
	v_cvt_scalef32_pk_f32_fp4 v[52:53], v190, 1.0 op_sel:[0,1,0]
	v_pk_fma_f32 v[40:41], s[36:37], v[52:53], v[40:41] op_sel_hi:[0,1,1]
	v_cvt_scalef32_pk_f32_fp4 v[52:53], v190, 1.0 op_sel:[1,1,0]
	v_pk_fma_f32 v[42:43], s[36:37], v[52:53], v[42:43] op_sel_hi:[0,1,1]
	v_cvt_scalef32_pk_f32_fp4 v[52:53], v191, 1.0
	v_pk_fma_f32 v[44:45], s[36:37], v[52:53], v[44:45] op_sel_hi:[0,1,1]
	v_cvt_scalef32_pk_f32_fp4 v[52:53], v191, 1.0 op_sel:[1,0,0]
	v_pk_fma_f32 v[46:47], s[36:37], v[52:53], v[46:47] op_sel_hi:[0,1,1]
	v_cvt_scalef32_pk_f32_fp4 v[52:53], v191, 1.0 op_sel:[0,1,0]
	v_pk_fma_f32 v[48:49], s[36:37], v[52:53], v[48:49] op_sel_hi:[0,1,1]
	v_cvt_scalef32_pk_f32_fp4 v[52:53], v191, 1.0 op_sel:[1,1,0]
	v_pk_fma_f32 v[50:51], s[36:37], v[52:53], v[50:51] op_sel_hi:[0,1,1]
	v_cvt_scalef32_pk_f32_fp4 v[52:53], v188, 1.0
	v_pk_fma_f32 v[36:37], s[34:35], v[52:53], v[36:37] op_sel_hi:[0,1,1]
	v_cvt_scalef32_pk_f32_fp4 v[52:53], v188, 1.0 op_sel:[1,0,0]
	v_pk_fma_f32 v[38:39], s[34:35], v[52:53], v[38:39] op_sel_hi:[0,1,1]
	v_cvt_scalef32_pk_f32_fp4 v[52:53], v188, 1.0 op_sel:[0,1,0]
	v_pk_fma_f32 v[40:41], s[34:35], v[52:53], v[40:41] op_sel_hi:[0,1,1]
	v_cvt_scalef32_pk_f32_fp4 v[52:53], v188, 1.0 op_sel:[1,1,0]
	v_pk_fma_f32 v[42:43], s[34:35], v[52:53], v[42:43] op_sel_hi:[0,1,1]
	v_cvt_scalef32_pk_f32_fp4 v[52:53], v189, 1.0
	v_pk_fma_f32 v[44:45], s[34:35], v[52:53], v[44:45] op_sel_hi:[0,1,1]
	v_cvt_scalef32_pk_f32_fp4 v[52:53], v189, 1.0 op_sel:[1,0,0]
	v_pk_fma_f32 v[46:47], s[34:35], v[52:53], v[46:47] op_sel_hi:[0,1,1]
	v_cvt_scalef32_pk_f32_fp4 v[52:53], v189, 1.0 op_sel:[0,1,0]
	v_pk_fma_f32 v[48:49], s[34:35], v[52:53], v[48:49] op_sel_hi:[0,1,1]
	v_cvt_scalef32_pk_f32_fp4 v[52:53], v189, 1.0 op_sel:[1,1,0]
	v_pk_fma_f32 v[50:51], s[34:35], v[52:53], v[50:51] op_sel_hi:[0,1,1]
	v_cvt_scalef32_pk_f32_fp4 v[52:53], v186, 1.0
	v_pk_fma_f32 v[36:37], s[48:49], v[52:53], v[36:37] op_sel_hi:[0,1,1]
	v_cvt_scalef32_pk_f32_fp4 v[52:53], v186, 1.0 op_sel:[1,0,0]
	v_pk_fma_f32 v[38:39], s[48:49], v[52:53], v[38:39] op_sel_hi:[0,1,1]
	v_cvt_scalef32_pk_f32_fp4 v[52:53], v186, 1.0 op_sel:[0,1,0]
	v_pk_fma_f32 v[40:41], s[48:49], v[52:53], v[40:41] op_sel_hi:[0,1,1]
	v_cvt_scalef32_pk_f32_fp4 v[52:53], v186, 1.0 op_sel:[1,1,0]
	v_pk_fma_f32 v[42:43], s[48:49], v[52:53], v[42:43] op_sel_hi:[0,1,1]
	v_cvt_scalef32_pk_f32_fp4 v[52:53], v187, 1.0
	v_pk_fma_f32 v[44:45], s[48:49], v[52:53], v[44:45] op_sel_hi:[0,1,1]
	v_cvt_scalef32_pk_f32_fp4 v[52:53], v187, 1.0 op_sel:[1,0,0]
	v_pk_fma_f32 v[46:47], s[48:49], v[52:53], v[46:47] op_sel_hi:[0,1,1]
	v_cvt_scalef32_pk_f32_fp4 v[52:53], v187, 1.0 op_sel:[0,1,0]
	v_pk_fma_f32 v[48:49], s[48:49], v[52:53], v[48:49] op_sel_hi:[0,1,1]
	v_cvt_scalef32_pk_f32_fp4 v[52:53], v187, 1.0 op_sel:[1,1,0]
	v_pk_fma_f32 v[50:51], s[48:49], v[52:53], v[50:51] op_sel_hi:[0,1,1]
	v_cvt_scalef32_pk_f32_fp4 v[52:53], v184, 1.0
	v_pk_fma_f32 v[36:37], s[46:47], v[52:53], v[36:37] op_sel_hi:[0,1,1]
	v_cvt_scalef32_pk_f32_fp4 v[52:53], v184, 1.0 op_sel:[1,0,0]
	v_pk_fma_f32 v[38:39], s[46:47], v[52:53], v[38:39] op_sel_hi:[0,1,1]
	v_cvt_scalef32_pk_f32_fp4 v[52:53], v184, 1.0 op_sel:[0,1,0]
	v_pk_fma_f32 v[40:41], s[46:47], v[52:53], v[40:41] op_sel_hi:[0,1,1]
	v_cvt_scalef32_pk_f32_fp4 v[52:53], v184, 1.0 op_sel:[1,1,0]
	v_pk_fma_f32 v[42:43], s[46:47], v[52:53], v[42:43] op_sel_hi:[0,1,1]
	v_cvt_scalef32_pk_f32_fp4 v[52:53], v185, 1.0
	v_pk_fma_f32 v[44:45], s[46:47], v[52:53], v[44:45] op_sel_hi:[0,1,1]
	v_cvt_scalef32_pk_f32_fp4 v[52:53], v185, 1.0 op_sel:[1,0,0]
	v_pk_fma_f32 v[46:47], s[46:47], v[52:53], v[46:47] op_sel_hi:[0,1,1]
	v_cvt_scalef32_pk_f32_fp4 v[52:53], v185, 1.0 op_sel:[0,1,0]
	v_pk_fma_f32 v[48:49], s[46:47], v[52:53], v[48:49] op_sel_hi:[0,1,1]
	v_cvt_scalef32_pk_f32_fp4 v[52:53], v185, 1.0 op_sel:[1,1,0]
	v_pk_fma_f32 v[50:51], s[46:47], v[52:53], v[50:51] op_sel_hi:[0,1,1]
	v_cvt_scalef32_pk_f32_fp4 v[52:53], v182, 1.0
	v_pk_fma_f32 v[36:37], s[44:45], v[52:53], v[36:37] op_sel_hi:[0,1,1]
	v_cvt_scalef32_pk_f32_fp4 v[52:53], v182, 1.0 op_sel:[1,0,0]
	v_pk_fma_f32 v[38:39], s[44:45], v[52:53], v[38:39] op_sel_hi:[0,1,1]
	v_cvt_scalef32_pk_f32_fp4 v[52:53], v182, 1.0 op_sel:[0,1,0]
	v_pk_fma_f32 v[40:41], s[44:45], v[52:53], v[40:41] op_sel_hi:[0,1,1]
	v_cvt_scalef32_pk_f32_fp4 v[52:53], v182, 1.0 op_sel:[1,1,0]
	v_pk_fma_f32 v[42:43], s[44:45], v[52:53], v[42:43] op_sel_hi:[0,1,1]
	v_cvt_scalef32_pk_f32_fp4 v[52:53], v183, 1.0
	v_pk_fma_f32 v[44:45], s[44:45], v[52:53], v[44:45] op_sel_hi:[0,1,1]
	v_cvt_scalef32_pk_f32_fp4 v[52:53], v183, 1.0 op_sel:[1,0,0]
	v_pk_fma_f32 v[46:47], s[44:45], v[52:53], v[46:47] op_sel_hi:[0,1,1]
	v_cvt_scalef32_pk_f32_fp4 v[52:53], v183, 1.0 op_sel:[0,1,0]
	v_pk_fma_f32 v[48:49], s[44:45], v[52:53], v[48:49] op_sel_hi:[0,1,1]
	v_cvt_scalef32_pk_f32_fp4 v[52:53], v183, 1.0 op_sel:[1,1,0]
	v_pk_fma_f32 v[50:51], s[44:45], v[52:53], v[50:51] op_sel_hi:[0,1,1]
	v_cvt_scalef32_pk_f32_fp4 v[52:53], v180, 1.0
	v_pk_fma_f32 v[36:37], s[42:43], v[52:53], v[36:37] op_sel_hi:[0,1,1]
	v_cvt_scalef32_pk_f32_fp4 v[52:53], v180, 1.0 op_sel:[1,0,0]
	v_pk_fma_f32 v[38:39], s[42:43], v[52:53], v[38:39] op_sel_hi:[0,1,1]
	v_cvt_scalef32_pk_f32_fp4 v[52:53], v180, 1.0 op_sel:[0,1,0]
	v_pk_fma_f32 v[40:41], s[42:43], v[52:53], v[40:41] op_sel_hi:[0,1,1]
	v_cvt_scalef32_pk_f32_fp4 v[52:53], v180, 1.0 op_sel:[1,1,0]
	v_pk_fma_f32 v[42:43], s[42:43], v[52:53], v[42:43] op_sel_hi:[0,1,1]
	v_cvt_scalef32_pk_f32_fp4 v[52:53], v181, 1.0
	v_pk_fma_f32 v[44:45], s[42:43], v[52:53], v[44:45] op_sel_hi:[0,1,1]
	v_cvt_scalef32_pk_f32_fp4 v[52:53], v181, 1.0 op_sel:[1,0,0]
	v_pk_fma_f32 v[46:47], s[42:43], v[52:53], v[46:47] op_sel_hi:[0,1,1]
	v_cvt_scalef32_pk_f32_fp4 v[52:53], v181, 1.0 op_sel:[0,1,0]
	v_pk_fma_f32 v[48:49], s[42:43], v[52:53], v[48:49] op_sel_hi:[0,1,1]
	v_cvt_scalef32_pk_f32_fp4 v[52:53], v181, 1.0 op_sel:[1,1,0]
	v_pk_fma_f32 v[50:51], s[42:43], v[52:53], v[50:51] op_sel_hi:[0,1,1]
	v_mov_b32_e32 v35, s59
	v_mov_b32_e32 v52, s35
	v_cndmask_b32_e64 v35, v35, v52, s[10:11]
	v_mov_b32_e32 v52, s43
	v_bfi_b32 v33, s55, v34, v33
	v_cndmask_b32_e64 v35, v35, v52, s[8:9]
	v_mov_b32_e32 v52, s13
	v_mul_f32_e32 v32, 0.5, v32
	v_add_f32_e32 v33, 1.0, v33
	v_cndmask_b32_e64 v35, v35, v52, s[6:7]
	v_mul_f32_e32 v32, v32, v33
	v_mul_f32_e32 v32, v35, v32
	v_cvt_scalef32_pk_f32_fp4 v[34:35], v178, 1.0 op_sel:[1,0,0]
	v_readlane_b32 s12, v32, 0
	v_readlane_b32 s26, v32, 32
	v_readlane_b32 s28, v32, 16
	v_readlane_b32 s30, v32, 48
	v_cvt_scalef32_pk_f32_fp4 v[32:33], v178, 1.0
	v_pk_fma_f32 v[32:33], s[12:13], v[32:33], v[36:37] op_sel_hi:[0,1,1]
	v_cvt_scalef32_pk_f32_fp4 v[36:37], v178, 1.0 op_sel:[0,1,0]
	v_pk_fma_f32 v[36:37], s[12:13], v[36:37], v[40:41] op_sel_hi:[0,1,1]
	v_cvt_scalef32_pk_f32_fp4 v[40:41], v179, 1.0
	v_pk_fma_f32 v[40:41], s[12:13], v[40:41], v[44:45] op_sel_hi:[0,1,1]
	v_cvt_scalef32_pk_f32_fp4 v[44:45], v179, 1.0 op_sel:[0,1,0]
	v_pk_fma_f32 v[44:45], s[12:13], v[44:45], v[48:49] op_sel_hi:[0,1,1]
	v_cvt_scalef32_pk_f32_fp4 v[48:49], v176, 1.0
	v_pk_fma_f32 v[34:35], s[12:13], v[34:35], v[38:39] op_sel_hi:[0,1,1]
	v_pk_fma_f32 v[32:33], s[26:27], v[48:49], v[32:33] op_sel_hi:[0,1,1]
	v_cvt_scalef32_pk_f32_fp4 v[48:49], v176, 1.0 op_sel:[1,0,0]
	v_cvt_scalef32_pk_f32_fp4 v[38:39], v178, 1.0 op_sel:[1,1,0]
	v_pk_fma_f32 v[34:35], s[26:27], v[48:49], v[34:35] op_sel_hi:[0,1,1]
	v_cvt_scalef32_pk_f32_fp4 v[48:49], v176, 1.0 op_sel:[0,1,0]
	v_pk_fma_f32 v[38:39], s[12:13], v[38:39], v[42:43] op_sel_hi:[0,1,1]
	v_pk_fma_f32 v[36:37], s[26:27], v[48:49], v[36:37] op_sel_hi:[0,1,1]
	v_cvt_scalef32_pk_f32_fp4 v[48:49], v176, 1.0 op_sel:[1,1,0]
	v_cvt_scalef32_pk_f32_fp4 v[42:43], v179, 1.0 op_sel:[1,0,0]
	v_pk_fma_f32 v[38:39], s[26:27], v[48:49], v[38:39] op_sel_hi:[0,1,1]
	v_cvt_scalef32_pk_f32_fp4 v[48:49], v177, 1.0
	v_pk_fma_f32 v[42:43], s[12:13], v[42:43], v[46:47] op_sel_hi:[0,1,1]
	v_pk_fma_f32 v[40:41], s[26:27], v[48:49], v[40:41] op_sel_hi:[0,1,1]
	v_cvt_scalef32_pk_f32_fp4 v[48:49], v177, 1.0 op_sel:[1,0,0]
	v_cvt_scalef32_pk_f32_fp4 v[46:47], v179, 1.0 op_sel:[1,1,0]
	v_pk_fma_f32 v[42:43], s[26:27], v[48:49], v[42:43] op_sel_hi:[0,1,1]
	v_cvt_scalef32_pk_f32_fp4 v[48:49], v177, 1.0 op_sel:[0,1,0]
	v_pk_fma_f32 v[46:47], s[12:13], v[46:47], v[50:51] op_sel_hi:[0,1,1]
	v_pk_fma_f32 v[44:45], s[26:27], v[48:49], v[44:45] op_sel_hi:[0,1,1]
	v_cvt_scalef32_pk_f32_fp4 v[48:49], v177, 1.0 op_sel:[1,1,0]
	v_pk_fma_f32 v[46:47], s[26:27], v[48:49], v[46:47] op_sel_hi:[0,1,1]
	v_cvt_scalef32_pk_f32_fp4 v[48:49], v174, 1.0
	v_pk_fma_f32 v[32:33], s[28:29], v[48:49], v[32:33] op_sel_hi:[0,1,1]
	v_cvt_scalef32_pk_f32_fp4 v[48:49], v174, 1.0 op_sel:[1,0,0]
	v_pk_fma_f32 v[34:35], s[28:29], v[48:49], v[34:35] op_sel_hi:[0,1,1]
	v_cvt_scalef32_pk_f32_fp4 v[48:49], v174, 1.0 op_sel:[0,1,0]
	v_pk_fma_f32 v[36:37], s[28:29], v[48:49], v[36:37] op_sel_hi:[0,1,1]
	v_cvt_scalef32_pk_f32_fp4 v[48:49], v174, 1.0 op_sel:[1,1,0]
	v_pk_fma_f32 v[38:39], s[28:29], v[48:49], v[38:39] op_sel_hi:[0,1,1]
	v_cvt_scalef32_pk_f32_fp4 v[48:49], v175, 1.0
	v_pk_fma_f32 v[40:41], s[28:29], v[48:49], v[40:41] op_sel_hi:[0,1,1]
	v_cvt_scalef32_pk_f32_fp4 v[48:49], v175, 1.0 op_sel:[1,0,0]
	v_pk_fma_f32 v[42:43], s[28:29], v[48:49], v[42:43] op_sel_hi:[0,1,1]
	v_cvt_scalef32_pk_f32_fp4 v[48:49], v175, 1.0 op_sel:[0,1,0]
	v_pk_fma_f32 v[44:45], s[28:29], v[48:49], v[44:45] op_sel_hi:[0,1,1]
	v_cvt_scalef32_pk_f32_fp4 v[48:49], v175, 1.0 op_sel:[1,1,0]
	v_pk_fma_f32 v[46:47], s[28:29], v[48:49], v[46:47] op_sel_hi:[0,1,1]
	v_cvt_scalef32_pk_f32_fp4 v[48:49], v172, 1.0
	v_pk_fma_f32 v[200:201], s[30:31], v[48:49], v[32:33] op_sel_hi:[0,1,1]
	v_cvt_scalef32_pk_f32_fp4 v[32:33], v172, 1.0 op_sel:[1,0,0]
	v_pk_fma_f32 v[218:219], s[30:31], v[32:33], v[34:35] op_sel_hi:[0,1,1]
	v_cvt_scalef32_pk_f32_fp4 v[32:33], v172, 1.0 op_sel:[0,1,0]
	v_pk_fma_f32 v[216:217], s[30:31], v[32:33], v[36:37] op_sel_hi:[0,1,1]
	v_cvt_scalef32_pk_f32_fp4 v[32:33], v172, 1.0 op_sel:[1,1,0]
	v_pk_fma_f32 v[214:215], s[30:31], v[32:33], v[38:39] op_sel_hi:[0,1,1]
	v_cvt_scalef32_pk_f32_fp4 v[32:33], v173, 1.0
	v_pk_fma_f32 v[212:213], s[30:31], v[32:33], v[40:41] op_sel_hi:[0,1,1]
	v_cvt_scalef32_pk_f32_fp4 v[32:33], v173, 1.0 op_sel:[1,0,0]
	v_pk_fma_f32 v[210:211], s[30:31], v[32:33], v[42:43] op_sel_hi:[0,1,1]
	v_cvt_scalef32_pk_f32_fp4 v[32:33], v173, 1.0 op_sel:[0,1,0]
	v_pk_fma_f32 v[208:209], s[30:31], v[32:33], v[44:45] op_sel_hi:[0,1,1]
	v_cvt_scalef32_pk_f32_fp4 v[32:33], v173, 1.0 op_sel:[1,1,0]
	v_pk_fma_f32 v[206:207], s[30:31], v[32:33], v[46:47] op_sel_hi:[0,1,1]
	s_and_b64 vcc, exec, s[24:25]
	s_cbranch_vccnz .LBB0_1385
	s_mov_b32 s26, s58
	s_add_i32 s58, s26, 16
	s_cmpk_gt_u32 s26, 0x6f
	s_cselect_b64 s[24:25], -1, 0
	s_cmpk_lt_u32 s26, 0x70
	s_cselect_b64 vcc, -1, 0
	s_bitcmp0_b32 s58, 6
	s_cselect_b64 s[12:13], -1, 0
	v_cndmask_b32_e64 v100, v116, v104, s[12:13]
	v_cndmask_b32_e32 v100, v118, v100, vcc
	s_nop 0
	s_waitcnt vmcnt(24)
	v_accvgpr_read_b32 v205, a43
	v_accvgpr_read_b32 v203, a45
	v_accvgpr_read_b32 v199, a47
	v_accvgpr_read_b32 v197, a49
	v_accvgpr_read_b32 v95, a23
	v_accvgpr_read_b32 v91, a31
	v_mov_b64_e32 v[84:85], v[232:233]
	v_mov_b64_e32 v[80:81], v[236:237]
	v_accvgpr_read_b32 v204, a42
	v_accvgpr_read_b32 v202, a44
	v_accvgpr_read_b32 v198, a46
	v_accvgpr_read_b32 v196, a48
	v_accvgpr_read_b32 v94, a22
	v_accvgpr_read_b32 v93, a21
	v_accvgpr_read_b32 v92, a20
	v_accvgpr_read_b32 v90, a30
	v_accvgpr_read_b32 v89, a29
	v_accvgpr_read_b32 v88, a28
	v_mov_b64_e32 v[86:87], v[234:235]
	v_mov_b64_e32 v[82:83], v[238:239]
	s_add_i32 s30, s26, 16
	v_readlane_b32 s28, v100, s30
	s_nop 1
	v_mad_i64_i32 v[136:137], s[12:13], s28, v130, v[96:97]
	global_load_dwordx4 a[20:23], v[136:137], off
	v_mad_i64_i32 v[136:137], s[12:13], s28, v130, v[98:99]
	global_load_dwordx2 a[42:43], v[136:137], off
	s_add_i32 s30, s26, 17
	v_readlane_b32 s28, v100, s30
	s_nop 1
	v_mad_i64_i32 v[136:137], s[12:13], s28, v130, v[96:97]
	global_load_dwordx4 a[28:31], v[136:137], off
	v_mad_i64_i32 v[136:137], s[12:13], s28, v130, v[98:99]
	global_load_dwordx2 a[44:45], v[136:137], off
	s_add_i32 s30, s26, 18
	v_readlane_b32 s28, v100, s30
	s_nop 1
	v_mad_i64_i32 v[136:137], s[12:13], s28, v130, v[96:97]
	global_load_dwordx4 v[232:235], v[136:137], off
	v_mad_i64_i32 v[136:137], s[12:13], s28, v130, v[98:99]
	global_load_dwordx2 a[46:47], v[136:137], off
	s_add_i32 s30, s26, 19
	v_readlane_b32 s28, v100, s30
	s_nop 1
	v_mad_i64_i32 v[136:137], s[12:13], s28, v130, v[96:97]
	global_load_dwordx4 v[236:239], v[136:137], off
	v_mad_i64_i32 v[136:137], s[12:13], s28, v130, v[98:99]
	global_load_dwordx2 a[48:49], v[136:137], off
	s_waitcnt vmcnt(24)
	v_accvgpr_read_b32 v195, a51
	v_accvgpr_read_b32 v193, a53
	v_accvgpr_read_b32 v191, a55
	v_accvgpr_read_b32 v189, a57
	v_mov_b64_e32 v[76:77], v[240:241]
	v_mov_b64_e32 v[72:73], v[244:245]
	v_mov_b64_e32 v[68:69], v[248:249]
	v_accvgpr_read_b32 v67, a3
	v_accvgpr_read_b32 v194, a50
	v_accvgpr_read_b32 v192, a52
	v_accvgpr_read_b32 v190, a54
	v_accvgpr_read_b32 v188, a56
	v_mov_b64_e32 v[78:79], v[242:243]
	v_mov_b64_e32 v[74:75], v[246:247]
	v_mov_b64_e32 v[70:71], v[250:251]
	v_accvgpr_read_b32 v66, a2
	v_accvgpr_read_b32 v65, a1
	v_accvgpr_read_b32 v64, a0
	s_add_i32 s30, s26, 20
	v_readlane_b32 s28, v100, s30
	s_nop 1
	v_mad_i64_i32 v[136:137], s[12:13], s28, v130, v[96:97]
	global_load_dwordx4 v[240:243], v[136:137], off
	v_mad_i64_i32 v[136:137], s[12:13], s28, v130, v[98:99]
	global_load_dwordx2 a[50:51], v[136:137], off
	s_add_i32 s30, s26, 21
	v_readlane_b32 s28, v100, s30
	s_nop 1
	v_mad_i64_i32 v[136:137], s[12:13], s28, v130, v[96:97]
	global_load_dwordx4 v[244:247], v[136:137], off
	v_mad_i64_i32 v[136:137], s[12:13], s28, v130, v[98:99]
	global_load_dwordx2 a[52:53], v[136:137], off
	s_add_i32 s30, s26, 22
	v_readlane_b32 s28, v100, s30
	s_nop 1
	v_mad_i64_i32 v[136:137], s[12:13], s28, v130, v[96:97]
	global_load_dwordx4 v[248:251], v[136:137], off
	v_mad_i64_i32 v[136:137], s[12:13], s28, v130, v[98:99]
	global_load_dwordx2 a[54:55], v[136:137], off
	s_add_i32 s30, s26, 23
	v_readlane_b32 s28, v100, s30
	s_nop 1
	v_mad_i64_i32 v[136:137], s[12:13], s28, v130, v[96:97]
	global_load_dwordx4 a[0:3], v[136:137], off
	v_mad_i64_i32 v[136:137], s[12:13], s28, v130, v[98:99]
	global_load_dwordx2 a[56:57], v[136:137], off
	s_waitcnt vmcnt(24)
	v_accvgpr_read_b32 v187, a59
	v_accvgpr_read_b32 v185, a61
	v_accvgpr_read_b32 v183, a63
	v_accvgpr_read_b32 v181, a65
	v_accvgpr_read_b32 v63, a7
	v_accvgpr_read_b32 v59, a11
	v_accvgpr_read_b32 v55, a15
	v_accvgpr_read_b32 v51, a19
	v_accvgpr_read_b32 v186, a58
	v_accvgpr_read_b32 v184, a60
	v_accvgpr_read_b32 v182, a62
	v_accvgpr_read_b32 v180, a64
	v_accvgpr_read_b32 v62, a6
	v_accvgpr_read_b32 v61, a5
	v_accvgpr_read_b32 v60, a4
	v_accvgpr_read_b32 v58, a10
	v_accvgpr_read_b32 v57, a9
	v_accvgpr_read_b32 v56, a8
	v_accvgpr_read_b32 v54, a14
	v_accvgpr_read_b32 v53, a13
	v_accvgpr_read_b32 v52, a12
	v_accvgpr_read_b32 v50, a18
	v_accvgpr_read_b32 v49, a17
	v_accvgpr_read_b32 v48, a16
	s_add_i32 s30, s26, 24
	v_readlane_b32 s28, v100, s30
	s_nop 1
	v_mad_i64_i32 v[136:137], s[12:13], s28, v130, v[96:97]
	global_load_dwordx4 a[4:7], v[136:137], off
	v_mad_i64_i32 v[136:137], s[12:13], s28, v130, v[98:99]
	global_load_dwordx2 a[58:59], v[136:137], off
	s_add_i32 s30, s26, 25
	v_readlane_b32 s28, v100, s30
	s_nop 1
	v_mad_i64_i32 v[136:137], s[12:13], s28, v130, v[96:97]
	global_load_dwordx4 a[8:11], v[136:137], off
	v_mad_i64_i32 v[136:137], s[12:13], s28, v130, v[98:99]
	global_load_dwordx2 a[60:61], v[136:137], off
	s_add_i32 s30, s26, 26
	v_readlane_b32 s28, v100, s30
	s_nop 1
	v_mad_i64_i32 v[136:137], s[12:13], s28, v130, v[96:97]
	global_load_dwordx4 a[12:15], v[136:137], off
	v_mad_i64_i32 v[136:137], s[12:13], s28, v130, v[98:99]
	global_load_dwordx2 a[62:63], v[136:137], off
	s_add_i32 s30, s26, 27
	v_readlane_b32 s28, v100, s30
	s_nop 1
	v_mad_i64_i32 v[136:137], s[12:13], s28, v130, v[96:97]
	global_load_dwordx4 a[16:19], v[136:137], off
	v_mad_i64_i32 v[136:137], s[12:13], s28, v130, v[98:99]
	global_load_dwordx2 a[64:65], v[136:137], off
	s_waitcnt vmcnt(24)
	v_accvgpr_read_b32 v179, a67
	v_accvgpr_read_b32 v173, a41
	v_accvgpr_read_b32 v47, a27
	v_mov_b64_e32 v[40:41], v[220:221]
	v_mov_b64_e32 v[36:37], v[224:225]
	v_mov_b64_e32 v[32:33], v[228:229]
	v_accvgpr_read_b32 v178, a66
	v_mov_b64_e32 v[176:177], v[148:149]
	v_mov_b64_e32 v[174:175], v[252:253]
	v_accvgpr_read_b32 v172, a40
	v_accvgpr_read_b32 v46, a26
	v_accvgpr_read_b32 v45, a25
	v_accvgpr_read_b32 v44, a24
	v_mov_b64_e32 v[42:43], v[222:223]
	v_mov_b64_e32 v[38:39], v[226:227]
	v_mov_b64_e32 v[34:35], v[230:231]
	s_add_i32 s30, s26, 28
	v_readlane_b32 s28, v100, s30
	s_nop 1
	v_mad_i64_i32 v[136:137], s[12:13], s28, v130, v[96:97]
	global_load_dwordx4 a[24:27], v[136:137], off
	v_mad_i64_i32 v[136:137], s[12:13], s28, v130, v[98:99]
	global_load_dwordx2 a[66:67], v[136:137], off
	s_add_i32 s30, s26, 29
	v_readlane_b32 s28, v100, s30
	s_nop 1
	v_mad_i64_i32 v[136:137], s[12:13], s28, v130, v[96:97]
	global_load_dwordx4 v[220:223], v[136:137], off
	v_mad_i64_i32 v[136:137], s[12:13], s28, v130, v[98:99]
	global_load_dwordx2 v[148:149], v[136:137], off
	s_add_i32 s30, s26, 30
	v_readlane_b32 s28, v100, s30
	s_nop 1
	v_mad_i64_i32 v[136:137], s[12:13], s28, v130, v[96:97]
	global_load_dwordx4 v[224:227], v[136:137], off
	v_mad_i64_i32 v[136:137], s[12:13], s28, v130, v[98:99]
	global_load_dwordx2 v[252:253], v[136:137], off
	s_add_i32 s30, s26, 31
	v_readlane_b32 s28, v100, s30
	s_nop 1
	v_mad_i64_i32 v[136:137], s[12:13], s28, v130, v[96:97]
	global_load_dwordx4 v[228:231], v[136:137], off
	v_mad_i64_i32 v[136:137], s[12:13], s28, v130, v[98:99]
	global_load_dwordx2 a[40:41], v[136:137], off
	s_cmp_lg_u32 s26, 64
	s_cbranch_scc1 .LBB0_1389
	global_load_dword a68, v[170:171], off
	global_load_dword a69, v[168:169], off
	global_load_dword v117, v[166:167], off
	global_load_dword v105, v[164:165], off
	s_branch .LBB0_1389

.LBB0_1461:
	s_and_b32 s2, s33, 0xff
	s_mul_i32 s2, s2, 27
	s_lshr_b32 s2, s2, 9
	s_add_i32 s61, s97, s2
	s_lshl_b32 s14, s61, 19
	v_lshl_add_u64 v[8:9], v[82:83], 0, s[14:15]
	v_add_co_u32_e32 v10, vcc, 0x10000, v8
	s_mul_i32 s2, s2, 19
	s_nop 0
	v_addc_co_u32_e32 v11, vcc, 0, v9, vcc
	v_add_co_u32_e32 v20, vcc, 0x20000, v8
	s_sub_i32 s2, s33, s2
	s_nop 0
	v_addc_co_u32_e32 v21, vcc, 0, v9, vcc
	v_add_co_u32_e32 v22, vcc, 0x30000, v8
	s_and_b32 s60, s2, 0xff
	s_nop 0
	v_addc_co_u32_e32 v23, vcc, 0, v9, vcc
	v_add_co_u32_e32 v28, vcc, 0x40000, v8
	global_load_dwordx4 v[0:3], v[8:9], off
	global_load_dwordx4 v[4:7], v[10:11], off
	v_addc_co_u32_e32 v29, vcc, 0, v9, vcc
	v_add_co_u32_e32 v30, vcc, 0x50000, v8
	s_lshl_b32 s2, s60, 18
	s_mov_b32 s3, s15
	v_addc_co_u32_e32 v31, vcc, 0, v9, vcc
	v_lshl_add_u64 v[16:17], v[84:85], 0, s[2:3]
	global_load_dwordx4 v[52:55], v[20:21], off
	global_load_dwordx4 v[76:79], v[16:17], off
	v_add_co_u32_e32 v32, vcc, 0x60000, v8
	global_load_dwordx4 v[56:59], v[22:23], off
	global_load_dwordx4 v[60:63], v[28:29], off
	v_addc_co_u32_e32 v33, vcc, 0, v9, vcc
	v_add_co_u32_e32 v34, vcc, 0x70000, v8
	s_mov_b32 s4, 0x10000
	s_nop 0
	v_addc_co_u32_e32 v35, vcc, 0, v9, vcc
	global_load_dwordx4 v[64:67], v[30:31], off
	global_load_dwordx4 v[68:71], v[32:33], off
	v_add_co_u32_e32 v116, vcc, s4, v16
	s_mov_b32 s4, 0x20000
	s_nop 0
	v_addc_co_u32_e32 v117, vcc, 0, v17, vcc
	global_load_dwordx4 v[72:75], v[34:35], off
	global_load_dwordx4 v[104:107], v[116:117], off
	v_add_co_u32_e32 v118, vcc, s4, v16
	s_mov_b32 s4, 0x30000
	s_nop 0
	v_addc_co_u32_e32 v119, vcc, 0, v17, vcc
	global_load_dwordx4 v[108:111], v[118:119], off
	v_add_co_u32_e32 v120, vcc, s4, v16
	s_mov_b32 s4, 0
	s_nop 0
	v_addc_co_u32_e32 v121, vcc, 0, v17, vcc
	global_load_dwordx4 v[112:115], v[120:121], off
	global_load_dwordx4 v[250:253], v[8:9], off offset:128
	s_nop 0
	global_load_dwordx4 v[246:249], v[10:11], off offset:128
	s_nop 0
	global_load_dwordx4 v[218:221], v[16:17], off offset:128
	s_nop 0
	global_load_dwordx4 v[242:245], v[20:21], off offset:128
	s_nop 0
	global_load_dwordx4 v[238:241], v[22:23], off offset:128
	s_nop 0
	global_load_dwordx4 v[234:237], v[28:29], off offset:128
	global_load_dwordx4 v[230:233], v[30:31], off offset:128
	global_load_dwordx4 v[226:229], v[32:33], off offset:128
	global_load_dwordx4 v[222:225], v[34:35], off offset:128
	s_nop 0
	global_load_dwordx4 v[214:217], v[116:117], off offset:128
	global_load_dwordx4 v[210:213], v[118:119], off offset:128
	v_accvgpr_write_b32 a47, 0
	v_accvgpr_write_b32 a46, 0
	v_accvgpr_write_b32 a45, 0
	v_accvgpr_write_b32 a44, 0
	v_accvgpr_write_b32 a43, 0
	v_accvgpr_write_b32 a42, 0
	v_accvgpr_write_b32 a41, 0
	v_accvgpr_write_b32 a40, 0
	v_accvgpr_write_b32 a39, 0
	v_accvgpr_write_b32 a38, 0
	v_accvgpr_write_b32 a37, 0
	v_accvgpr_write_b32 a36, 0
	v_accvgpr_write_b32 a35, 0
	v_accvgpr_write_b32 a34, 0
	v_accvgpr_write_b32 a33, 0
	v_accvgpr_write_b32 a32, 0
	v_accvgpr_write_b32 a63, 0
	v_accvgpr_write_b32 a62, 0
	v_accvgpr_write_b32 a61, 0
	v_accvgpr_write_b32 a60, 0
	v_accvgpr_write_b32 a59, 0
	v_accvgpr_write_b32 a58, 0
	v_accvgpr_write_b32 a57, 0
	v_accvgpr_write_b32 a56, 0
	v_accvgpr_write_b32 a55, 0
	s_waitcnt vmcnt(22)
	ds_write_b128 v152, v[0:3]
	s_waitcnt vmcnt(21)
	ds_write_b128 v152, v[4:7] offset:4608
	s_waitcnt vmcnt(19)
	ds_write_b128 v152, v[76:79] offset:36864
	ds_write_b128 v152, v[52:55] offset:9216
	s_waitcnt vmcnt(18)
	ds_write_b128 v152, v[56:59] offset:13824
	s_waitcnt vmcnt(17)
	ds_write_b128 v152, v[60:63] offset:18432
	s_waitcnt vmcnt(16)
	ds_write_b128 v152, v[64:67] offset:23040
	s_waitcnt vmcnt(15)
	ds_write_b128 v152, v[68:71] offset:27648
	s_waitcnt vmcnt(14)
	ds_write_b128 v152, v[72:75] offset:32256
	s_waitcnt vmcnt(13)
	ds_write_b128 v152, v[104:107] offset:41472
	s_waitcnt vmcnt(12)
	ds_write_b128 v152, v[108:111] offset:46080
	global_load_dwordx4 v[206:209], v[120:121], off offset:128
	v_lshl_add_u64 v[4:5], v[102:103], 0, s[14:15]
	v_lshl_add_u64 v[6:7], v[102:103], 0, s[2:3]
	v_accvgpr_write_b32 a54, 0
	v_accvgpr_write_b32 a53, 0
	v_accvgpr_write_b32 a52, 0
	v_accvgpr_write_b32 a51, 0
	v_accvgpr_write_b32 a50, 0
	v_accvgpr_write_b32 a49, 0
	v_accvgpr_write_b32 a48, 0
	v_accvgpr_write_b32 a79, 0
	v_accvgpr_write_b32 a78, 0
	v_accvgpr_write_b32 a77, 0
	v_accvgpr_write_b32 a76, 0
	v_accvgpr_write_b32 a75, 0
	v_accvgpr_write_b32 a74, 0
	v_accvgpr_write_b32 a73, 0
	v_accvgpr_write_b32 a72, 0
	v_accvgpr_write_b32 a71, 0
	v_accvgpr_write_b32 a70, 0
	v_accvgpr_write_b32 a69, 0
	v_accvgpr_write_b32 a68, 0
	v_accvgpr_write_b32 a67, 0
	v_accvgpr_write_b32 a66, 0
	v_accvgpr_write_b32 a65, 0
	v_accvgpr_write_b32 a64, 0
	v_accvgpr_write_b32 a111, 0
	v_accvgpr_write_b32 a110, 0
	v_accvgpr_write_b32 a109, 0
	v_accvgpr_write_b32 a108, 0
	v_accvgpr_write_b32 a107, 0
	v_accvgpr_write_b32 a106, 0
	v_accvgpr_write_b32 a105, 0
	v_accvgpr_write_b32 a104, 0
	v_accvgpr_write_b32 a103, 0
	v_accvgpr_write_b32 a102, 0
	v_accvgpr_write_b32 a101, 0
	v_accvgpr_write_b32 a100, 0
	v_accvgpr_write_b32 a99, 0
	v_accvgpr_write_b32 a98, 0
	v_accvgpr_write_b32 a97, 0
	v_accvgpr_write_b32 a96, 0
	v_accvgpr_write_b32 a95, 0
	v_accvgpr_write_b32 a94, 0
	v_accvgpr_write_b32 a93, 0
	v_accvgpr_write_b32 a92, 0
	v_accvgpr_write_b32 a91, 0
	v_accvgpr_write_b32 a90, 0
	v_accvgpr_write_b32 a89, 0
	v_accvgpr_write_b32 a88, 0
	v_accvgpr_write_b32 a87, 0
	v_accvgpr_write_b32 a86, 0
	v_accvgpr_write_b32 a85, 0
	v_accvgpr_write_b32 a84, 0
	v_accvgpr_write_b32 a83, 0
	v_accvgpr_write_b32 a82, 0
	v_accvgpr_write_b32 a81, 0
	v_accvgpr_write_b32 a80, 0
	v_accvgpr_write_b32 a127, 0
	v_accvgpr_write_b32 a126, 0
	v_accvgpr_write_b32 a125, 0
	v_accvgpr_write_b32 a124, 0
	v_accvgpr_write_b32 a123, 0
	v_accvgpr_write_b32 a122, 0
	v_accvgpr_write_b32 a121, 0
	v_accvgpr_write_b32 a120, 0
	v_accvgpr_write_b32 a119, 0
	v_accvgpr_write_b32 a118, 0
	v_accvgpr_write_b32 a117, 0
	v_accvgpr_write_b32 a116, 0
	v_accvgpr_write_b32 a115, 0
	v_accvgpr_write_b32 a114, 0
	v_accvgpr_write_b32 a113, 0
	v_accvgpr_write_b32 a112, 0
	v_accvgpr_write_b32 a31, 0
	v_accvgpr_write_b32 a30, 0
	v_accvgpr_write_b32 a29, 0
	v_accvgpr_write_b32 a28, 0
	v_accvgpr_write_b32 a27, 0
	v_accvgpr_write_b32 a26, 0
	v_accvgpr_write_b32 a25, 0
	v_accvgpr_write_b32 a24, 0
	v_accvgpr_write_b32 a23, 0
	v_accvgpr_write_b32 a22, 0
	v_accvgpr_write_b32 a21, 0
	v_accvgpr_write_b32 a20, 0
	v_accvgpr_write_b32 a19, 0
	v_accvgpr_write_b32 a18, 0
	v_accvgpr_write_b32 a17, 0
	v_accvgpr_write_b32 a16, 0
	v_accvgpr_write_b32 a15, 0
	v_accvgpr_write_b32 a14, 0
	v_accvgpr_write_b32 a13, 0
	v_accvgpr_write_b32 a12, 0
	v_accvgpr_write_b32 a11, 0
	v_accvgpr_write_b32 a10, 0
	v_accvgpr_write_b32 a9, 0
	v_accvgpr_write_b32 a8, 0
	v_accvgpr_write_b32 a7, 0
	v_accvgpr_write_b32 a6, 0
	v_accvgpr_write_b32 a5, 0
	v_accvgpr_write_b32 a4, 0
	v_accvgpr_write_b32 a3, 0
	v_accvgpr_write_b32 a2, 0
	v_accvgpr_write_b32 a1, 0
	v_accvgpr_write_b32 a0, 0
	s_mov_b64 s[2:3], 0
	s_waitcnt vmcnt(12)
	ds_write_b128 v152, v[112:115] offset:50688
	s_waitcnt lgkmcnt(0)
	s_barrier
	s_waitcnt vmcnt(0)
	v_readfirstlane_b32 s100, v4
	v_readfirstlane_b32 s101, v5
	v_readfirstlane_b32 s98, v6
	v_readfirstlane_b32 s99, v7
	s_nop 1
	v_subrev_u32_e32 v194, s100, v4
	v_subrev_u32_e32 v193, s98, v6
	v_add_u32_e32 v254, 0x126fa000, v194
	v_add_u32_e32 v205, 0x1270a000, v194
	v_add_u32_e32 v204, 0x1271a000, v194
	v_add_u32_e32 v203, 0x1272a000, v194
	v_add_u32_e32 v202, 0x1273a000, v194
	v_add_u32_e32 v201, 0x1274a000, v194
	v_add_u32_e32 v200, 0x1275a000, v194
	v_add_u32_e32 v199, 0x1276a000, v194
	v_add_u32_e32 v198, 0x4c0000, v193
	v_add_u32_e32 v197, 0x4d0000, v193
	v_add_u32_e32 v196, 0x4e0000, v193
	v_add_u32_e32 v195, 0x4f0000, v193
	s_add_u32 s100, s100, s2
	s_addc_u32 s101, s101, s3
	s_add_u32 s98, s98, s2
	s_addc_u32 s99, s99, s3
	v_add_u32_e32 v192, v148, v153
	v_add_u32_e32 v191, v148, v154
	v_add_u32_e32 v190, v148, v155
	s_and_b32 s5, s4, 1
	s_mul_i32 s8, s5, 0xd800
	v_add_u32_e32 v189, s8, v192
	v_add_u32_e32 v188, s8, v191
	v_add_u32_e32 v187, s8, v190
	ds_read_b128 v[52:55], v189
	ds_read_b128 v[8:11], v187 offset:36864
	ds_read_b128 v[56:59], v189 offset:4608
	ds_read_b128 v[12:15], v187 offset:41472
	ds_read_b128 v[60:63], v189 offset:9216
	ds_read_b128 v[64:67], v188
	s_getreg_b32 s5, hwreg(HW_REG_HW_ID, 4, 1)
	s_cmp_lg_u32 s5, 0
	s_cbranch_scc1 xg5_varB_5
.LBB0_1462:
	s_and_b32 s5, s4, 1
	s_mul_i32 s8, s5, 0xd800
	s_xor_b32 s5, s5, 1
	s_mul_i32 s5, s5, 0xd800
	s_add_i32 s4, s4, 1
	v_add_u32_e32 v186, s5, v152
	ds_read_b128 v[16:19], v189 offset:32
	ds_read_b128 v[28:31], v187 offset:36896
	ds_read_b128 v[20:23], v189 offset:4640
	ds_read_b128 v[32:35], v187 offset:41504
	ds_read_b128 v[24:27], v189 offset:9248
	ds_read_b128 v[0:3], v188 offset:32
	s_waitcnt lgkmcnt(10)
	v_mfma_f32_32x32x16_bf16 a[32:47], v[52:55], v[8:11], a[32:47]
	s_waitcnt vmcnt(11)
	ds_write_b128 v186, v[250:253]
	s_waitcnt lgkmcnt(9)
	v_mfma_f32_32x32x16_bf16 a[48:63], v[52:55], v[12:15], a[48:63]
	s_waitcnt vmcnt(10)
	ds_write_b128 v186, v[246:249] offset:4608
	global_load_dwordx4 v[250:253], v254, s[100:101] offset:512
	v_mfma_f32_32x32x16_bf16 a[64:79], v[56:59], v[8:11], a[64:79]
	s_waitcnt vmcnt(10)
	ds_write_b128 v186, v[242:245] offset:9216
	global_load_dwordx4 v[246:249], v205, s[100:101] offset:512
	v_mfma_f32_32x32x16_bf16 a[96:111], v[56:59], v[12:15], a[96:111]
	s_waitcnt vmcnt(10)
	ds_write_b128 v186, v[238:241] offset:13824
	global_load_dwordx4 v[242:245], v204, s[100:101] offset:512
	s_waitcnt lgkmcnt(11)
	v_mfma_f32_32x32x16_bf16 a[80:95], v[60:63], v[8:11], a[80:95]
	s_waitcnt vmcnt(10)
	ds_write_b128 v186, v[234:237] offset:18432
	global_load_dwordx4 v[238:241], v203, s[100:101] offset:512
	v_mfma_f32_32x32x16_bf16 a[112:127], v[60:63], v[12:15], a[112:127]
	s_waitcnt vmcnt(10)
	ds_write_b128 v186, v[230:233] offset:23040
	global_load_dwordx4 v[234:237], v202, s[100:101] offset:512
	s_waitcnt lgkmcnt(12)
	v_mfma_f32_32x32x16_bf16 a[16:31], v[64:67], v[8:11], a[16:31]
	s_waitcnt vmcnt(10)
	ds_write_b128 v186, v[226:229] offset:27648
	global_load_dwordx4 v[230:233], v201, s[100:101] offset:512
	v_mfma_f32_32x32x16_bf16 a[0:15], v[64:67], v[12:15], a[0:15]
	s_waitcnt vmcnt(10)
	ds_write_b128 v186, v[222:225] offset:32256
	global_load_dwordx4 v[226:229], v200, s[100:101] offset:512
	ds_read_b128 v[52:55], v189 offset:64
	ds_read_b128 v[8:11], v187 offset:36928
	ds_read_b128 v[56:59], v189 offset:4672
	ds_read_b128 v[12:15], v187 offset:41536
	ds_read_b128 v[60:63], v189 offset:9280
	ds_read_b128 v[64:67], v188 offset:64
	s_waitcnt lgkmcnt(15)
	v_mfma_f32_32x32x16_bf16 a[32:47], v[16:19], v[28:31], a[32:47]
	s_waitcnt vmcnt(10)
	ds_write_b128 v186, v[218:221] offset:36864
	global_load_dwordx4 v[222:225], v199, s[100:101] offset:512
	v_mfma_f32_32x32x16_bf16 a[48:63], v[16:19], v[32:35], a[48:63]
	s_waitcnt vmcnt(10)
	ds_write_b128 v186, v[214:217] offset:41472
	global_load_dwordx4 v[218:221], v198, s[98:99] offset:256
	v_mfma_f32_32x32x16_bf16 a[64:79], v[20:23], v[28:31], a[64:79]
	s_waitcnt vmcnt(10)
	ds_write_b128 v186, v[210:213] offset:46080
	global_load_dwordx4 v[214:217], v197, s[98:99] offset:256
	v_mfma_f32_32x32x16_bf16 a[96:111], v[20:23], v[32:35], a[96:111]
	s_waitcnt vmcnt(10)
	ds_write_b128 v186, v[206:209] offset:50688
	global_load_dwordx4 v[210:213], v196, s[98:99] offset:256
	v_mfma_f32_32x32x16_bf16 a[80:95], v[24:27], v[28:31], a[80:95]
	global_load_dwordx4 v[206:209], v195, s[98:99] offset:256
	s_add_u32 s100, s100, 0x80
	s_addc_u32 s101, s101, 0
	s_add_u32 s98, s98, 0x80
	s_addc_u32 s99, s99, 0
	v_mfma_f32_32x32x16_bf16 a[112:127], v[24:27], v[32:35], a[112:127]
	s_waitcnt lgkmcnt(15)
	v_mfma_f32_32x32x16_bf16 a[16:31], v[0:3], v[28:31], a[16:31]
	v_mfma_f32_32x32x16_bf16 a[0:15], v[0:3], v[32:35], a[0:15]
	ds_read_b128 v[16:19], v189 offset:96
	ds_read_b128 v[28:31], v187 offset:36960
	ds_read_b128 v[20:23], v189 offset:4704
	ds_read_b128 v[32:35], v187 offset:41568
	ds_read_b128 v[24:27], v189 offset:9312
	ds_read_b128 v[0:3], v188 offset:96
	s_waitcnt lgkmcnt(14)
	v_mfma_f32_32x32x16_bf16 a[32:47], v[52:55], v[8:11], a[32:47]
	s_waitcnt lgkmcnt(12)
	v_mfma_f32_32x32x16_bf16 a[48:63], v[52:55], v[12:15], a[48:63]
	v_mfma_f32_32x32x16_bf16 a[64:79], v[56:59], v[8:11], a[64:79]
	v_mfma_f32_32x32x16_bf16 a[96:111], v[56:59], v[12:15], a[96:111]
	s_waitcnt lgkmcnt(11)
	v_mfma_f32_32x32x16_bf16 a[80:95], v[60:63], v[8:11], a[80:95]
	v_mfma_f32_32x32x16_bf16 a[112:127], v[60:63], v[12:15], a[112:127]
	s_waitcnt lgkmcnt(10)
	v_mfma_f32_32x32x16_bf16 a[16:31], v[64:67], v[8:11], a[16:31]
	v_mfma_f32_32x32x16_bf16 a[0:15], v[64:67], v[12:15], a[0:15]
	s_waitcnt lgkmcnt(0)
	v_mfma_f32_32x32x16_bf16 a[32:47], v[16:19], v[28:31], a[32:47]
	v_mfma_f32_32x32x16_bf16 a[48:63], v[16:19], v[32:35], a[48:63]
	v_mfma_f32_32x32x16_bf16 a[64:79], v[20:23], v[28:31], a[64:79]
	v_mfma_f32_32x32x16_bf16 a[96:111], v[20:23], v[32:35], a[96:111]
	s_barrier
	v_add_u32_e32 v189, s5, v192
	v_add_u32_e32 v188, s5, v191
	v_add_u32_e32 v187, s5, v190
	ds_read_b128 v[52:55], v189
	ds_read_b128 v[8:11], v187 offset:36864
	ds_read_b128 v[56:59], v189 offset:4608
	ds_read_b128 v[12:15], v187 offset:41472
	ds_read_b128 v[60:63], v189 offset:9216
	ds_read_b128 v[64:67], v188
	v_mfma_f32_32x32x16_bf16 a[80:95], v[24:27], v[28:31], a[80:95]
	v_mfma_f32_32x32x16_bf16 a[112:127], v[24:27], v[32:35], a[112:127]
	v_mfma_f32_32x32x16_bf16 a[16:31], v[0:3], v[28:31], a[16:31]
	v_mfma_f32_32x32x16_bf16 a[0:15], v[0:3], v[32:35], a[0:15]
	s_add_u32 s2, s2, 0x80
	s_addc_u32 s3, s3, 0
	s_cmpk_lg_i32 s2, 0x700
	s_cbranch_scc1 .LBB0_1462
	s_branch xg5_tail_5
xg5_varB_5:
	s_and_b32 s5, s4, 1
	s_mul_i32 s8, s5, 0xd800
	s_xor_b32 s5, s5, 1
	s_mul_i32 s5, s5, 0xd800
	s_add_i32 s4, s4, 1
	v_add_u32_e32 v186, s5, v152
	ds_read_b128 v[16:19], v189 offset:32
	ds_read_b128 v[28:31], v187 offset:36896
	ds_read_b128 v[20:23], v189 offset:4640
	ds_read_b128 v[32:35], v187 offset:41504
	ds_read_b128 v[24:27], v189 offset:9248
	ds_read_b128 v[0:3], v188 offset:32
	s_waitcnt lgkmcnt(10)
	v_mfma_f32_32x32x16_bf16 a[32:47], v[52:55], v[8:11], a[32:47]
	s_waitcnt lgkmcnt(8)
	v_mfma_f32_32x32x16_bf16 a[48:63], v[52:55], v[12:15], a[48:63]
	v_mfma_f32_32x32x16_bf16 a[64:79], v[56:59], v[8:11], a[64:79]
	v_mfma_f32_32x32x16_bf16 a[96:111], v[56:59], v[12:15], a[96:111]
	s_waitcnt lgkmcnt(7)
	v_mfma_f32_32x32x16_bf16 a[80:95], v[60:63], v[8:11], a[80:95]
	v_mfma_f32_32x32x16_bf16 a[112:127], v[60:63], v[12:15], a[112:127]
	s_waitcnt lgkmcnt(6)
	v_mfma_f32_32x32x16_bf16 a[16:31], v[64:67], v[8:11], a[16:31]
	v_mfma_f32_32x32x16_bf16 a[0:15], v[64:67], v[12:15], a[0:15]
	ds_read_b128 v[52:55], v189 offset:64
	ds_read_b128 v[8:11], v187 offset:36928
	ds_read_b128 v[56:59], v189 offset:4672
	ds_read_b128 v[12:15], v187 offset:41536
	ds_read_b128 v[60:63], v189 offset:9280
	ds_read_b128 v[64:67], v188 offset:64
	s_waitcnt lgkmcnt(10)
	v_mfma_f32_32x32x16_bf16 a[32:47], v[16:19], v[28:31], a[32:47]
	s_waitcnt lgkmcnt(8)
	v_mfma_f32_32x32x16_bf16 a[48:63], v[16:19], v[32:35], a[48:63]
	v_mfma_f32_32x32x16_bf16 a[64:79], v[20:23], v[28:31], a[64:79]
	v_mfma_f32_32x32x16_bf16 a[96:111], v[20:23], v[32:35], a[96:111]
	s_waitcnt lgkmcnt(7)
	v_mfma_f32_32x32x16_bf16 a[80:95], v[24:27], v[28:31], a[80:95]
	s_waitcnt vmcnt(11)
	ds_write_b128 v186, v[250:253]
	v_mfma_f32_32x32x16_bf16 a[112:127], v[24:27], v[32:35], a[112:127]
	s_waitcnt vmcnt(10)
	ds_write_b128 v186, v[246:249] offset:4608
	global_load_dwordx4 v[250:253], v254, s[100:101] offset:512
	s_waitcnt lgkmcnt(8)
	v_mfma_f32_32x32x16_bf16 a[16:31], v[0:3], v[28:31], a[16:31]
	s_waitcnt vmcnt(10)
	ds_write_b128 v186, v[242:245] offset:9216
	global_load_dwordx4 v[246:249], v205, s[100:101] offset:512
	v_mfma_f32_32x32x16_bf16 a[0:15], v[0:3], v[32:35], a[0:15]
	s_waitcnt vmcnt(10)
	ds_write_b128 v186, v[238:241] offset:13824
	global_load_dwordx4 v[242:245], v204, s[100:101] offset:512
	ds_read_b128 v[16:19], v189 offset:96
	ds_read_b128 v[28:31], v187 offset:36960
	ds_read_b128 v[20:23], v189 offset:4704
	ds_read_b128 v[32:35], v187 offset:41568
	ds_read_b128 v[24:27], v189 offset:9312
	ds_read_b128 v[0:3], v188 offset:96
	s_waitcnt lgkmcnt(14)
	v_mfma_f32_32x32x16_bf16 a[32:47], v[52:55], v[8:11], a[32:47]
	s_waitcnt vmcnt(10)
	ds_write_b128 v186, v[234:237] offset:18432
	global_load_dwordx4 v[238:241], v203, s[100:101] offset:512
	s_waitcnt lgkmcnt(13)
	v_mfma_f32_32x32x16_bf16 a[48:63], v[52:55], v[12:15], a[48:63]
	s_waitcnt vmcnt(10)
	ds_write_b128 v186, v[230:233] offset:23040
	global_load_dwordx4 v[234:237], v202, s[100:101] offset:512
	v_mfma_f32_32x32x16_bf16 a[64:79], v[56:59], v[8:11], a[64:79]
	s_waitcnt vmcnt(10)
	ds_write_b128 v186, v[226:229] offset:27648
	global_load_dwordx4 v[230:233], v201, s[100:101] offset:512
	v_mfma_f32_32x32x16_bf16 a[96:111], v[56:59], v[12:15], a[96:111]
	s_waitcnt vmcnt(10)
	ds_write_b128 v186, v[222:225] offset:32256
	global_load_dwordx4 v[226:229], v200, s[100:101] offset:512
	s_waitcnt lgkmcnt(15)
	v_mfma_f32_32x32x16_bf16 a[80:95], v[60:63], v[8:11], a[80:95]
	s_waitcnt vmcnt(10)
	ds_write_b128 v186, v[218:221] offset:36864
	global_load_dwordx4 v[222:225], v199, s[100:101] offset:512
	v_mfma_f32_32x32x16_bf16 a[112:127], v[60:63], v[12:15], a[112:127]
	s_waitcnt vmcnt(10)
	ds_write_b128 v186, v[214:217] offset:41472
	global_load_dwordx4 v[218:221], v198, s[98:99] offset:256
	s_waitcnt lgkmcnt(15)
	v_mfma_f32_32x32x16_bf16 a[16:31], v[64:67], v[8:11], a[16:31]
	s_waitcnt vmcnt(10)
	ds_write_b128 v186, v[210:213] offset:46080
	global_load_dwordx4 v[214:217], v197, s[98:99] offset:256
	v_mfma_f32_32x32x16_bf16 a[0:15], v[64:67], v[12:15], a[0:15]
	s_waitcnt vmcnt(10)
	ds_write_b128 v186, v[206:209] offset:50688
	global_load_dwordx4 v[210:213], v196, s[98:99] offset:256
	s_waitcnt lgkmcnt(0)
	v_mfma_f32_32x32x16_bf16 a[32:47], v[16:19], v[28:31], a[32:47]
	global_load_dwordx4 v[206:209], v195, s[98:99] offset:256
	s_add_u32 s100, s100, 0x80
	s_addc_u32 s101, s101, 0
	s_add_u32 s98, s98, 0x80
	s_addc_u32 s99, s99, 0
	v_mfma_f32_32x32x16_bf16 a[48:63], v[16:19], v[32:35], a[48:63]
	v_mfma_f32_32x32x16_bf16 a[64:79], v[20:23], v[28:31], a[64:79]
	v_mfma_f32_32x32x16_bf16 a[96:111], v[20:23], v[32:35], a[96:111]
	s_barrier
	v_add_u32_e32 v189, s5, v192
	v_add_u32_e32 v188, s5, v191
	v_add_u32_e32 v187, s5, v190
	ds_read_b128 v[52:55], v189
	ds_read_b128 v[8:11], v187 offset:36864
	ds_read_b128 v[56:59], v189 offset:4608
	ds_read_b128 v[12:15], v187 offset:41472
	ds_read_b128 v[60:63], v189 offset:9216
	ds_read_b128 v[64:67], v188
	v_mfma_f32_32x32x16_bf16 a[80:95], v[24:27], v[28:31], a[80:95]
	v_mfma_f32_32x32x16_bf16 a[112:127], v[24:27], v[32:35], a[112:127]
	v_mfma_f32_32x32x16_bf16 a[16:31], v[0:3], v[28:31], a[16:31]
	v_mfma_f32_32x32x16_bf16 a[0:15], v[0:3], v[32:35], a[0:15]
	s_add_u32 s2, s2, 0x80
	s_addc_u32 s3, s3, 0
	s_cmpk_lg_i32 s2, 0x700
	s_cbranch_scc1 xg5_varB_5
xg5_tail_5:
	ds_read_b128 v[4:7], v165
	ds_read_b128 v[52:55], v165 offset:4608
	ds_read_b128 v[56:59], v165 offset:9216
	ds_read_b128 v[60:63], v166
	ds_read_b128 v[64:67], v167 offset:36864
	ds_read_b128 v[68:71], v167 offset:41472
	s_waitcnt vmcnt(11)
	s_waitcnt vmcnt(0)
	ds_write_b128 v168, v[250:253] offset:55296
	s_waitcnt vmcnt(10)
	ds_write_b128 v168, v[246:249] offset:59904
	s_waitcnt vmcnt(9)
	ds_write_b128 v168, v[242:245] offset:64512
	s_waitcnt vmcnt(8)
	ds_write_b128 v129, v[238:241] offset:55296
	s_waitcnt vmcnt(7)
	ds_write_b128 v135, v[234:237] offset:55296
	s_waitcnt vmcnt(6)
	ds_write_b128 v139, v[230:233] offset:55296
	s_waitcnt vmcnt(5)
	ds_write_b128 v157, v[226:229] offset:55296
	s_waitcnt vmcnt(4)
	ds_write_b128 v158, v[222:225] offset:55296
	s_waitcnt vmcnt(3)
	ds_write_b128 v159, v[218:221]
	s_waitcnt vmcnt(2)
	ds_write_b128 v159, v[214:217] offset:4608
	s_waitcnt vmcnt(1)
	ds_write_b128 v159, v[210:213] offset:9216
	s_waitcnt vmcnt(0)
	ds_write_b128 v159, v[206:209] offset:13824
	s_lshl_b32 s22, s61, 8
	s_cmp_gt_u32 s61, 31
	s_waitcnt lgkmcnt(13)
	v_mfma_f32_32x32x16_bf16 a[144:159], v[52:55], v[64:67], a[64:79]
	s_cselect_b64 s[2:3], -1, 0
	s_add_i32 s4, s22, 0xffffe000
	s_lshr_b32 s14, s4, 12
	s_cmp_lt_u32 s61, 32
	s_cselect_b64 s[4:5], -1, 0
	s_and_b64 s[8:9], s[4:5], exec
	s_cselect_b32 s8, 32, 0xf00
	s_waitcnt lgkmcnt(12)
	v_mfma_f32_32x32x16_bf16 a[160:175], v[4:7], v[68:71], a[48:63]
	s_cselect_b32 s24, s61, s14
	s_and_b32 s23, s8, s22
	s_cmp_lg_u32 s60, 5
	s_cselect_b64 s[72:73], -1, 0
	s_mov_b64 s[8:9], -1
	s_and_b64 vcc, exec, s[72:73]
	v_mfma_f32_32x32x16_bf16 a[128:143], v[52:55], v[68:71], a[96:111]
	v_mfma_f32_32x32x16_bf16 a[64:79], v[56:59], v[64:67], a[80:95]
	v_mfma_f32_32x32x16_bf16 a[48:63], v[56:59], v[68:71], a[112:127]
	v_mfma_f32_32x32x16_bf16 a[176:191], v[4:7], v[64:67], a[32:47]
	ds_read_b128 v[0:3], v165 offset:4640
	ds_read_b128 v[4:7], v165 offset:9248
	ds_read_b128 v[8:11], v167 offset:41504
	ds_read_b128 v[12:15], v167 offset:36896
	ds_read_b128 v[16:19], v167 offset:36928
	ds_read_b128 v[20:23], v165 offset:32
	ds_read_b128 v[24:27], v165 offset:64
	v_mfma_f32_32x32x16_bf16 a[32:47], v[60:63], v[64:67], a[16:31]
	v_mfma_f32_32x32x16_bf16 a[16:31], v[60:63], v[68:71], a[0:15]
	s_waitcnt lgkmcnt(3)
	v_mfma_f32_32x32x16_bf16 a[144:159], v[0:3], v[12:15], a[144:159]
	v_mfma_f32_32x32x16_bf16 a[128:143], v[0:3], v[8:11], a[128:143]
	v_mfma_f32_32x32x16_bf16 a[64:79], v[4:7], v[12:15], a[64:79]
	v_mfma_f32_32x32x16_bf16 a[48:63], v[4:7], v[8:11], a[48:63]
	ds_read_b128 v[0:3], v166 offset:32
	ds_read_b128 v[4:7], v166 offset:64
	s_waitcnt lgkmcnt(3)
	v_mfma_f32_32x32x16_bf16 a[176:191], v[20:23], v[12:15], a[176:191]
	v_mfma_f32_32x32x16_bf16 a[160:175], v[20:23], v[8:11], a[160:175]
	s_waitcnt lgkmcnt(1)
	v_mfma_f32_32x32x16_bf16 a[32:47], v[0:3], v[12:15], a[32:47]
	v_mfma_f32_32x32x16_bf16 a[16:31], v[0:3], v[8:11], a[16:31]
	ds_read_b128 v[0:3], v167 offset:41536
	ds_read_b128 v[8:11], v165 offset:9280
	ds_read_b128 v[12:15], v165 offset:4672
	v_mfma_f32_32x32x16_bf16 a[176:191], v[24:27], v[16:19], a[176:191]
	s_waitcnt lgkmcnt(0)
	v_mfma_f32_32x32x16_bf16 a[144:159], v[12:15], v[16:19], a[144:159]
	v_mfma_f32_32x32x16_bf16 a[128:143], v[12:15], v[0:3], a[128:143]
	v_mfma_f32_32x32x16_bf16 a[64:79], v[8:11], v[16:19], a[64:79]
	v_mfma_f32_32x32x16_bf16 a[48:63], v[8:11], v[0:3], a[48:63]
	v_mfma_f32_32x32x16_bf16 a[160:175], v[24:27], v[0:3], a[160:175]
	v_mfma_f32_32x32x16_bf16 a[32:47], v[4:7], v[16:19], a[32:47]
	v_mfma_f32_32x32x16_bf16 a[16:31], v[4:7], v[0:3], a[16:31]
	ds_read_b128 v[0:3], v167 offset:41568
	ds_read_b128 v[4:7], v167 offset:36960
	ds_read_b128 v[8:11], v166 offset:96
	ds_read_b128 v[12:15], v165 offset:9312
	ds_read_b128 v[16:19], v165 offset:4704
	ds_read_b128 v[20:23], v165 offset:96
	s_waitcnt lgkmcnt(0)
	s_barrier
	v_mfma_f32_32x32x16_bf16 a[176:191], v[20:23], v[4:7], a[176:191]
	v_mfma_f32_32x32x16_bf16 a[144:159], v[16:19], v[4:7], a[144:159]
	v_mfma_f32_32x32x16_bf16 a[128:143], v[16:19], v[0:3], a[128:143]
	v_mfma_f32_32x32x16_bf16 a[64:79], v[12:15], v[4:7], a[64:79]
	v_mfma_f32_32x32x16_bf16 a[48:63], v[12:15], v[0:3], a[48:63]
	v_mfma_f32_32x32x16_bf16 a[160:175], v[20:23], v[0:3], a[160:175]
	v_mfma_f32_32x32x16_bf16 a[32:47], v[8:11], v[4:7], a[32:47]
	v_mfma_f32_32x32x16_bf16 a[16:31], v[8:11], v[0:3], a[16:31]
	ds_read_b128 v[0:3], v165 offset:59904
	ds_read_b128 v[4:7], v165 offset:64512
	ds_read_b128 v[8:11], v160 offset:4608
	ds_read_b128 v[12:15], v165 offset:55296
	ds_read_b128 v[16:19], v165 offset:55328
	ds_read_b128 v[20:23], v160
	ds_read_b128 v[24:27], v160 offset:32
	s_waitcnt lgkmcnt(1)
	v_mfma_f32_32x32x16_bf16 a[176:191], v[12:15], v[20:23], a[176:191]
	v_mfma_f32_32x32x16_bf16 a[144:159], v[0:3], v[20:23], a[144:159]
	v_mfma_f32_32x32x16_bf16 a[128:143], v[0:3], v[8:11], a[128:143]
	v_mfma_f32_32x32x16_bf16 a[64:79], v[4:7], v[20:23], a[64:79]
	v_mfma_f32_32x32x16_bf16 a[48:63], v[4:7], v[8:11], a[48:63]
	ds_read_b128 v[0:3], v166 offset:55296
	ds_read_b128 v[4:7], v166 offset:55328
	v_mfma_f32_32x32x16_bf16 a[160:175], v[12:15], v[8:11], a[160:175]
	s_waitcnt lgkmcnt(1)
	v_mfma_f32_32x32x16_bf16 a[32:47], v[0:3], v[20:23], a[32:47]
	v_mfma_f32_32x32x16_bf16 a[16:31], v[0:3], v[8:11], a[16:31]
	ds_read_b128 v[0:3], v165 offset:64544
	ds_read_b128 v[8:11], v165 offset:59936
	ds_read_b128 v[12:15], v160 offset:4640
	v_mfma_f32_32x32x16_bf16 a[176:191], v[16:19], v[24:27], a[176:191]
	s_waitcnt lgkmcnt(0)
	v_mfma_f32_32x32x16_bf16 a[160:175], v[16:19], v[12:15], a[160:175]
	v_mfma_f32_32x32x16_bf16 a[144:159], v[8:11], v[24:27], a[144:159]
	v_mfma_f32_32x32x16_bf16 a[128:143], v[8:11], v[12:15], a[128:143]
	v_mfma_f32_32x32x16_bf16 a[64:79], v[0:3], v[24:27], a[64:79]
	v_mfma_f32_32x32x16_bf16 a[48:63], v[0:3], v[12:15], a[48:63]
	v_mfma_f32_32x32x16_bf16 a[32:47], v[4:7], v[24:27], a[32:47]
	v_mfma_f32_32x32x16_bf16 a[16:31], v[4:7], v[12:15], a[16:31]
	ds_read_b128 v[0:3], v166 offset:55360
	ds_read_b128 v[4:7], v165 offset:64576
	ds_read_b128 v[8:11], v165 offset:59968
	ds_read_b128 v[12:15], v165 offset:55360
	ds_read_b128 v[16:19], v160 offset:64
	ds_read_b128 v[20:23], v160 offset:4672
	s_waitcnt lgkmcnt(1)
	v_mfma_f32_32x32x16_bf16 a[176:191], v[12:15], v[16:19], a[176:191]
	s_waitcnt lgkmcnt(0)
	v_mfma_f32_32x32x16_bf16 a[160:175], v[12:15], v[20:23], a[160:175]
	v_mfma_f32_32x32x16_bf16 a[144:159], v[8:11], v[16:19], a[144:159]
	v_mfma_f32_32x32x16_bf16 a[128:143], v[8:11], v[20:23], a[128:143]
	v_mfma_f32_32x32x16_bf16 a[64:79], v[4:7], v[16:19], a[64:79]
	v_mfma_f32_32x32x16_bf16 a[48:63], v[4:7], v[20:23], a[48:63]
	v_mfma_f32_32x32x16_bf16 a[32:47], v[0:3], v[16:19], a[32:47]
	v_mfma_f32_32x32x16_bf16 a[16:31], v[0:3], v[20:23], a[16:31]
	ds_read_b128 v[0:3], v166 offset:55392
	ds_read_b128 v[4:7], v165 offset:64608
	ds_read_b128 v[8:11], v165 offset:60000
	ds_read_b128 v[12:15], v165 offset:55392
	ds_read_b128 v[16:19], v160 offset:96
	ds_read_b128 v[20:23], v160 offset:4704
	s_waitcnt lgkmcnt(0)
	s_barrier
	v_mfma_f32_32x32x16_bf16 a[176:191], v[12:15], v[16:19], a[176:191]
	v_mfma_f32_32x32x16_bf16 a[32:47], v[0:3], v[16:19], a[32:47]
	v_mfma_f32_32x32x16_bf16 a[16:31], v[0:3], v[20:23], a[16:31]
	v_accvgpr_read_b32 v0, a212
	v_lshlrev_b32_e32 v0, 5, v0
	v_lshlrev_b32_e32 v104, 1, v0
	v_mfma_f32_32x32x16_bf16 a[160:175], v[12:15], v[20:23], a[160:175]
	v_mfma_f32_32x32x16_bf16 a[144:159], v[8:11], v[16:19], a[144:159]
	v_mfma_f32_32x32x16_bf16 a[128:143], v[8:11], v[20:23], a[128:143]
	v_mfma_f32_32x32x16_bf16 a[64:79], v[4:7], v[16:19], a[64:79]
	v_mfma_f32_32x32x16_bf16 a[48:63], v[4:7], v[20:23], a[48:63]
	s_nop 1
	ds_write_b32 v156, a176
	ds_write_b32 v156, a177 offset:516
	ds_write_b32 v156, a178 offset:1032
	ds_write_b32 v156, a179 offset:1548
	ds_write_b32 v156, a180 offset:4128
	ds_write_b32 v156, a181 offset:4644
	ds_write_b32 v156, a182 offset:5160
	ds_write_b32 v156, a183 offset:5676
	ds_write_b32 v156, a184 offset:8256
	ds_write_b32 v156, a185 offset:8772
	ds_write_b32 v156, a186 offset:9288
	ds_write_b32 v156, a187 offset:9804
	ds_write_b32 v156, a188 offset:12384
	ds_write_b32 v156, a189 offset:12900
	ds_write_b32 v156, a190 offset:13416
	ds_write_b32 v156, a191 offset:13932
	ds_write_b32 v156, a160 offset:128
	ds_write_b32 v156, a161 offset:644
	ds_write_b32 v156, a162 offset:1160
	ds_write_b32 v156, a163 offset:1676
	ds_write_b32 v156, a164 offset:4256
	ds_write_b32 v156, a165 offset:4772
	ds_write_b32 v156, a166 offset:5288
	ds_write_b32 v156, a167 offset:5804
	ds_write_b32 v156, a168 offset:8384
	ds_write_b32 v156, a169 offset:8900
	ds_write_b32 v156, a170 offset:9416
	ds_write_b32 v156, a171 offset:9932
	ds_write_b32 v156, a172 offset:12512
	ds_write_b32 v156, a173 offset:13028
	ds_write_b32 v156, a174 offset:13544
	ds_write_b32 v156, a175 offset:14060
	ds_write_b32 v156, a144 offset:16512
	ds_write_b32 v156, a145 offset:17028
	ds_write_b32 v156, a146 offset:17544
	ds_write_b32 v156, a147 offset:18060
	ds_write_b32 v156, a148 offset:20640
	ds_write_b32 v156, a149 offset:21156
	ds_write_b32 v156, a150 offset:21672
	ds_write_b32 v156, a151 offset:22188
	ds_write_b32 v156, a152 offset:24768
	ds_write_b32 v156, a153 offset:25284
	ds_write_b32 v156, a154 offset:25800
	ds_write_b32 v156, a155 offset:26316
	ds_write_b32 v156, a156 offset:28896
	ds_write_b32 v156, a157 offset:29412
	ds_write_b32 v156, a158 offset:29928
	ds_write_b32 v156, a159 offset:30444
	ds_write_b32 v156, a128 offset:16640
	ds_write_b32 v156, a129 offset:17156
	ds_write_b32 v156, a130 offset:17672
	ds_write_b32 v156, a131 offset:18188
	ds_write_b32 v156, a132 offset:20768
	ds_write_b32 v156, a133 offset:21284
	ds_write_b32 v156, a134 offset:21800
	ds_write_b32 v156, a135 offset:22316
	ds_write_b32 v156, a136 offset:24896
	ds_write_b32 v156, a137 offset:25412
	ds_write_b32 v156, a138 offset:25928
	ds_write_b32 v156, a139 offset:26444
	ds_write_b32 v156, a140 offset:29024
	ds_write_b32 v156, a141 offset:29540
	ds_write_b32 v156, a142 offset:30056
	ds_write_b32 v156, a143 offset:30572
	ds_write_b32 v156, a64 offset:33024
	ds_write_b32 v156, a65 offset:33540
	ds_write_b32 v156, a66 offset:34056
	ds_write_b32 v156, a67 offset:34572
	ds_write_b32 v156, a68 offset:37152
	ds_write_b32 v156, a69 offset:37668
	ds_write_b32 v156, a70 offset:38184
	ds_write_b32 v156, a71 offset:38700
	ds_write_b32 v156, a72 offset:41280
	ds_write_b32 v156, a73 offset:41796
	ds_write_b32 v156, a74 offset:42312
	ds_write_b32 v156, a75 offset:42828
	ds_write_b32 v156, a76 offset:45408
	ds_write_b32 v156, a77 offset:45924
	ds_write_b32 v156, a78 offset:46440
	ds_write_b32 v156, a79 offset:46956
	ds_write_b32 v156, a48 offset:33152
	ds_write_b32 v156, a49 offset:33668
	ds_write_b32 v156, a50 offset:34184
	ds_write_b32 v156, a51 offset:34700
	ds_write_b32 v156, a52 offset:37280
	ds_write_b32 v156, a53 offset:37796
	ds_write_b32 v156, a54 offset:38312
	ds_write_b32 v156, a55 offset:38828
	ds_write_b32 v156, a56 offset:41408
	ds_write_b32 v156, a57 offset:41924
	ds_write_b32 v156, a58 offset:42440
	ds_write_b32 v156, a59 offset:42956
	ds_write_b32 v156, a60 offset:45536
	ds_write_b32 v156, a61 offset:46052
	ds_write_b32 v156, a62 offset:46568
	ds_write_b32 v156, a63 offset:47084
	ds_write_b32 v156, a32 offset:49536
	ds_write_b32 v156, a33 offset:50052
	ds_write_b32 v156, a34 offset:50568
	ds_write_b32 v156, a35 offset:51084
	ds_write_b32 v156, a36 offset:53664
	ds_write_b32 v156, a37 offset:54180
	ds_write_b32 v156, a38 offset:54696
	ds_write_b32 v156, a39 offset:55212
	ds_write_b32 v156, a40 offset:57792
	ds_write_b32 v156, a41 offset:58308
	ds_write_b32 v156, a42 offset:58824
	ds_write_b32 v156, a43 offset:59340
	ds_write_b32 v156, a44 offset:61920
	ds_write_b32 v156, a45 offset:62436
	ds_write_b32 v156, a46 offset:62952
	ds_write_b32 v156, a47 offset:63468
	ds_write_b32 v156, a16 offset:49664
	ds_write_b32 v156, a17 offset:50180
	ds_write_b32 v156, a18 offset:50696
	ds_write_b32 v156, a19 offset:51212
	ds_write_b32 v156, a20 offset:53792
	ds_write_b32 v156, a21 offset:54308
	ds_write_b32 v156, a22 offset:54824
	ds_write_b32 v156, a23 offset:55340
	ds_write_b32 v156, a24 offset:57920
	ds_write_b32 v156, a25 offset:58436
	ds_write_b32 v156, a26 offset:58952
	ds_write_b32 v156, a27 offset:59468
	ds_write_b32 v156, a28 offset:62048
	ds_write_b32 v156, a29 offset:62564
	ds_write_b32 v156, a30 offset:63080
	ds_write_b32 v156, a31 offset:63596
	s_waitcnt lgkmcnt(0)
	s_barrier
	s_cbranch_vccz .LBB0_1502
	s_cmp_eq_u32 s60, 18
	s_cselect_b64 s[74:75], -1, 0
	s_cmp_gt_u32 s60, 3
	s_cselect_b64 s[78:79], -1, 0
	s_cmp_lg_u32 s60, 4
	v_accvgpr_read_b32 v0, a210
	s_cselect_b64 s[80:81], -1, 0
	s_cmp_gt_u32 s60, 7
	v_add_u32_e32 v4, s22, v0
	s_cselect_b64 s[82:83], -1, 0
	s_cmp_gt_u32 s60, 9
	s_cselect_b64 s[84:85], -1, 0
	s_cmp_gt_u32 s60, 13
	v_lshlrev_b32_e32 v80, 7, v4
	s_cselect_b64 s[86:87], -1, 0
	s_cmp_gt_u32 s60, 17
	v_lshl_add_u64 v[106:107], s[18:19], 0, v[80:81]
	v_lshlrev_b32_e32 v80, 10, v4
	v_add_u32_e32 v5, s23, v0
	s_cselect_b64 s[88:89], -1, 0
	v_lshl_add_u64 v[0:1], s[10:11], 0, v[80:81]
	s_lshl_b32 s14, s60, 8
	v_lshl_add_u64 v[2:3], v[0:1], 0, s[14:15]
	v_mov_b32_e32 v105, v81
	v_lshl_add_u64 v[2:3], v[2:3], 0, v[104:105]
	v_lshl_add_u64 v[108:109], v[2:3], 0, s[62:63]
	v_lshl_add_u64 v[110:111], v[2:3], 0, s[64:65]
	v_lshlrev_b32_e32 v2, 9, v4
	v_sub_co_u32_e32 v2, vcc, 0, v2
	s_lshl_b32 s25, s60, 7
	s_nop 0
	v_subb_co_u32_e64 v3, s[8:9], 0, 0, vcc
	v_lshl_add_u64 v[0:1], v[0:1], 0, v[2:3]
	v_lshl_add_u64 v[0:1], v[0:1], 0, s[14:15]
	v_lshl_add_u64 v[0:1], v[0:1], 0, v[104:105]
	v_lshl_add_u64 v[112:113], v[0:1], 0, s[66:67]
	v_lshl_add_u64 v[114:115], v[0:1], 0, s[68:69]
	v_lshrrev_b32_e32 v0, 6, v5
	v_accvgpr_read_b32 v1, a211
	v_cndmask_b32_e64 v0, v1, v0, s[6:7]
	v_lshlrev_b32_e32 v80, 7, v0
	v_lshlrev_b32_e32 v0, 7, v5
	v_mov_b32_e32 v1, v81
	v_lshl_add_u64 v[118:119], v[88:89], 0, v[0:1]
	s_lshl_b32 s14, s24, 9
	v_add_u32_e32 v0, 0x100, v5
	v_lshl_add_u64 v[0:1], v[0:1], 0, s[14:15]
	v_lshlrev_b64 v[0:1], 9, v[0:1]
	v_lshlrev_b32_e32 v2, 11, v4
	v_mov_b32_e32 v3, v81
	v_lshl_add_u64 v[116:117], s[16:17], 0, v[80:81]
	s_lshl_b32 s26, s24, 1
	v_mov_b32_e32 v80, v5
	v_lshl_add_u64 v[120:121], v[90:91], 0, v[2:3]
	v_lshl_add_u64 v[122:123], v[94:95], 0, v[0:1]
	s_mov_b32 s27, 0
	s_mov_b64 s[92:93], -1
	s_mov_b64 s[90:91], 0
	s_branch .LBB0_1467

.LBB0_1963:
	s_lshr_b32 s48, s47, 3
	s_lshl_b32 s42, s48, 18
	s_add_i32 s42, s68, s42
	v_lshl_add_u64 v[10:11], s[42:43], 1, v[8:9]
	s_and_b32 s42, s46, 7
	s_lshl_b32 s42, s42, 18
	s_add_i32 s48, s48, s65
	v_lshl_add_u64 v[12:13], v[8:9], 0, s[42:43]
	s_lshl_b32 s42, s48, 19
	v_lshl_add_u64 v[14:15], v[2:3], 0, s[42:43]
	v_add_co_u32_e32 v16, vcc, s69, v14
	s_and_b32 s49, s47, 7
	s_nop 0
	v_addc_co_u32_e32 v17, vcc, 0, v15, vcc
	v_add_co_u32_e32 v18, vcc, s70, v14
	s_lshl_b32 s42, s49, 18
	s_nop 0
	v_addc_co_u32_e32 v19, vcc, 0, v15, vcc
	v_add_co_u32_e32 v76, vcc, s71, v14
	v_lshl_add_u64 v[90:91], v[4:5], 0, s[42:43]
	s_nop 0
	v_addc_co_u32_e32 v77, vcc, 0, v15, vcc
	v_add_co_u32_e32 v78, vcc, s72, v14
	global_load_dwordx4 v[108:111], v[14:15], off
	global_load_dwordx4 v[112:115], v[16:17], off
	v_addc_co_u32_e32 v79, vcc, 0, v15, vcc
	v_add_co_u32_e32 v80, vcc, s73, v14
	global_load_dwordx4 v[116:119], v[18:19], off
	global_load_dwordx4 v[120:123], v[76:77], off
	v_addc_co_u32_e32 v81, vcc, 0, v15, vcc
	v_add_co_u32_e32 v82, vcc, s74, v14
	global_load_dwordx4 v[124:127], v[78:79], off
	global_load_dwordx4 v[128:131], v[80:81], off
	v_addc_co_u32_e32 v83, vcc, 0, v15, vcc
	v_add_co_u32_e32 v88, vcc, s75, v14
	global_load_dwordx4 v[140:143], v[82:83], off
	s_nop 0
	v_addc_co_u32_e32 v89, vcc, 0, v15, vcc
	v_add_co_u32_e32 v92, vcc, s69, v90
	global_load_dwordx4 v[144:147], v[88:89], off
	s_nop 0
	v_addc_co_u32_e32 v93, vcc, 0, v91, vcc
	v_add_co_u32_e32 v104, vcc, s70, v90
	global_load_dwordx4 v[148:151], v[90:91], off
	global_load_dwordx4 v[152:155], v[92:93], off
	v_addc_co_u32_e32 v105, vcc, 0, v91, vcc
	v_add_co_u32_e32 v106, vcc, s71, v90
	global_load_dwordx4 v[156:159], v[104:105], off
	s_nop 0
	v_addc_co_u32_e32 v107, vcc, 0, v91, vcc
	global_load_dwordx4 v[160:163], v[106:107], off
	global_load_dwordx4 v[250:253], v[14:15], off offset:128
	global_load_dwordx4 v[246:249], v[16:17], off offset:128
	global_load_dwordx4 v[242:245], v[18:19], off offset:128
	s_nop 0
	global_load_dwordx4 v[238:241], v[76:77], off offset:128
	global_load_dwordx4 v[234:237], v[78:79], off offset:128
	global_load_dwordx4 v[230:233], v[80:81], off offset:128
	s_nop 0
	global_load_dwordx4 v[226:229], v[82:83], off offset:128
	s_nop 0
	global_load_dwordx4 v[222:225], v[88:89], off offset:128
	global_load_dwordx4 v[218:221], v[90:91], off offset:128
	s_nop 0
	global_load_dwordx4 v[214:217], v[92:93], off offset:128
	s_nop 0
	global_load_dwordx4 v[210:213], v[104:105], off offset:128
	s_nop 0
	global_load_dwordx4 v[206:209], v[106:107], off offset:128
	s_mov_b32 s42, 0
	v_accvgpr_write_b32 a47, 0
	v_accvgpr_write_b32 a46, 0
	v_accvgpr_write_b32 a45, 0
	v_accvgpr_write_b32 a44, 0
	v_accvgpr_write_b32 a43, 0
	v_accvgpr_write_b32 a42, 0
	v_accvgpr_write_b32 a41, 0
	v_accvgpr_write_b32 a40, 0
	v_accvgpr_write_b32 a39, 0
	v_accvgpr_write_b32 a38, 0
	v_accvgpr_write_b32 a37, 0
	v_accvgpr_write_b32 a36, 0
	v_accvgpr_write_b32 a35, 0
	v_accvgpr_write_b32 a34, 0
	v_accvgpr_write_b32 a33, 0
	v_accvgpr_write_b32 a32, 0
	v_accvgpr_write_b32 a63, 0
	v_accvgpr_write_b32 a62, 0
	v_accvgpr_write_b32 a61, 0
	v_accvgpr_write_b32 a60, 0
	v_accvgpr_write_b32 a59, 0
	v_accvgpr_write_b32 a58, 0
	v_accvgpr_write_b32 a57, 0
	v_accvgpr_write_b32 a56, 0
	v_accvgpr_write_b32 a55, 0
	v_accvgpr_write_b32 a54, 0
	v_accvgpr_write_b32 a53, 0
	v_accvgpr_write_b32 a52, 0
	v_accvgpr_write_b32 a51, 0
	v_accvgpr_write_b32 a50, 0
	v_accvgpr_write_b32 a49, 0
	v_accvgpr_write_b32 a48, 0
	v_accvgpr_write_b32 a79, 0
	v_accvgpr_write_b32 a78, 0
	v_accvgpr_write_b32 a77, 0
	v_accvgpr_write_b32 a76, 0
	v_accvgpr_write_b32 a75, 0
	v_accvgpr_write_b32 a74, 0
	v_accvgpr_write_b32 a73, 0
	v_accvgpr_write_b32 a72, 0
	v_accvgpr_write_b32 a71, 0
	v_accvgpr_write_b32 a70, 0
	v_accvgpr_write_b32 a69, 0
	v_accvgpr_write_b32 a68, 0
	v_accvgpr_write_b32 a67, 0
	v_accvgpr_write_b32 a66, 0
	v_accvgpr_write_b32 a65, 0
	v_accvgpr_write_b32 a64, 0
	v_accvgpr_write_b32 a111, 0
	v_accvgpr_write_b32 a110, 0
	v_accvgpr_write_b32 a109, 0
	v_accvgpr_write_b32 a108, 0
	v_accvgpr_write_b32 a107, 0
	v_accvgpr_write_b32 a106, 0
	v_accvgpr_write_b32 a105, 0
	v_accvgpr_write_b32 a104, 0
	v_accvgpr_write_b32 a103, 0
	v_accvgpr_write_b32 a102, 0
	v_accvgpr_write_b32 a101, 0
	v_accvgpr_write_b32 a100, 0
	v_accvgpr_write_b32 a99, 0
	v_accvgpr_write_b32 a98, 0
	v_accvgpr_write_b32 a97, 0
	v_accvgpr_write_b32 a96, 0
	v_accvgpr_write_b32 a95, 0
	v_accvgpr_write_b32 a94, 0
	v_accvgpr_write_b32 a93, 0
	v_accvgpr_write_b32 a92, 0
	v_accvgpr_write_b32 a91, 0
	v_accvgpr_write_b32 a90, 0
	v_accvgpr_write_b32 a89, 0
	v_accvgpr_write_b32 a88, 0
	v_accvgpr_write_b32 a87, 0
	v_accvgpr_write_b32 a86, 0
	v_accvgpr_write_b32 a85, 0
	v_accvgpr_write_b32 a84, 0
	v_accvgpr_write_b32 a83, 0
	v_accvgpr_write_b32 a82, 0
	v_accvgpr_write_b32 a81, 0
	v_accvgpr_write_b32 a80, 0
	v_accvgpr_write_b32 a127, 0
	v_accvgpr_write_b32 a126, 0
	v_accvgpr_write_b32 a125, 0
	v_accvgpr_write_b32 a124, 0
	v_accvgpr_write_b32 a123, 0
	v_accvgpr_write_b32 a122, 0
	v_accvgpr_write_b32 a121, 0
	v_accvgpr_write_b32 a120, 0
	v_accvgpr_write_b32 a119, 0
	v_accvgpr_write_b32 a118, 0
	v_accvgpr_write_b32 a117, 0
	v_accvgpr_write_b32 a116, 0
	v_accvgpr_write_b32 a115, 0
	v_accvgpr_write_b32 a114, 0
	v_accvgpr_write_b32 a113, 0
	v_accvgpr_write_b32 a112, 0
	v_accvgpr_write_b32 a31, 0
	v_accvgpr_write_b32 a30, 0
	v_accvgpr_write_b32 a29, 0
	v_accvgpr_write_b32 a28, 0
	v_accvgpr_write_b32 a27, 0
	v_accvgpr_write_b32 a26, 0
	v_accvgpr_write_b32 a25, 0
	v_accvgpr_write_b32 a24, 0
	v_accvgpr_write_b32 a23, 0
	v_accvgpr_write_b32 a22, 0
	v_accvgpr_write_b32 a21, 0
	v_accvgpr_write_b32 a20, 0
	v_accvgpr_write_b32 a19, 0
	v_accvgpr_write_b32 a18, 0
	v_accvgpr_write_b32 a17, 0
	v_accvgpr_write_b32 a16, 0
	v_accvgpr_write_b32 a15, 0
	v_accvgpr_write_b32 a14, 0
	v_accvgpr_write_b32 a13, 0
	v_accvgpr_write_b32 a12, 0
	v_accvgpr_write_b32 a11, 0
	v_accvgpr_write_b32 a10, 0
	v_accvgpr_write_b32 a9, 0
	v_accvgpr_write_b32 a8, 0
	v_accvgpr_write_b32 a7, 0
	v_accvgpr_write_b32 a6, 0
	v_accvgpr_write_b32 a5, 0
	v_accvgpr_write_b32 a4, 0
	v_accvgpr_write_b32 a3, 0
	v_accvgpr_write_b32 a2, 0
	v_accvgpr_write_b32 a1, 0
	v_accvgpr_write_b32 a0, 0
	s_mov_b64 s[44:45], 0
	s_waitcnt vmcnt(23)
	ds_write_b128 v45, v[108:111]
	s_waitcnt vmcnt(22)
	ds_write_b128 v45, v[112:115] offset:4608
	s_waitcnt vmcnt(21)
	ds_write_b128 v45, v[116:119] offset:9216
	s_waitcnt vmcnt(20)
	ds_write_b128 v45, v[120:123] offset:13824
	s_waitcnt vmcnt(19)
	ds_write_b128 v45, v[124:127] offset:18432
	s_waitcnt vmcnt(18)
	ds_write_b128 v45, v[128:131] offset:23040
	s_waitcnt vmcnt(17)
	ds_write_b128 v45, v[140:143] offset:27648
	s_waitcnt vmcnt(16)
	ds_write_b128 v45, v[144:147] offset:32256
	s_waitcnt vmcnt(15)
	ds_write_b128 v45, v[148:151] offset:36864
	s_waitcnt vmcnt(14)
	ds_write_b128 v45, v[152:155] offset:41472
	s_waitcnt vmcnt(13)
	ds_write_b128 v45, v[156:159] offset:46080
	s_waitcnt vmcnt(12)
	ds_write_b128 v45, v[160:163] offset:50688
	s_waitcnt lgkmcnt(0)
	s_barrier
	s_waitcnt vmcnt(0)
	v_readfirstlane_b32 s100, v10
	v_readfirstlane_b32 s101, v11
	v_readfirstlane_b32 s98, v12
	v_readfirstlane_b32 s99, v13
	s_nop 1
	v_subrev_u32_e32 v194, s100, v10
	v_subrev_u32_e32 v193, s98, v12
	v_add_u32_e32 v254, s78, v194
	v_add_u32_e32 v205, s79, v194
	v_add_u32_e32 v204, s80, v194
	v_add_u32_e32 v203, s81, v194
	v_add_u32_e32 v202, s82, v194
	v_add_u32_e32 v201, s83, v194
	v_add_u32_e32 v200, s84, v194
	v_add_u32_e32 v199, s85, v194
	v_add_u32_e32 v198, s86, v193
	v_add_u32_e32 v197, s87, v193
	v_add_u32_e32 v196, s88, v193
	v_add_u32_e32 v195, s89, v193
	s_add_u32 s100, s100, s44
	s_addc_u32 s101, s101, s45
	s_add_u32 s98, s98, s44
	s_addc_u32 s99, s99, s45
	v_add_u32_e32 v192, v20, v46
	v_add_u32_e32 v191, v20, v47
	v_add_u32_e32 v190, v20, v48
	s_and_b32 s50, s42, 1
	s_mul_i32 s51, s50, 0xd800
	v_add_u32_e32 v189, s51, v192
	v_add_u32_e32 v188, s51, v191
	v_add_u32_e32 v187, s51, v190
	ds_read_b128 v[108:111], v189
	ds_read_b128 v[14:17], v187 offset:36864
	ds_read_b128 v[112:115], v189 offset:4608
	ds_read_b128 v[64:67], v187 offset:41472
	ds_read_b128 v[116:119], v189 offset:9216
	ds_read_b128 v[120:123], v188
	s_getreg_b32 s50, hwreg(HW_REG_HW_ID, 4, 1)
	s_cmp_lg_u32 s50, 0
	s_cbranch_scc1 xg5_varB_6
.LBB0_1964:
	s_and_b32 s50, s42, 1
	s_mul_i32 s51, s50, 0xd800
	s_xor_b32 s50, s50, 1
	s_mul_i32 s50, s50, 0xd800
	s_add_i32 s42, s42, 1
	v_add_u32_e32 v186, s50, v45
	ds_read_b128 v[68:71], v189 offset:32
	ds_read_b128 v[80:83], v187 offset:36896
	ds_read_b128 v[72:75], v189 offset:4640
	ds_read_b128 v[84:87], v187 offset:41504
	ds_read_b128 v[76:79], v189 offset:9248
	ds_read_b128 v[104:107], v188 offset:32
	s_waitcnt lgkmcnt(10)
	v_mfma_f32_32x32x16_bf16 a[32:47], v[108:111], v[14:17], a[32:47]
	s_waitcnt vmcnt(11)
	ds_write_b128 v186, v[250:253]
	s_waitcnt lgkmcnt(9)
	v_mfma_f32_32x32x16_bf16 a[48:63], v[108:111], v[64:67], a[48:63]
	s_waitcnt vmcnt(10)
	ds_write_b128 v186, v[246:249] offset:4608
	global_load_dwordx4 v[250:253], v254, s[100:101] offset:512
	v_mfma_f32_32x32x16_bf16 a[64:79], v[112:115], v[14:17], a[64:79]
	s_waitcnt vmcnt(10)
	ds_write_b128 v186, v[242:245] offset:9216
	global_load_dwordx4 v[246:249], v205, s[100:101] offset:512
	v_mfma_f32_32x32x16_bf16 a[96:111], v[112:115], v[64:67], a[96:111]
	s_waitcnt vmcnt(10)
	ds_write_b128 v186, v[238:241] offset:13824
	global_load_dwordx4 v[242:245], v204, s[100:101] offset:512
	s_waitcnt lgkmcnt(11)
	v_mfma_f32_32x32x16_bf16 a[80:95], v[116:119], v[14:17], a[80:95]
	s_waitcnt vmcnt(10)
	ds_write_b128 v186, v[234:237] offset:18432
	global_load_dwordx4 v[238:241], v203, s[100:101] offset:512
	v_mfma_f32_32x32x16_bf16 a[112:127], v[116:119], v[64:67], a[112:127]
	s_waitcnt vmcnt(10)
	ds_write_b128 v186, v[230:233] offset:23040
	global_load_dwordx4 v[234:237], v202, s[100:101] offset:512
	s_waitcnt lgkmcnt(12)
	v_mfma_f32_32x32x16_bf16 a[16:31], v[120:123], v[14:17], a[16:31]
	s_waitcnt vmcnt(10)
	ds_write_b128 v186, v[226:229] offset:27648
	global_load_dwordx4 v[230:233], v201, s[100:101] offset:512
	v_mfma_f32_32x32x16_bf16 a[0:15], v[120:123], v[64:67], a[0:15]
	s_waitcnt vmcnt(10)
	ds_write_b128 v186, v[222:225] offset:32256
	global_load_dwordx4 v[226:229], v200, s[100:101] offset:512
	ds_read_b128 v[108:111], v189 offset:64
	ds_read_b128 v[14:17], v187 offset:36928
	ds_read_b128 v[112:115], v189 offset:4672
	ds_read_b128 v[64:67], v187 offset:41536
	ds_read_b128 v[116:119], v189 offset:9280
	ds_read_b128 v[120:123], v188 offset:64
	s_waitcnt lgkmcnt(15)
	v_mfma_f32_32x32x16_bf16 a[32:47], v[68:71], v[80:83], a[32:47]
	s_waitcnt vmcnt(10)
	ds_write_b128 v186, v[218:221] offset:36864
	global_load_dwordx4 v[222:225], v199, s[100:101] offset:512
	v_mfma_f32_32x32x16_bf16 a[48:63], v[68:71], v[84:87], a[48:63]
	s_waitcnt vmcnt(10)
	ds_write_b128 v186, v[214:217] offset:41472
	global_load_dwordx4 v[218:221], v198, s[98:99] offset:256
	v_mfma_f32_32x32x16_bf16 a[64:79], v[72:75], v[80:83], a[64:79]
	s_waitcnt vmcnt(10)
	ds_write_b128 v186, v[210:213] offset:46080
	global_load_dwordx4 v[214:217], v197, s[98:99] offset:256
	v_mfma_f32_32x32x16_bf16 a[96:111], v[72:75], v[84:87], a[96:111]
	s_waitcnt vmcnt(10)
	ds_write_b128 v186, v[206:209] offset:50688
	global_load_dwordx4 v[210:213], v196, s[98:99] offset:256
	v_mfma_f32_32x32x16_bf16 a[80:95], v[76:79], v[80:83], a[80:95]
	global_load_dwordx4 v[206:209], v195, s[98:99] offset:256
	s_add_u32 s100, s100, 0x80
	s_addc_u32 s101, s101, 0
	s_add_u32 s98, s98, 0x80
	s_addc_u32 s99, s99, 0
	v_mfma_f32_32x32x16_bf16 a[112:127], v[76:79], v[84:87], a[112:127]
	s_waitcnt lgkmcnt(15)
	v_mfma_f32_32x32x16_bf16 a[16:31], v[104:107], v[80:83], a[16:31]
	v_mfma_f32_32x32x16_bf16 a[0:15], v[104:107], v[84:87], a[0:15]
	ds_read_b128 v[68:71], v189 offset:96
	ds_read_b128 v[80:83], v187 offset:36960
	ds_read_b128 v[72:75], v189 offset:4704
	ds_read_b128 v[84:87], v187 offset:41568
	ds_read_b128 v[76:79], v189 offset:9312
	ds_read_b128 v[104:107], v188 offset:96
	s_waitcnt lgkmcnt(14)
	v_mfma_f32_32x32x16_bf16 a[32:47], v[108:111], v[14:17], a[32:47]
	s_waitcnt lgkmcnt(12)
	v_mfma_f32_32x32x16_bf16 a[48:63], v[108:111], v[64:67], a[48:63]
	v_mfma_f32_32x32x16_bf16 a[64:79], v[112:115], v[14:17], a[64:79]
	v_mfma_f32_32x32x16_bf16 a[96:111], v[112:115], v[64:67], a[96:111]
	s_waitcnt lgkmcnt(11)
	v_mfma_f32_32x32x16_bf16 a[80:95], v[116:119], v[14:17], a[80:95]
	v_mfma_f32_32x32x16_bf16 a[112:127], v[116:119], v[64:67], a[112:127]
	s_waitcnt lgkmcnt(10)
	v_mfma_f32_32x32x16_bf16 a[16:31], v[120:123], v[14:17], a[16:31]
	v_mfma_f32_32x32x16_bf16 a[0:15], v[120:123], v[64:67], a[0:15]
	s_waitcnt lgkmcnt(0)
	v_mfma_f32_32x32x16_bf16 a[32:47], v[68:71], v[80:83], a[32:47]
	v_mfma_f32_32x32x16_bf16 a[48:63], v[68:71], v[84:87], a[48:63]
	v_mfma_f32_32x32x16_bf16 a[64:79], v[72:75], v[80:83], a[64:79]
	v_mfma_f32_32x32x16_bf16 a[96:111], v[72:75], v[84:87], a[96:111]
	s_barrier
	v_add_u32_e32 v189, s50, v192
	v_add_u32_e32 v188, s50, v191
	v_add_u32_e32 v187, s50, v190
	ds_read_b128 v[108:111], v189
	ds_read_b128 v[14:17], v187 offset:36864
	ds_read_b128 v[112:115], v189 offset:4608
	ds_read_b128 v[64:67], v187 offset:41472
	ds_read_b128 v[116:119], v189 offset:9216
	ds_read_b128 v[120:123], v188
	v_mfma_f32_32x32x16_bf16 a[80:95], v[76:79], v[80:83], a[80:95]
	v_mfma_f32_32x32x16_bf16 a[112:127], v[76:79], v[84:87], a[112:127]
	v_mfma_f32_32x32x16_bf16 a[16:31], v[104:107], v[80:83], a[16:31]
	v_mfma_f32_32x32x16_bf16 a[0:15], v[104:107], v[84:87], a[0:15]
	s_add_u32 s44, s44, 0x80
	s_addc_u32 s45, s45, 0
	s_cmpk_lg_i32 s44, 0x700
	s_cbranch_scc1 .LBB0_1964
	s_branch xg5_tail_6
xg5_varB_6:
	s_and_b32 s50, s42, 1
	s_mul_i32 s51, s50, 0xd800
	s_xor_b32 s50, s50, 1
	s_mul_i32 s50, s50, 0xd800
	s_add_i32 s42, s42, 1
	v_add_u32_e32 v186, s50, v45
	ds_read_b128 v[68:71], v189 offset:32
	ds_read_b128 v[80:83], v187 offset:36896
	ds_read_b128 v[72:75], v189 offset:4640
	ds_read_b128 v[84:87], v187 offset:41504
	ds_read_b128 v[76:79], v189 offset:9248
	ds_read_b128 v[104:107], v188 offset:32
	s_waitcnt lgkmcnt(10)
	v_mfma_f32_32x32x16_bf16 a[32:47], v[108:111], v[14:17], a[32:47]
	s_waitcnt lgkmcnt(8)
	v_mfma_f32_32x32x16_bf16 a[48:63], v[108:111], v[64:67], a[48:63]
	v_mfma_f32_32x32x16_bf16 a[64:79], v[112:115], v[14:17], a[64:79]
	v_mfma_f32_32x32x16_bf16 a[96:111], v[112:115], v[64:67], a[96:111]
	s_waitcnt lgkmcnt(7)
	v_mfma_f32_32x32x16_bf16 a[80:95], v[116:119], v[14:17], a[80:95]
	v_mfma_f32_32x32x16_bf16 a[112:127], v[116:119], v[64:67], a[112:127]
	s_waitcnt lgkmcnt(6)
	v_mfma_f32_32x32x16_bf16 a[16:31], v[120:123], v[14:17], a[16:31]
	v_mfma_f32_32x32x16_bf16 a[0:15], v[120:123], v[64:67], a[0:15]
	ds_read_b128 v[108:111], v189 offset:64
	ds_read_b128 v[14:17], v187 offset:36928
	ds_read_b128 v[112:115], v189 offset:4672
	ds_read_b128 v[64:67], v187 offset:41536
	ds_read_b128 v[116:119], v189 offset:9280
	ds_read_b128 v[120:123], v188 offset:64
	s_waitcnt lgkmcnt(10)
	v_mfma_f32_32x32x16_bf16 a[32:47], v[68:71], v[80:83], a[32:47]
	s_waitcnt lgkmcnt(8)
	v_mfma_f32_32x32x16_bf16 a[48:63], v[68:71], v[84:87], a[48:63]
	v_mfma_f32_32x32x16_bf16 a[64:79], v[72:75], v[80:83], a[64:79]
	v_mfma_f32_32x32x16_bf16 a[96:111], v[72:75], v[84:87], a[96:111]
	s_waitcnt lgkmcnt(7)
	v_mfma_f32_32x32x16_bf16 a[80:95], v[76:79], v[80:83], a[80:95]
	s_waitcnt vmcnt(11)
	ds_write_b128 v186, v[250:253]
	v_mfma_f32_32x32x16_bf16 a[112:127], v[76:79], v[84:87], a[112:127]
	s_waitcnt vmcnt(10)
	ds_write_b128 v186, v[246:249] offset:4608
	global_load_dwordx4 v[250:253], v254, s[100:101] offset:512
	s_waitcnt lgkmcnt(8)
	v_mfma_f32_32x32x16_bf16 a[16:31], v[104:107], v[80:83], a[16:31]
	s_waitcnt vmcnt(10)
	ds_write_b128 v186, v[242:245] offset:9216
	global_load_dwordx4 v[246:249], v205, s[100:101] offset:512
	v_mfma_f32_32x32x16_bf16 a[0:15], v[104:107], v[84:87], a[0:15]
	s_waitcnt vmcnt(10)
	ds_write_b128 v186, v[238:241] offset:13824
	global_load_dwordx4 v[242:245], v204, s[100:101] offset:512
	ds_read_b128 v[68:71], v189 offset:96
	ds_read_b128 v[80:83], v187 offset:36960
	ds_read_b128 v[72:75], v189 offset:4704
	ds_read_b128 v[84:87], v187 offset:41568
	ds_read_b128 v[76:79], v189 offset:9312
	ds_read_b128 v[104:107], v188 offset:96
	s_waitcnt lgkmcnt(14)
	v_mfma_f32_32x32x16_bf16 a[32:47], v[108:111], v[14:17], a[32:47]
	s_waitcnt vmcnt(10)
	ds_write_b128 v186, v[234:237] offset:18432
	global_load_dwordx4 v[238:241], v203, s[100:101] offset:512
	s_waitcnt lgkmcnt(13)
	v_mfma_f32_32x32x16_bf16 a[48:63], v[108:111], v[64:67], a[48:63]
	s_waitcnt vmcnt(10)
	ds_write_b128 v186, v[230:233] offset:23040
	global_load_dwordx4 v[234:237], v202, s[100:101] offset:512
	v_mfma_f32_32x32x16_bf16 a[64:79], v[112:115], v[14:17], a[64:79]
	s_waitcnt vmcnt(10)
	ds_write_b128 v186, v[226:229] offset:27648
	global_load_dwordx4 v[230:233], v201, s[100:101] offset:512
	v_mfma_f32_32x32x16_bf16 a[96:111], v[112:115], v[64:67], a[96:111]
	s_waitcnt vmcnt(10)
	ds_write_b128 v186, v[222:225] offset:32256
	global_load_dwordx4 v[226:229], v200, s[100:101] offset:512
	s_waitcnt lgkmcnt(15)
	v_mfma_f32_32x32x16_bf16 a[80:95], v[116:119], v[14:17], a[80:95]
	s_waitcnt vmcnt(10)
	ds_write_b128 v186, v[218:221] offset:36864
	global_load_dwordx4 v[222:225], v199, s[100:101] offset:512
	v_mfma_f32_32x32x16_bf16 a[112:127], v[116:119], v[64:67], a[112:127]
	s_waitcnt vmcnt(10)
	ds_write_b128 v186, v[214:217] offset:41472
	global_load_dwordx4 v[218:221], v198, s[98:99] offset:256
	s_waitcnt lgkmcnt(15)
	v_mfma_f32_32x32x16_bf16 a[16:31], v[120:123], v[14:17], a[16:31]
	s_waitcnt vmcnt(10)
	ds_write_b128 v186, v[210:213] offset:46080
	global_load_dwordx4 v[214:217], v197, s[98:99] offset:256
	v_mfma_f32_32x32x16_bf16 a[0:15], v[120:123], v[64:67], a[0:15]
	s_waitcnt vmcnt(10)
	ds_write_b128 v186, v[206:209] offset:50688
	global_load_dwordx4 v[210:213], v196, s[98:99] offset:256
	s_waitcnt lgkmcnt(0)
	v_mfma_f32_32x32x16_bf16 a[32:47], v[68:71], v[80:83], a[32:47]
	global_load_dwordx4 v[206:209], v195, s[98:99] offset:256
	s_add_u32 s100, s100, 0x80
	s_addc_u32 s101, s101, 0
	s_add_u32 s98, s98, 0x80
	s_addc_u32 s99, s99, 0
	v_mfma_f32_32x32x16_bf16 a[48:63], v[68:71], v[84:87], a[48:63]
	v_mfma_f32_32x32x16_bf16 a[64:79], v[72:75], v[80:83], a[64:79]
	v_mfma_f32_32x32x16_bf16 a[96:111], v[72:75], v[84:87], a[96:111]
	s_barrier
	v_add_u32_e32 v189, s50, v192
	v_add_u32_e32 v188, s50, v191
	v_add_u32_e32 v187, s50, v190
	ds_read_b128 v[108:111], v189
	ds_read_b128 v[14:17], v187 offset:36864
	ds_read_b128 v[112:115], v189 offset:4608
	ds_read_b128 v[64:67], v187 offset:41472
	ds_read_b128 v[116:119], v189 offset:9216
	ds_read_b128 v[120:123], v188
	v_mfma_f32_32x32x16_bf16 a[80:95], v[76:79], v[80:83], a[80:95]
	v_mfma_f32_32x32x16_bf16 a[112:127], v[76:79], v[84:87], a[112:127]
	v_mfma_f32_32x32x16_bf16 a[16:31], v[104:107], v[80:83], a[16:31]
	v_mfma_f32_32x32x16_bf16 a[0:15], v[104:107], v[84:87], a[0:15]
	s_add_u32 s44, s44, 0x80
	s_addc_u32 s45, s45, 0
	s_cmpk_lg_i32 s44, 0x700
	s_cbranch_scc1 xg5_varB_6
xg5_tail_6:
	ds_read_b128 v[10:13], v60
	ds_read_b128 v[108:111], v62 offset:36864
	ds_read_b128 v[112:115], v60 offset:4608
	ds_read_b128 v[116:119], v62 offset:41472
	s_lshl_b32 s44, s48, 8
	s_lshl_b32 s42, s49, 8
	s_waitcnt lgkmcnt(2)
	v_mfma_f32_32x32x16_bf16 a[176:191], v[10:13], v[108:111], a[32:47]
	s_add_i32 s47, s47, s77
	s_add_i32 s46, s46, s77
	s_waitcnt lgkmcnt(0)
	v_mfma_f32_32x32x16_bf16 a[160:175], v[10:13], v[116:119], a[48:63]
	v_mfma_f32_32x32x16_bf16 a[144:159], v[112:115], v[108:111], a[64:79]
	v_mfma_f32_32x32x16_bf16 a[128:143], v[112:115], v[116:119], a[96:111]
	ds_read_b128 v[10:13], v60 offset:9216
	ds_read_b128 v[112:115], v61
	s_waitcnt vmcnt(11)
	s_waitcnt vmcnt(0)
	ds_write_b128 v63, v[250:253] offset:55296
	s_waitcnt vmcnt(10)
	ds_write_b128 v63, v[246:249] offset:59904
	s_waitcnt vmcnt(9)
	ds_write_b128 v63, v[242:245] offset:64512
	s_waitcnt vmcnt(8)
	ds_write_b128 v50, v[238:241] offset:55296
	s_waitcnt vmcnt(7)
	ds_write_b128 v51, v[234:237] offset:55296
	s_waitcnt vmcnt(6)
	ds_write_b128 v52, v[230:233] offset:55296
	s_waitcnt vmcnt(5)
	ds_write_b128 v53, v[226:229] offset:55296
	s_waitcnt vmcnt(4)
	ds_write_b128 v54, v[222:225] offset:55296
	s_waitcnt vmcnt(3)
	ds_write_b128 v55, v[218:221]
	s_waitcnt vmcnt(2)
	ds_write_b128 v55, v[214:217] offset:4608
	s_waitcnt vmcnt(1)
	ds_write_b128 v55, v[210:213] offset:9216
	s_waitcnt vmcnt(0)
	ds_write_b128 v55, v[206:209] offset:13824
	s_waitcnt lgkmcnt(13)
	v_mfma_f32_32x32x16_bf16 a[64:79], v[10:13], v[108:111], a[80:95]
	v_mfma_f32_32x32x16_bf16 a[48:63], v[10:13], v[116:119], a[112:127]
	ds_read_b128 v[10:13], v60 offset:32
	ds_read_b128 v[14:17], v62 offset:36896
	ds_read_b128 v[64:67], v62 offset:36928
	ds_read_b128 v[68:71], v60 offset:64
	ds_read_b128 v[72:75], v62 offset:41504
	ds_read_b128 v[76:79], v62 offset:36960
	s_waitcnt lgkmcnt(4)
	v_mfma_f32_32x32x16_bf16 a[176:191], v[10:13], v[14:17], a[176:191]
	s_waitcnt lgkmcnt(1)
	v_mfma_f32_32x32x16_bf16 a[160:175], v[10:13], v[72:75], a[160:175]
	ds_read_b128 v[10:13], v60 offset:4640
	ds_read_b128 v[80:83], v60 offset:96
	v_mfma_f32_32x32x16_bf16 a[32:47], v[112:115], v[108:111], a[16:31]
	v_mfma_f32_32x32x16_bf16 a[16:31], v[112:115], v[116:119], a[0:15]
	s_waitcnt lgkmcnt(1)
	v_mfma_f32_32x32x16_bf16 a[144:159], v[10:13], v[14:17], a[144:159]
	v_mfma_f32_32x32x16_bf16 a[128:143], v[10:13], v[72:75], a[128:143]
	ds_read_b128 v[10:13], v60 offset:9248
	ds_read_b128 v[84:87], v60 offset:9280
	s_waitcnt lgkmcnt(1)
	v_mfma_f32_32x32x16_bf16 a[64:79], v[10:13], v[14:17], a[64:79]
	v_mfma_f32_32x32x16_bf16 a[48:63], v[10:13], v[72:75], a[48:63]
	ds_read_b128 v[10:13], v61 offset:32
	ds_read_b128 v[88:91], v60 offset:9312
	s_waitcnt lgkmcnt(1)
	v_mfma_f32_32x32x16_bf16 a[32:47], v[10:13], v[14:17], a[32:47]
	v_mfma_f32_32x32x16_bf16 a[16:31], v[10:13], v[72:75], a[16:31]
	ds_read_b128 v[10:13], v62 offset:41536
	ds_read_b128 v[14:17], v62 offset:41568
	v_mfma_f32_32x32x16_bf16 a[176:191], v[68:71], v[64:67], a[176:191]
	s_waitcnt lgkmcnt(1)
	v_mfma_f32_32x32x16_bf16 a[160:175], v[68:71], v[10:13], a[160:175]
	ds_read_b128 v[68:71], v60 offset:4672
	ds_read_b128 v[72:75], v60 offset:4704
	s_waitcnt lgkmcnt(1)
	v_mfma_f32_32x32x16_bf16 a[144:159], v[68:71], v[64:67], a[144:159]
	v_mfma_f32_32x32x16_bf16 a[128:143], v[68:71], v[10:13], a[128:143]
	v_mfma_f32_32x32x16_bf16 a[64:79], v[84:87], v[64:67], a[64:79]
	v_mfma_f32_32x32x16_bf16 a[48:63], v[84:87], v[10:13], a[48:63]
	ds_read_b128 v[68:71], v61 offset:64
	ds_read_b128 v[84:87], v61 offset:96
	s_waitcnt lgkmcnt(0)
	s_barrier
	v_mfma_f32_32x32x16_bf16 a[32:47], v[68:71], v[64:67], a[32:47]
	v_mfma_f32_32x32x16_bf16 a[16:31], v[68:71], v[10:13], a[16:31]
	v_mfma_f32_32x32x16_bf16 a[176:191], v[80:83], v[76:79], a[176:191]
	v_mfma_f32_32x32x16_bf16 a[160:175], v[80:83], v[14:17], a[160:175]
	v_mfma_f32_32x32x16_bf16 a[144:159], v[72:75], v[76:79], a[144:159]
	v_mfma_f32_32x32x16_bf16 a[128:143], v[72:75], v[14:17], a[128:143]
	v_mfma_f32_32x32x16_bf16 a[64:79], v[88:91], v[76:79], a[64:79]
	v_mfma_f32_32x32x16_bf16 a[48:63], v[88:91], v[14:17], a[48:63]
	v_mfma_f32_32x32x16_bf16 a[32:47], v[84:87], v[76:79], a[32:47]
	v_mfma_f32_32x32x16_bf16 a[16:31], v[84:87], v[14:17], a[16:31]
	ds_read_b128 v[10:13], v60 offset:55296
	ds_read_b128 v[14:17], v56
	ds_read_b128 v[64:67], v60 offset:55328
	ds_read_b128 v[68:71], v56 offset:32
	ds_read_b128 v[72:75], v56 offset:4608
	ds_read_b128 v[76:79], v56 offset:4640
	s_waitcnt lgkmcnt(4)
	v_mfma_f32_32x32x16_bf16 a[176:191], v[10:13], v[14:17], a[176:191]
	s_waitcnt lgkmcnt(1)
	v_mfma_f32_32x32x16_bf16 a[160:175], v[10:13], v[72:75], a[160:175]
	ds_read_b128 v[10:13], v60 offset:59904
	ds_read_b128 v[80:83], v60 offset:59936
	s_waitcnt lgkmcnt(1)
	v_mfma_f32_32x32x16_bf16 a[144:159], v[10:13], v[14:17], a[144:159]
	v_mfma_f32_32x32x16_bf16 a[128:143], v[10:13], v[72:75], a[128:143]
	ds_read_b128 v[10:13], v60 offset:64512
	ds_read_b128 v[84:87], v60 offset:64544
	s_waitcnt lgkmcnt(1)
	v_mfma_f32_32x32x16_bf16 a[64:79], v[10:13], v[14:17], a[64:79]
	v_mfma_f32_32x32x16_bf16 a[48:63], v[10:13], v[72:75], a[48:63]
	ds_read_b128 v[10:13], v61 offset:55296
	ds_read_b128 v[88:91], v61 offset:55328
	s_waitcnt lgkmcnt(1)
	v_mfma_f32_32x32x16_bf16 a[32:47], v[10:13], v[14:17], a[32:47]
	v_mfma_f32_32x32x16_bf16 a[16:31], v[10:13], v[72:75], a[16:31]
	ds_read_b128 v[10:13], v60 offset:55360
	v_mfma_f32_32x32x16_bf16 a[176:191], v[64:67], v[68:71], a[176:191]
	v_mfma_f32_32x32x16_bf16 a[160:175], v[64:67], v[76:79], a[160:175]
	v_mfma_f32_32x32x16_bf16 a[144:159], v[80:83], v[68:71], a[144:159]
	v_mfma_f32_32x32x16_bf16 a[128:143], v[80:83], v[76:79], a[128:143]
	v_mfma_f32_32x32x16_bf16 a[64:79], v[84:87], v[68:71], a[64:79]
	v_mfma_f32_32x32x16_bf16 a[48:63], v[84:87], v[76:79], a[48:63]
	ds_read_b128 v[14:17], v56 offset:64
	ds_read_b128 v[64:67], v61 offset:55360
	ds_read_b128 v[72:75], v61 offset:55392
	ds_read_b128 v[80:83], v60 offset:64576
	ds_read_b128 v[84:87], v60 offset:64608
	ds_read_b128 v[92:95], v60 offset:55392
	ds_read_b128 v[96:99], v56 offset:96
	ds_read_b128 v[100:103], v60 offset:59968
	ds_read_b128 v[104:107], v60 offset:60000
	ds_read_b128 v[108:111], v56 offset:4672
	ds_read_b128 v[112:115], v56 offset:4704
	s_waitcnt lgkmcnt(0)
	s_barrier
	v_mfma_f32_32x32x16_bf16 a[32:47], v[88:91], v[68:71], a[32:47]
	v_add_u32_e32 v70, 0x2048, v21
	v_mfma_f32_32x32x16_bf16 a[16:31], v[88:91], v[76:79], a[16:31]
	v_mfma_f32_32x32x16_bf16 a[176:191], v[10:13], v[14:17], a[176:191]
	v_mfma_f32_32x32x16_bf16 a[160:175], v[10:13], v[108:111], a[160:175]
	v_lshl_add_u64 v[10:11], v[6:7], 0, s[42:43]
	v_mfma_f32_32x32x16_bf16 a[144:159], v[100:103], v[14:17], a[144:159]
	v_mfma_f32_32x32x16_bf16 a[128:143], v[100:103], v[108:111], a[128:143]
	v_mfma_f32_32x32x16_bf16 a[64:79], v[80:83], v[14:17], a[64:79]
	v_mfma_f32_32x32x16_bf16 a[48:63], v[80:83], v[108:111], a[48:63]
	v_mfma_f32_32x32x16_bf16 a[32:47], v[64:67], v[14:17], a[32:47]
	v_mfma_f32_32x32x16_bf16 a[16:31], v[64:67], v[108:111], a[16:31]
	v_add_u32_e32 v66, 0x1028, v21
	v_mfma_f32_32x32x16_bf16 a[176:191], v[92:95], v[96:99], a[176:191]
	s_nop 11
	ds_write_b32 v49, a176
	ds_write_b32 v49, a177 offset:516
	ds_write_b32 v49, a178 offset:1032
	ds_write_b32 v49, a179 offset:1548
	ds_write_b32 v49, a180 offset:4128
	ds_write_b32 v49, a181 offset:4644
	ds_write_b32 v49, a182 offset:5160
	v_mfma_f32_32x32x16_bf16 a[160:175], v[92:95], v[112:115], a[160:175]
	ds_write_b32 v49, a183 offset:5676
	ds_write_b32 v49, a184 offset:8256
	ds_write_b32 v49, a185 offset:8772
	ds_write_b32 v49, a186 offset:9288
	ds_write_b32 v49, a187 offset:9804
	ds_write_b32 v49, a188 offset:12384
	ds_write_b32 v49, a189 offset:12900
	ds_write_b32 v49, a190 offset:13416
	ds_write_b32 v49, a191 offset:13932
	s_nop 2
	ds_write_b32 v49, a160 offset:128
	ds_write_b32 v49, a161 offset:644
	ds_write_b32 v49, a162 offset:1160
	ds_write_b32 v49, a163 offset:1676
	ds_write_b32 v49, a164 offset:4256
	ds_write_b32 v49, a165 offset:4772
	ds_write_b32 v49, a166 offset:5288
	ds_write_b32 v49, a167 offset:5804
	ds_write_b32 v49, a168 offset:8384
	ds_write_b32 v49, a169 offset:8900
	ds_write_b32 v49, a170 offset:9416
	ds_write_b32 v49, a171 offset:9932
	v_mfma_f32_32x32x16_bf16 a[144:159], v[104:107], v[96:99], a[144:159]
	ds_write_b32 v49, a172 offset:12512
	ds_write_b32 v49, a173 offset:13028
	ds_write_b32 v49, a174 offset:13544
	ds_write_b32 v49, a175 offset:14060
	s_nop 7
	ds_write_b32 v49, a144 offset:16512
	ds_write_b32 v49, a145 offset:17028
	ds_write_b32 v49, a146 offset:17544
	ds_write_b32 v49, a147 offset:18060
	ds_write_b32 v49, a148 offset:20640
	ds_write_b32 v49, a149 offset:21156
	ds_write_b32 v49, a150 offset:21672
	ds_write_b32 v49, a151 offset:22188
	ds_write_b32 v49, a152 offset:24768
	ds_write_b32 v49, a153 offset:25284
	v_mfma_f32_32x32x16_bf16 a[128:143], v[104:107], v[112:115], a[128:143]
	ds_write_b32 v49, a154 offset:25800
	ds_write_b32 v49, a155 offset:26316
	ds_write_b32 v49, a156 offset:28896
	ds_write_b32 v49, a157 offset:29412
	ds_write_b32 v49, a158 offset:29928
	ds_write_b32 v49, a159 offset:30444
	s_nop 5
	ds_write_b32 v49, a128 offset:16640
	ds_write_b32 v49, a129 offset:17156
	ds_write_b32 v49, a130 offset:17672
	ds_write_b32 v49, a131 offset:18188
	ds_write_b32 v49, a132 offset:20768
	ds_write_b32 v49, a133 offset:21284
	ds_write_b32 v49, a134 offset:21800
	ds_write_b32 v49, a135 offset:22316
	v_mfma_f32_32x32x16_bf16 a[64:79], v[84:87], v[96:99], a[64:79]
	ds_write_b32 v49, a136 offset:24896
	ds_write_b32 v49, a137 offset:25412
	ds_write_b32 v49, a138 offset:25928
	ds_write_b32 v49, a139 offset:26444
	ds_write_b32 v49, a140 offset:29024
	ds_write_b32 v49, a141 offset:29540
	ds_write_b32 v49, a142 offset:30056
	ds_write_b32 v49, a143 offset:30572
	s_nop 3
	ds_write_b32 v49, a64 offset:33024
	ds_write_b32 v49, a65 offset:33540
	ds_write_b32 v49, a66 offset:34056
	ds_write_b32 v49, a67 offset:34572
	ds_write_b32 v49, a68 offset:37152
	ds_write_b32 v49, a69 offset:37668
	v_mfma_f32_32x32x16_bf16 a[48:63], v[84:87], v[112:115], a[48:63]
	ds_write_b32 v49, a70 offset:38184
	ds_write_b32 v49, a71 offset:38700
	ds_write_b32 v49, a72 offset:41280
	ds_write_b32 v49, a73 offset:41796
	ds_write_b32 v49, a74 offset:42312
	ds_write_b32 v49, a75 offset:42828
	ds_write_b32 v49, a76 offset:45408
	ds_write_b32 v49, a77 offset:45924
	ds_write_b32 v49, a78 offset:46440
	ds_write_b32 v49, a79 offset:46956
	s_nop 1
	ds_write_b32 v49, a48 offset:33152
	ds_write_b32 v49, a49 offset:33668
	ds_write_b32 v49, a50 offset:34184
	ds_write_b32 v49, a51 offset:34700
	ds_write_b32 v49, a52 offset:37280
	ds_write_b32 v49, a53 offset:37796
	ds_write_b32 v49, a54 offset:38312
	ds_write_b32 v49, a55 offset:38828
	ds_write_b32 v49, a56 offset:41408
	ds_write_b32 v49, a57 offset:41924
	ds_write_b32 v49, a58 offset:42440
	v_mfma_f32_32x32x16_bf16 a[32:47], v[72:75], v[96:99], a[32:47]
	ds_write_b32 v49, a59 offset:42956
	ds_write_b32 v49, a60 offset:45536
	ds_write_b32 v49, a61 offset:46052
	ds_write_b32 v49, a62 offset:46568
	ds_write_b32 v49, a63 offset:47084
	s_nop 6
	ds_write_b32 v49, a32 offset:49536
	ds_write_b32 v49, a33 offset:50052
	ds_write_b32 v49, a34 offset:50568
	ds_write_b32 v49, a35 offset:51084
	ds_write_b32 v49, a36 offset:53664
	ds_write_b32 v49, a37 offset:54180
	ds_write_b32 v49, a38 offset:54696
	ds_write_b32 v49, a39 offset:55212
	ds_write_b32 v49, a40 offset:57792
	v_mfma_f32_32x32x16_bf16 a[16:31], v[72:75], v[112:115], a[16:31]
	ds_write_b32 v49, a41 offset:58308
	ds_write_b32 v49, a42 offset:58824
	ds_write_b32 v49, a43 offset:59340
	ds_write_b32 v49, a44 offset:61920
	ds_write_b32 v49, a45 offset:62436
	ds_write_b32 v49, a46 offset:62952
	ds_write_b32 v49, a47 offset:63468
	s_nop 4
	ds_write_b32 v49, a16 offset:49664
	ds_write_b32 v49, a17 offset:50180
	ds_write_b32 v49, a18 offset:50696
	ds_write_b32 v49, a19 offset:51212
	ds_write_b32 v49, a20 offset:53792
	ds_write_b32 v49, a21 offset:54308
	ds_write_b32 v49, a22 offset:54824
	ds_write_b32 v49, a23 offset:55340
	ds_write_b32 v49, a24 offset:57920
	ds_write_b32 v49, a25 offset:58436
	ds_write_b32 v49, a26 offset:58952
	ds_write_b32 v49, a27 offset:59468
	ds_write_b32 v49, a28 offset:62048
	ds_write_b32 v49, a29 offset:62564
	ds_write_b32 v49, a30 offset:63080
	ds_write_b32 v49, a31 offset:63596
	s_waitcnt lgkmcnt(0)
	s_barrier
	ds_read2_b32 v[16:17], v21 offset1:1
	ds_read2_b32 v[18:19], v21 offset0:2 offset1:3
	v_accvgpr_read_b32 v72, a218
	v_or_b32_e32 v0, s44, v72
	v_lshlrev_b32_e32 v0, 11, v0
	s_waitcnt lgkmcnt(1)
	v_cvt_pk_bf16_f32 v16, v16, v17
	s_waitcnt lgkmcnt(0)
	v_cvt_pk_bf16_f32 v17, v18, v19
	v_lshl_add_u64 v[18:19], v[10:11], 0, v[0:1]
	v_add_u32_e32 v0, 0x1020, v21
	ds_read2_b32 v[12:13], v29 offset1:1
	ds_read2_b32 v[14:15], v29 offset0:2 offset1:3
	ds_read2_b32 v[64:65], v0 offset1:1
	ds_read2_b32 v[66:67], v66 offset1:1
	v_accvgpr_read_b32 v73, a219
	v_or_b32_e32 v0, s44, v73
	v_lshlrev_b32_e32 v0, 11, v0
	global_store_dwordx2 v[18:19], v[16:17], off
	s_waitcnt lgkmcnt(1)
	v_cvt_pk_bf16_f32 v64, v64, v65
	s_waitcnt lgkmcnt(0)
	v_cvt_pk_bf16_f32 v65, v66, v67
	v_lshl_add_u64 v[66:67], v[10:11], 0, v[0:1]
	v_add_u32_e32 v0, 0x2040, v21
	ds_read2_b32 v[16:17], v44 offset1:1
	ds_read2_b32 v[18:19], v44 offset0:2 offset1:3
	ds_read2_b32 v[68:69], v0 offset1:1
	ds_read2_b32 v[70:71], v70 offset1:1
	global_store_dwordx2 v[66:67], v[64:65], off
	v_add_u32_e32 v0, 0x3060, v21
	v_add_u32_e32 v66, 0x3068, v21
	ds_read2_b32 v[64:65], v0 offset1:1
	ds_read2_b32 v[66:67], v66 offset1:1
	v_or_b32_e32 v0, s44, v132
	v_lshlrev_b32_e32 v0, 11, v0
	s_waitcnt lgkmcnt(3)
	v_cvt_pk_bf16_f32 v68, v68, v69
	s_waitcnt lgkmcnt(2)
	v_cvt_pk_bf16_f32 v69, v70, v71
	v_lshl_add_u64 v[70:71], v[10:11], 0, v[0:1]
	v_or_b32_e32 v0, s44, v133
	v_lshlrev_b32_e32 v0, 11, v0
	global_store_dwordx2 v[70:71], v[68:69], off
	s_waitcnt lgkmcnt(1)
	v_cvt_pk_bf16_f32 v64, v64, v65
	s_waitcnt lgkmcnt(0)
	v_cvt_pk_bf16_f32 v65, v66, v67
	v_lshl_add_u64 v[66:67], v[10:11], 0, v[0:1]
	v_add_u32_e32 v0, 0x4080, v21
	v_add_u32_e32 v70, 0x4088, v21
	ds_read2_b32 v[68:69], v0 offset1:1
	ds_read2_b32 v[70:71], v70 offset1:1
	global_store_dwordx2 v[66:67], v[64:65], off
	v_add_u32_e32 v0, 0x50a0, v21
	v_add_u32_e32 v66, 0x50a8, v21
	ds_read2_b32 v[64:65], v0 offset1:1
	ds_read2_b32 v[66:67], v66 offset1:1
	v_or_b32_e32 v0, s44, v136
	v_lshlrev_b32_e32 v0, 11, v0
	s_waitcnt lgkmcnt(3)
	v_cvt_pk_bf16_f32 v68, v68, v69
	s_waitcnt lgkmcnt(2)
	v_cvt_pk_bf16_f32 v69, v70, v71
	v_lshl_add_u64 v[70:71], v[10:11], 0, v[0:1]
	v_or_b32_e32 v0, s44, v137
	v_lshlrev_b32_e32 v0, 11, v0
	global_store_dwordx2 v[70:71], v[68:69], off
	s_waitcnt lgkmcnt(1)
	v_cvt_pk_bf16_f32 v64, v64, v65
	s_waitcnt lgkmcnt(0)
	v_cvt_pk_bf16_f32 v65, v66, v67
	v_lshl_add_u64 v[66:67], v[10:11], 0, v[0:1]
	v_add_u32_e32 v0, 0x60c0, v21
	v_add_u32_e32 v70, 0x60c8, v21
	ds_read2_b32 v[68:69], v0 offset1:1
	ds_read2_b32 v[70:71], v70 offset1:1
	global_store_dwordx2 v[66:67], v[64:65], off
	v_add_u32_e32 v0, 0x70e0, v21
	v_add_u32_e32 v66, 0x70e8, v21
	ds_read2_b32 v[64:65], v0 offset1:1
	ds_read2_b32 v[66:67], v66 offset1:1
	v_or_b32_e32 v0, s44, v139
	v_lshlrev_b32_e32 v0, 11, v0
	v_accvgpr_read_b32 v74, a225
	s_waitcnt lgkmcnt(3)
	v_cvt_pk_bf16_f32 v68, v68, v69
	s_waitcnt lgkmcnt(2)
	v_cvt_pk_bf16_f32 v69, v70, v71
	v_lshl_add_u64 v[70:71], v[10:11], 0, v[0:1]
	v_or_b32_e32 v0, s44, v74
	v_lshlrev_b32_e32 v0, 11, v0
	global_store_dwordx2 v[70:71], v[68:69], off
	s_waitcnt lgkmcnt(1)
	v_cvt_pk_bf16_f32 v64, v64, v65
	s_waitcnt lgkmcnt(0)
	v_cvt_pk_bf16_f32 v65, v66, v67
	v_lshl_add_u64 v[66:67], v[10:11], 0, v[0:1]
	v_add_u32_e32 v0, 0x8100, v21
	v_add_u32_e32 v70, 0x8108, v21
	ds_read2_b32 v[68:69], v0 offset1:1
	ds_read2_b32 v[70:71], v70 offset1:1
	global_store_dwordx2 v[66:67], v[64:65], off
	v_add_u32_e32 v0, 0x9120, v21
	v_add_u32_e32 v66, 0x9128, v21
	ds_read2_b32 v[64:65], v0 offset1:1
	ds_read2_b32 v[66:67], v66 offset1:1
	v_accvgpr_read_b32 v75, a226
	v_or_b32_e32 v0, s44, v75
	v_lshlrev_b32_e32 v0, 11, v0
	s_waitcnt lgkmcnt(3)
	v_cvt_pk_bf16_f32 v68, v68, v69
	s_waitcnt lgkmcnt(2)
	v_cvt_pk_bf16_f32 v69, v70, v71
	v_lshl_add_u64 v[70:71], v[10:11], 0, v[0:1]
	v_or_b32_e32 v0, s44, v22
	v_lshlrev_b32_e32 v0, 11, v0
	global_store_dwordx2 v[70:71], v[68:69], off
	s_waitcnt lgkmcnt(1)
	v_cvt_pk_bf16_f32 v64, v64, v65
	s_waitcnt lgkmcnt(0)
	v_cvt_pk_bf16_f32 v65, v66, v67
	v_lshl_add_u64 v[66:67], v[10:11], 0, v[0:1]
	v_add_u32_e32 v0, 0xa140, v21
	v_add_u32_e32 v70, 0xa148, v21
	ds_read2_b32 v[68:69], v0 offset1:1
	ds_read2_b32 v[70:71], v70 offset1:1
	global_store_dwordx2 v[66:67], v[64:65], off
	v_add_u32_e32 v0, 0xb160, v21
	v_add_u32_e32 v66, 0xb168, v21
	ds_read2_b32 v[64:65], v0 offset1:1
	ds_read2_b32 v[66:67], v66 offset1:1
	v_or_b32_e32 v0, s44, v23
	v_lshlrev_b32_e32 v0, 11, v0
	s_waitcnt lgkmcnt(3)
	v_cvt_pk_bf16_f32 v68, v68, v69
	s_waitcnt lgkmcnt(2)
	v_cvt_pk_bf16_f32 v69, v70, v71
	v_lshl_add_u64 v[70:71], v[10:11], 0, v[0:1]
	v_or_b32_e32 v0, s44, v24
	v_lshlrev_b32_e32 v0, 11, v0
	global_store_dwordx2 v[70:71], v[68:69], off
	s_waitcnt lgkmcnt(1)
	v_cvt_pk_bf16_f32 v64, v64, v65
	s_waitcnt lgkmcnt(0)
	v_cvt_pk_bf16_f32 v65, v66, v67
	v_lshl_add_u64 v[66:67], v[10:11], 0, v[0:1]
	v_add_u32_e32 v0, 0xc180, v21
	v_add_u32_e32 v70, 0xc188, v21
	ds_read2_b32 v[68:69], v0 offset1:1
	ds_read2_b32 v[70:71], v70 offset1:1
	global_store_dwordx2 v[66:67], v[64:65], off
	v_add_u32_e32 v0, 0xd1a0, v21
	v_add_u32_e32 v66, 0xd1a8, v21
	ds_read2_b32 v[64:65], v0 offset1:1
	ds_read2_b32 v[66:67], v66 offset1:1
	v_or_b32_e32 v0, s44, v25
	v_lshlrev_b32_e32 v0, 11, v0
	s_waitcnt lgkmcnt(3)
	v_cvt_pk_bf16_f32 v68, v68, v69
	s_waitcnt lgkmcnt(2)
	v_cvt_pk_bf16_f32 v69, v70, v71
	v_lshl_add_u64 v[70:71], v[10:11], 0, v[0:1]
	v_or_b32_e32 v0, s44, v26
	v_lshlrev_b32_e32 v0, 11, v0
	global_store_dwordx2 v[70:71], v[68:69], off
	s_waitcnt lgkmcnt(1)
	v_cvt_pk_bf16_f32 v64, v64, v65
	s_waitcnt lgkmcnt(0)
	v_cvt_pk_bf16_f32 v65, v66, v67
	v_lshl_add_u64 v[66:67], v[10:11], 0, v[0:1]
	v_add_u32_e32 v0, 0xe1c0, v21
	v_add_u32_e32 v70, 0xe1c8, v21
	ds_read2_b32 v[68:69], v0 offset1:1
	ds_read2_b32 v[70:71], v70 offset1:1
	global_store_dwordx2 v[66:67], v[64:65], off
	v_add_u32_e32 v0, 0xf1e0, v21
	v_add_u32_e32 v66, 0xf1e8, v21
	ds_read2_b32 v[64:65], v0 offset1:1
	ds_read2_b32 v[66:67], v66 offset1:1
	v_or_b32_e32 v0, s44, v27
	v_lshlrev_b32_e32 v0, 11, v0
	s_waitcnt lgkmcnt(3)
	v_cvt_pk_bf16_f32 v68, v68, v69
	s_waitcnt lgkmcnt(2)
	v_cvt_pk_bf16_f32 v69, v70, v71
	v_lshl_add_u64 v[70:71], v[10:11], 0, v[0:1]
	v_or_b32_e32 v0, s44, v28
	v_lshlrev_b32_e32 v0, 11, v0
	s_bitset1_b32 s44, 7
	s_waitcnt lgkmcnt(1)
	v_cvt_pk_bf16_f32 v64, v64, v65
	s_waitcnt lgkmcnt(0)
	v_cvt_pk_bf16_f32 v65, v66, v67
	v_lshl_add_u64 v[66:67], v[10:11], 0, v[0:1]
	v_or_b32_e32 v0, s44, v72
	global_store_dwordx2 v[70:71], v[68:69], off
	global_store_dwordx2 v[66:67], v[64:65], off
	v_lshlrev_b32_e32 v0, 11, v0
	v_cvt_pk_bf16_f32 v12, v12, v13
	v_cvt_pk_bf16_f32 v13, v14, v15
	v_lshl_add_u64 v[14:15], v[10:11], 0, v[0:1]
	ds_read2_b32 v[64:65], v30 offset1:1
	ds_read2_b32 v[66:67], v30 offset0:2 offset1:3
	global_store_dwordx2 v[14:15], v[12:13], off
	ds_read2_b32 v[12:13], v31 offset1:1
	ds_read2_b32 v[14:15], v31 offset0:2 offset1:3
	v_or_b32_e32 v0, s44, v73
	v_lshlrev_b32_e32 v0, 11, v0
	s_waitcnt lgkmcnt(3)
	v_cvt_pk_bf16_f32 v64, v64, v65
	s_waitcnt lgkmcnt(2)
	v_cvt_pk_bf16_f32 v65, v66, v67
	v_lshl_add_u64 v[66:67], v[10:11], 0, v[0:1]
	v_or_b32_e32 v0, s44, v132
	global_store_dwordx2 v[66:67], v[64:65], off
	v_lshlrev_b32_e32 v0, 11, v0
	s_waitcnt lgkmcnt(1)
	v_cvt_pk_bf16_f32 v12, v12, v13
	s_waitcnt lgkmcnt(0)
	v_cvt_pk_bf16_f32 v13, v14, v15
	v_lshl_add_u64 v[14:15], v[10:11], 0, v[0:1]
	ds_read2_b32 v[64:65], v32 offset1:1
	ds_read2_b32 v[66:67], v32 offset0:2 offset1:3
	global_store_dwordx2 v[14:15], v[12:13], off
	ds_read2_b32 v[12:13], v33 offset1:1
	ds_read2_b32 v[14:15], v33 offset0:2 offset1:3
	v_or_b32_e32 v0, s44, v133
	v_lshlrev_b32_e32 v0, 11, v0
	s_waitcnt lgkmcnt(3)
	v_cvt_pk_bf16_f32 v64, v64, v65
	s_waitcnt lgkmcnt(2)
	v_cvt_pk_bf16_f32 v65, v66, v67
	v_lshl_add_u64 v[66:67], v[10:11], 0, v[0:1]
	v_or_b32_e32 v0, s44, v136
	global_store_dwordx2 v[66:67], v[64:65], off
	v_lshlrev_b32_e32 v0, 11, v0
	s_waitcnt lgkmcnt(1)
	v_cvt_pk_bf16_f32 v12, v12, v13
	s_waitcnt lgkmcnt(0)
	v_cvt_pk_bf16_f32 v13, v14, v15
	v_lshl_add_u64 v[14:15], v[10:11], 0, v[0:1]
	ds_read2_b32 v[64:65], v34 offset1:1
	ds_read2_b32 v[66:67], v34 offset0:2 offset1:3
	global_store_dwordx2 v[14:15], v[12:13], off
	ds_read2_b32 v[12:13], v35 offset1:1
	ds_read2_b32 v[14:15], v35 offset0:2 offset1:3
	v_or_b32_e32 v0, s44, v137
	v_lshlrev_b32_e32 v0, 11, v0
	s_waitcnt lgkmcnt(3)
	v_cvt_pk_bf16_f32 v64, v64, v65
	s_waitcnt lgkmcnt(2)
	v_cvt_pk_bf16_f32 v65, v66, v67
	v_lshl_add_u64 v[66:67], v[10:11], 0, v[0:1]
	v_or_b32_e32 v0, s44, v139
	global_store_dwordx2 v[66:67], v[64:65], off
	v_lshlrev_b32_e32 v0, 11, v0
	s_waitcnt lgkmcnt(1)
	v_cvt_pk_bf16_f32 v12, v12, v13
	s_waitcnt lgkmcnt(0)
	v_cvt_pk_bf16_f32 v13, v14, v15
	v_lshl_add_u64 v[14:15], v[10:11], 0, v[0:1]
	ds_read2_b32 v[64:65], v36 offset1:1
	ds_read2_b32 v[66:67], v36 offset0:2 offset1:3
	global_store_dwordx2 v[14:15], v[12:13], off
	ds_read2_b32 v[12:13], v37 offset1:1
	ds_read2_b32 v[14:15], v37 offset0:2 offset1:3
	v_or_b32_e32 v0, s44, v74
	v_lshlrev_b32_e32 v0, 11, v0
	s_waitcnt lgkmcnt(3)
	v_cvt_pk_bf16_f32 v64, v64, v65
	s_waitcnt lgkmcnt(2)
	v_cvt_pk_bf16_f32 v65, v66, v67
	v_lshl_add_u64 v[66:67], v[10:11], 0, v[0:1]
	v_or_b32_e32 v0, s44, v75
	global_store_dwordx2 v[66:67], v[64:65], off
	v_lshlrev_b32_e32 v0, 11, v0
	s_waitcnt lgkmcnt(1)
	v_cvt_pk_bf16_f32 v12, v12, v13
	s_waitcnt lgkmcnt(0)
	v_cvt_pk_bf16_f32 v13, v14, v15
	v_lshl_add_u64 v[14:15], v[10:11], 0, v[0:1]
	ds_read2_b32 v[64:65], v38 offset1:1
	ds_read2_b32 v[66:67], v38 offset0:2 offset1:3
	global_store_dwordx2 v[14:15], v[12:13], off
	ds_read2_b32 v[12:13], v39 offset1:1
	ds_read2_b32 v[14:15], v39 offset0:2 offset1:3
	v_or_b32_e32 v0, s44, v22
	v_lshlrev_b32_e32 v0, 11, v0
	s_waitcnt lgkmcnt(3)
	v_cvt_pk_bf16_f32 v64, v64, v65
	s_waitcnt lgkmcnt(2)
	v_cvt_pk_bf16_f32 v65, v66, v67
	v_lshl_add_u64 v[66:67], v[10:11], 0, v[0:1]
	v_or_b32_e32 v0, s44, v23
	global_store_dwordx2 v[66:67], v[64:65], off
	v_lshlrev_b32_e32 v0, 11, v0
	s_waitcnt lgkmcnt(1)
	v_cvt_pk_bf16_f32 v12, v12, v13
	s_waitcnt lgkmcnt(0)
	v_cvt_pk_bf16_f32 v13, v14, v15
	v_lshl_add_u64 v[14:15], v[10:11], 0, v[0:1]
	ds_read2_b32 v[64:65], v40 offset1:1
	ds_read2_b32 v[66:67], v40 offset0:2 offset1:3
	global_store_dwordx2 v[14:15], v[12:13], off
	ds_read2_b32 v[12:13], v41 offset1:1
	ds_read2_b32 v[14:15], v41 offset0:2 offset1:3
	v_or_b32_e32 v0, s44, v24
	v_lshlrev_b32_e32 v0, 11, v0
	s_waitcnt lgkmcnt(3)
	v_cvt_pk_bf16_f32 v64, v64, v65
	s_waitcnt lgkmcnt(2)
	v_cvt_pk_bf16_f32 v65, v66, v67
	v_lshl_add_u64 v[66:67], v[10:11], 0, v[0:1]
	v_or_b32_e32 v0, s44, v25
	v_lshlrev_b32_e32 v0, 11, v0
	global_store_dwordx2 v[66:67], v[64:65], off
	s_waitcnt lgkmcnt(1)
	v_cvt_pk_bf16_f32 v12, v12, v13
	s_waitcnt lgkmcnt(0)
	v_cvt_pk_bf16_f32 v13, v14, v15
	v_lshl_add_u64 v[14:15], v[10:11], 0, v[0:1]
	ds_read2_b32 v[64:65], v42 offset1:1
	ds_read2_b32 v[66:67], v42 offset0:2 offset1:3
	global_store_dwordx2 v[14:15], v[12:13], off
	ds_read2_b32 v[12:13], v43 offset1:1
	ds_read2_b32 v[14:15], v43 offset0:2 offset1:3
	v_add_lshl_u32 v0, s44, v26, 11
	s_waitcnt lgkmcnt(3)
	v_cvt_pk_bf16_f32 v64, v64, v65
	s_waitcnt lgkmcnt(2)
	v_cvt_pk_bf16_f32 v65, v66, v67
	v_lshl_add_u64 v[66:67], v[10:11], 0, v[0:1]
	v_add_lshl_u32 v0, s44, v27, 11
	s_waitcnt lgkmcnt(1)
	v_cvt_pk_bf16_f32 v12, v12, v13
	s_waitcnt lgkmcnt(0)
	v_cvt_pk_bf16_f32 v13, v14, v15
	v_lshl_add_u64 v[14:15], v[10:11], 0, v[0:1]
	v_add_lshl_u32 v0, s44, v28, 11
	global_store_dwordx2 v[14:15], v[12:13], off
	v_cvt_pk_bf16_f32 v12, v16, v17
	v_cvt_pk_bf16_f32 v13, v18, v19
	v_lshl_add_u64 v[10:11], v[10:11], 0, v[0:1]
	s_cmpk_lt_u32 s47, 0x60
	global_store_dwordx2 v[66:67], v[64:65], off
	global_store_dwordx2 v[10:11], v[12:13], off
	s_barrier
	s_cbranch_scc1 .LBB0_1963

.LBB0_2102:
	s_andn2_saveexec_b64 s[50:51], s[50:51]
	v_mul_f32_e32 v34, v33, v33
	v_fmamk_f32 v35, v34, 0xba1345e1, v139
	v_fmaak_f32 v35, v34, v35, 0xbcdac9b8
	v_fmaak_f32 v35, v34, v35, 0x3de703be
	v_fmaak_f32 v35, v34, v35, 0xbec09330
	v_fmaak_f32 v34, v34, v35, 0x3e0375d0
	v_fma_f32 v34, |v33|, v34, |v33|
	s_or_b64 exec, exec, s[50:51]
	v_cvt_scalef32_pk_f32_fp4 v[36:37], v202, 1.0
	v_pk_fma_f32 v[36:37], s[30:31], v[36:37], v[198:199] op_sel_hi:[0,1,1]
	v_cvt_scalef32_pk_f32_fp4 v[38:39], v202, 1.0 op_sel:[1,0,0]
	v_cvt_scalef32_pk_f32_fp4 v[52:53], v200, 1.0
	v_pk_fma_f32 v[38:39], s[30:31], v[38:39], v[216:217] op_sel_hi:[0,1,1]
	v_cvt_scalef32_pk_f32_fp4 v[40:41], v202, 1.0 op_sel:[0,1,0]
	v_pk_fma_f32 v[36:37], s[28:29], v[52:53], v[36:37] op_sel_hi:[0,1,1]
	v_cvt_scalef32_pk_f32_fp4 v[52:53], v200, 1.0 op_sel:[1,0,0]
	v_pk_fma_f32 v[40:41], s[30:31], v[40:41], v[214:215] op_sel_hi:[0,1,1]
	v_cvt_scalef32_pk_f32_fp4 v[42:43], v202, 1.0 op_sel:[1,1,0]
	v_pk_fma_f32 v[38:39], s[28:29], v[52:53], v[38:39] op_sel_hi:[0,1,1]
	v_cvt_scalef32_pk_f32_fp4 v[52:53], v200, 1.0 op_sel:[0,1,0]
	v_pk_fma_f32 v[42:43], s[30:31], v[42:43], v[212:213] op_sel_hi:[0,1,1]
	v_cvt_scalef32_pk_f32_fp4 v[44:45], v203, 1.0
	v_pk_fma_f32 v[40:41], s[28:29], v[52:53], v[40:41] op_sel_hi:[0,1,1]
	v_cvt_scalef32_pk_f32_fp4 v[52:53], v200, 1.0 op_sel:[1,1,0]
	v_pk_fma_f32 v[44:45], s[30:31], v[44:45], v[210:211] op_sel_hi:[0,1,1]
	v_cvt_scalef32_pk_f32_fp4 v[46:47], v203, 1.0 op_sel:[1,0,0]
	v_pk_fma_f32 v[42:43], s[28:29], v[52:53], v[42:43] op_sel_hi:[0,1,1]
	v_cvt_scalef32_pk_f32_fp4 v[52:53], v201, 1.0
	v_pk_fma_f32 v[46:47], s[30:31], v[46:47], v[208:209] op_sel_hi:[0,1,1]
	v_cvt_scalef32_pk_f32_fp4 v[48:49], v203, 1.0 op_sel:[0,1,0]
	v_pk_fma_f32 v[44:45], s[28:29], v[52:53], v[44:45] op_sel_hi:[0,1,1]
	v_cvt_scalef32_pk_f32_fp4 v[52:53], v201, 1.0 op_sel:[1,0,0]
	v_pk_fma_f32 v[48:49], s[30:31], v[48:49], v[206:207] op_sel_hi:[0,1,1]
	v_cvt_scalef32_pk_f32_fp4 v[50:51], v203, 1.0 op_sel:[1,1,0]
	v_pk_fma_f32 v[46:47], s[28:29], v[52:53], v[46:47] op_sel_hi:[0,1,1]
	v_cvt_scalef32_pk_f32_fp4 v[52:53], v201, 1.0 op_sel:[0,1,0]
	v_pk_fma_f32 v[50:51], s[30:31], v[50:51], v[204:205] op_sel_hi:[0,1,1]
	v_pk_fma_f32 v[48:49], s[28:29], v[52:53], v[48:49] op_sel_hi:[0,1,1]
	v_cvt_scalef32_pk_f32_fp4 v[52:53], v201, 1.0 op_sel:[1,1,0]
	v_pk_fma_f32 v[50:51], s[28:29], v[52:53], v[50:51] op_sel_hi:[0,1,1]
	v_cvt_scalef32_pk_f32_fp4 v[52:53], v196, 1.0
	v_pk_fma_f32 v[36:37], s[26:27], v[52:53], v[36:37] op_sel_hi:[0,1,1]
	v_cvt_scalef32_pk_f32_fp4 v[52:53], v196, 1.0 op_sel:[1,0,0]
	v_pk_fma_f32 v[38:39], s[26:27], v[52:53], v[38:39] op_sel_hi:[0,1,1]
	v_cvt_scalef32_pk_f32_fp4 v[52:53], v196, 1.0 op_sel:[0,1,0]
	v_pk_fma_f32 v[40:41], s[26:27], v[52:53], v[40:41] op_sel_hi:[0,1,1]
	v_cvt_scalef32_pk_f32_fp4 v[52:53], v196, 1.0 op_sel:[1,1,0]
	v_pk_fma_f32 v[42:43], s[26:27], v[52:53], v[42:43] op_sel_hi:[0,1,1]
	v_cvt_scalef32_pk_f32_fp4 v[52:53], v197, 1.0
	v_pk_fma_f32 v[44:45], s[26:27], v[52:53], v[44:45] op_sel_hi:[0,1,1]
	v_cvt_scalef32_pk_f32_fp4 v[52:53], v197, 1.0 op_sel:[1,0,0]
	v_pk_fma_f32 v[46:47], s[26:27], v[52:53], v[46:47] op_sel_hi:[0,1,1]
	v_cvt_scalef32_pk_f32_fp4 v[52:53], v197, 1.0 op_sel:[0,1,0]
	v_pk_fma_f32 v[48:49], s[26:27], v[52:53], v[48:49] op_sel_hi:[0,1,1]
	v_cvt_scalef32_pk_f32_fp4 v[52:53], v197, 1.0 op_sel:[1,1,0]
	v_pk_fma_f32 v[50:51], s[26:27], v[52:53], v[50:51] op_sel_hi:[0,1,1]
	v_cvt_scalef32_pk_f32_fp4 v[52:53], v194, 1.0
	v_pk_fma_f32 v[36:37], s[12:13], v[52:53], v[36:37] op_sel_hi:[0,1,1]
	v_cvt_scalef32_pk_f32_fp4 v[52:53], v194, 1.0 op_sel:[1,0,0]
	v_pk_fma_f32 v[38:39], s[12:13], v[52:53], v[38:39] op_sel_hi:[0,1,1]
	v_cvt_scalef32_pk_f32_fp4 v[52:53], v194, 1.0 op_sel:[0,1,0]
	v_pk_fma_f32 v[40:41], s[12:13], v[52:53], v[40:41] op_sel_hi:[0,1,1]
	v_cvt_scalef32_pk_f32_fp4 v[52:53], v194, 1.0 op_sel:[1,1,0]
	v_pk_fma_f32 v[42:43], s[12:13], v[52:53], v[42:43] op_sel_hi:[0,1,1]
	v_cvt_scalef32_pk_f32_fp4 v[52:53], v195, 1.0
	v_pk_fma_f32 v[44:45], s[12:13], v[52:53], v[44:45] op_sel_hi:[0,1,1]
	v_cvt_scalef32_pk_f32_fp4 v[52:53], v195, 1.0 op_sel:[1,0,0]
	v_pk_fma_f32 v[46:47], s[12:13], v[52:53], v[46:47] op_sel_hi:[0,1,1]
	v_cvt_scalef32_pk_f32_fp4 v[52:53], v195, 1.0 op_sel:[0,1,0]
	v_pk_fma_f32 v[48:49], s[12:13], v[52:53], v[48:49] op_sel_hi:[0,1,1]
	v_cvt_scalef32_pk_f32_fp4 v[52:53], v195, 1.0 op_sel:[1,1,0]
	v_pk_fma_f32 v[50:51], s[12:13], v[52:53], v[50:51] op_sel_hi:[0,1,1]
	v_cvt_scalef32_pk_f32_fp4 v[52:53], v192, 1.0
	v_pk_fma_f32 v[36:37], s[40:41], v[52:53], v[36:37] op_sel_hi:[0,1,1]
	v_cvt_scalef32_pk_f32_fp4 v[52:53], v192, 1.0 op_sel:[1,0,0]
	v_pk_fma_f32 v[38:39], s[40:41], v[52:53], v[38:39] op_sel_hi:[0,1,1]
	v_cvt_scalef32_pk_f32_fp4 v[52:53], v192, 1.0 op_sel:[0,1,0]
	v_pk_fma_f32 v[40:41], s[40:41], v[52:53], v[40:41] op_sel_hi:[0,1,1]
	v_cvt_scalef32_pk_f32_fp4 v[52:53], v192, 1.0 op_sel:[1,1,0]
	v_pk_fma_f32 v[42:43], s[40:41], v[52:53], v[42:43] op_sel_hi:[0,1,1]
	v_cvt_scalef32_pk_f32_fp4 v[52:53], v193, 1.0
	v_pk_fma_f32 v[44:45], s[40:41], v[52:53], v[44:45] op_sel_hi:[0,1,1]
	v_cvt_scalef32_pk_f32_fp4 v[52:53], v193, 1.0 op_sel:[1,0,0]
	v_pk_fma_f32 v[46:47], s[40:41], v[52:53], v[46:47] op_sel_hi:[0,1,1]
	v_cvt_scalef32_pk_f32_fp4 v[52:53], v193, 1.0 op_sel:[0,1,0]
	v_pk_fma_f32 v[48:49], s[40:41], v[52:53], v[48:49] op_sel_hi:[0,1,1]
	v_cvt_scalef32_pk_f32_fp4 v[52:53], v193, 1.0 op_sel:[1,1,0]
	v_pk_fma_f32 v[50:51], s[40:41], v[52:53], v[50:51] op_sel_hi:[0,1,1]
	v_cvt_scalef32_pk_f32_fp4 v[52:53], v190, 1.0
	v_pk_fma_f32 v[36:37], s[38:39], v[52:53], v[36:37] op_sel_hi:[0,1,1]
	v_cvt_scalef32_pk_f32_fp4 v[52:53], v190, 1.0 op_sel:[1,0,0]
	v_pk_fma_f32 v[38:39], s[38:39], v[52:53], v[38:39] op_sel_hi:[0,1,1]
	v_cvt_scalef32_pk_f32_fp4 v[52:53], v190, 1.0 op_sel:[0,1,0]
	v_pk_fma_f32 v[40:41], s[38:39], v[52:53], v[40:41] op_sel_hi:[0,1,1]
	v_cvt_scalef32_pk_f32_fp4 v[52:53], v190, 1.0 op_sel:[1,1,0]
	v_pk_fma_f32 v[42:43], s[38:39], v[52:53], v[42:43] op_sel_hi:[0,1,1]
	v_cvt_scalef32_pk_f32_fp4 v[52:53], v191, 1.0
	v_pk_fma_f32 v[44:45], s[38:39], v[52:53], v[44:45] op_sel_hi:[0,1,1]
	v_cvt_scalef32_pk_f32_fp4 v[52:53], v191, 1.0 op_sel:[1,0,0]
	v_pk_fma_f32 v[46:47], s[38:39], v[52:53], v[46:47] op_sel_hi:[0,1,1]
	v_cvt_scalef32_pk_f32_fp4 v[52:53], v191, 1.0 op_sel:[0,1,0]
	v_pk_fma_f32 v[48:49], s[38:39], v[52:53], v[48:49] op_sel_hi:[0,1,1]
	v_cvt_scalef32_pk_f32_fp4 v[52:53], v191, 1.0 op_sel:[1,1,0]
	v_pk_fma_f32 v[50:51], s[38:39], v[52:53], v[50:51] op_sel_hi:[0,1,1]
	v_cvt_scalef32_pk_f32_fp4 v[52:53], v188, 1.0
	v_pk_fma_f32 v[36:37], s[36:37], v[52:53], v[36:37] op_sel_hi:[0,1,1]
	v_cvt_scalef32_pk_f32_fp4 v[52:53], v188, 1.0 op_sel:[1,0,0]
	v_pk_fma_f32 v[38:39], s[36:37], v[52:53], v[38:39] op_sel_hi:[0,1,1]
	v_cvt_scalef32_pk_f32_fp4 v[52:53], v188, 1.0 op_sel:[0,1,0]
	v_pk_fma_f32 v[40:41], s[36:37], v[52:53], v[40:41] op_sel_hi:[0,1,1]
	v_cvt_scalef32_pk_f32_fp4 v[52:53], v188, 1.0 op_sel:[1,1,0]
	v_pk_fma_f32 v[42:43], s[36:37], v[52:53], v[42:43] op_sel_hi:[0,1,1]
	v_cvt_scalef32_pk_f32_fp4 v[52:53], v189, 1.0
	v_pk_fma_f32 v[44:45], s[36:37], v[52:53], v[44:45] op_sel_hi:[0,1,1]
	v_cvt_scalef32_pk_f32_fp4 v[52:53], v189, 1.0 op_sel:[1,0,0]
	v_pk_fma_f32 v[46:47], s[36:37], v[52:53], v[46:47] op_sel_hi:[0,1,1]
	v_cvt_scalef32_pk_f32_fp4 v[52:53], v189, 1.0 op_sel:[0,1,0]
	v_pk_fma_f32 v[48:49], s[36:37], v[52:53], v[48:49] op_sel_hi:[0,1,1]
	v_cvt_scalef32_pk_f32_fp4 v[52:53], v189, 1.0 op_sel:[1,1,0]
	v_pk_fma_f32 v[50:51], s[36:37], v[52:53], v[50:51] op_sel_hi:[0,1,1]
	v_cvt_scalef32_pk_f32_fp4 v[52:53], v186, 1.0
	v_pk_fma_f32 v[36:37], s[34:35], v[52:53], v[36:37] op_sel_hi:[0,1,1]
	v_cvt_scalef32_pk_f32_fp4 v[52:53], v186, 1.0 op_sel:[1,0,0]
	v_pk_fma_f32 v[38:39], s[34:35], v[52:53], v[38:39] op_sel_hi:[0,1,1]
	v_cvt_scalef32_pk_f32_fp4 v[52:53], v186, 1.0 op_sel:[0,1,0]
	v_pk_fma_f32 v[40:41], s[34:35], v[52:53], v[40:41] op_sel_hi:[0,1,1]
	v_cvt_scalef32_pk_f32_fp4 v[52:53], v186, 1.0 op_sel:[1,1,0]
	v_pk_fma_f32 v[42:43], s[34:35], v[52:53], v[42:43] op_sel_hi:[0,1,1]
	v_cvt_scalef32_pk_f32_fp4 v[52:53], v187, 1.0
	v_pk_fma_f32 v[44:45], s[34:35], v[52:53], v[44:45] op_sel_hi:[0,1,1]
	v_cvt_scalef32_pk_f32_fp4 v[52:53], v187, 1.0 op_sel:[1,0,0]
	v_pk_fma_f32 v[46:47], s[34:35], v[52:53], v[46:47] op_sel_hi:[0,1,1]
	v_cvt_scalef32_pk_f32_fp4 v[52:53], v187, 1.0 op_sel:[0,1,0]
	v_pk_fma_f32 v[48:49], s[34:35], v[52:53], v[48:49] op_sel_hi:[0,1,1]
	v_cvt_scalef32_pk_f32_fp4 v[52:53], v187, 1.0 op_sel:[1,1,0]
	v_pk_fma_f32 v[50:51], s[34:35], v[52:53], v[50:51] op_sel_hi:[0,1,1]
	v_cvt_scalef32_pk_f32_fp4 v[52:53], v184, 1.0
	v_pk_fma_f32 v[36:37], s[48:49], v[52:53], v[36:37] op_sel_hi:[0,1,1]
	v_cvt_scalef32_pk_f32_fp4 v[52:53], v184, 1.0 op_sel:[1,0,0]
	v_pk_fma_f32 v[38:39], s[48:49], v[52:53], v[38:39] op_sel_hi:[0,1,1]
	v_cvt_scalef32_pk_f32_fp4 v[52:53], v184, 1.0 op_sel:[0,1,0]
	v_pk_fma_f32 v[40:41], s[48:49], v[52:53], v[40:41] op_sel_hi:[0,1,1]
	v_cvt_scalef32_pk_f32_fp4 v[52:53], v184, 1.0 op_sel:[1,1,0]
	v_pk_fma_f32 v[42:43], s[48:49], v[52:53], v[42:43] op_sel_hi:[0,1,1]
	v_cvt_scalef32_pk_f32_fp4 v[52:53], v185, 1.0
	v_pk_fma_f32 v[44:45], s[48:49], v[52:53], v[44:45] op_sel_hi:[0,1,1]
	v_cvt_scalef32_pk_f32_fp4 v[52:53], v185, 1.0 op_sel:[1,0,0]
	v_pk_fma_f32 v[46:47], s[48:49], v[52:53], v[46:47] op_sel_hi:[0,1,1]
	v_cvt_scalef32_pk_f32_fp4 v[52:53], v185, 1.0 op_sel:[0,1,0]
	v_pk_fma_f32 v[48:49], s[48:49], v[52:53], v[48:49] op_sel_hi:[0,1,1]
	v_cvt_scalef32_pk_f32_fp4 v[52:53], v185, 1.0 op_sel:[1,1,0]
	v_pk_fma_f32 v[50:51], s[48:49], v[52:53], v[50:51] op_sel_hi:[0,1,1]
	v_cvt_scalef32_pk_f32_fp4 v[52:53], v182, 1.0
	v_pk_fma_f32 v[36:37], s[46:47], v[52:53], v[36:37] op_sel_hi:[0,1,1]
	v_cvt_scalef32_pk_f32_fp4 v[52:53], v182, 1.0 op_sel:[1,0,0]
	v_pk_fma_f32 v[38:39], s[46:47], v[52:53], v[38:39] op_sel_hi:[0,1,1]
	v_cvt_scalef32_pk_f32_fp4 v[52:53], v182, 1.0 op_sel:[0,1,0]
	v_pk_fma_f32 v[40:41], s[46:47], v[52:53], v[40:41] op_sel_hi:[0,1,1]
	v_cvt_scalef32_pk_f32_fp4 v[52:53], v182, 1.0 op_sel:[1,1,0]
	v_pk_fma_f32 v[42:43], s[46:47], v[52:53], v[42:43] op_sel_hi:[0,1,1]
	v_cvt_scalef32_pk_f32_fp4 v[52:53], v183, 1.0
	v_pk_fma_f32 v[44:45], s[46:47], v[52:53], v[44:45] op_sel_hi:[0,1,1]
	v_cvt_scalef32_pk_f32_fp4 v[52:53], v183, 1.0 op_sel:[1,0,0]
	v_pk_fma_f32 v[46:47], s[46:47], v[52:53], v[46:47] op_sel_hi:[0,1,1]
	v_cvt_scalef32_pk_f32_fp4 v[52:53], v183, 1.0 op_sel:[0,1,0]
	v_pk_fma_f32 v[48:49], s[46:47], v[52:53], v[48:49] op_sel_hi:[0,1,1]
	v_cvt_scalef32_pk_f32_fp4 v[52:53], v183, 1.0 op_sel:[1,1,0]
	v_pk_fma_f32 v[50:51], s[46:47], v[52:53], v[50:51] op_sel_hi:[0,1,1]
	v_cvt_scalef32_pk_f32_fp4 v[52:53], v180, 1.0
	v_pk_fma_f32 v[36:37], s[44:45], v[52:53], v[36:37] op_sel_hi:[0,1,1]
	v_cvt_scalef32_pk_f32_fp4 v[52:53], v180, 1.0 op_sel:[1,0,0]
	v_pk_fma_f32 v[38:39], s[44:45], v[52:53], v[38:39] op_sel_hi:[0,1,1]
	v_cvt_scalef32_pk_f32_fp4 v[52:53], v180, 1.0 op_sel:[0,1,0]
	v_pk_fma_f32 v[40:41], s[44:45], v[52:53], v[40:41] op_sel_hi:[0,1,1]
	v_cvt_scalef32_pk_f32_fp4 v[52:53], v180, 1.0 op_sel:[1,1,0]
	v_pk_fma_f32 v[42:43], s[44:45], v[52:53], v[42:43] op_sel_hi:[0,1,1]
	v_cvt_scalef32_pk_f32_fp4 v[52:53], v181, 1.0
	v_pk_fma_f32 v[44:45], s[44:45], v[52:53], v[44:45] op_sel_hi:[0,1,1]
	v_cvt_scalef32_pk_f32_fp4 v[52:53], v181, 1.0 op_sel:[1,0,0]
	v_pk_fma_f32 v[46:47], s[44:45], v[52:53], v[46:47] op_sel_hi:[0,1,1]
	v_cvt_scalef32_pk_f32_fp4 v[52:53], v181, 1.0 op_sel:[0,1,0]
	v_pk_fma_f32 v[48:49], s[44:45], v[52:53], v[48:49] op_sel_hi:[0,1,1]
	v_cvt_scalef32_pk_f32_fp4 v[52:53], v181, 1.0 op_sel:[1,1,0]
	v_pk_fma_f32 v[50:51], s[44:45], v[52:53], v[50:51] op_sel_hi:[0,1,1]
	v_cvt_scalef32_pk_f32_fp4 v[52:53], v178, 1.0
	v_pk_fma_f32 v[36:37], s[42:43], v[52:53], v[36:37] op_sel_hi:[0,1,1]
	v_cvt_scalef32_pk_f32_fp4 v[52:53], v178, 1.0 op_sel:[1,0,0]
	v_pk_fma_f32 v[38:39], s[42:43], v[52:53], v[38:39] op_sel_hi:[0,1,1]
	v_cvt_scalef32_pk_f32_fp4 v[52:53], v178, 1.0 op_sel:[0,1,0]
	v_pk_fma_f32 v[40:41], s[42:43], v[52:53], v[40:41] op_sel_hi:[0,1,1]
	v_cvt_scalef32_pk_f32_fp4 v[52:53], v178, 1.0 op_sel:[1,1,0]
	v_pk_fma_f32 v[42:43], s[42:43], v[52:53], v[42:43] op_sel_hi:[0,1,1]
	v_cvt_scalef32_pk_f32_fp4 v[52:53], v179, 1.0
	v_pk_fma_f32 v[44:45], s[42:43], v[52:53], v[44:45] op_sel_hi:[0,1,1]
	v_cvt_scalef32_pk_f32_fp4 v[52:53], v179, 1.0 op_sel:[1,0,0]
	v_pk_fma_f32 v[46:47], s[42:43], v[52:53], v[46:47] op_sel_hi:[0,1,1]
	v_cvt_scalef32_pk_f32_fp4 v[52:53], v179, 1.0 op_sel:[0,1,0]
	v_pk_fma_f32 v[48:49], s[42:43], v[52:53], v[48:49] op_sel_hi:[0,1,1]
	v_cvt_scalef32_pk_f32_fp4 v[52:53], v179, 1.0 op_sel:[1,1,0]
	v_pk_fma_f32 v[50:51], s[42:43], v[52:53], v[50:51] op_sel_hi:[0,1,1]
	v_mov_b32_e32 v35, s59
	v_mov_b32_e32 v52, s35
	v_cndmask_b32_e64 v35, v35, v52, s[10:11]
	v_mov_b32_e32 v52, s43
	v_bfi_b32 v33, s55, v34, v33
	v_cndmask_b32_e64 v35, v35, v52, s[8:9]
	v_mov_b32_e32 v52, s13
	v_mul_f32_e32 v32, 0.5, v32
	v_add_f32_e32 v33, 1.0, v33
	v_cndmask_b32_e64 v35, v35, v52, s[6:7]
	v_mul_f32_e32 v32, v32, v33
	v_mul_f32_e32 v32, v35, v32
	v_cvt_scalef32_pk_f32_fp4 v[34:35], v176, 1.0 op_sel:[1,0,0]
	v_readlane_b32 s12, v32, 0
	v_readlane_b32 s26, v32, 32
	v_readlane_b32 s28, v32, 16
	v_readlane_b32 s30, v32, 48
	v_cvt_scalef32_pk_f32_fp4 v[32:33], v176, 1.0
	v_pk_fma_f32 v[32:33], s[12:13], v[32:33], v[36:37] op_sel_hi:[0,1,1]
	v_cvt_scalef32_pk_f32_fp4 v[36:37], v176, 1.0 op_sel:[0,1,0]
	v_pk_fma_f32 v[36:37], s[12:13], v[36:37], v[40:41] op_sel_hi:[0,1,1]
	v_cvt_scalef32_pk_f32_fp4 v[40:41], v177, 1.0
	v_pk_fma_f32 v[40:41], s[12:13], v[40:41], v[44:45] op_sel_hi:[0,1,1]
	v_cvt_scalef32_pk_f32_fp4 v[44:45], v177, 1.0 op_sel:[0,1,0]
	v_pk_fma_f32 v[44:45], s[12:13], v[44:45], v[48:49] op_sel_hi:[0,1,1]
	v_cvt_scalef32_pk_f32_fp4 v[48:49], v174, 1.0
	v_pk_fma_f32 v[34:35], s[12:13], v[34:35], v[38:39] op_sel_hi:[0,1,1]
	v_pk_fma_f32 v[32:33], s[26:27], v[48:49], v[32:33] op_sel_hi:[0,1,1]
	v_cvt_scalef32_pk_f32_fp4 v[48:49], v174, 1.0 op_sel:[1,0,0]
	v_cvt_scalef32_pk_f32_fp4 v[38:39], v176, 1.0 op_sel:[1,1,0]
	v_pk_fma_f32 v[34:35], s[26:27], v[48:49], v[34:35] op_sel_hi:[0,1,1]
	v_cvt_scalef32_pk_f32_fp4 v[48:49], v174, 1.0 op_sel:[0,1,0]
	v_pk_fma_f32 v[38:39], s[12:13], v[38:39], v[42:43] op_sel_hi:[0,1,1]
	v_pk_fma_f32 v[36:37], s[26:27], v[48:49], v[36:37] op_sel_hi:[0,1,1]
	v_cvt_scalef32_pk_f32_fp4 v[48:49], v174, 1.0 op_sel:[1,1,0]
	v_cvt_scalef32_pk_f32_fp4 v[42:43], v177, 1.0 op_sel:[1,0,0]
	v_pk_fma_f32 v[38:39], s[26:27], v[48:49], v[38:39] op_sel_hi:[0,1,1]
	v_cvt_scalef32_pk_f32_fp4 v[48:49], v175, 1.0
	v_pk_fma_f32 v[42:43], s[12:13], v[42:43], v[46:47] op_sel_hi:[0,1,1]
	v_pk_fma_f32 v[40:41], s[26:27], v[48:49], v[40:41] op_sel_hi:[0,1,1]
	v_cvt_scalef32_pk_f32_fp4 v[48:49], v175, 1.0 op_sel:[1,0,0]
	v_cvt_scalef32_pk_f32_fp4 v[46:47], v177, 1.0 op_sel:[1,1,0]
	v_pk_fma_f32 v[42:43], s[26:27], v[48:49], v[42:43] op_sel_hi:[0,1,1]
	v_cvt_scalef32_pk_f32_fp4 v[48:49], v175, 1.0 op_sel:[0,1,0]
	v_pk_fma_f32 v[46:47], s[12:13], v[46:47], v[50:51] op_sel_hi:[0,1,1]
	v_pk_fma_f32 v[44:45], s[26:27], v[48:49], v[44:45] op_sel_hi:[0,1,1]
	v_cvt_scalef32_pk_f32_fp4 v[48:49], v175, 1.0 op_sel:[1,1,0]
	v_pk_fma_f32 v[46:47], s[26:27], v[48:49], v[46:47] op_sel_hi:[0,1,1]
	v_cvt_scalef32_pk_f32_fp4 v[48:49], v172, 1.0
	v_pk_fma_f32 v[32:33], s[28:29], v[48:49], v[32:33] op_sel_hi:[0,1,1]
	v_cvt_scalef32_pk_f32_fp4 v[48:49], v172, 1.0 op_sel:[1,0,0]
	v_pk_fma_f32 v[34:35], s[28:29], v[48:49], v[34:35] op_sel_hi:[0,1,1]
	v_cvt_scalef32_pk_f32_fp4 v[48:49], v172, 1.0 op_sel:[0,1,0]
	v_pk_fma_f32 v[36:37], s[28:29], v[48:49], v[36:37] op_sel_hi:[0,1,1]
	v_cvt_scalef32_pk_f32_fp4 v[48:49], v172, 1.0 op_sel:[1,1,0]
	v_pk_fma_f32 v[38:39], s[28:29], v[48:49], v[38:39] op_sel_hi:[0,1,1]
	v_cvt_scalef32_pk_f32_fp4 v[48:49], v173, 1.0
	v_pk_fma_f32 v[40:41], s[28:29], v[48:49], v[40:41] op_sel_hi:[0,1,1]
	v_cvt_scalef32_pk_f32_fp4 v[48:49], v173, 1.0 op_sel:[1,0,0]
	v_pk_fma_f32 v[42:43], s[28:29], v[48:49], v[42:43] op_sel_hi:[0,1,1]
	v_cvt_scalef32_pk_f32_fp4 v[48:49], v173, 1.0 op_sel:[0,1,0]
	v_pk_fma_f32 v[44:45], s[28:29], v[48:49], v[44:45] op_sel_hi:[0,1,1]
	v_cvt_scalef32_pk_f32_fp4 v[48:49], v173, 1.0 op_sel:[1,1,0]
	v_pk_fma_f32 v[46:47], s[28:29], v[48:49], v[46:47] op_sel_hi:[0,1,1]
	v_cvt_scalef32_pk_f32_fp4 v[48:49], v170, 1.0
	v_pk_fma_f32 v[198:199], s[30:31], v[48:49], v[32:33] op_sel_hi:[0,1,1]
	v_cvt_scalef32_pk_f32_fp4 v[32:33], v170, 1.0 op_sel:[1,0,0]
	v_pk_fma_f32 v[216:217], s[30:31], v[32:33], v[34:35] op_sel_hi:[0,1,1]
	v_cvt_scalef32_pk_f32_fp4 v[32:33], v170, 1.0 op_sel:[0,1,0]
	v_pk_fma_f32 v[214:215], s[30:31], v[32:33], v[36:37] op_sel_hi:[0,1,1]
	v_cvt_scalef32_pk_f32_fp4 v[32:33], v170, 1.0 op_sel:[1,1,0]
	v_pk_fma_f32 v[212:213], s[30:31], v[32:33], v[38:39] op_sel_hi:[0,1,1]
	v_cvt_scalef32_pk_f32_fp4 v[32:33], v171, 1.0
	v_pk_fma_f32 v[210:211], s[30:31], v[32:33], v[40:41] op_sel_hi:[0,1,1]
	v_cvt_scalef32_pk_f32_fp4 v[32:33], v171, 1.0 op_sel:[1,0,0]
	v_pk_fma_f32 v[208:209], s[30:31], v[32:33], v[42:43] op_sel_hi:[0,1,1]
	v_cvt_scalef32_pk_f32_fp4 v[32:33], v171, 1.0 op_sel:[0,1,0]
	v_pk_fma_f32 v[206:207], s[30:31], v[32:33], v[44:45] op_sel_hi:[0,1,1]
	v_cvt_scalef32_pk_f32_fp4 v[32:33], v171, 1.0 op_sel:[1,1,0]
	v_pk_fma_f32 v[204:205], s[30:31], v[32:33], v[46:47] op_sel_hi:[0,1,1]
	s_and_b64 vcc, exec, s[24:25]
	s_cbranch_vccnz .LBB0_2084
	s_mov_b32 s26, s58
	s_add_i32 s58, s26, 16
	s_cmpk_gt_u32 s26, 0x6f
	s_cselect_b64 s[24:25], -1, 0
	s_cmpk_lt_u32 s26, 0x70
	s_cselect_b64 vcc, -1, 0
	s_bitcmp0_b32 s58, 6
	s_cselect_b64 s[12:13], -1, 0
	v_cndmask_b32_e64 v100, v116, v102, s[12:13]
	v_cndmask_b32_e32 v100, v118, v100, vcc
	s_nop 0
	s_waitcnt vmcnt(24)
	v_accvgpr_read_b32 v203, a43
	v_accvgpr_read_b32 v201, a45
	v_accvgpr_read_b32 v197, a47
	v_accvgpr_read_b32 v195, a49
	v_accvgpr_read_b32 v95, a23
	v_accvgpr_read_b32 v91, a27
	v_mov_b64_e32 v[84:85], v[230:231]
	v_mov_b64_e32 v[80:81], v[234:235]
	v_accvgpr_read_b32 v202, a42
	v_accvgpr_read_b32 v200, a44
	v_accvgpr_read_b32 v196, a46
	v_accvgpr_read_b32 v194, a48
	v_accvgpr_read_b32 v94, a22
	v_accvgpr_read_b32 v93, a21
	v_accvgpr_read_b32 v92, a20
	v_accvgpr_read_b32 v90, a26
	v_accvgpr_read_b32 v89, a25
	v_accvgpr_read_b32 v88, a24
	v_mov_b64_e32 v[86:87], v[232:233]
	v_mov_b64_e32 v[82:83], v[236:237]
	s_add_i32 s30, s26, 16
	v_readlane_b32 s28, v100, s30
	s_nop 1
	v_mad_i64_i32 v[136:137], s[12:13], s28, v130, v[96:97]
	global_load_dwordx4 a[20:23], v[136:137], off
	v_mad_i64_i32 v[136:137], s[12:13], s28, v130, v[98:99]
	global_load_dwordx2 a[42:43], v[136:137], off
	s_add_i32 s30, s26, 17
	v_readlane_b32 s28, v100, s30
	s_nop 1
	v_mad_i64_i32 v[136:137], s[12:13], s28, v130, v[96:97]
	global_load_dwordx4 a[24:27], v[136:137], off
	v_mad_i64_i32 v[136:137], s[12:13], s28, v130, v[98:99]
	global_load_dwordx2 a[44:45], v[136:137], off
	s_add_i32 s30, s26, 18
	v_readlane_b32 s28, v100, s30
	s_nop 1
	v_mad_i64_i32 v[136:137], s[12:13], s28, v130, v[96:97]
	global_load_dwordx4 v[230:233], v[136:137], off
	v_mad_i64_i32 v[136:137], s[12:13], s28, v130, v[98:99]
	global_load_dwordx2 a[46:47], v[136:137], off
	s_add_i32 s30, s26, 19
	v_readlane_b32 s28, v100, s30
	s_nop 1
	v_mad_i64_i32 v[136:137], s[12:13], s28, v130, v[96:97]
	global_load_dwordx4 v[234:237], v[136:137], off
	v_mad_i64_i32 v[136:137], s[12:13], s28, v130, v[98:99]
	global_load_dwordx2 a[48:49], v[136:137], off
	s_waitcnt vmcnt(24)
	v_accvgpr_read_b32 v193, a51
	v_accvgpr_read_b32 v191, a53
	v_accvgpr_read_b32 v189, a55
	v_accvgpr_read_b32 v187, a57
	v_mov_b64_e32 v[76:77], v[238:239]
	v_mov_b64_e32 v[72:73], v[242:243]
	v_mov_b64_e32 v[68:69], v[246:247]
	v_mov_b64_e32 v[64:65], v[250:251]
	v_accvgpr_read_b32 v192, a50
	v_accvgpr_read_b32 v190, a52
	v_accvgpr_read_b32 v188, a54
	v_accvgpr_read_b32 v186, a56
	v_mov_b64_e32 v[78:79], v[240:241]
	v_mov_b64_e32 v[74:75], v[244:245]
	v_mov_b64_e32 v[70:71], v[248:249]
	v_mov_b64_e32 v[66:67], v[252:253]
	s_add_i32 s30, s26, 20
	v_readlane_b32 s28, v100, s30
	s_nop 1
	v_mad_i64_i32 v[136:137], s[12:13], s28, v130, v[96:97]
	global_load_dwordx4 v[238:241], v[136:137], off
	v_mad_i64_i32 v[136:137], s[12:13], s28, v130, v[98:99]
	global_load_dwordx2 a[50:51], v[136:137], off
	s_add_i32 s30, s26, 21
	v_readlane_b32 s28, v100, s30
	s_nop 1
	v_mad_i64_i32 v[136:137], s[12:13], s28, v130, v[96:97]
	global_load_dwordx4 v[242:245], v[136:137], off
	v_mad_i64_i32 v[136:137], s[12:13], s28, v130, v[98:99]
	global_load_dwordx2 a[52:53], v[136:137], off
	s_add_i32 s30, s26, 22
	v_readlane_b32 s28, v100, s30
	s_nop 1
	v_mad_i64_i32 v[136:137], s[12:13], s28, v130, v[96:97]
	global_load_dwordx4 v[246:249], v[136:137], off
	v_mad_i64_i32 v[136:137], s[12:13], s28, v130, v[98:99]
	global_load_dwordx2 a[54:55], v[136:137], off
	s_add_i32 s30, s26, 23
	v_readlane_b32 s28, v100, s30
	s_nop 1
	v_mad_i64_i32 v[136:137], s[12:13], s28, v130, v[96:97]
	global_load_dwordx4 v[250:253], v[136:137], off
	v_mad_i64_i32 v[136:137], s[12:13], s28, v130, v[98:99]
	global_load_dwordx2 a[56:57], v[136:137], off
	s_waitcnt vmcnt(24)
	v_accvgpr_read_b32 v185, a59
	v_accvgpr_read_b32 v183, a61
	v_accvgpr_read_b32 v181, a63
	v_accvgpr_read_b32 v179, a65
	v_accvgpr_read_b32 v63, a3
	v_accvgpr_read_b32 v59, a7
	v_accvgpr_read_b32 v55, a11
	v_accvgpr_read_b32 v51, a15
	v_accvgpr_read_b32 v184, a58
	v_accvgpr_read_b32 v182, a60
	v_accvgpr_read_b32 v180, a62
	v_accvgpr_read_b32 v178, a64
	v_accvgpr_read_b32 v62, a2
	v_accvgpr_read_b32 v61, a1
	v_accvgpr_read_b32 v60, a0
	v_accvgpr_read_b32 v58, a6
	v_accvgpr_read_b32 v57, a5
	v_accvgpr_read_b32 v56, a4
	v_accvgpr_read_b32 v54, a10
	v_accvgpr_read_b32 v53, a9
	v_accvgpr_read_b32 v52, a8
	v_accvgpr_read_b32 v50, a14
	v_accvgpr_read_b32 v49, a13
	v_accvgpr_read_b32 v48, a12
	s_add_i32 s30, s26, 24
	v_readlane_b32 s28, v100, s30
	s_nop 1
	v_mad_i64_i32 v[136:137], s[12:13], s28, v130, v[96:97]
	global_load_dwordx4 a[0:3], v[136:137], off
	v_mad_i64_i32 v[136:137], s[12:13], s28, v130, v[98:99]
	global_load_dwordx2 a[58:59], v[136:137], off
	s_add_i32 s30, s26, 25
	v_readlane_b32 s28, v100, s30
	s_nop 1
	v_mad_i64_i32 v[136:137], s[12:13], s28, v130, v[96:97]
	global_load_dwordx4 a[4:7], v[136:137], off
	v_mad_i64_i32 v[136:137], s[12:13], s28, v130, v[98:99]
	global_load_dwordx2 a[60:61], v[136:137], off
	s_add_i32 s30, s26, 26
	v_readlane_b32 s28, v100, s30
	s_nop 1
	v_mad_i64_i32 v[136:137], s[12:13], s28, v130, v[96:97]
	global_load_dwordx4 a[8:11], v[136:137], off
	v_mad_i64_i32 v[136:137], s[12:13], s28, v130, v[98:99]
	global_load_dwordx2 a[62:63], v[136:137], off
	s_add_i32 s30, s26, 27
	v_readlane_b32 s28, v100, s30
	s_nop 1
	v_mad_i64_i32 v[136:137], s[12:13], s28, v130, v[96:97]
	global_load_dwordx4 a[12:15], v[136:137], off
	v_mad_i64_i32 v[136:137], s[12:13], s28, v130, v[98:99]
	global_load_dwordx2 a[64:65], v[136:137], off
	s_waitcnt vmcnt(24)
	v_accvgpr_read_b32 v177, a67
	v_accvgpr_read_b32 v175, a37
	v_accvgpr_read_b32 v173, a39
	v_accvgpr_read_b32 v171, a41
	v_accvgpr_read_b32 v47, a19
	v_mov_b64_e32 v[40:41], v[218:219]
	v_mov_b64_e32 v[36:37], v[222:223]
	v_mov_b64_e32 v[32:33], v[226:227]
	v_accvgpr_read_b32 v176, a66
	v_accvgpr_read_b32 v174, a36
	v_accvgpr_read_b32 v172, a38
	v_accvgpr_read_b32 v170, a40
	v_accvgpr_read_b32 v46, a18
	v_accvgpr_read_b32 v45, a17
	v_accvgpr_read_b32 v44, a16
	v_mov_b64_e32 v[42:43], v[220:221]
	v_mov_b64_e32 v[38:39], v[224:225]
	v_mov_b64_e32 v[34:35], v[228:229]
	s_add_i32 s30, s26, 28
	v_readlane_b32 s28, v100, s30
	s_nop 1
	v_mad_i64_i32 v[136:137], s[12:13], s28, v130, v[96:97]
	global_load_dwordx4 a[16:19], v[136:137], off
	v_mad_i64_i32 v[136:137], s[12:13], s28, v130, v[98:99]
	global_load_dwordx2 a[66:67], v[136:137], off
	s_add_i32 s30, s26, 29
	v_readlane_b32 s28, v100, s30
	s_nop 1
	v_mad_i64_i32 v[136:137], s[12:13], s28, v130, v[96:97]
	global_load_dwordx4 v[218:221], v[136:137], off
	v_mad_i64_i32 v[136:137], s[12:13], s28, v130, v[98:99]
	global_load_dwordx2 a[36:37], v[136:137], off
	s_add_i32 s30, s26, 30
	v_readlane_b32 s28, v100, s30
	s_nop 1
	v_mad_i64_i32 v[136:137], s[12:13], s28, v130, v[96:97]
	global_load_dwordx4 v[222:225], v[136:137], off
	v_mad_i64_i32 v[136:137], s[12:13], s28, v130, v[98:99]
	global_load_dwordx2 a[38:39], v[136:137], off
	s_add_i32 s30, s26, 31
	v_readlane_b32 s28, v100, s30
	s_nop 1
	v_mad_i64_i32 v[136:137], s[12:13], s28, v130, v[96:97]
	global_load_dwordx4 v[226:229], v[136:137], off
	v_mad_i64_i32 v[136:137], s[12:13], s28, v130, v[98:99]
	global_load_dwordx2 a[40:41], v[136:137], off
	s_cmp_lg_u32 s26, 64
	s_cbranch_scc1 .LBB0_2088
	global_load_dword a68, v[168:169], off
	global_load_dword a69, v[166:167], off
	global_load_dword v117, v[164:165], off
	global_load_dword v103, v[162:163], off
	s_branch .LBB0_2088

.LBB0_2160:
	s_and_b32 s4, s72, 0xffff
	s_mul_i32 s4, s4, 0xaaab
	s_lshr_b32 s4, s4, 20
	s_add_i32 s74, s77, s4
	s_mul_i32 s4, s4, 24
	s_sub_i32 s11, s72, s4
	s_lshl_b32 s4, s74, 19
	v_lshl_add_u64 v[4:5], v[56:57], 0, s[4:5]
	v_add_co_u32_e32 v12, vcc, 0x10000, v4
	s_lshl_b32 s8, s11, 18
	s_nop 0
	v_addc_co_u32_e32 v13, vcc, 0, v5, vcc
	v_add_co_u32_e32 v14, vcc, 0x20000, v4
	s_mov_b32 s9, s5
	s_nop 0
	v_addc_co_u32_e32 v15, vcc, 0, v5, vcc
	v_add_co_u32_e32 v24, vcc, 0x30000, v4
	global_load_dwordx4 v[0:3], v[4:5], off
	s_nop 0
	v_addc_co_u32_e32 v25, vcc, 0, v5, vcc
	v_add_co_u32_e32 v26, vcc, 0x40000, v4
	v_lshl_add_u64 v[8:9], v[58:59], 0, s[8:9]
	s_nop 0
	v_addc_co_u32_e32 v27, vcc, 0, v5, vcc
	v_add_co_u32_e32 v28, vcc, 0x50000, v4
	global_load_dwordx4 v[104:107], v[8:9], off
	s_nop 0
	v_addc_co_u32_e32 v29, vcc, 0, v5, vcc
	global_load_dwordx4 v[76:79], v[12:13], off
	global_load_dwordx4 v[80:83], v[14:15], off
	v_add_co_u32_e32 v30, vcc, 0x60000, v4
	global_load_dwordx4 v[84:87], v[24:25], off
	global_load_dwordx4 v[88:91], v[26:27], off
	v_addc_co_u32_e32 v31, vcc, 0, v5, vcc
	v_add_co_u32_e32 v32, vcc, 0x70000, v4
	global_load_dwordx4 v[92:95], v[28:29], off
	global_load_dwordx4 v[96:99], v[30:31], off
	v_addc_co_u32_e32 v33, vcc, 0, v5, vcc
	v_add_co_u32_e32 v120, vcc, s81, v8
	s_mov_b32 s10, 0x20000
	s_nop 0
	v_addc_co_u32_e32 v121, vcc, 0, v9, vcc
	global_load_dwordx4 v[100:103], v[32:33], off
	global_load_dwordx4 v[108:111], v[120:121], off
	v_add_co_u32_e32 v122, vcc, s10, v8
	s_mov_b32 s10, 0x30000
	s_nop 0
	v_addc_co_u32_e32 v123, vcc, 0, v9, vcc
	global_load_dwordx4 v[112:115], v[122:123], off
	v_add_co_u32_e32 v124, vcc, s10, v8
	s_mov_b32 s10, 0
	s_nop 0
	v_addc_co_u32_e32 v125, vcc, 0, v9, vcc
	global_load_dwordx4 v[116:119], v[124:125], off
	s_nop 0
	global_load_dwordx4 v[250:253], v[4:5], off offset:128
	s_nop 0
	global_load_dwordx4 v[218:221], v[8:9], off offset:128
	s_nop 0
	global_load_dwordx4 v[246:249], v[12:13], off offset:128
	global_load_dwordx4 v[242:245], v[14:15], off offset:128
	s_nop 0
	global_load_dwordx4 v[238:241], v[24:25], off offset:128
	global_load_dwordx4 v[234:237], v[26:27], off offset:128
	global_load_dwordx4 v[230:233], v[28:29], off offset:128
	global_load_dwordx4 v[226:229], v[30:31], off offset:128
	s_nop 0
	global_load_dwordx4 v[222:225], v[32:33], off offset:128
	s_nop 0
	global_load_dwordx4 v[214:217], v[120:121], off offset:128
	global_load_dwordx4 v[210:213], v[122:123], off offset:128
	s_and_b32 s73, s11, 0xffff
	v_accvgpr_write_b32 a47, 0
	v_accvgpr_write_b32 a46, 0
	v_accvgpr_write_b32 a45, 0
	v_accvgpr_write_b32 a44, 0
	v_accvgpr_write_b32 a43, 0
	v_accvgpr_write_b32 a42, 0
	v_accvgpr_write_b32 a41, 0
	v_accvgpr_write_b32 a40, 0
	v_accvgpr_write_b32 a39, 0
	v_accvgpr_write_b32 a38, 0
	v_accvgpr_write_b32 a37, 0
	v_accvgpr_write_b32 a36, 0
	v_accvgpr_write_b32 a35, 0
	v_accvgpr_write_b32 a34, 0
	v_accvgpr_write_b32 a33, 0
	v_accvgpr_write_b32 a32, 0
	v_accvgpr_write_b32 a63, 0
	v_accvgpr_write_b32 a62, 0
	v_accvgpr_write_b32 a61, 0
	v_accvgpr_write_b32 a60, 0
	v_accvgpr_write_b32 a59, 0
	v_accvgpr_write_b32 a58, 0
	v_accvgpr_write_b32 a57, 0
	v_accvgpr_write_b32 a56, 0
	v_accvgpr_write_b32 a55, 0
	v_accvgpr_write_b32 a54, 0
	s_waitcnt vmcnt(22)
	ds_write_b128 v130, v[0:3]
	s_waitcnt vmcnt(21)
	ds_write_b128 v130, v[104:107] offset:36864
	s_waitcnt vmcnt(20)
	ds_write_b128 v130, v[76:79] offset:4608
	s_waitcnt vmcnt(19)
	ds_write_b128 v130, v[80:83] offset:9216
	s_waitcnt vmcnt(18)
	ds_write_b128 v130, v[84:87] offset:13824
	s_waitcnt vmcnt(17)
	ds_write_b128 v130, v[88:91] offset:18432
	s_waitcnt vmcnt(16)
	ds_write_b128 v130, v[92:95] offset:23040
	s_waitcnt vmcnt(15)
	ds_write_b128 v130, v[96:99] offset:27648
	s_waitcnt vmcnt(14)
	ds_write_b128 v130, v[100:103] offset:32256
	s_waitcnt vmcnt(13)
	ds_write_b128 v130, v[108:111] offset:41472
	s_waitcnt vmcnt(12)
	ds_write_b128 v130, v[112:115] offset:46080
	global_load_dwordx4 v[206:209], v[124:125], off offset:128
	v_lshl_add_u64 v[0:1], v[74:75], 0, s[4:5]
	v_lshl_add_u64 v[2:3], v[74:75], 0, s[8:9]
	v_accvgpr_write_b32 a53, 0
	v_accvgpr_write_b32 a52, 0
	v_accvgpr_write_b32 a51, 0
	v_accvgpr_write_b32 a50, 0
	v_accvgpr_write_b32 a49, 0
	v_accvgpr_write_b32 a48, 0
	v_accvgpr_write_b32 a79, 0
	v_accvgpr_write_b32 a78, 0
	v_accvgpr_write_b32 a77, 0
	v_accvgpr_write_b32 a76, 0
	v_accvgpr_write_b32 a75, 0
	v_accvgpr_write_b32 a74, 0
	v_accvgpr_write_b32 a73, 0
	v_accvgpr_write_b32 a72, 0
	v_accvgpr_write_b32 a71, 0
	v_accvgpr_write_b32 a70, 0
	v_accvgpr_write_b32 a69, 0
	v_accvgpr_write_b32 a68, 0
	v_accvgpr_write_b32 a67, 0
	v_accvgpr_write_b32 a66, 0
	v_accvgpr_write_b32 a65, 0
	v_accvgpr_write_b32 a64, 0
	v_accvgpr_write_b32 a111, 0
	v_accvgpr_write_b32 a110, 0
	v_accvgpr_write_b32 a109, 0
	v_accvgpr_write_b32 a108, 0
	v_accvgpr_write_b32 a107, 0
	v_accvgpr_write_b32 a106, 0
	v_accvgpr_write_b32 a105, 0
	v_accvgpr_write_b32 a104, 0
	v_accvgpr_write_b32 a103, 0
	v_accvgpr_write_b32 a102, 0
	v_accvgpr_write_b32 a101, 0
	v_accvgpr_write_b32 a100, 0
	v_accvgpr_write_b32 a99, 0
	v_accvgpr_write_b32 a98, 0
	v_accvgpr_write_b32 a97, 0
	v_accvgpr_write_b32 a96, 0
	v_accvgpr_write_b32 a95, 0
	v_accvgpr_write_b32 a94, 0
	v_accvgpr_write_b32 a93, 0
	v_accvgpr_write_b32 a92, 0
	v_accvgpr_write_b32 a91, 0
	v_accvgpr_write_b32 a90, 0
	v_accvgpr_write_b32 a89, 0
	v_accvgpr_write_b32 a88, 0
	v_accvgpr_write_b32 a87, 0
	v_accvgpr_write_b32 a86, 0
	v_accvgpr_write_b32 a85, 0
	v_accvgpr_write_b32 a84, 0
	v_accvgpr_write_b32 a83, 0
	v_accvgpr_write_b32 a82, 0
	v_accvgpr_write_b32 a81, 0
	v_accvgpr_write_b32 a80, 0
	v_accvgpr_write_b32 a127, 0
	v_accvgpr_write_b32 a126, 0
	v_accvgpr_write_b32 a125, 0
	v_accvgpr_write_b32 a124, 0
	v_accvgpr_write_b32 a123, 0
	v_accvgpr_write_b32 a122, 0
	v_accvgpr_write_b32 a121, 0
	v_accvgpr_write_b32 a120, 0
	v_accvgpr_write_b32 a119, 0
	v_accvgpr_write_b32 a118, 0
	v_accvgpr_write_b32 a117, 0
	v_accvgpr_write_b32 a116, 0
	v_accvgpr_write_b32 a115, 0
	v_accvgpr_write_b32 a114, 0
	v_accvgpr_write_b32 a113, 0
	v_accvgpr_write_b32 a112, 0
	v_accvgpr_write_b32 a31, 0
	v_accvgpr_write_b32 a30, 0
	v_accvgpr_write_b32 a29, 0
	v_accvgpr_write_b32 a28, 0
	v_accvgpr_write_b32 a27, 0
	v_accvgpr_write_b32 a26, 0
	v_accvgpr_write_b32 a25, 0
	v_accvgpr_write_b32 a24, 0
	v_accvgpr_write_b32 a23, 0
	v_accvgpr_write_b32 a22, 0
	v_accvgpr_write_b32 a21, 0
	v_accvgpr_write_b32 a20, 0
	v_accvgpr_write_b32 a19, 0
	v_accvgpr_write_b32 a18, 0
	v_accvgpr_write_b32 a17, 0
	v_accvgpr_write_b32 a16, 0
	v_accvgpr_write_b32 a15, 0
	v_accvgpr_write_b32 a14, 0
	v_accvgpr_write_b32 a13, 0
	v_accvgpr_write_b32 a12, 0
	v_accvgpr_write_b32 a11, 0
	v_accvgpr_write_b32 a10, 0
	v_accvgpr_write_b32 a9, 0
	v_accvgpr_write_b32 a8, 0
	v_accvgpr_write_b32 a7, 0
	v_accvgpr_write_b32 a6, 0
	v_accvgpr_write_b32 a5, 0
	v_accvgpr_write_b32 a4, 0
	v_accvgpr_write_b32 a3, 0
	v_accvgpr_write_b32 a2, 0
	v_accvgpr_write_b32 a1, 0
	v_accvgpr_write_b32 a0, 0
	s_mov_b64 s[8:9], 0
	s_waitcnt vmcnt(12)
	ds_write_b128 v130, v[116:119] offset:50688
	s_waitcnt lgkmcnt(0)
	s_barrier
	s_waitcnt vmcnt(0)
	v_readfirstlane_b32 s100, v0
	v_readfirstlane_b32 s101, v1
	v_readfirstlane_b32 s98, v2
	v_readfirstlane_b32 s99, v3
	s_nop 1
	v_subrev_u32_e32 v194, s100, v0
	v_subrev_u32_e32 v193, s98, v2
	v_add_u32_e32 v254, 0x126fa000, v194
	v_add_u32_e32 v205, 0x1270a000, v194
	v_add_u32_e32 v204, 0x1271a000, v194
	v_add_u32_e32 v203, 0x1272a000, v194
	v_add_u32_e32 v202, s82, v194
	v_add_u32_e32 v201, s83, v194
	v_add_u32_e32 v200, s84, v194
	v_add_u32_e32 v199, s85, v194
	v_add_u32_e32 v198, s86, v193
	v_add_u32_e32 v197, s87, v193
	v_add_u32_e32 v196, s88, v193
	v_add_u32_e32 v195, s89, v193
	s_add_u32 s100, s100, s8
	s_addc_u32 s101, s101, s9
	s_add_u32 s98, s98, s8
	s_addc_u32 s99, s99, s9
	v_add_u32_e32 v192, v49, v131
	v_add_u32_e32 v191, v49, v132
	v_add_u32_e32 v190, v49, v133
	s_and_b32 s4, s10, 1
	s_mul_i32 s11, s4, 0xd800
	v_add_u32_e32 v189, s11, v192
	v_add_u32_e32 v188, s11, v191
	v_add_u32_e32 v187, s11, v190
	ds_read_b128 v[80:83], v189
	ds_read_b128 v[4:7], v187 offset:36864
	ds_read_b128 v[84:87], v189 offset:4608
	ds_read_b128 v[8:11], v187 offset:41472
	ds_read_b128 v[88:91], v189 offset:9216
	ds_read_b128 v[92:95], v188
	s_getreg_b32 s4, hwreg(HW_REG_HW_ID, 4, 1)
	s_cmp_lg_u32 s4, 0
	s_cbranch_scc1 xg5_varB_7
.LBB0_2161:
	s_and_b32 s4, s10, 1
	s_mul_i32 s11, s4, 0xd800
	s_xor_b32 s4, s4, 1
	s_mul_i32 s4, s4, 0xd800
	s_add_i32 s10, s10, 1
	v_add_u32_e32 v186, s4, v130
	ds_read_b128 v[12:15], v189 offset:32
	ds_read_b128 v[24:27], v187 offset:36896
	ds_read_b128 v[16:19], v189 offset:4640
	ds_read_b128 v[28:31], v187 offset:41504
	ds_read_b128 v[20:23], v189 offset:9248
	ds_read_b128 v[76:79], v188 offset:32
	s_waitcnt lgkmcnt(10)
	v_mfma_f32_32x32x16_bf16 a[32:47], v[80:83], v[4:7], a[32:47]
	s_waitcnt vmcnt(11)
	ds_write_b128 v186, v[250:253]
	s_waitcnt lgkmcnt(9)
	v_mfma_f32_32x32x16_bf16 a[48:63], v[80:83], v[8:11], a[48:63]
	s_waitcnt vmcnt(10)
	ds_write_b128 v186, v[246:249] offset:4608
	global_load_dwordx4 v[250:253], v254, s[100:101] offset:512
	v_mfma_f32_32x32x16_bf16 a[64:79], v[84:87], v[4:7], a[64:79]
	s_waitcnt vmcnt(10)
	ds_write_b128 v186, v[242:245] offset:9216
	global_load_dwordx4 v[246:249], v205, s[100:101] offset:512
	v_mfma_f32_32x32x16_bf16 a[96:111], v[84:87], v[8:11], a[96:111]
	s_waitcnt vmcnt(10)
	ds_write_b128 v186, v[238:241] offset:13824
	global_load_dwordx4 v[242:245], v204, s[100:101] offset:512
	s_waitcnt lgkmcnt(11)
	v_mfma_f32_32x32x16_bf16 a[80:95], v[88:91], v[4:7], a[80:95]
	s_waitcnt vmcnt(10)
	ds_write_b128 v186, v[234:237] offset:18432
	global_load_dwordx4 v[238:241], v203, s[100:101] offset:512
	v_mfma_f32_32x32x16_bf16 a[112:127], v[88:91], v[8:11], a[112:127]
	s_waitcnt vmcnt(10)
	ds_write_b128 v186, v[230:233] offset:23040
	global_load_dwordx4 v[234:237], v202, s[100:101] offset:512
	s_waitcnt lgkmcnt(12)
	v_mfma_f32_32x32x16_bf16 a[16:31], v[92:95], v[4:7], a[16:31]
	s_waitcnt vmcnt(10)
	ds_write_b128 v186, v[226:229] offset:27648
	global_load_dwordx4 v[230:233], v201, s[100:101] offset:512
	v_mfma_f32_32x32x16_bf16 a[0:15], v[92:95], v[8:11], a[0:15]
	s_waitcnt vmcnt(10)
	ds_write_b128 v186, v[222:225] offset:32256
	global_load_dwordx4 v[226:229], v200, s[100:101] offset:512
	ds_read_b128 v[80:83], v189 offset:64
	ds_read_b128 v[4:7], v187 offset:36928
	ds_read_b128 v[84:87], v189 offset:4672
	ds_read_b128 v[8:11], v187 offset:41536
	ds_read_b128 v[88:91], v189 offset:9280
	ds_read_b128 v[92:95], v188 offset:64
	s_waitcnt lgkmcnt(15)
	v_mfma_f32_32x32x16_bf16 a[32:47], v[12:15], v[24:27], a[32:47]
	s_waitcnt vmcnt(10)
	ds_write_b128 v186, v[218:221] offset:36864
	global_load_dwordx4 v[222:225], v199, s[100:101] offset:512
	v_mfma_f32_32x32x16_bf16 a[48:63], v[12:15], v[28:31], a[48:63]
	s_waitcnt vmcnt(10)
	ds_write_b128 v186, v[214:217] offset:41472
	global_load_dwordx4 v[218:221], v198, s[98:99] offset:256
	v_mfma_f32_32x32x16_bf16 a[64:79], v[16:19], v[24:27], a[64:79]
	s_waitcnt vmcnt(10)
	ds_write_b128 v186, v[210:213] offset:46080
	global_load_dwordx4 v[214:217], v197, s[98:99] offset:256
	v_mfma_f32_32x32x16_bf16 a[96:111], v[16:19], v[28:31], a[96:111]
	s_waitcnt vmcnt(10)
	ds_write_b128 v186, v[206:209] offset:50688
	global_load_dwordx4 v[210:213], v196, s[98:99] offset:256
	v_mfma_f32_32x32x16_bf16 a[80:95], v[20:23], v[24:27], a[80:95]
	global_load_dwordx4 v[206:209], v195, s[98:99] offset:256
	s_add_u32 s100, s100, 0x80
	s_addc_u32 s101, s101, 0
	s_add_u32 s98, s98, 0x80
	s_addc_u32 s99, s99, 0
	v_mfma_f32_32x32x16_bf16 a[112:127], v[20:23], v[28:31], a[112:127]
	s_waitcnt lgkmcnt(15)
	v_mfma_f32_32x32x16_bf16 a[16:31], v[76:79], v[24:27], a[16:31]
	v_mfma_f32_32x32x16_bf16 a[0:15], v[76:79], v[28:31], a[0:15]
	ds_read_b128 v[12:15], v189 offset:96
	ds_read_b128 v[24:27], v187 offset:36960
	ds_read_b128 v[16:19], v189 offset:4704
	ds_read_b128 v[28:31], v187 offset:41568
	ds_read_b128 v[20:23], v189 offset:9312
	ds_read_b128 v[76:79], v188 offset:96
	s_waitcnt lgkmcnt(14)
	v_mfma_f32_32x32x16_bf16 a[32:47], v[80:83], v[4:7], a[32:47]
	s_waitcnt lgkmcnt(12)
	v_mfma_f32_32x32x16_bf16 a[48:63], v[80:83], v[8:11], a[48:63]
	v_mfma_f32_32x32x16_bf16 a[64:79], v[84:87], v[4:7], a[64:79]
	v_mfma_f32_32x32x16_bf16 a[96:111], v[84:87], v[8:11], a[96:111]
	s_waitcnt lgkmcnt(11)
	v_mfma_f32_32x32x16_bf16 a[80:95], v[88:91], v[4:7], a[80:95]
	v_mfma_f32_32x32x16_bf16 a[112:127], v[88:91], v[8:11], a[112:127]
	s_waitcnt lgkmcnt(10)
	v_mfma_f32_32x32x16_bf16 a[16:31], v[92:95], v[4:7], a[16:31]
	v_mfma_f32_32x32x16_bf16 a[0:15], v[92:95], v[8:11], a[0:15]
	s_waitcnt lgkmcnt(0)
	v_mfma_f32_32x32x16_bf16 a[32:47], v[12:15], v[24:27], a[32:47]
	v_mfma_f32_32x32x16_bf16 a[48:63], v[12:15], v[28:31], a[48:63]
	v_mfma_f32_32x32x16_bf16 a[64:79], v[16:19], v[24:27], a[64:79]
	v_mfma_f32_32x32x16_bf16 a[96:111], v[16:19], v[28:31], a[96:111]
	s_barrier
	v_add_u32_e32 v189, s4, v192
	v_add_u32_e32 v188, s4, v191
	v_add_u32_e32 v187, s4, v190
	ds_read_b128 v[80:83], v189
	ds_read_b128 v[4:7], v187 offset:36864
	ds_read_b128 v[84:87], v189 offset:4608
	ds_read_b128 v[8:11], v187 offset:41472
	ds_read_b128 v[88:91], v189 offset:9216
	ds_read_b128 v[92:95], v188
	v_mfma_f32_32x32x16_bf16 a[80:95], v[20:23], v[24:27], a[80:95]
	v_mfma_f32_32x32x16_bf16 a[112:127], v[20:23], v[28:31], a[112:127]
	v_mfma_f32_32x32x16_bf16 a[16:31], v[76:79], v[24:27], a[16:31]
	v_mfma_f32_32x32x16_bf16 a[0:15], v[76:79], v[28:31], a[0:15]
	s_add_u32 s8, s8, 0x80
	s_addc_u32 s9, s9, 0
	s_cmpk_lg_i32 s8, 0x700
	s_cbranch_scc1 .LBB0_2161
	s_branch xg5_tail_7
xg5_varB_7:
	s_and_b32 s4, s10, 1
	s_mul_i32 s11, s4, 0xd800
	s_xor_b32 s4, s4, 1
	s_mul_i32 s4, s4, 0xd800
	s_add_i32 s10, s10, 1
	v_add_u32_e32 v186, s4, v130
	ds_read_b128 v[12:15], v189 offset:32
	ds_read_b128 v[24:27], v187 offset:36896
	ds_read_b128 v[16:19], v189 offset:4640
	ds_read_b128 v[28:31], v187 offset:41504
	ds_read_b128 v[20:23], v189 offset:9248
	ds_read_b128 v[76:79], v188 offset:32
	s_waitcnt lgkmcnt(10)
	v_mfma_f32_32x32x16_bf16 a[32:47], v[80:83], v[4:7], a[32:47]
	s_waitcnt lgkmcnt(8)
	v_mfma_f32_32x32x16_bf16 a[48:63], v[80:83], v[8:11], a[48:63]
	v_mfma_f32_32x32x16_bf16 a[64:79], v[84:87], v[4:7], a[64:79]
	v_mfma_f32_32x32x16_bf16 a[96:111], v[84:87], v[8:11], a[96:111]
	s_waitcnt lgkmcnt(7)
	v_mfma_f32_32x32x16_bf16 a[80:95], v[88:91], v[4:7], a[80:95]
	v_mfma_f32_32x32x16_bf16 a[112:127], v[88:91], v[8:11], a[112:127]
	s_waitcnt lgkmcnt(6)
	v_mfma_f32_32x32x16_bf16 a[16:31], v[92:95], v[4:7], a[16:31]
	v_mfma_f32_32x32x16_bf16 a[0:15], v[92:95], v[8:11], a[0:15]
	ds_read_b128 v[80:83], v189 offset:64
	ds_read_b128 v[4:7], v187 offset:36928
	ds_read_b128 v[84:87], v189 offset:4672
	ds_read_b128 v[8:11], v187 offset:41536
	ds_read_b128 v[88:91], v189 offset:9280
	ds_read_b128 v[92:95], v188 offset:64
	s_waitcnt lgkmcnt(10)
	v_mfma_f32_32x32x16_bf16 a[32:47], v[12:15], v[24:27], a[32:47]
	s_waitcnt lgkmcnt(8)
	v_mfma_f32_32x32x16_bf16 a[48:63], v[12:15], v[28:31], a[48:63]
	v_mfma_f32_32x32x16_bf16 a[64:79], v[16:19], v[24:27], a[64:79]
	v_mfma_f32_32x32x16_bf16 a[96:111], v[16:19], v[28:31], a[96:111]
	s_waitcnt lgkmcnt(7)
	v_mfma_f32_32x32x16_bf16 a[80:95], v[20:23], v[24:27], a[80:95]
	s_waitcnt vmcnt(11)
	ds_write_b128 v186, v[250:253]
	v_mfma_f32_32x32x16_bf16 a[112:127], v[20:23], v[28:31], a[112:127]
	s_waitcnt vmcnt(10)
	ds_write_b128 v186, v[246:249] offset:4608
	global_load_dwordx4 v[250:253], v254, s[100:101] offset:512
	s_waitcnt lgkmcnt(8)
	v_mfma_f32_32x32x16_bf16 a[16:31], v[76:79], v[24:27], a[16:31]
	s_waitcnt vmcnt(10)
	ds_write_b128 v186, v[242:245] offset:9216
	global_load_dwordx4 v[246:249], v205, s[100:101] offset:512
	v_mfma_f32_32x32x16_bf16 a[0:15], v[76:79], v[28:31], a[0:15]
	s_waitcnt vmcnt(10)
	ds_write_b128 v186, v[238:241] offset:13824
	global_load_dwordx4 v[242:245], v204, s[100:101] offset:512
	ds_read_b128 v[12:15], v189 offset:96
	ds_read_b128 v[24:27], v187 offset:36960
	ds_read_b128 v[16:19], v189 offset:4704
	ds_read_b128 v[28:31], v187 offset:41568
	ds_read_b128 v[20:23], v189 offset:9312
	ds_read_b128 v[76:79], v188 offset:96
	s_waitcnt lgkmcnt(14)
	v_mfma_f32_32x32x16_bf16 a[32:47], v[80:83], v[4:7], a[32:47]
	s_waitcnt vmcnt(10)
	ds_write_b128 v186, v[234:237] offset:18432
	global_load_dwordx4 v[238:241], v203, s[100:101] offset:512
	s_waitcnt lgkmcnt(13)
	v_mfma_f32_32x32x16_bf16 a[48:63], v[80:83], v[8:11], a[48:63]
	s_waitcnt vmcnt(10)
	ds_write_b128 v186, v[230:233] offset:23040
	global_load_dwordx4 v[234:237], v202, s[100:101] offset:512
	v_mfma_f32_32x32x16_bf16 a[64:79], v[84:87], v[4:7], a[64:79]
	s_waitcnt vmcnt(10)
	ds_write_b128 v186, v[226:229] offset:27648
	global_load_dwordx4 v[230:233], v201, s[100:101] offset:512
	v_mfma_f32_32x32x16_bf16 a[96:111], v[84:87], v[8:11], a[96:111]
	s_waitcnt vmcnt(10)
	ds_write_b128 v186, v[222:225] offset:32256
	global_load_dwordx4 v[226:229], v200, s[100:101] offset:512
	s_waitcnt lgkmcnt(15)
	v_mfma_f32_32x32x16_bf16 a[80:95], v[88:91], v[4:7], a[80:95]
	s_waitcnt vmcnt(10)
	ds_write_b128 v186, v[218:221] offset:36864
	global_load_dwordx4 v[222:225], v199, s[100:101] offset:512
	v_mfma_f32_32x32x16_bf16 a[112:127], v[88:91], v[8:11], a[112:127]
	s_waitcnt vmcnt(10)
	ds_write_b128 v186, v[214:217] offset:41472
	global_load_dwordx4 v[218:221], v198, s[98:99] offset:256
	s_waitcnt lgkmcnt(15)
	v_mfma_f32_32x32x16_bf16 a[16:31], v[92:95], v[4:7], a[16:31]
	s_waitcnt vmcnt(10)
	ds_write_b128 v186, v[210:213] offset:46080
	global_load_dwordx4 v[214:217], v197, s[98:99] offset:256
	v_mfma_f32_32x32x16_bf16 a[0:15], v[92:95], v[8:11], a[0:15]
	s_waitcnt vmcnt(10)
	ds_write_b128 v186, v[206:209] offset:50688
	global_load_dwordx4 v[210:213], v196, s[98:99] offset:256
	s_waitcnt lgkmcnt(0)
	v_mfma_f32_32x32x16_bf16 a[32:47], v[12:15], v[24:27], a[32:47]
	global_load_dwordx4 v[206:209], v195, s[98:99] offset:256
	s_add_u32 s100, s100, 0x80
	s_addc_u32 s101, s101, 0
	s_add_u32 s98, s98, 0x80
	s_addc_u32 s99, s99, 0
	v_mfma_f32_32x32x16_bf16 a[48:63], v[12:15], v[28:31], a[48:63]
	v_mfma_f32_32x32x16_bf16 a[64:79], v[16:19], v[24:27], a[64:79]
	v_mfma_f32_32x32x16_bf16 a[96:111], v[16:19], v[28:31], a[96:111]
	s_barrier
	v_add_u32_e32 v189, s4, v192
	v_add_u32_e32 v188, s4, v191
	v_add_u32_e32 v187, s4, v190
	ds_read_b128 v[80:83], v189
	ds_read_b128 v[4:7], v187 offset:36864
	ds_read_b128 v[84:87], v189 offset:4608
	ds_read_b128 v[8:11], v187 offset:41472
	ds_read_b128 v[88:91], v189 offset:9216
	ds_read_b128 v[92:95], v188
	v_mfma_f32_32x32x16_bf16 a[80:95], v[20:23], v[24:27], a[80:95]
	v_mfma_f32_32x32x16_bf16 a[112:127], v[20:23], v[28:31], a[112:127]
	v_mfma_f32_32x32x16_bf16 a[16:31], v[76:79], v[24:27], a[16:31]
	v_mfma_f32_32x32x16_bf16 a[0:15], v[76:79], v[28:31], a[0:15]
	s_add_u32 s8, s8, 0x80
	s_addc_u32 s9, s9, 0
	s_cmpk_lg_i32 s8, 0x700
	s_cbranch_scc1 xg5_varB_7
xg5_tail_7:
	ds_read_b128 v[0:3], v153
	ds_read_b128 v[80:83], v155 offset:36864
	ds_read_b128 v[84:87], v153 offset:4608
	ds_read_b128 v[88:91], v155 offset:41472
	s_lshl_b32 s75, s74, 8
	s_cmp_gt_u32 s74, 31
	s_waitcnt lgkmcnt(2)
	v_mfma_f32_32x32x16_bf16 a[176:191], v[0:3], v[80:83], a[32:47]
	s_cselect_b64 s[60:61], -1, 0
	s_add_i32 s4, s75, 0xffffe000
	s_lshr_b32 s4, s4, 12
	s_cmp_lt_u32 s74, 32
	s_cselect_b64 s[10:11], -1, 0
	s_and_b64 s[8:9], s[10:11], exec
	s_cselect_b32 s8, 32, 0xf00
	s_waitcnt lgkmcnt(0)
	v_mfma_f32_32x32x16_bf16 a[160:175], v[0:3], v[88:91], a[48:63]
	s_cselect_b32 s95, s74, s4
	s_and_b32 s94, s8, s75
	s_cmp_lt_u32 s73, 16
	s_cselect_b64 s[62:63], -1, 0
	s_mov_b64 s[8:9], -1
	s_and_b64 vcc, exec, s[62:63]
	v_mfma_f32_32x32x16_bf16 a[144:159], v[84:87], v[80:83], a[64:79]
	v_mfma_f32_32x32x16_bf16 a[128:143], v[84:87], v[88:91], a[96:111]
	ds_read_b128 v[0:3], v153 offset:9216
	ds_read_b128 v[84:87], v154
	s_waitcnt vmcnt(11)
	s_waitcnt vmcnt(0)
	ds_write_b128 v156, v[250:253] offset:55296
	s_waitcnt vmcnt(10)
	ds_write_b128 v156, v[246:249] offset:59904
	s_waitcnt vmcnt(9)
	ds_write_b128 v156, v[242:245] offset:64512
	s_waitcnt vmcnt(8)
	ds_write_b128 v55, v[238:241] offset:55296
	s_waitcnt vmcnt(7)
	ds_write_b128 v135, v[234:237] offset:55296
	s_waitcnt vmcnt(6)
	ds_write_b128 v137, v[230:233] offset:55296
	s_waitcnt vmcnt(5)
	ds_write_b128 v139, v[226:229] offset:55296
	s_waitcnt vmcnt(4)
	ds_write_b128 v146, v[222:225] offset:55296
	s_waitcnt vmcnt(3)
	ds_write_b128 v147, v[218:221]
	s_waitcnt vmcnt(2)
	ds_write_b128 v147, v[214:217] offset:4608
	s_waitcnt vmcnt(1)
	ds_write_b128 v147, v[210:213] offset:9216
	s_waitcnt vmcnt(0)
	ds_write_b128 v147, v[206:209] offset:13824
	s_waitcnt lgkmcnt(13)
	v_mfma_f32_32x32x16_bf16 a[64:79], v[0:3], v[80:83], a[80:95]
	v_mfma_f32_32x32x16_bf16 a[48:63], v[0:3], v[88:91], a[112:127]
	ds_read_b128 v[0:3], v153 offset:32
	ds_read_b128 v[4:7], v155 offset:36896
	ds_read_b128 v[8:11], v155 offset:36928
	ds_read_b128 v[12:15], v153 offset:64
	ds_read_b128 v[16:19], v155 offset:41504
	ds_read_b128 v[20:23], v155 offset:36960
	s_waitcnt lgkmcnt(4)
	v_mfma_f32_32x32x16_bf16 a[176:191], v[0:3], v[4:7], a[176:191]
	s_waitcnt lgkmcnt(1)
	v_mfma_f32_32x32x16_bf16 a[160:175], v[0:3], v[16:19], a[160:175]
	ds_read_b128 v[0:3], v153 offset:4640
	ds_read_b128 v[24:27], v153 offset:96
	v_mfma_f32_32x32x16_bf16 a[32:47], v[84:87], v[80:83], a[16:31]
	v_mfma_f32_32x32x16_bf16 a[16:31], v[84:87], v[88:91], a[0:15]
	s_waitcnt lgkmcnt(1)
	v_mfma_f32_32x32x16_bf16 a[144:159], v[0:3], v[4:7], a[144:159]
	v_mfma_f32_32x32x16_bf16 a[128:143], v[0:3], v[16:19], a[128:143]
	ds_read_b128 v[0:3], v153 offset:9248
	ds_read_b128 v[28:31], v153 offset:9280
	s_waitcnt lgkmcnt(1)
	v_mfma_f32_32x32x16_bf16 a[64:79], v[0:3], v[4:7], a[64:79]
	v_mfma_f32_32x32x16_bf16 a[48:63], v[0:3], v[16:19], a[48:63]
	ds_read_b128 v[0:3], v154 offset:32
	ds_read_b128 v[32:35], v153 offset:9312
	s_waitcnt lgkmcnt(1)
	v_mfma_f32_32x32x16_bf16 a[32:47], v[0:3], v[4:7], a[32:47]
	v_mfma_f32_32x32x16_bf16 a[16:31], v[0:3], v[16:19], a[16:31]
	ds_read_b128 v[0:3], v155 offset:41536
	ds_read_b128 v[4:7], v155 offset:41568
	v_mfma_f32_32x32x16_bf16 a[176:191], v[12:15], v[8:11], a[176:191]
	s_waitcnt lgkmcnt(1)
	v_mfma_f32_32x32x16_bf16 a[160:175], v[12:15], v[0:3], a[160:175]
	ds_read_b128 v[12:15], v153 offset:4672
	ds_read_b128 v[16:19], v153 offset:4704
	s_waitcnt lgkmcnt(1)
	v_mfma_f32_32x32x16_bf16 a[144:159], v[12:15], v[8:11], a[144:159]
	v_mfma_f32_32x32x16_bf16 a[128:143], v[12:15], v[0:3], a[128:143]
	v_mfma_f32_32x32x16_bf16 a[64:79], v[28:31], v[8:11], a[64:79]
	v_mfma_f32_32x32x16_bf16 a[48:63], v[28:31], v[0:3], a[48:63]
	ds_read_b128 v[12:15], v154 offset:64
	ds_read_b128 v[28:31], v154 offset:96
	s_waitcnt lgkmcnt(0)
	s_barrier
	v_mfma_f32_32x32x16_bf16 a[32:47], v[12:15], v[8:11], a[32:47]
	v_mfma_f32_32x32x16_bf16 a[16:31], v[12:15], v[0:3], a[16:31]
	v_mfma_f32_32x32x16_bf16 a[176:191], v[24:27], v[20:23], a[176:191]
	v_mfma_f32_32x32x16_bf16 a[160:175], v[24:27], v[4:7], a[160:175]
	v_mfma_f32_32x32x16_bf16 a[144:159], v[16:19], v[20:23], a[144:159]
	v_mfma_f32_32x32x16_bf16 a[128:143], v[16:19], v[4:7], a[128:143]
	v_mfma_f32_32x32x16_bf16 a[64:79], v[32:35], v[20:23], a[64:79]
	v_mfma_f32_32x32x16_bf16 a[48:63], v[32:35], v[4:7], a[48:63]
	v_mfma_f32_32x32x16_bf16 a[32:47], v[28:31], v[20:23], a[32:47]
	v_mfma_f32_32x32x16_bf16 a[16:31], v[28:31], v[4:7], a[16:31]
	ds_read_b128 v[0:3], v153 offset:55296
	ds_read_b128 v[4:7], v148
	ds_read_b128 v[8:11], v153 offset:55328
	ds_read_b128 v[12:15], v148 offset:32
	ds_read_b128 v[16:19], v148 offset:4608
	ds_read_b128 v[20:23], v148 offset:4640
	s_waitcnt lgkmcnt(4)
	v_mfma_f32_32x32x16_bf16 a[176:191], v[0:3], v[4:7], a[176:191]
	s_waitcnt lgkmcnt(1)
	v_mfma_f32_32x32x16_bf16 a[160:175], v[0:3], v[16:19], a[160:175]
	ds_read_b128 v[0:3], v153 offset:59904
	ds_read_b128 v[24:27], v153 offset:59936
	s_waitcnt lgkmcnt(1)
	v_mfma_f32_32x32x16_bf16 a[144:159], v[0:3], v[4:7], a[144:159]
	v_mfma_f32_32x32x16_bf16 a[128:143], v[0:3], v[16:19], a[128:143]
	ds_read_b128 v[0:3], v153 offset:64512
	ds_read_b128 v[28:31], v153 offset:64544
	s_waitcnt lgkmcnt(1)
	v_mfma_f32_32x32x16_bf16 a[64:79], v[0:3], v[4:7], a[64:79]
	v_mfma_f32_32x32x16_bf16 a[48:63], v[0:3], v[16:19], a[48:63]
	ds_read_b128 v[0:3], v154 offset:55296
	ds_read_b128 v[32:35], v154 offset:55328
	s_waitcnt lgkmcnt(1)
	v_mfma_f32_32x32x16_bf16 a[32:47], v[0:3], v[4:7], a[32:47]
	v_mfma_f32_32x32x16_bf16 a[16:31], v[0:3], v[16:19], a[16:31]
	ds_read_b128 v[0:3], v153 offset:55360
	v_mfma_f32_32x32x16_bf16 a[176:191], v[8:11], v[12:15], a[176:191]
	v_mfma_f32_32x32x16_bf16 a[160:175], v[8:11], v[20:23], a[160:175]
	v_mfma_f32_32x32x16_bf16 a[144:159], v[24:27], v[12:15], a[144:159]
	v_mfma_f32_32x32x16_bf16 a[128:143], v[24:27], v[20:23], a[128:143]
	v_mfma_f32_32x32x16_bf16 a[64:79], v[28:31], v[12:15], a[64:79]
	v_mfma_f32_32x32x16_bf16 a[48:63], v[28:31], v[20:23], a[48:63]
	ds_read_b128 v[4:7], v148 offset:64
	ds_read_b128 v[8:11], v154 offset:55360
	ds_read_b128 v[16:19], v154 offset:55392
	ds_read_b128 v[24:27], v153 offset:64576
	ds_read_b128 v[28:31], v153 offset:64608
	ds_read_b128 v[36:39], v153 offset:55392
	ds_read_b128 v[40:43], v148 offset:96
	ds_read_b128 v[44:47], v153 offset:59968
	ds_read_b128 v[76:79], v153 offset:60000
	ds_read_b128 v[80:83], v148 offset:4672
	ds_read_b128 v[84:87], v148 offset:4704
	s_waitcnt lgkmcnt(0)
	s_barrier
	v_mfma_f32_32x32x16_bf16 a[32:47], v[32:35], v[12:15], a[32:47]
	v_mfma_f32_32x32x16_bf16 a[16:31], v[32:35], v[20:23], a[16:31]
	v_mfma_f32_32x32x16_bf16 a[176:191], v[0:3], v[4:7], a[176:191]
	v_mfma_f32_32x32x16_bf16 a[160:175], v[0:3], v[80:83], a[160:175]
	v_mfma_f32_32x32x16_bf16 a[144:159], v[44:47], v[4:7], a[144:159]
	v_mfma_f32_32x32x16_bf16 a[128:143], v[44:47], v[80:83], a[128:143]
	v_mfma_f32_32x32x16_bf16 a[64:79], v[24:27], v[4:7], a[64:79]
	v_mfma_f32_32x32x16_bf16 a[48:63], v[24:27], v[80:83], a[48:63]
	v_mfma_f32_32x32x16_bf16 a[32:47], v[8:11], v[4:7], a[32:47]
	v_mfma_f32_32x32x16_bf16 a[16:31], v[8:11], v[80:83], a[16:31]
	v_mfma_f32_32x32x16_bf16 a[176:191], v[36:39], v[40:43], a[176:191]
	s_nop 11
	ds_write_b32 v136, a176
	ds_write_b32 v136, a177 offset:516
	ds_write_b32 v136, a178 offset:1032
	ds_write_b32 v136, a179 offset:1548
	ds_write_b32 v136, a180 offset:4128
	ds_write_b32 v136, a181 offset:4644
	ds_write_b32 v136, a182 offset:5160
	v_mfma_f32_32x32x16_bf16 a[160:175], v[36:39], v[84:87], a[160:175]
	ds_write_b32 v136, a183 offset:5676
	ds_write_b32 v136, a184 offset:8256
	ds_write_b32 v136, a185 offset:8772
	ds_write_b32 v136, a186 offset:9288
	ds_write_b32 v136, a187 offset:9804
	ds_write_b32 v136, a188 offset:12384
	ds_write_b32 v136, a189 offset:12900
	ds_write_b32 v136, a190 offset:13416
	ds_write_b32 v136, a191 offset:13932
	s_nop 2
	ds_write_b32 v136, a160 offset:128
	ds_write_b32 v136, a161 offset:644
	ds_write_b32 v136, a162 offset:1160
	ds_write_b32 v136, a163 offset:1676
	ds_write_b32 v136, a164 offset:4256
	ds_write_b32 v136, a165 offset:4772
	ds_write_b32 v136, a166 offset:5288
	ds_write_b32 v136, a167 offset:5804
	ds_write_b32 v136, a168 offset:8384
	ds_write_b32 v136, a169 offset:8900
	ds_write_b32 v136, a170 offset:9416
	ds_write_b32 v136, a171 offset:9932
	v_mfma_f32_32x32x16_bf16 a[144:159], v[76:79], v[40:43], a[144:159]
	ds_write_b32 v136, a172 offset:12512
	ds_write_b32 v136, a173 offset:13028
	ds_write_b32 v136, a174 offset:13544
	ds_write_b32 v136, a175 offset:14060
	s_nop 7
	ds_write_b32 v136, a144 offset:16512
	ds_write_b32 v136, a145 offset:17028
	ds_write_b32 v136, a146 offset:17544
	ds_write_b32 v136, a147 offset:18060
	ds_write_b32 v136, a148 offset:20640
	ds_write_b32 v136, a149 offset:21156
	ds_write_b32 v136, a150 offset:21672
	ds_write_b32 v136, a151 offset:22188
	ds_write_b32 v136, a152 offset:24768
	ds_write_b32 v136, a153 offset:25284
	v_mfma_f32_32x32x16_bf16 a[128:143], v[76:79], v[84:87], a[128:143]
	v_lshlrev_b32_e32 v76, 1, v48
	ds_write_b32 v136, a154 offset:25800
	ds_write_b32 v136, a155 offset:26316
	ds_write_b32 v136, a156 offset:28896
	ds_write_b32 v136, a157 offset:29412
	ds_write_b32 v136, a158 offset:29928
	ds_write_b32 v136, a159 offset:30444
	s_nop 4
	ds_write_b32 v136, a128 offset:16640
	ds_write_b32 v136, a129 offset:17156
	ds_write_b32 v136, a130 offset:17672
	ds_write_b32 v136, a131 offset:18188
	ds_write_b32 v136, a132 offset:20768
	ds_write_b32 v136, a133 offset:21284
	ds_write_b32 v136, a134 offset:21800
	ds_write_b32 v136, a135 offset:22316
	v_mfma_f32_32x32x16_bf16 a[64:79], v[28:31], v[40:43], a[64:79]
	ds_write_b32 v136, a136 offset:24896
	ds_write_b32 v136, a137 offset:25412
	ds_write_b32 v136, a138 offset:25928
	ds_write_b32 v136, a139 offset:26444
	ds_write_b32 v136, a140 offset:29024
	ds_write_b32 v136, a141 offset:29540
	ds_write_b32 v136, a142 offset:30056
	ds_write_b32 v136, a143 offset:30572
	s_nop 3
	ds_write_b32 v136, a64 offset:33024
	ds_write_b32 v136, a65 offset:33540
	ds_write_b32 v136, a66 offset:34056
	ds_write_b32 v136, a67 offset:34572
	ds_write_b32 v136, a68 offset:37152
	ds_write_b32 v136, a69 offset:37668
	v_mfma_f32_32x32x16_bf16 a[48:63], v[28:31], v[84:87], a[48:63]
	ds_write_b32 v136, a70 offset:38184
	ds_write_b32 v136, a71 offset:38700
	ds_write_b32 v136, a72 offset:41280
	ds_write_b32 v136, a73 offset:41796
	ds_write_b32 v136, a74 offset:42312
	ds_write_b32 v136, a75 offset:42828
	ds_write_b32 v136, a76 offset:45408
	ds_write_b32 v136, a77 offset:45924
	ds_write_b32 v136, a78 offset:46440
	ds_write_b32 v136, a79 offset:46956
	s_nop 1
	ds_write_b32 v136, a48 offset:33152
	ds_write_b32 v136, a49 offset:33668
	ds_write_b32 v136, a50 offset:34184
	ds_write_b32 v136, a51 offset:34700
	ds_write_b32 v136, a52 offset:37280
	ds_write_b32 v136, a53 offset:37796
	ds_write_b32 v136, a54 offset:38312
	ds_write_b32 v136, a55 offset:38828
	ds_write_b32 v136, a56 offset:41408
	ds_write_b32 v136, a57 offset:41924
	ds_write_b32 v136, a58 offset:42440
	v_mfma_f32_32x32x16_bf16 a[32:47], v[16:19], v[40:43], a[32:47]
	ds_write_b32 v136, a59 offset:42956
	ds_write_b32 v136, a60 offset:45536
	ds_write_b32 v136, a61 offset:46052
	ds_write_b32 v136, a62 offset:46568
	ds_write_b32 v136, a63 offset:47084
	s_nop 6
	ds_write_b32 v136, a32 offset:49536
	ds_write_b32 v136, a33 offset:50052
	ds_write_b32 v136, a34 offset:50568
	ds_write_b32 v136, a35 offset:51084
	ds_write_b32 v136, a36 offset:53664
	ds_write_b32 v136, a37 offset:54180
	ds_write_b32 v136, a38 offset:54696
	ds_write_b32 v136, a39 offset:55212
	ds_write_b32 v136, a40 offset:57792
	v_mfma_f32_32x32x16_bf16 a[16:31], v[16:19], v[84:87], a[16:31]
	ds_write_b32 v136, a41 offset:58308
	ds_write_b32 v136, a42 offset:58824
	ds_write_b32 v136, a43 offset:59340
	ds_write_b32 v136, a44 offset:61920
	ds_write_b32 v136, a45 offset:62436
	ds_write_b32 v136, a46 offset:62952
	ds_write_b32 v136, a47 offset:63468
	s_nop 4
	ds_write_b32 v136, a16 offset:49664
	ds_write_b32 v136, a17 offset:50180
	ds_write_b32 v136, a18 offset:50696
	ds_write_b32 v136, a19 offset:51212
	ds_write_b32 v136, a20 offset:53792
	ds_write_b32 v136, a21 offset:54308
	ds_write_b32 v136, a22 offset:54824
	ds_write_b32 v136, a23 offset:55340
	ds_write_b32 v136, a24 offset:57920
	ds_write_b32 v136, a25 offset:58436
	ds_write_b32 v136, a26 offset:58952
	ds_write_b32 v136, a27 offset:59468
	ds_write_b32 v136, a28 offset:62048
	ds_write_b32 v136, a29 offset:62564
	ds_write_b32 v136, a30 offset:63080
	ds_write_b32 v136, a31 offset:63596
	s_waitcnt lgkmcnt(0)
	s_barrier
	s_cbranch_vccz .LBB0_2179
	v_accvgpr_read_b32 v1, a210
	v_add_u32_e32 v4, s94, v1
	v_add_u32_e32 v0, s75, v1
	v_lshrrev_b32_e32 v1, 6, v4
	v_accvgpr_read_b32 v2, a211
	s_cmp_gt_u32 s73, 7
	v_cndmask_b32_e64 v1, v2, v1, s[6:7]
	s_cselect_b64 s[64:65], -1, 0
	s_add_i32 s8, s73, -8
	v_lshlrev_b32_e32 v50, 7, v1
	s_lshl_b32 s4, s95, 3
	v_mov_b32_e32 v1, v51
	s_add_i32 s68, s4, s8
	s_lshl_b32 s4, s95, 9
	v_add_u32_e32 v2, 0x100, v4
	v_mov_b32_e32 v3, v51
	s_mov_b32 s9, s5
	v_lshlrev_b64 v[0:1], 11, v[0:1]
	s_ashr_i32 s69, s68, 31
	v_lshl_add_u64 v[2:3], v[2:3], 0, s[4:5]
	s_lshl_b64 s[8:9], s[8:9], 1
	v_lshl_add_u64 v[0:1], s[14:15], 0, v[0:1]
	s_lshl_b32 s4, s73, 8
	v_lshl_add_u64 v[80:81], v[2:3], 4, s[8:9]
	v_lshl_add_u64 v[0:1], v[0:1], 0, s[4:5]
	v_mov_b32_e32 v77, v51
	s_lshl_b64 s[8:9], s[68:69], 16
	v_lshl_add_u64 v[82:83], v[0:1], 0, v[76:77]
	v_lshlrev_b32_e32 v0, 7, v4
	v_mov_b32_e32 v1, v51
	v_lshl_add_u64 v[2:3], v[62:63], 0, s[8:9]
	v_lshl_add_u64 v[84:85], v[2:3], 0, v[0:1]
	v_and_b32_e32 v1, 64, v157
	v_xor_b32_e32 v0, 1, v157
	v_add_u32_e32 v1, 64, v1
	v_cmp_lt_i32_e32 vcc, v0, v1
	v_lshl_add_u64 v[78:79], s[12:13], 0, v[50:51]
	s_lshl_b64 s[66:67], s[68:69], 1
	v_cndmask_b32_e32 v0, v157, v0, vcc
	v_mov_b32_e32 v50, v4
	s_mov_b32 s4, 0
	v_lshlrev_b32_e32 v77, 2, v0
	s_mov_b64 s[68:69], -1
	s_branch .LBB0_2166

.LBB0_2448:
	s_lshr_b32 s48, s47, 3
	s_lshl_b32 s42, s48, 18
	s_add_i32 s42, s69, s42
	v_lshl_add_u64 v[10:11], s[42:43], 1, v[8:9]
	s_and_b32 s42, s46, 7
	s_lshl_b32 s42, s42, 18
	s_add_i32 s48, s48, s66
	v_lshl_add_u64 v[12:13], v[8:9], 0, s[42:43]
	s_lshl_b32 s42, s48, 19
	v_lshl_add_u64 v[14:15], v[2:3], 0, s[42:43]
	v_add_co_u32_e32 v16, vcc, s70, v14
	s_and_b32 s49, s47, 7
	s_nop 0
	v_addc_co_u32_e32 v17, vcc, 0, v15, vcc
	v_add_co_u32_e32 v18, vcc, s71, v14
	s_lshl_b32 s42, s49, 18
	s_nop 0
	v_addc_co_u32_e32 v19, vcc, 0, v15, vcc
	v_add_co_u32_e32 v76, vcc, s72, v14
	v_lshl_add_u64 v[90:91], v[4:5], 0, s[42:43]
	s_nop 0
	v_addc_co_u32_e32 v77, vcc, 0, v15, vcc
	v_add_co_u32_e32 v78, vcc, s73, v14
	global_load_dwordx4 v[108:111], v[14:15], off
	global_load_dwordx4 v[112:115], v[16:17], off
	v_addc_co_u32_e32 v79, vcc, 0, v15, vcc
	v_add_co_u32_e32 v80, vcc, s74, v14
	global_load_dwordx4 v[116:119], v[18:19], off
	global_load_dwordx4 v[120:123], v[76:77], off
	v_addc_co_u32_e32 v81, vcc, 0, v15, vcc
	v_add_co_u32_e32 v82, vcc, s75, v14
	global_load_dwordx4 v[124:127], v[78:79], off
	global_load_dwordx4 v[128:131], v[80:81], off
	v_addc_co_u32_e32 v83, vcc, 0, v15, vcc
	v_add_co_u32_e32 v88, vcc, s77, v14
	global_load_dwordx4 v[132:135], v[82:83], off
	s_nop 0
	v_addc_co_u32_e32 v89, vcc, 0, v15, vcc
	v_add_co_u32_e32 v92, vcc, s70, v90
	global_load_dwordx4 v[140:143], v[88:89], off
	s_nop 0
	v_addc_co_u32_e32 v93, vcc, 0, v91, vcc
	v_add_co_u32_e32 v104, vcc, s71, v90
	global_load_dwordx4 v[144:147], v[90:91], off
	global_load_dwordx4 v[148:151], v[92:93], off
	v_addc_co_u32_e32 v105, vcc, 0, v91, vcc
	v_add_co_u32_e32 v106, vcc, s72, v90
	global_load_dwordx4 v[152:155], v[104:105], off
	s_nop 0
	v_addc_co_u32_e32 v107, vcc, 0, v91, vcc
	global_load_dwordx4 v[156:159], v[106:107], off
	global_load_dwordx4 v[250:253], v[14:15], off offset:128
	global_load_dwordx4 v[246:249], v[16:17], off offset:128
	global_load_dwordx4 v[242:245], v[18:19], off offset:128
	s_nop 0
	global_load_dwordx4 v[238:241], v[76:77], off offset:128
	global_load_dwordx4 v[234:237], v[78:79], off offset:128
	global_load_dwordx4 v[230:233], v[80:81], off offset:128
	s_nop 0
	global_load_dwordx4 v[226:229], v[82:83], off offset:128
	s_nop 0
	global_load_dwordx4 v[222:225], v[88:89], off offset:128
	global_load_dwordx4 v[218:221], v[90:91], off offset:128
	s_nop 0
	global_load_dwordx4 v[214:217], v[92:93], off offset:128
	s_nop 0
	global_load_dwordx4 v[210:213], v[104:105], off offset:128
	s_nop 0
	global_load_dwordx4 v[206:209], v[106:107], off offset:128
	s_mov_b32 s42, 0
	v_accvgpr_write_b32 a47, 0
	v_accvgpr_write_b32 a46, 0
	v_accvgpr_write_b32 a45, 0
	v_accvgpr_write_b32 a44, 0
	v_accvgpr_write_b32 a43, 0
	v_accvgpr_write_b32 a42, 0
	v_accvgpr_write_b32 a41, 0
	v_accvgpr_write_b32 a40, 0
	v_accvgpr_write_b32 a39, 0
	v_accvgpr_write_b32 a38, 0
	v_accvgpr_write_b32 a37, 0
	v_accvgpr_write_b32 a36, 0
	v_accvgpr_write_b32 a35, 0
	v_accvgpr_write_b32 a34, 0
	v_accvgpr_write_b32 a33, 0
	v_accvgpr_write_b32 a32, 0
	v_accvgpr_write_b32 a63, 0
	v_accvgpr_write_b32 a62, 0
	v_accvgpr_write_b32 a61, 0
	v_accvgpr_write_b32 a60, 0
	v_accvgpr_write_b32 a59, 0
	v_accvgpr_write_b32 a58, 0
	v_accvgpr_write_b32 a57, 0
	v_accvgpr_write_b32 a56, 0
	v_accvgpr_write_b32 a55, 0
	v_accvgpr_write_b32 a54, 0
	v_accvgpr_write_b32 a53, 0
	v_accvgpr_write_b32 a52, 0
	v_accvgpr_write_b32 a51, 0
	v_accvgpr_write_b32 a50, 0
	v_accvgpr_write_b32 a49, 0
	v_accvgpr_write_b32 a48, 0
	v_accvgpr_write_b32 a79, 0
	v_accvgpr_write_b32 a78, 0
	v_accvgpr_write_b32 a77, 0
	v_accvgpr_write_b32 a76, 0
	v_accvgpr_write_b32 a75, 0
	v_accvgpr_write_b32 a74, 0
	v_accvgpr_write_b32 a73, 0
	v_accvgpr_write_b32 a72, 0
	v_accvgpr_write_b32 a71, 0
	v_accvgpr_write_b32 a70, 0
	v_accvgpr_write_b32 a69, 0
	v_accvgpr_write_b32 a68, 0
	v_accvgpr_write_b32 a67, 0
	v_accvgpr_write_b32 a66, 0
	v_accvgpr_write_b32 a65, 0
	v_accvgpr_write_b32 a64, 0
	v_accvgpr_write_b32 a111, 0
	v_accvgpr_write_b32 a110, 0
	v_accvgpr_write_b32 a109, 0
	v_accvgpr_write_b32 a108, 0
	v_accvgpr_write_b32 a107, 0
	v_accvgpr_write_b32 a106, 0
	v_accvgpr_write_b32 a105, 0
	v_accvgpr_write_b32 a104, 0
	v_accvgpr_write_b32 a103, 0
	v_accvgpr_write_b32 a102, 0
	v_accvgpr_write_b32 a101, 0
	v_accvgpr_write_b32 a100, 0
	v_accvgpr_write_b32 a99, 0
	v_accvgpr_write_b32 a98, 0
	v_accvgpr_write_b32 a97, 0
	v_accvgpr_write_b32 a96, 0
	v_accvgpr_write_b32 a95, 0
	v_accvgpr_write_b32 a94, 0
	v_accvgpr_write_b32 a93, 0
	v_accvgpr_write_b32 a92, 0
	v_accvgpr_write_b32 a91, 0
	v_accvgpr_write_b32 a90, 0
	v_accvgpr_write_b32 a89, 0
	v_accvgpr_write_b32 a88, 0
	v_accvgpr_write_b32 a87, 0
	v_accvgpr_write_b32 a86, 0
	v_accvgpr_write_b32 a85, 0
	v_accvgpr_write_b32 a84, 0
	v_accvgpr_write_b32 a83, 0
	v_accvgpr_write_b32 a82, 0
	v_accvgpr_write_b32 a81, 0
	v_accvgpr_write_b32 a80, 0
	v_accvgpr_write_b32 a127, 0
	v_accvgpr_write_b32 a126, 0
	v_accvgpr_write_b32 a125, 0
	v_accvgpr_write_b32 a124, 0
	v_accvgpr_write_b32 a123, 0
	v_accvgpr_write_b32 a122, 0
	v_accvgpr_write_b32 a121, 0
	v_accvgpr_write_b32 a120, 0
	v_accvgpr_write_b32 a119, 0
	v_accvgpr_write_b32 a118, 0
	v_accvgpr_write_b32 a117, 0
	v_accvgpr_write_b32 a116, 0
	v_accvgpr_write_b32 a115, 0
	v_accvgpr_write_b32 a114, 0
	v_accvgpr_write_b32 a113, 0
	v_accvgpr_write_b32 a112, 0
	v_accvgpr_write_b32 a31, 0
	v_accvgpr_write_b32 a30, 0
	v_accvgpr_write_b32 a29, 0
	v_accvgpr_write_b32 a28, 0
	v_accvgpr_write_b32 a27, 0
	v_accvgpr_write_b32 a26, 0
	v_accvgpr_write_b32 a25, 0
	v_accvgpr_write_b32 a24, 0
	v_accvgpr_write_b32 a23, 0
	v_accvgpr_write_b32 a22, 0
	v_accvgpr_write_b32 a21, 0
	v_accvgpr_write_b32 a20, 0
	v_accvgpr_write_b32 a19, 0
	v_accvgpr_write_b32 a18, 0
	v_accvgpr_write_b32 a17, 0
	v_accvgpr_write_b32 a16, 0
	v_accvgpr_write_b32 a15, 0
	v_accvgpr_write_b32 a14, 0
	v_accvgpr_write_b32 a13, 0
	v_accvgpr_write_b32 a12, 0
	v_accvgpr_write_b32 a11, 0
	v_accvgpr_write_b32 a10, 0
	v_accvgpr_write_b32 a9, 0
	v_accvgpr_write_b32 a8, 0
	v_accvgpr_write_b32 a7, 0
	v_accvgpr_write_b32 a6, 0
	v_accvgpr_write_b32 a5, 0
	v_accvgpr_write_b32 a4, 0
	v_accvgpr_write_b32 a3, 0
	v_accvgpr_write_b32 a2, 0
	v_accvgpr_write_b32 a1, 0
	v_accvgpr_write_b32 a0, 0
	s_mov_b64 s[44:45], 0
	s_waitcnt vmcnt(23)
	ds_write_b128 v45, v[108:111]
	s_waitcnt vmcnt(22)
	ds_write_b128 v45, v[112:115] offset:4608
	s_waitcnt vmcnt(21)
	ds_write_b128 v45, v[116:119] offset:9216
	s_waitcnt vmcnt(20)
	ds_write_b128 v45, v[120:123] offset:13824
	s_waitcnt vmcnt(19)
	ds_write_b128 v45, v[124:127] offset:18432
	s_waitcnt vmcnt(18)
	ds_write_b128 v45, v[128:131] offset:23040
	s_waitcnt vmcnt(17)
	ds_write_b128 v45, v[132:135] offset:27648
	s_waitcnt vmcnt(16)
	ds_write_b128 v45, v[140:143] offset:32256
	s_waitcnt vmcnt(15)
	ds_write_b128 v45, v[144:147] offset:36864
	s_waitcnt vmcnt(14)
	ds_write_b128 v45, v[148:151] offset:41472
	s_waitcnt vmcnt(13)
	ds_write_b128 v45, v[152:155] offset:46080
	s_waitcnt vmcnt(12)
	ds_write_b128 v45, v[156:159] offset:50688
	s_waitcnt lgkmcnt(0)
	s_barrier
	s_waitcnt vmcnt(0)
	v_readfirstlane_b32 s100, v10
	v_readfirstlane_b32 s101, v11
	v_readfirstlane_b32 s98, v12
	v_readfirstlane_b32 s99, v13
	s_nop 1
	v_subrev_u32_e32 v194, s100, v10
	v_subrev_u32_e32 v193, s98, v12
	v_add_u32_e32 v254, s78, v194
	v_add_u32_e32 v205, s79, v194
	v_add_u32_e32 v204, s80, v194
	v_add_u32_e32 v203, s81, v194
	v_add_u32_e32 v202, s82, v194
	v_add_u32_e32 v201, s83, v194
	v_add_u32_e32 v200, s84, v194
	v_add_u32_e32 v199, s85, v194
	v_add_u32_e32 v198, s86, v193
	v_add_u32_e32 v197, s87, v193
	v_add_u32_e32 v196, s88, v193
	v_add_u32_e32 v195, s89, v193
	s_add_u32 s100, s100, s44
	s_addc_u32 s101, s101, s45
	s_add_u32 s98, s98, s44
	s_addc_u32 s99, s99, s45
	v_add_u32_e32 v192, v20, v46
	v_add_u32_e32 v191, v20, v47
	v_add_u32_e32 v190, v20, v48
	s_and_b32 s50, s42, 1
	s_mul_i32 s51, s50, 0xd800
	v_add_u32_e32 v189, s51, v192
	v_add_u32_e32 v188, s51, v191
	v_add_u32_e32 v187, s51, v190
	ds_read_b128 v[108:111], v189
	ds_read_b128 v[14:17], v187 offset:36864
	ds_read_b128 v[112:115], v189 offset:4608
	ds_read_b128 v[64:67], v187 offset:41472
	ds_read_b128 v[116:119], v189 offset:9216
	ds_read_b128 v[120:123], v188
	s_getreg_b32 s50, hwreg(HW_REG_HW_ID, 4, 1)
	s_cmp_lg_u32 s50, 0
	s_cbranch_scc1 xg5_varB_8
.LBB0_2449:
	s_and_b32 s50, s42, 1
	s_mul_i32 s51, s50, 0xd800
	s_xor_b32 s50, s50, 1
	s_mul_i32 s50, s50, 0xd800
	s_add_i32 s42, s42, 1
	v_add_u32_e32 v186, s50, v45
	ds_read_b128 v[68:71], v189 offset:32
	ds_read_b128 v[80:83], v187 offset:36896
	ds_read_b128 v[72:75], v189 offset:4640
	ds_read_b128 v[84:87], v187 offset:41504
	ds_read_b128 v[76:79], v189 offset:9248
	ds_read_b128 v[104:107], v188 offset:32
	s_waitcnt lgkmcnt(10)
	v_mfma_f32_32x32x16_bf16 a[32:47], v[108:111], v[14:17], a[32:47]
	s_waitcnt vmcnt(11)
	ds_write_b128 v186, v[250:253]
	s_waitcnt lgkmcnt(9)
	v_mfma_f32_32x32x16_bf16 a[48:63], v[108:111], v[64:67], a[48:63]
	s_waitcnt vmcnt(10)
	ds_write_b128 v186, v[246:249] offset:4608
	global_load_dwordx4 v[250:253], v254, s[100:101] offset:512
	v_mfma_f32_32x32x16_bf16 a[64:79], v[112:115], v[14:17], a[64:79]
	s_waitcnt vmcnt(10)
	ds_write_b128 v186, v[242:245] offset:9216
	global_load_dwordx4 v[246:249], v205, s[100:101] offset:512
	v_mfma_f32_32x32x16_bf16 a[96:111], v[112:115], v[64:67], a[96:111]
	s_waitcnt vmcnt(10)
	ds_write_b128 v186, v[238:241] offset:13824
	global_load_dwordx4 v[242:245], v204, s[100:101] offset:512
	s_waitcnt lgkmcnt(11)
	v_mfma_f32_32x32x16_bf16 a[80:95], v[116:119], v[14:17], a[80:95]
	s_waitcnt vmcnt(10)
	ds_write_b128 v186, v[234:237] offset:18432
	global_load_dwordx4 v[238:241], v203, s[100:101] offset:512
	v_mfma_f32_32x32x16_bf16 a[112:127], v[116:119], v[64:67], a[112:127]
	s_waitcnt vmcnt(10)
	ds_write_b128 v186, v[230:233] offset:23040
	global_load_dwordx4 v[234:237], v202, s[100:101] offset:512
	s_waitcnt lgkmcnt(12)
	v_mfma_f32_32x32x16_bf16 a[16:31], v[120:123], v[14:17], a[16:31]
	s_waitcnt vmcnt(10)
	ds_write_b128 v186, v[226:229] offset:27648
	global_load_dwordx4 v[230:233], v201, s[100:101] offset:512
	v_mfma_f32_32x32x16_bf16 a[0:15], v[120:123], v[64:67], a[0:15]
	s_waitcnt vmcnt(10)
	ds_write_b128 v186, v[222:225] offset:32256
	global_load_dwordx4 v[226:229], v200, s[100:101] offset:512
	ds_read_b128 v[108:111], v189 offset:64
	ds_read_b128 v[14:17], v187 offset:36928
	ds_read_b128 v[112:115], v189 offset:4672
	ds_read_b128 v[64:67], v187 offset:41536
	ds_read_b128 v[116:119], v189 offset:9280
	ds_read_b128 v[120:123], v188 offset:64
	s_waitcnt lgkmcnt(15)
	v_mfma_f32_32x32x16_bf16 a[32:47], v[68:71], v[80:83], a[32:47]
	s_waitcnt vmcnt(10)
	ds_write_b128 v186, v[218:221] offset:36864
	global_load_dwordx4 v[222:225], v199, s[100:101] offset:512
	v_mfma_f32_32x32x16_bf16 a[48:63], v[68:71], v[84:87], a[48:63]
	s_waitcnt vmcnt(10)
	ds_write_b128 v186, v[214:217] offset:41472
	global_load_dwordx4 v[218:221], v198, s[98:99] offset:256
	v_mfma_f32_32x32x16_bf16 a[64:79], v[72:75], v[80:83], a[64:79]
	s_waitcnt vmcnt(10)
	ds_write_b128 v186, v[210:213] offset:46080
	global_load_dwordx4 v[214:217], v197, s[98:99] offset:256
	v_mfma_f32_32x32x16_bf16 a[96:111], v[72:75], v[84:87], a[96:111]
	s_waitcnt vmcnt(10)
	ds_write_b128 v186, v[206:209] offset:50688
	global_load_dwordx4 v[210:213], v196, s[98:99] offset:256
	v_mfma_f32_32x32x16_bf16 a[80:95], v[76:79], v[80:83], a[80:95]
	global_load_dwordx4 v[206:209], v195, s[98:99] offset:256
	s_add_u32 s100, s100, 0x80
	s_addc_u32 s101, s101, 0
	s_add_u32 s98, s98, 0x80
	s_addc_u32 s99, s99, 0
	v_mfma_f32_32x32x16_bf16 a[112:127], v[76:79], v[84:87], a[112:127]
	s_waitcnt lgkmcnt(15)
	v_mfma_f32_32x32x16_bf16 a[16:31], v[104:107], v[80:83], a[16:31]
	v_mfma_f32_32x32x16_bf16 a[0:15], v[104:107], v[84:87], a[0:15]
	ds_read_b128 v[68:71], v189 offset:96
	ds_read_b128 v[80:83], v187 offset:36960
	ds_read_b128 v[72:75], v189 offset:4704
	ds_read_b128 v[84:87], v187 offset:41568
	ds_read_b128 v[76:79], v189 offset:9312
	ds_read_b128 v[104:107], v188 offset:96
	s_waitcnt lgkmcnt(14)
	v_mfma_f32_32x32x16_bf16 a[32:47], v[108:111], v[14:17], a[32:47]
	s_waitcnt lgkmcnt(12)
	v_mfma_f32_32x32x16_bf16 a[48:63], v[108:111], v[64:67], a[48:63]
	v_mfma_f32_32x32x16_bf16 a[64:79], v[112:115], v[14:17], a[64:79]
	v_mfma_f32_32x32x16_bf16 a[96:111], v[112:115], v[64:67], a[96:111]
	s_waitcnt lgkmcnt(11)
	v_mfma_f32_32x32x16_bf16 a[80:95], v[116:119], v[14:17], a[80:95]
	v_mfma_f32_32x32x16_bf16 a[112:127], v[116:119], v[64:67], a[112:127]
	s_waitcnt lgkmcnt(10)
	v_mfma_f32_32x32x16_bf16 a[16:31], v[120:123], v[14:17], a[16:31]
	v_mfma_f32_32x32x16_bf16 a[0:15], v[120:123], v[64:67], a[0:15]
	s_waitcnt lgkmcnt(0)
	v_mfma_f32_32x32x16_bf16 a[32:47], v[68:71], v[80:83], a[32:47]
	v_mfma_f32_32x32x16_bf16 a[48:63], v[68:71], v[84:87], a[48:63]
	v_mfma_f32_32x32x16_bf16 a[64:79], v[72:75], v[80:83], a[64:79]
	v_mfma_f32_32x32x16_bf16 a[96:111], v[72:75], v[84:87], a[96:111]
	s_barrier
	v_add_u32_e32 v189, s50, v192
	v_add_u32_e32 v188, s50, v191
	v_add_u32_e32 v187, s50, v190
	ds_read_b128 v[108:111], v189
	ds_read_b128 v[14:17], v187 offset:36864
	ds_read_b128 v[112:115], v189 offset:4608
	ds_read_b128 v[64:67], v187 offset:41472
	ds_read_b128 v[116:119], v189 offset:9216
	ds_read_b128 v[120:123], v188
	v_mfma_f32_32x32x16_bf16 a[80:95], v[76:79], v[80:83], a[80:95]
	v_mfma_f32_32x32x16_bf16 a[112:127], v[76:79], v[84:87], a[112:127]
	v_mfma_f32_32x32x16_bf16 a[16:31], v[104:107], v[80:83], a[16:31]
	v_mfma_f32_32x32x16_bf16 a[0:15], v[104:107], v[84:87], a[0:15]
	s_add_u32 s44, s44, 0x80
	s_addc_u32 s45, s45, 0
	s_cmpk_lg_i32 s44, 0x700
	s_cbranch_scc1 .LBB0_2449
	s_branch xg5_tail_8
xg5_varB_8:
	s_and_b32 s50, s42, 1
	s_mul_i32 s51, s50, 0xd800
	s_xor_b32 s50, s50, 1
	s_mul_i32 s50, s50, 0xd800
	s_add_i32 s42, s42, 1
	v_add_u32_e32 v186, s50, v45
	ds_read_b128 v[68:71], v189 offset:32
	ds_read_b128 v[80:83], v187 offset:36896
	ds_read_b128 v[72:75], v189 offset:4640
	ds_read_b128 v[84:87], v187 offset:41504
	ds_read_b128 v[76:79], v189 offset:9248
	ds_read_b128 v[104:107], v188 offset:32
	s_waitcnt lgkmcnt(10)
	v_mfma_f32_32x32x16_bf16 a[32:47], v[108:111], v[14:17], a[32:47]
	s_waitcnt lgkmcnt(8)
	v_mfma_f32_32x32x16_bf16 a[48:63], v[108:111], v[64:67], a[48:63]
	v_mfma_f32_32x32x16_bf16 a[64:79], v[112:115], v[14:17], a[64:79]
	v_mfma_f32_32x32x16_bf16 a[96:111], v[112:115], v[64:67], a[96:111]
	s_waitcnt lgkmcnt(7)
	v_mfma_f32_32x32x16_bf16 a[80:95], v[116:119], v[14:17], a[80:95]
	v_mfma_f32_32x32x16_bf16 a[112:127], v[116:119], v[64:67], a[112:127]
	s_waitcnt lgkmcnt(6)
	v_mfma_f32_32x32x16_bf16 a[16:31], v[120:123], v[14:17], a[16:31]
	v_mfma_f32_32x32x16_bf16 a[0:15], v[120:123], v[64:67], a[0:15]
	ds_read_b128 v[108:111], v189 offset:64
	ds_read_b128 v[14:17], v187 offset:36928
	ds_read_b128 v[112:115], v189 offset:4672
	ds_read_b128 v[64:67], v187 offset:41536
	ds_read_b128 v[116:119], v189 offset:9280
	ds_read_b128 v[120:123], v188 offset:64
	s_waitcnt lgkmcnt(10)
	v_mfma_f32_32x32x16_bf16 a[32:47], v[68:71], v[80:83], a[32:47]
	s_waitcnt lgkmcnt(8)
	v_mfma_f32_32x32x16_bf16 a[48:63], v[68:71], v[84:87], a[48:63]
	v_mfma_f32_32x32x16_bf16 a[64:79], v[72:75], v[80:83], a[64:79]
	v_mfma_f32_32x32x16_bf16 a[96:111], v[72:75], v[84:87], a[96:111]
	s_waitcnt lgkmcnt(7)
	v_mfma_f32_32x32x16_bf16 a[80:95], v[76:79], v[80:83], a[80:95]
	s_waitcnt vmcnt(11)
	ds_write_b128 v186, v[250:253]
	v_mfma_f32_32x32x16_bf16 a[112:127], v[76:79], v[84:87], a[112:127]
	s_waitcnt vmcnt(10)
	ds_write_b128 v186, v[246:249] offset:4608
	global_load_dwordx4 v[250:253], v254, s[100:101] offset:512
	s_waitcnt lgkmcnt(8)
	v_mfma_f32_32x32x16_bf16 a[16:31], v[104:107], v[80:83], a[16:31]
	s_waitcnt vmcnt(10)
	ds_write_b128 v186, v[242:245] offset:9216
	global_load_dwordx4 v[246:249], v205, s[100:101] offset:512
	v_mfma_f32_32x32x16_bf16 a[0:15], v[104:107], v[84:87], a[0:15]
	s_waitcnt vmcnt(10)
	ds_write_b128 v186, v[238:241] offset:13824
	global_load_dwordx4 v[242:245], v204, s[100:101] offset:512
	ds_read_b128 v[68:71], v189 offset:96
	ds_read_b128 v[80:83], v187 offset:36960
	ds_read_b128 v[72:75], v189 offset:4704
	ds_read_b128 v[84:87], v187 offset:41568
	ds_read_b128 v[76:79], v189 offset:9312
	ds_read_b128 v[104:107], v188 offset:96
	s_waitcnt lgkmcnt(14)
	v_mfma_f32_32x32x16_bf16 a[32:47], v[108:111], v[14:17], a[32:47]
	s_waitcnt vmcnt(10)
	ds_write_b128 v186, v[234:237] offset:18432
	global_load_dwordx4 v[238:241], v203, s[100:101] offset:512
	s_waitcnt lgkmcnt(13)
	v_mfma_f32_32x32x16_bf16 a[48:63], v[108:111], v[64:67], a[48:63]
	s_waitcnt vmcnt(10)
	ds_write_b128 v186, v[230:233] offset:23040
	global_load_dwordx4 v[234:237], v202, s[100:101] offset:512
	v_mfma_f32_32x32x16_bf16 a[64:79], v[112:115], v[14:17], a[64:79]
	s_waitcnt vmcnt(10)
	ds_write_b128 v186, v[226:229] offset:27648
	global_load_dwordx4 v[230:233], v201, s[100:101] offset:512
	v_mfma_f32_32x32x16_bf16 a[96:111], v[112:115], v[64:67], a[96:111]
	s_waitcnt vmcnt(10)
	ds_write_b128 v186, v[222:225] offset:32256
	global_load_dwordx4 v[226:229], v200, s[100:101] offset:512
	s_waitcnt lgkmcnt(15)
	v_mfma_f32_32x32x16_bf16 a[80:95], v[116:119], v[14:17], a[80:95]
	s_waitcnt vmcnt(10)
	ds_write_b128 v186, v[218:221] offset:36864
	global_load_dwordx4 v[222:225], v199, s[100:101] offset:512
	v_mfma_f32_32x32x16_bf16 a[112:127], v[116:119], v[64:67], a[112:127]
	s_waitcnt vmcnt(10)
	ds_write_b128 v186, v[214:217] offset:41472
	global_load_dwordx4 v[218:221], v198, s[98:99] offset:256
	s_waitcnt lgkmcnt(15)
	v_mfma_f32_32x32x16_bf16 a[16:31], v[120:123], v[14:17], a[16:31]
	s_waitcnt vmcnt(10)
	ds_write_b128 v186, v[210:213] offset:46080
	global_load_dwordx4 v[214:217], v197, s[98:99] offset:256
	v_mfma_f32_32x32x16_bf16 a[0:15], v[120:123], v[64:67], a[0:15]
	s_waitcnt vmcnt(10)
	ds_write_b128 v186, v[206:209] offset:50688
	global_load_dwordx4 v[210:213], v196, s[98:99] offset:256
	s_waitcnt lgkmcnt(0)
	v_mfma_f32_32x32x16_bf16 a[32:47], v[68:71], v[80:83], a[32:47]
	global_load_dwordx4 v[206:209], v195, s[98:99] offset:256
	s_add_u32 s100, s100, 0x80
	s_addc_u32 s101, s101, 0
	s_add_u32 s98, s98, 0x80
	s_addc_u32 s99, s99, 0
	v_mfma_f32_32x32x16_bf16 a[48:63], v[68:71], v[84:87], a[48:63]
	v_mfma_f32_32x32x16_bf16 a[64:79], v[72:75], v[80:83], a[64:79]
	v_mfma_f32_32x32x16_bf16 a[96:111], v[72:75], v[84:87], a[96:111]
	s_barrier
	v_add_u32_e32 v189, s50, v192
	v_add_u32_e32 v188, s50, v191
	v_add_u32_e32 v187, s50, v190
	ds_read_b128 v[108:111], v189
	ds_read_b128 v[14:17], v187 offset:36864
	ds_read_b128 v[112:115], v189 offset:4608
	ds_read_b128 v[64:67], v187 offset:41472
	ds_read_b128 v[116:119], v189 offset:9216
	ds_read_b128 v[120:123], v188
	v_mfma_f32_32x32x16_bf16 a[80:95], v[76:79], v[80:83], a[80:95]
	v_mfma_f32_32x32x16_bf16 a[112:127], v[76:79], v[84:87], a[112:127]
	v_mfma_f32_32x32x16_bf16 a[16:31], v[104:107], v[80:83], a[16:31]
	v_mfma_f32_32x32x16_bf16 a[0:15], v[104:107], v[84:87], a[0:15]
	s_add_u32 s44, s44, 0x80
	s_addc_u32 s45, s45, 0
	s_cmpk_lg_i32 s44, 0x700
	s_cbranch_scc1 xg5_varB_8
xg5_tail_8:
	ds_read_b128 v[10:13], v60
	ds_read_b128 v[108:111], v62 offset:36864
	ds_read_b128 v[112:115], v60 offset:4608
	ds_read_b128 v[116:119], v62 offset:41472
	s_lshl_b32 s44, s48, 8
	s_lshl_b32 s42, s49, 8
	s_waitcnt lgkmcnt(2)
	v_mfma_f32_32x32x16_bf16 a[176:191], v[10:13], v[108:111], a[32:47]
	s_add_i32 s47, s47, s76
	s_add_i32 s46, s46, s76
	s_waitcnt lgkmcnt(0)
	v_mfma_f32_32x32x16_bf16 a[160:175], v[10:13], v[116:119], a[48:63]
	v_mfma_f32_32x32x16_bf16 a[144:159], v[112:115], v[108:111], a[64:79]
	v_mfma_f32_32x32x16_bf16 a[128:143], v[112:115], v[116:119], a[96:111]
	ds_read_b128 v[10:13], v60 offset:9216
	ds_read_b128 v[112:115], v61
	s_waitcnt vmcnt(11)
	s_waitcnt vmcnt(0)
	ds_write_b128 v63, v[250:253] offset:55296
	s_waitcnt vmcnt(10)
	ds_write_b128 v63, v[246:249] offset:59904
	s_waitcnt vmcnt(9)
	ds_write_b128 v63, v[242:245] offset:64512
	s_waitcnt vmcnt(8)
	ds_write_b128 v50, v[238:241] offset:55296
	s_waitcnt vmcnt(7)
	ds_write_b128 v51, v[234:237] offset:55296
	s_waitcnt vmcnt(6)
	ds_write_b128 v52, v[230:233] offset:55296
	s_waitcnt vmcnt(5)
	ds_write_b128 v53, v[226:229] offset:55296
	s_waitcnt vmcnt(4)
	ds_write_b128 v54, v[222:225] offset:55296
	s_waitcnt vmcnt(3)
	ds_write_b128 v55, v[218:221]
	s_waitcnt vmcnt(2)
	ds_write_b128 v55, v[214:217] offset:4608
	s_waitcnt vmcnt(1)
	ds_write_b128 v55, v[210:213] offset:9216
	s_waitcnt vmcnt(0)
	ds_write_b128 v55, v[206:209] offset:13824
	s_waitcnt lgkmcnt(13)
	v_mfma_f32_32x32x16_bf16 a[64:79], v[10:13], v[108:111], a[80:95]
	v_mfma_f32_32x32x16_bf16 a[48:63], v[10:13], v[116:119], a[112:127]
	ds_read_b128 v[10:13], v60 offset:32
	ds_read_b128 v[14:17], v62 offset:36896
	ds_read_b128 v[64:67], v62 offset:36928
	ds_read_b128 v[68:71], v60 offset:64
	ds_read_b128 v[72:75], v62 offset:41504
	ds_read_b128 v[76:79], v62 offset:36960
	s_waitcnt lgkmcnt(4)
	v_mfma_f32_32x32x16_bf16 a[176:191], v[10:13], v[14:17], a[176:191]
	s_waitcnt lgkmcnt(1)
	v_mfma_f32_32x32x16_bf16 a[160:175], v[10:13], v[72:75], a[160:175]
	ds_read_b128 v[10:13], v60 offset:4640
	ds_read_b128 v[80:83], v60 offset:96
	v_mfma_f32_32x32x16_bf16 a[32:47], v[112:115], v[108:111], a[16:31]
	v_mfma_f32_32x32x16_bf16 a[16:31], v[112:115], v[116:119], a[0:15]
	s_waitcnt lgkmcnt(1)
	v_mfma_f32_32x32x16_bf16 a[144:159], v[10:13], v[14:17], a[144:159]
	v_mfma_f32_32x32x16_bf16 a[128:143], v[10:13], v[72:75], a[128:143]
	ds_read_b128 v[10:13], v60 offset:9248
	ds_read_b128 v[84:87], v60 offset:9280
	s_waitcnt lgkmcnt(1)
	v_mfma_f32_32x32x16_bf16 a[64:79], v[10:13], v[14:17], a[64:79]
	v_mfma_f32_32x32x16_bf16 a[48:63], v[10:13], v[72:75], a[48:63]
	ds_read_b128 v[10:13], v61 offset:32
	ds_read_b128 v[88:91], v60 offset:9312
	s_waitcnt lgkmcnt(1)
	v_mfma_f32_32x32x16_bf16 a[32:47], v[10:13], v[14:17], a[32:47]
	v_mfma_f32_32x32x16_bf16 a[16:31], v[10:13], v[72:75], a[16:31]
	ds_read_b128 v[10:13], v62 offset:41536
	ds_read_b128 v[14:17], v62 offset:41568
	v_mfma_f32_32x32x16_bf16 a[176:191], v[68:71], v[64:67], a[176:191]
	s_waitcnt lgkmcnt(1)
	v_mfma_f32_32x32x16_bf16 a[160:175], v[68:71], v[10:13], a[160:175]
	ds_read_b128 v[68:71], v60 offset:4672
	ds_read_b128 v[72:75], v60 offset:4704
	s_waitcnt lgkmcnt(1)
	v_mfma_f32_32x32x16_bf16 a[144:159], v[68:71], v[64:67], a[144:159]
	v_mfma_f32_32x32x16_bf16 a[128:143], v[68:71], v[10:13], a[128:143]
	v_mfma_f32_32x32x16_bf16 a[64:79], v[84:87], v[64:67], a[64:79]
	v_mfma_f32_32x32x16_bf16 a[48:63], v[84:87], v[10:13], a[48:63]
	ds_read_b128 v[68:71], v61 offset:64
	ds_read_b128 v[84:87], v61 offset:96
	s_waitcnt lgkmcnt(0)
	s_barrier
	v_mfma_f32_32x32x16_bf16 a[32:47], v[68:71], v[64:67], a[32:47]
	v_mfma_f32_32x32x16_bf16 a[16:31], v[68:71], v[10:13], a[16:31]
	v_mfma_f32_32x32x16_bf16 a[176:191], v[80:83], v[76:79], a[176:191]
	v_mfma_f32_32x32x16_bf16 a[160:175], v[80:83], v[14:17], a[160:175]
	v_mfma_f32_32x32x16_bf16 a[144:159], v[72:75], v[76:79], a[144:159]
	v_mfma_f32_32x32x16_bf16 a[128:143], v[72:75], v[14:17], a[128:143]
	v_mfma_f32_32x32x16_bf16 a[64:79], v[88:91], v[76:79], a[64:79]
	v_mfma_f32_32x32x16_bf16 a[48:63], v[88:91], v[14:17], a[48:63]
	v_mfma_f32_32x32x16_bf16 a[32:47], v[84:87], v[76:79], a[32:47]
	v_mfma_f32_32x32x16_bf16 a[16:31], v[84:87], v[14:17], a[16:31]
	ds_read_b128 v[10:13], v60 offset:55296
	ds_read_b128 v[14:17], v56
	ds_read_b128 v[64:67], v60 offset:55328
	ds_read_b128 v[68:71], v56 offset:32
	ds_read_b128 v[72:75], v56 offset:4608
	ds_read_b128 v[76:79], v56 offset:4640
	s_waitcnt lgkmcnt(4)
	v_mfma_f32_32x32x16_bf16 a[176:191], v[10:13], v[14:17], a[176:191]
	s_waitcnt lgkmcnt(1)
	v_mfma_f32_32x32x16_bf16 a[160:175], v[10:13], v[72:75], a[160:175]
	ds_read_b128 v[10:13], v60 offset:59904
	ds_read_b128 v[80:83], v60 offset:59936
	s_waitcnt lgkmcnt(1)
	v_mfma_f32_32x32x16_bf16 a[144:159], v[10:13], v[14:17], a[144:159]
	v_mfma_f32_32x32x16_bf16 a[128:143], v[10:13], v[72:75], a[128:143]
	ds_read_b128 v[10:13], v60 offset:64512
	ds_read_b128 v[84:87], v60 offset:64544
	s_waitcnt lgkmcnt(1)
	v_mfma_f32_32x32x16_bf16 a[64:79], v[10:13], v[14:17], a[64:79]
	v_mfma_f32_32x32x16_bf16 a[48:63], v[10:13], v[72:75], a[48:63]
	ds_read_b128 v[10:13], v61 offset:55296
	ds_read_b128 v[88:91], v61 offset:55328
	s_waitcnt lgkmcnt(1)
	v_mfma_f32_32x32x16_bf16 a[32:47], v[10:13], v[14:17], a[32:47]
	v_mfma_f32_32x32x16_bf16 a[16:31], v[10:13], v[72:75], a[16:31]
	ds_read_b128 v[10:13], v60 offset:55360
	v_mfma_f32_32x32x16_bf16 a[176:191], v[64:67], v[68:71], a[176:191]
	v_mfma_f32_32x32x16_bf16 a[160:175], v[64:67], v[76:79], a[160:175]
	v_mfma_f32_32x32x16_bf16 a[144:159], v[80:83], v[68:71], a[144:159]
	v_mfma_f32_32x32x16_bf16 a[128:143], v[80:83], v[76:79], a[128:143]
	v_mfma_f32_32x32x16_bf16 a[64:79], v[84:87], v[68:71], a[64:79]
	v_mfma_f32_32x32x16_bf16 a[48:63], v[84:87], v[76:79], a[48:63]
	ds_read_b128 v[14:17], v56 offset:64
	ds_read_b128 v[64:67], v61 offset:55360
	ds_read_b128 v[72:75], v61 offset:55392
	ds_read_b128 v[80:83], v60 offset:64576
	ds_read_b128 v[84:87], v60 offset:64608
	ds_read_b128 v[92:95], v60 offset:55392
	ds_read_b128 v[96:99], v56 offset:96
	ds_read_b128 v[100:103], v60 offset:59968
	ds_read_b128 v[104:107], v60 offset:60000
	ds_read_b128 v[108:111], v56 offset:4672
	ds_read_b128 v[112:115], v56 offset:4704
	s_waitcnt lgkmcnt(0)
	s_barrier
	v_mfma_f32_32x32x16_bf16 a[32:47], v[88:91], v[68:71], a[32:47]
	v_add_u32_e32 v70, 0x2048, v21
	v_mfma_f32_32x32x16_bf16 a[16:31], v[88:91], v[76:79], a[16:31]
	v_accvgpr_read_b32 v76, a225
	v_accvgpr_read_b32 v77, a226
	v_mfma_f32_32x32x16_bf16 a[176:191], v[10:13], v[14:17], a[176:191]
	v_mfma_f32_32x32x16_bf16 a[160:175], v[10:13], v[108:111], a[160:175]
	v_lshl_add_u64 v[10:11], v[6:7], 0, s[42:43]
	v_mfma_f32_32x32x16_bf16 a[144:159], v[100:103], v[14:17], a[144:159]
	v_mfma_f32_32x32x16_bf16 a[128:143], v[100:103], v[108:111], a[128:143]
	v_mfma_f32_32x32x16_bf16 a[64:79], v[80:83], v[14:17], a[64:79]
	v_mfma_f32_32x32x16_bf16 a[48:63], v[80:83], v[108:111], a[48:63]
	v_mfma_f32_32x32x16_bf16 a[32:47], v[64:67], v[14:17], a[32:47]
	v_mfma_f32_32x32x16_bf16 a[16:31], v[64:67], v[108:111], a[16:31]
	v_add_u32_e32 v66, 0x1028, v21
	v_mfma_f32_32x32x16_bf16 a[176:191], v[92:95], v[96:99], a[176:191]
	s_nop 11
	ds_write_b32 v49, a176
	ds_write_b32 v49, a177 offset:516
	ds_write_b32 v49, a178 offset:1032
	ds_write_b32 v49, a179 offset:1548
	ds_write_b32 v49, a180 offset:4128
	ds_write_b32 v49, a181 offset:4644
	ds_write_b32 v49, a182 offset:5160
	v_mfma_f32_32x32x16_bf16 a[160:175], v[92:95], v[112:115], a[160:175]
	ds_write_b32 v49, a183 offset:5676
	ds_write_b32 v49, a184 offset:8256
	ds_write_b32 v49, a185 offset:8772
	ds_write_b32 v49, a186 offset:9288
	ds_write_b32 v49, a187 offset:9804
	ds_write_b32 v49, a188 offset:12384
	ds_write_b32 v49, a189 offset:12900
	ds_write_b32 v49, a190 offset:13416
	ds_write_b32 v49, a191 offset:13932
	s_nop 2
	ds_write_b32 v49, a160 offset:128
	ds_write_b32 v49, a161 offset:644
	ds_write_b32 v49, a162 offset:1160
	ds_write_b32 v49, a163 offset:1676
	ds_write_b32 v49, a164 offset:4256
	ds_write_b32 v49, a165 offset:4772
	ds_write_b32 v49, a166 offset:5288
	ds_write_b32 v49, a167 offset:5804
	ds_write_b32 v49, a168 offset:8384
	ds_write_b32 v49, a169 offset:8900
	ds_write_b32 v49, a170 offset:9416
	ds_write_b32 v49, a171 offset:9932
	v_mfma_f32_32x32x16_bf16 a[144:159], v[104:107], v[96:99], a[144:159]
	ds_write_b32 v49, a172 offset:12512
	ds_write_b32 v49, a173 offset:13028
	ds_write_b32 v49, a174 offset:13544
	ds_write_b32 v49, a175 offset:14060
	s_nop 7
	ds_write_b32 v49, a144 offset:16512
	ds_write_b32 v49, a145 offset:17028
	ds_write_b32 v49, a146 offset:17544
	ds_write_b32 v49, a147 offset:18060
	ds_write_b32 v49, a148 offset:20640
	ds_write_b32 v49, a149 offset:21156
	ds_write_b32 v49, a150 offset:21672
	ds_write_b32 v49, a151 offset:22188
	ds_write_b32 v49, a152 offset:24768
	ds_write_b32 v49, a153 offset:25284
	v_mfma_f32_32x32x16_bf16 a[128:143], v[104:107], v[112:115], a[128:143]
	ds_write_b32 v49, a154 offset:25800
	ds_write_b32 v49, a155 offset:26316
	ds_write_b32 v49, a156 offset:28896
	ds_write_b32 v49, a157 offset:29412
	ds_write_b32 v49, a158 offset:29928
	ds_write_b32 v49, a159 offset:30444
	s_nop 5
	ds_write_b32 v49, a128 offset:16640
	ds_write_b32 v49, a129 offset:17156
	ds_write_b32 v49, a130 offset:17672
	ds_write_b32 v49, a131 offset:18188
	ds_write_b32 v49, a132 offset:20768
	ds_write_b32 v49, a133 offset:21284
	ds_write_b32 v49, a134 offset:21800
	ds_write_b32 v49, a135 offset:22316
	v_mfma_f32_32x32x16_bf16 a[64:79], v[84:87], v[96:99], a[64:79]
	ds_write_b32 v49, a136 offset:24896
	ds_write_b32 v49, a137 offset:25412
	ds_write_b32 v49, a138 offset:25928
	ds_write_b32 v49, a139 offset:26444
	ds_write_b32 v49, a140 offset:29024
	ds_write_b32 v49, a141 offset:29540
	ds_write_b32 v49, a142 offset:30056
	ds_write_b32 v49, a143 offset:30572
	s_nop 3
	ds_write_b32 v49, a64 offset:33024
	ds_write_b32 v49, a65 offset:33540
	ds_write_b32 v49, a66 offset:34056
	ds_write_b32 v49, a67 offset:34572
	ds_write_b32 v49, a68 offset:37152
	ds_write_b32 v49, a69 offset:37668
	v_mfma_f32_32x32x16_bf16 a[48:63], v[84:87], v[112:115], a[48:63]
	ds_write_b32 v49, a70 offset:38184
	ds_write_b32 v49, a71 offset:38700
	ds_write_b32 v49, a72 offset:41280
	ds_write_b32 v49, a73 offset:41796
	ds_write_b32 v49, a74 offset:42312
	ds_write_b32 v49, a75 offset:42828
	ds_write_b32 v49, a76 offset:45408
	ds_write_b32 v49, a77 offset:45924
	ds_write_b32 v49, a78 offset:46440
	ds_write_b32 v49, a79 offset:46956
	s_nop 1
	ds_write_b32 v49, a48 offset:33152
	ds_write_b32 v49, a49 offset:33668
	ds_write_b32 v49, a50 offset:34184
	ds_write_b32 v49, a51 offset:34700
	ds_write_b32 v49, a52 offset:37280
	ds_write_b32 v49, a53 offset:37796
	ds_write_b32 v49, a54 offset:38312
	ds_write_b32 v49, a55 offset:38828
	ds_write_b32 v49, a56 offset:41408
	ds_write_b32 v49, a57 offset:41924
	ds_write_b32 v49, a58 offset:42440
	v_mfma_f32_32x32x16_bf16 a[32:47], v[72:75], v[96:99], a[32:47]
	ds_write_b32 v49, a59 offset:42956
	ds_write_b32 v49, a60 offset:45536
	ds_write_b32 v49, a61 offset:46052
	ds_write_b32 v49, a62 offset:46568
	ds_write_b32 v49, a63 offset:47084
	s_nop 6
	ds_write_b32 v49, a32 offset:49536
	ds_write_b32 v49, a33 offset:50052
	ds_write_b32 v49, a34 offset:50568
	ds_write_b32 v49, a35 offset:51084
	ds_write_b32 v49, a36 offset:53664
	ds_write_b32 v49, a37 offset:54180
	ds_write_b32 v49, a38 offset:54696
	ds_write_b32 v49, a39 offset:55212
	ds_write_b32 v49, a40 offset:57792
	v_mfma_f32_32x32x16_bf16 a[16:31], v[72:75], v[112:115], a[16:31]
	ds_write_b32 v49, a41 offset:58308
	ds_write_b32 v49, a42 offset:58824
	ds_write_b32 v49, a43 offset:59340
	ds_write_b32 v49, a44 offset:61920
	ds_write_b32 v49, a45 offset:62436
	ds_write_b32 v49, a46 offset:62952
	ds_write_b32 v49, a47 offset:63468
	s_nop 4
	ds_write_b32 v49, a16 offset:49664
	ds_write_b32 v49, a17 offset:50180
	ds_write_b32 v49, a18 offset:50696
	ds_write_b32 v49, a19 offset:51212
	ds_write_b32 v49, a20 offset:53792
	ds_write_b32 v49, a21 offset:54308
	ds_write_b32 v49, a22 offset:54824
	ds_write_b32 v49, a23 offset:55340
	ds_write_b32 v49, a24 offset:57920
	ds_write_b32 v49, a25 offset:58436
	ds_write_b32 v49, a26 offset:58952
	ds_write_b32 v49, a27 offset:59468
	ds_write_b32 v49, a28 offset:62048
	ds_write_b32 v49, a29 offset:62564
	ds_write_b32 v49, a30 offset:63080
	ds_write_b32 v49, a31 offset:63596
	s_waitcnt lgkmcnt(0)
	s_barrier
	ds_read2_b32 v[16:17], v21 offset1:1
	ds_read2_b32 v[18:19], v21 offset0:2 offset1:3
	v_accvgpr_read_b32 v72, a218
	v_or_b32_e32 v0, s44, v72
	v_lshlrev_b32_e32 v0, 11, v0
	s_waitcnt lgkmcnt(1)
	v_cvt_pk_bf16_f32 v16, v16, v17
	s_waitcnt lgkmcnt(0)
	v_cvt_pk_bf16_f32 v17, v18, v19
	v_lshl_add_u64 v[18:19], v[10:11], 0, v[0:1]
	v_add_u32_e32 v0, 0x1020, v21
	ds_read2_b32 v[12:13], v29 offset1:1
	ds_read2_b32 v[14:15], v29 offset0:2 offset1:3
	ds_read2_b32 v[64:65], v0 offset1:1
	ds_read2_b32 v[66:67], v66 offset1:1
	v_accvgpr_read_b32 v73, a219
	v_or_b32_e32 v0, s44, v73
	v_lshlrev_b32_e32 v0, 11, v0
	global_store_dwordx2 v[18:19], v[16:17], off
	s_waitcnt lgkmcnt(1)
	v_cvt_pk_bf16_f32 v64, v64, v65
	s_waitcnt lgkmcnt(0)
	v_cvt_pk_bf16_f32 v65, v66, v67
	v_lshl_add_u64 v[66:67], v[10:11], 0, v[0:1]
	v_add_u32_e32 v0, 0x2040, v21
	ds_read2_b32 v[16:17], v44 offset1:1
	ds_read2_b32 v[18:19], v44 offset0:2 offset1:3
	ds_read2_b32 v[68:69], v0 offset1:1
	ds_read2_b32 v[70:71], v70 offset1:1
	global_store_dwordx2 v[66:67], v[64:65], off
	v_add_u32_e32 v0, 0x3060, v21
	v_add_u32_e32 v66, 0x3068, v21
	ds_read2_b32 v[64:65], v0 offset1:1
	ds_read2_b32 v[66:67], v66 offset1:1
	v_or_b32_e32 v0, s44, v136
	v_lshlrev_b32_e32 v0, 11, v0
	s_waitcnt lgkmcnt(3)
	v_cvt_pk_bf16_f32 v68, v68, v69
	s_waitcnt lgkmcnt(2)
	v_cvt_pk_bf16_f32 v69, v70, v71
	v_lshl_add_u64 v[70:71], v[10:11], 0, v[0:1]
	v_or_b32_e32 v0, s44, v137
	v_lshlrev_b32_e32 v0, 11, v0
	global_store_dwordx2 v[70:71], v[68:69], off
	s_waitcnt lgkmcnt(1)
	v_cvt_pk_bf16_f32 v64, v64, v65
	s_waitcnt lgkmcnt(0)
	v_cvt_pk_bf16_f32 v65, v66, v67
	v_lshl_add_u64 v[66:67], v[10:11], 0, v[0:1]
	v_add_u32_e32 v0, 0x4080, v21
	v_add_u32_e32 v70, 0x4088, v21
	ds_read2_b32 v[68:69], v0 offset1:1
	ds_read2_b32 v[70:71], v70 offset1:1
	global_store_dwordx2 v[66:67], v[64:65], off
	v_add_u32_e32 v0, 0x50a0, v21
	v_add_u32_e32 v66, 0x50a8, v21
	ds_read2_b32 v[64:65], v0 offset1:1
	ds_read2_b32 v[66:67], v66 offset1:1
	v_or_b32_e32 v0, s44, v139
	v_lshlrev_b32_e32 v0, 11, v0
	v_accvgpr_read_b32 v74, a223
	s_waitcnt lgkmcnt(3)
	v_cvt_pk_bf16_f32 v68, v68, v69
	s_waitcnt lgkmcnt(2)
	v_cvt_pk_bf16_f32 v69, v70, v71
	v_lshl_add_u64 v[70:71], v[10:11], 0, v[0:1]
	v_or_b32_e32 v0, s44, v74
	v_lshlrev_b32_e32 v0, 11, v0
	global_store_dwordx2 v[70:71], v[68:69], off
	s_waitcnt lgkmcnt(1)
	v_cvt_pk_bf16_f32 v64, v64, v65
	s_waitcnt lgkmcnt(0)
	v_cvt_pk_bf16_f32 v65, v66, v67
	v_lshl_add_u64 v[66:67], v[10:11], 0, v[0:1]
	v_add_u32_e32 v0, 0x60c0, v21
	v_add_u32_e32 v70, 0x60c8, v21
	ds_read2_b32 v[68:69], v0 offset1:1
	ds_read2_b32 v[70:71], v70 offset1:1
	global_store_dwordx2 v[66:67], v[64:65], off
	v_add_u32_e32 v0, 0x70e0, v21
	v_add_u32_e32 v66, 0x70e8, v21
	ds_read2_b32 v[64:65], v0 offset1:1
	ds_read2_b32 v[66:67], v66 offset1:1
	v_accvgpr_read_b32 v75, a224
	v_or_b32_e32 v0, s44, v75
	v_lshlrev_b32_e32 v0, 11, v0
	s_waitcnt lgkmcnt(3)
	v_cvt_pk_bf16_f32 v68, v68, v69
	s_waitcnt lgkmcnt(2)
	v_cvt_pk_bf16_f32 v69, v70, v71
	v_lshl_add_u64 v[70:71], v[10:11], 0, v[0:1]
	v_or_b32_e32 v0, s44, v76
	v_lshlrev_b32_e32 v0, 11, v0
	global_store_dwordx2 v[70:71], v[68:69], off
	s_waitcnt lgkmcnt(1)
	v_cvt_pk_bf16_f32 v64, v64, v65
	s_waitcnt lgkmcnt(0)
	v_cvt_pk_bf16_f32 v65, v66, v67
	v_lshl_add_u64 v[66:67], v[10:11], 0, v[0:1]
	v_add_u32_e32 v0, 0x8100, v21
	v_add_u32_e32 v70, 0x8108, v21
	ds_read2_b32 v[68:69], v0 offset1:1
	ds_read2_b32 v[70:71], v70 offset1:1
	global_store_dwordx2 v[66:67], v[64:65], off
	v_add_u32_e32 v0, 0x9120, v21
	v_add_u32_e32 v66, 0x9128, v21
	ds_read2_b32 v[64:65], v0 offset1:1
	ds_read2_b32 v[66:67], v66 offset1:1
	v_or_b32_e32 v0, s44, v77
	v_lshlrev_b32_e32 v0, 11, v0
	s_waitcnt lgkmcnt(3)
	v_cvt_pk_bf16_f32 v68, v68, v69
	s_waitcnt lgkmcnt(2)
	v_cvt_pk_bf16_f32 v69, v70, v71
	v_lshl_add_u64 v[70:71], v[10:11], 0, v[0:1]
	v_or_b32_e32 v0, s44, v22
	v_lshlrev_b32_e32 v0, 11, v0
	global_store_dwordx2 v[70:71], v[68:69], off
	s_waitcnt lgkmcnt(1)
	v_cvt_pk_bf16_f32 v64, v64, v65
	s_waitcnt lgkmcnt(0)
	v_cvt_pk_bf16_f32 v65, v66, v67
	v_lshl_add_u64 v[66:67], v[10:11], 0, v[0:1]
	v_add_u32_e32 v0, 0xa140, v21
	v_add_u32_e32 v70, 0xa148, v21
	ds_read2_b32 v[68:69], v0 offset1:1
	ds_read2_b32 v[70:71], v70 offset1:1
	global_store_dwordx2 v[66:67], v[64:65], off
	v_add_u32_e32 v0, 0xb160, v21
	v_add_u32_e32 v66, 0xb168, v21
	ds_read2_b32 v[64:65], v0 offset1:1
	ds_read2_b32 v[66:67], v66 offset1:1
	v_or_b32_e32 v0, s44, v23
	v_lshlrev_b32_e32 v0, 11, v0
	s_waitcnt lgkmcnt(3)
	v_cvt_pk_bf16_f32 v68, v68, v69
	s_waitcnt lgkmcnt(2)
	v_cvt_pk_bf16_f32 v69, v70, v71
	v_lshl_add_u64 v[70:71], v[10:11], 0, v[0:1]
	v_or_b32_e32 v0, s44, v24
	v_lshlrev_b32_e32 v0, 11, v0
	global_store_dwordx2 v[70:71], v[68:69], off
	s_waitcnt lgkmcnt(1)
	v_cvt_pk_bf16_f32 v64, v64, v65
	s_waitcnt lgkmcnt(0)
	v_cvt_pk_bf16_f32 v65, v66, v67
	v_lshl_add_u64 v[66:67], v[10:11], 0, v[0:1]
	v_add_u32_e32 v0, 0xc180, v21
	v_add_u32_e32 v70, 0xc188, v21
	ds_read2_b32 v[68:69], v0 offset1:1
	ds_read2_b32 v[70:71], v70 offset1:1
	global_store_dwordx2 v[66:67], v[64:65], off
	v_add_u32_e32 v0, 0xd1a0, v21
	v_add_u32_e32 v66, 0xd1a8, v21
	ds_read2_b32 v[64:65], v0 offset1:1
	ds_read2_b32 v[66:67], v66 offset1:1
	v_or_b32_e32 v0, s44, v25
	v_lshlrev_b32_e32 v0, 11, v0
	s_waitcnt lgkmcnt(3)
	v_cvt_pk_bf16_f32 v68, v68, v69
	s_waitcnt lgkmcnt(2)
	v_cvt_pk_bf16_f32 v69, v70, v71
	v_lshl_add_u64 v[70:71], v[10:11], 0, v[0:1]
	v_or_b32_e32 v0, s44, v26
	v_lshlrev_b32_e32 v0, 11, v0
	global_store_dwordx2 v[70:71], v[68:69], off
	s_waitcnt lgkmcnt(1)
	v_cvt_pk_bf16_f32 v64, v64, v65
	s_waitcnt lgkmcnt(0)
	v_cvt_pk_bf16_f32 v65, v66, v67
	v_lshl_add_u64 v[66:67], v[10:11], 0, v[0:1]
	v_add_u32_e32 v0, 0xe1c0, v21
	v_add_u32_e32 v70, 0xe1c8, v21
	ds_read2_b32 v[68:69], v0 offset1:1
	ds_read2_b32 v[70:71], v70 offset1:1
	global_store_dwordx2 v[66:67], v[64:65], off
	v_add_u32_e32 v0, 0xf1e0, v21
	v_add_u32_e32 v66, 0xf1e8, v21
	ds_read2_b32 v[64:65], v0 offset1:1
	ds_read2_b32 v[66:67], v66 offset1:1
	v_or_b32_e32 v0, s44, v27
	v_lshlrev_b32_e32 v0, 11, v0
	s_waitcnt lgkmcnt(3)
	v_cvt_pk_bf16_f32 v68, v68, v69
	s_waitcnt lgkmcnt(2)
	v_cvt_pk_bf16_f32 v69, v70, v71
	v_lshl_add_u64 v[70:71], v[10:11], 0, v[0:1]
	v_or_b32_e32 v0, s44, v28
	v_lshlrev_b32_e32 v0, 11, v0
	s_bitset1_b32 s44, 7
	s_waitcnt lgkmcnt(1)
	v_cvt_pk_bf16_f32 v64, v64, v65
	s_waitcnt lgkmcnt(0)
	v_cvt_pk_bf16_f32 v65, v66, v67
	v_lshl_add_u64 v[66:67], v[10:11], 0, v[0:1]
	v_or_b32_e32 v0, s44, v72
	global_store_dwordx2 v[70:71], v[68:69], off
	global_store_dwordx2 v[66:67], v[64:65], off
	v_lshlrev_b32_e32 v0, 11, v0
	v_cvt_pk_bf16_f32 v12, v12, v13
	v_cvt_pk_bf16_f32 v13, v14, v15
	v_lshl_add_u64 v[14:15], v[10:11], 0, v[0:1]
	ds_read2_b32 v[64:65], v30 offset1:1
	ds_read2_b32 v[66:67], v30 offset0:2 offset1:3
	global_store_dwordx2 v[14:15], v[12:13], off
	ds_read2_b32 v[12:13], v31 offset1:1
	ds_read2_b32 v[14:15], v31 offset0:2 offset1:3
	v_or_b32_e32 v0, s44, v73
	v_lshlrev_b32_e32 v0, 11, v0
	s_waitcnt lgkmcnt(3)
	v_cvt_pk_bf16_f32 v64, v64, v65
	s_waitcnt lgkmcnt(2)
	v_cvt_pk_bf16_f32 v65, v66, v67
	v_lshl_add_u64 v[66:67], v[10:11], 0, v[0:1]
	v_or_b32_e32 v0, s44, v136
	global_store_dwordx2 v[66:67], v[64:65], off
	v_lshlrev_b32_e32 v0, 11, v0
	s_waitcnt lgkmcnt(1)
	v_cvt_pk_bf16_f32 v12, v12, v13
	s_waitcnt lgkmcnt(0)
	v_cvt_pk_bf16_f32 v13, v14, v15
	v_lshl_add_u64 v[14:15], v[10:11], 0, v[0:1]
	ds_read2_b32 v[64:65], v32 offset1:1
	ds_read2_b32 v[66:67], v32 offset0:2 offset1:3
	global_store_dwordx2 v[14:15], v[12:13], off
	ds_read2_b32 v[12:13], v33 offset1:1
	ds_read2_b32 v[14:15], v33 offset0:2 offset1:3
	v_or_b32_e32 v0, s44, v137
	v_lshlrev_b32_e32 v0, 11, v0
	s_waitcnt lgkmcnt(3)
	v_cvt_pk_bf16_f32 v64, v64, v65
	s_waitcnt lgkmcnt(2)
	v_cvt_pk_bf16_f32 v65, v66, v67
	v_lshl_add_u64 v[66:67], v[10:11], 0, v[0:1]
	v_or_b32_e32 v0, s44, v139
	global_store_dwordx2 v[66:67], v[64:65], off
	v_lshlrev_b32_e32 v0, 11, v0
	s_waitcnt lgkmcnt(1)
	v_cvt_pk_bf16_f32 v12, v12, v13
	s_waitcnt lgkmcnt(0)
	v_cvt_pk_bf16_f32 v13, v14, v15
	v_lshl_add_u64 v[14:15], v[10:11], 0, v[0:1]
	ds_read2_b32 v[64:65], v34 offset1:1
	ds_read2_b32 v[66:67], v34 offset0:2 offset1:3
	global_store_dwordx2 v[14:15], v[12:13], off
	ds_read2_b32 v[12:13], v35 offset1:1
	ds_read2_b32 v[14:15], v35 offset0:2 offset1:3
	v_or_b32_e32 v0, s44, v74
	v_lshlrev_b32_e32 v0, 11, v0
	s_waitcnt lgkmcnt(3)
	v_cvt_pk_bf16_f32 v64, v64, v65
	s_waitcnt lgkmcnt(2)
	v_cvt_pk_bf16_f32 v65, v66, v67
	v_lshl_add_u64 v[66:67], v[10:11], 0, v[0:1]
	v_or_b32_e32 v0, s44, v75
	global_store_dwordx2 v[66:67], v[64:65], off
	v_lshlrev_b32_e32 v0, 11, v0
	s_waitcnt lgkmcnt(1)
	v_cvt_pk_bf16_f32 v12, v12, v13
	s_waitcnt lgkmcnt(0)
	v_cvt_pk_bf16_f32 v13, v14, v15
	v_lshl_add_u64 v[14:15], v[10:11], 0, v[0:1]
	ds_read2_b32 v[64:65], v36 offset1:1
	ds_read2_b32 v[66:67], v36 offset0:2 offset1:3
	global_store_dwordx2 v[14:15], v[12:13], off
	ds_read2_b32 v[12:13], v37 offset1:1
	ds_read2_b32 v[14:15], v37 offset0:2 offset1:3
	v_or_b32_e32 v0, s44, v76
	v_lshlrev_b32_e32 v0, 11, v0
	s_waitcnt lgkmcnt(3)
	v_cvt_pk_bf16_f32 v64, v64, v65
	s_waitcnt lgkmcnt(2)
	v_cvt_pk_bf16_f32 v65, v66, v67
	v_lshl_add_u64 v[66:67], v[10:11], 0, v[0:1]
	v_or_b32_e32 v0, s44, v77
	global_store_dwordx2 v[66:67], v[64:65], off
	v_lshlrev_b32_e32 v0, 11, v0
	s_waitcnt lgkmcnt(1)
	v_cvt_pk_bf16_f32 v12, v12, v13
	s_waitcnt lgkmcnt(0)
	v_cvt_pk_bf16_f32 v13, v14, v15
	v_lshl_add_u64 v[14:15], v[10:11], 0, v[0:1]
	ds_read2_b32 v[64:65], v38 offset1:1
	ds_read2_b32 v[66:67], v38 offset0:2 offset1:3
	global_store_dwordx2 v[14:15], v[12:13], off
	ds_read2_b32 v[12:13], v39 offset1:1
	ds_read2_b32 v[14:15], v39 offset0:2 offset1:3
	v_or_b32_e32 v0, s44, v22
	v_lshlrev_b32_e32 v0, 11, v0
	s_waitcnt lgkmcnt(3)
	v_cvt_pk_bf16_f32 v64, v64, v65
	s_waitcnt lgkmcnt(2)
	v_cvt_pk_bf16_f32 v65, v66, v67
	v_lshl_add_u64 v[66:67], v[10:11], 0, v[0:1]
	v_or_b32_e32 v0, s44, v23
	global_store_dwordx2 v[66:67], v[64:65], off
	v_lshlrev_b32_e32 v0, 11, v0
	s_waitcnt lgkmcnt(1)
	v_cvt_pk_bf16_f32 v12, v12, v13
	s_waitcnt lgkmcnt(0)
	v_cvt_pk_bf16_f32 v13, v14, v15
	v_lshl_add_u64 v[14:15], v[10:11], 0, v[0:1]
	ds_read2_b32 v[64:65], v40 offset1:1
	ds_read2_b32 v[66:67], v40 offset0:2 offset1:3
	global_store_dwordx2 v[14:15], v[12:13], off
	ds_read2_b32 v[12:13], v41 offset1:1
	ds_read2_b32 v[14:15], v41 offset0:2 offset1:3
	v_or_b32_e32 v0, s44, v24
	v_lshlrev_b32_e32 v0, 11, v0
	s_waitcnt lgkmcnt(3)
	v_cvt_pk_bf16_f32 v64, v64, v65
	s_waitcnt lgkmcnt(2)
	v_cvt_pk_bf16_f32 v65, v66, v67
	v_lshl_add_u64 v[66:67], v[10:11], 0, v[0:1]
	v_or_b32_e32 v0, s44, v25
	v_lshlrev_b32_e32 v0, 11, v0
	global_store_dwordx2 v[66:67], v[64:65], off
	s_waitcnt lgkmcnt(1)
	v_cvt_pk_bf16_f32 v12, v12, v13
	s_waitcnt lgkmcnt(0)
	v_cvt_pk_bf16_f32 v13, v14, v15
	v_lshl_add_u64 v[14:15], v[10:11], 0, v[0:1]
	ds_read2_b32 v[64:65], v42 offset1:1
	ds_read2_b32 v[66:67], v42 offset0:2 offset1:3
	global_store_dwordx2 v[14:15], v[12:13], off
	ds_read2_b32 v[12:13], v43 offset1:1
	ds_read2_b32 v[14:15], v43 offset0:2 offset1:3
	v_add_lshl_u32 v0, s44, v26, 11
	s_waitcnt lgkmcnt(3)
	v_cvt_pk_bf16_f32 v64, v64, v65
	s_waitcnt lgkmcnt(2)
	v_cvt_pk_bf16_f32 v65, v66, v67
	v_lshl_add_u64 v[66:67], v[10:11], 0, v[0:1]
	v_add_lshl_u32 v0, s44, v27, 11
	s_waitcnt lgkmcnt(1)
	v_cvt_pk_bf16_f32 v12, v12, v13
	s_waitcnt lgkmcnt(0)
	v_cvt_pk_bf16_f32 v13, v14, v15
	v_lshl_add_u64 v[14:15], v[10:11], 0, v[0:1]
	v_add_lshl_u32 v0, s44, v28, 11
	global_store_dwordx2 v[14:15], v[12:13], off
	v_cvt_pk_bf16_f32 v12, v16, v17
	v_cvt_pk_bf16_f32 v13, v18, v19
	v_lshl_add_u64 v[10:11], v[10:11], 0, v[0:1]
	s_cmpk_lt_u32 s47, 0x60
	global_store_dwordx2 v[66:67], v[64:65], off
	global_store_dwordx2 v[10:11], v[12:13], off
	s_barrier
	s_cbranch_scc1 .LBB0_2448

.LBB0_2587:
	s_andn2_saveexec_b64 s[42:43], s[42:43]
	v_mul_f32_e32 v34, v33, v33
	v_fmamk_f32 v35, v34, 0xba1345e1, v195
	v_fmaak_f32 v35, v34, v35, 0xbcdac9b8
	v_fmaak_f32 v35, v34, v35, 0x3de703be
	v_fmaak_f32 v35, v34, v35, 0xbec09330
	v_fmaak_f32 v34, v34, v35, 0x3e0375d0
	v_fma_f32 v34, |v33|, v34, |v33|
	s_or_b64 exec, exec, s[42:43]
	v_cvt_scalef32_pk_f32_fp4 v[36:37], v182, 1.0
	v_pk_fma_f32 v[36:37], s[22:23], v[36:37], v[174:175] op_sel_hi:[0,1,1]
	v_cvt_scalef32_pk_f32_fp4 v[38:39], v182, 1.0 op_sel:[1,0,0]
	v_cvt_scalef32_pk_f32_fp4 v[52:53], v176, 1.0
	v_pk_fma_f32 v[38:39], s[22:23], v[38:39], v[192:193] op_sel_hi:[0,1,1]
	v_cvt_scalef32_pk_f32_fp4 v[40:41], v182, 1.0 op_sel:[0,1,0]
	v_pk_fma_f32 v[36:37], s[20:21], v[52:53], v[36:37] op_sel_hi:[0,1,1]
	v_cvt_scalef32_pk_f32_fp4 v[52:53], v176, 1.0 op_sel:[1,0,0]
	v_pk_fma_f32 v[40:41], s[22:23], v[40:41], v[188:189] op_sel_hi:[0,1,1]
	v_cvt_scalef32_pk_f32_fp4 v[42:43], v182, 1.0 op_sel:[1,1,0]
	v_pk_fma_f32 v[38:39], s[20:21], v[52:53], v[38:39] op_sel_hi:[0,1,1]
	v_cvt_scalef32_pk_f32_fp4 v[52:53], v176, 1.0 op_sel:[0,1,0]
	v_pk_fma_f32 v[42:43], s[22:23], v[42:43], v[190:191] op_sel_hi:[0,1,1]
	v_cvt_scalef32_pk_f32_fp4 v[44:45], v183, 1.0
	v_pk_fma_f32 v[40:41], s[20:21], v[52:53], v[40:41] op_sel_hi:[0,1,1]
	v_cvt_scalef32_pk_f32_fp4 v[52:53], v176, 1.0 op_sel:[1,1,0]
	v_pk_fma_f32 v[44:45], s[22:23], v[44:45], v[184:185] op_sel_hi:[0,1,1]
	v_cvt_scalef32_pk_f32_fp4 v[46:47], v183, 1.0 op_sel:[1,0,0]
	v_pk_fma_f32 v[42:43], s[20:21], v[52:53], v[42:43] op_sel_hi:[0,1,1]
	v_cvt_scalef32_pk_f32_fp4 v[52:53], v177, 1.0
	v_pk_fma_f32 v[46:47], s[22:23], v[46:47], v[186:187] op_sel_hi:[0,1,1]
	v_cvt_scalef32_pk_f32_fp4 v[48:49], v183, 1.0 op_sel:[0,1,0]
	v_pk_fma_f32 v[44:45], s[20:21], v[52:53], v[44:45] op_sel_hi:[0,1,1]
	v_cvt_scalef32_pk_f32_fp4 v[52:53], v177, 1.0 op_sel:[1,0,0]
	v_pk_fma_f32 v[48:49], s[22:23], v[48:49], v[178:179] op_sel_hi:[0,1,1]
	v_cvt_scalef32_pk_f32_fp4 v[50:51], v183, 1.0 op_sel:[1,1,0]
	v_pk_fma_f32 v[46:47], s[20:21], v[52:53], v[46:47] op_sel_hi:[0,1,1]
	v_cvt_scalef32_pk_f32_fp4 v[52:53], v177, 1.0 op_sel:[0,1,0]
	v_pk_fma_f32 v[50:51], s[22:23], v[50:51], v[180:181] op_sel_hi:[0,1,1]
	v_pk_fma_f32 v[48:49], s[20:21], v[52:53], v[48:49] op_sel_hi:[0,1,1]
	v_cvt_scalef32_pk_f32_fp4 v[52:53], v177, 1.0 op_sel:[1,1,0]
	v_pk_fma_f32 v[50:51], s[20:21], v[52:53], v[50:51] op_sel_hi:[0,1,1]
	v_cvt_scalef32_pk_f32_fp4 v[52:53], v172, 1.0
	v_pk_fma_f32 v[36:37], s[18:19], v[52:53], v[36:37] op_sel_hi:[0,1,1]
	v_cvt_scalef32_pk_f32_fp4 v[52:53], v172, 1.0 op_sel:[1,0,0]
	v_pk_fma_f32 v[38:39], s[18:19], v[52:53], v[38:39] op_sel_hi:[0,1,1]
	v_cvt_scalef32_pk_f32_fp4 v[52:53], v172, 1.0 op_sel:[0,1,0]
	v_pk_fma_f32 v[40:41], s[18:19], v[52:53], v[40:41] op_sel_hi:[0,1,1]
	v_cvt_scalef32_pk_f32_fp4 v[52:53], v172, 1.0 op_sel:[1,1,0]
	v_pk_fma_f32 v[42:43], s[18:19], v[52:53], v[42:43] op_sel_hi:[0,1,1]
	v_cvt_scalef32_pk_f32_fp4 v[52:53], v173, 1.0
	v_pk_fma_f32 v[44:45], s[18:19], v[52:53], v[44:45] op_sel_hi:[0,1,1]
	v_cvt_scalef32_pk_f32_fp4 v[52:53], v173, 1.0 op_sel:[1,0,0]
	v_pk_fma_f32 v[46:47], s[18:19], v[52:53], v[46:47] op_sel_hi:[0,1,1]
	v_cvt_scalef32_pk_f32_fp4 v[52:53], v173, 1.0 op_sel:[0,1,0]
	v_pk_fma_f32 v[48:49], s[18:19], v[52:53], v[48:49] op_sel_hi:[0,1,1]
	v_cvt_scalef32_pk_f32_fp4 v[52:53], v173, 1.0 op_sel:[1,1,0]
	v_pk_fma_f32 v[50:51], s[18:19], v[52:53], v[50:51] op_sel_hi:[0,1,1]
	v_cvt_scalef32_pk_f32_fp4 v[52:53], v170, 1.0
	v_pk_fma_f32 v[36:37], s[6:7], v[52:53], v[36:37] op_sel_hi:[0,1,1]
	v_cvt_scalef32_pk_f32_fp4 v[52:53], v170, 1.0 op_sel:[1,0,0]
	v_pk_fma_f32 v[38:39], s[6:7], v[52:53], v[38:39] op_sel_hi:[0,1,1]
	v_cvt_scalef32_pk_f32_fp4 v[52:53], v170, 1.0 op_sel:[0,1,0]
	v_pk_fma_f32 v[40:41], s[6:7], v[52:53], v[40:41] op_sel_hi:[0,1,1]
	v_cvt_scalef32_pk_f32_fp4 v[52:53], v170, 1.0 op_sel:[1,1,0]
	v_pk_fma_f32 v[42:43], s[6:7], v[52:53], v[42:43] op_sel_hi:[0,1,1]
	v_cvt_scalef32_pk_f32_fp4 v[52:53], v171, 1.0
	v_pk_fma_f32 v[44:45], s[6:7], v[52:53], v[44:45] op_sel_hi:[0,1,1]
	v_cvt_scalef32_pk_f32_fp4 v[52:53], v171, 1.0 op_sel:[1,0,0]
	v_pk_fma_f32 v[46:47], s[6:7], v[52:53], v[46:47] op_sel_hi:[0,1,1]
	v_cvt_scalef32_pk_f32_fp4 v[52:53], v171, 1.0 op_sel:[0,1,0]
	v_pk_fma_f32 v[48:49], s[6:7], v[52:53], v[48:49] op_sel_hi:[0,1,1]
	v_cvt_scalef32_pk_f32_fp4 v[52:53], v171, 1.0 op_sel:[1,1,0]
	v_pk_fma_f32 v[50:51], s[6:7], v[52:53], v[50:51] op_sel_hi:[0,1,1]
	v_cvt_scalef32_pk_f32_fp4 v[52:53], v168, 1.0
	v_pk_fma_f32 v[36:37], s[30:31], v[52:53], v[36:37] op_sel_hi:[0,1,1]
	v_cvt_scalef32_pk_f32_fp4 v[52:53], v168, 1.0 op_sel:[1,0,0]
	v_pk_fma_f32 v[38:39], s[30:31], v[52:53], v[38:39] op_sel_hi:[0,1,1]
	v_cvt_scalef32_pk_f32_fp4 v[52:53], v168, 1.0 op_sel:[0,1,0]
	v_pk_fma_f32 v[40:41], s[30:31], v[52:53], v[40:41] op_sel_hi:[0,1,1]
	v_cvt_scalef32_pk_f32_fp4 v[52:53], v168, 1.0 op_sel:[1,1,0]
	v_pk_fma_f32 v[42:43], s[30:31], v[52:53], v[42:43] op_sel_hi:[0,1,1]
	v_cvt_scalef32_pk_f32_fp4 v[52:53], v169, 1.0
	v_pk_fma_f32 v[44:45], s[30:31], v[52:53], v[44:45] op_sel_hi:[0,1,1]
	v_cvt_scalef32_pk_f32_fp4 v[52:53], v169, 1.0 op_sel:[1,0,0]
	v_pk_fma_f32 v[46:47], s[30:31], v[52:53], v[46:47] op_sel_hi:[0,1,1]
	v_cvt_scalef32_pk_f32_fp4 v[52:53], v169, 1.0 op_sel:[0,1,0]
	v_pk_fma_f32 v[48:49], s[30:31], v[52:53], v[48:49] op_sel_hi:[0,1,1]
	v_cvt_scalef32_pk_f32_fp4 v[52:53], v169, 1.0 op_sel:[1,1,0]
	v_pk_fma_f32 v[50:51], s[30:31], v[52:53], v[50:51] op_sel_hi:[0,1,1]
	v_cvt_scalef32_pk_f32_fp4 v[52:53], v166, 1.0
	v_pk_fma_f32 v[36:37], s[28:29], v[52:53], v[36:37] op_sel_hi:[0,1,1]
	v_cvt_scalef32_pk_f32_fp4 v[52:53], v166, 1.0 op_sel:[1,0,0]
	v_pk_fma_f32 v[38:39], s[28:29], v[52:53], v[38:39] op_sel_hi:[0,1,1]
	v_cvt_scalef32_pk_f32_fp4 v[52:53], v166, 1.0 op_sel:[0,1,0]
	v_pk_fma_f32 v[40:41], s[28:29], v[52:53], v[40:41] op_sel_hi:[0,1,1]
	v_cvt_scalef32_pk_f32_fp4 v[52:53], v166, 1.0 op_sel:[1,1,0]
	v_pk_fma_f32 v[42:43], s[28:29], v[52:53], v[42:43] op_sel_hi:[0,1,1]
	v_cvt_scalef32_pk_f32_fp4 v[52:53], v167, 1.0
	v_pk_fma_f32 v[44:45], s[28:29], v[52:53], v[44:45] op_sel_hi:[0,1,1]
	v_cvt_scalef32_pk_f32_fp4 v[52:53], v167, 1.0 op_sel:[1,0,0]
	v_pk_fma_f32 v[46:47], s[28:29], v[52:53], v[46:47] op_sel_hi:[0,1,1]
	v_cvt_scalef32_pk_f32_fp4 v[52:53], v167, 1.0 op_sel:[0,1,0]
	v_pk_fma_f32 v[48:49], s[28:29], v[52:53], v[48:49] op_sel_hi:[0,1,1]
	v_cvt_scalef32_pk_f32_fp4 v[52:53], v167, 1.0 op_sel:[1,1,0]
	v_pk_fma_f32 v[50:51], s[28:29], v[52:53], v[50:51] op_sel_hi:[0,1,1]
	v_cvt_scalef32_pk_f32_fp4 v[52:53], v164, 1.0
	v_pk_fma_f32 v[36:37], s[26:27], v[52:53], v[36:37] op_sel_hi:[0,1,1]
	v_cvt_scalef32_pk_f32_fp4 v[52:53], v164, 1.0 op_sel:[1,0,0]
	v_pk_fma_f32 v[38:39], s[26:27], v[52:53], v[38:39] op_sel_hi:[0,1,1]
	v_cvt_scalef32_pk_f32_fp4 v[52:53], v164, 1.0 op_sel:[0,1,0]
	v_pk_fma_f32 v[40:41], s[26:27], v[52:53], v[40:41] op_sel_hi:[0,1,1]
	v_cvt_scalef32_pk_f32_fp4 v[52:53], v164, 1.0 op_sel:[1,1,0]
	v_pk_fma_f32 v[42:43], s[26:27], v[52:53], v[42:43] op_sel_hi:[0,1,1]
	v_cvt_scalef32_pk_f32_fp4 v[52:53], v165, 1.0
	v_pk_fma_f32 v[44:45], s[26:27], v[52:53], v[44:45] op_sel_hi:[0,1,1]
	v_cvt_scalef32_pk_f32_fp4 v[52:53], v165, 1.0 op_sel:[1,0,0]
	v_pk_fma_f32 v[46:47], s[26:27], v[52:53], v[46:47] op_sel_hi:[0,1,1]
	v_cvt_scalef32_pk_f32_fp4 v[52:53], v165, 1.0 op_sel:[0,1,0]
	v_pk_fma_f32 v[48:49], s[26:27], v[52:53], v[48:49] op_sel_hi:[0,1,1]
	v_cvt_scalef32_pk_f32_fp4 v[52:53], v165, 1.0 op_sel:[1,1,0]
	v_pk_fma_f32 v[50:51], s[26:27], v[52:53], v[50:51] op_sel_hi:[0,1,1]
	v_cvt_scalef32_pk_f32_fp4 v[52:53], v162, 1.0
	v_pk_fma_f32 v[36:37], s[24:25], v[52:53], v[36:37] op_sel_hi:[0,1,1]
	v_cvt_scalef32_pk_f32_fp4 v[52:53], v162, 1.0 op_sel:[1,0,0]
	v_pk_fma_f32 v[38:39], s[24:25], v[52:53], v[38:39] op_sel_hi:[0,1,1]
	v_cvt_scalef32_pk_f32_fp4 v[52:53], v162, 1.0 op_sel:[0,1,0]
	v_pk_fma_f32 v[40:41], s[24:25], v[52:53], v[40:41] op_sel_hi:[0,1,1]
	v_cvt_scalef32_pk_f32_fp4 v[52:53], v162, 1.0 op_sel:[1,1,0]
	v_pk_fma_f32 v[42:43], s[24:25], v[52:53], v[42:43] op_sel_hi:[0,1,1]
	v_cvt_scalef32_pk_f32_fp4 v[52:53], v163, 1.0
	v_pk_fma_f32 v[44:45], s[24:25], v[52:53], v[44:45] op_sel_hi:[0,1,1]
	v_cvt_scalef32_pk_f32_fp4 v[52:53], v163, 1.0 op_sel:[1,0,0]
	v_pk_fma_f32 v[46:47], s[24:25], v[52:53], v[46:47] op_sel_hi:[0,1,1]
	v_cvt_scalef32_pk_f32_fp4 v[52:53], v163, 1.0 op_sel:[0,1,0]
	v_pk_fma_f32 v[48:49], s[24:25], v[52:53], v[48:49] op_sel_hi:[0,1,1]
	v_cvt_scalef32_pk_f32_fp4 v[52:53], v163, 1.0 op_sel:[1,1,0]
	v_pk_fma_f32 v[50:51], s[24:25], v[52:53], v[50:51] op_sel_hi:[0,1,1]
	v_cvt_scalef32_pk_f32_fp4 v[52:53], v160, 1.0
	v_pk_fma_f32 v[36:37], s[40:41], v[52:53], v[36:37] op_sel_hi:[0,1,1]
	v_cvt_scalef32_pk_f32_fp4 v[52:53], v160, 1.0 op_sel:[1,0,0]
	v_pk_fma_f32 v[38:39], s[40:41], v[52:53], v[38:39] op_sel_hi:[0,1,1]
	v_cvt_scalef32_pk_f32_fp4 v[52:53], v160, 1.0 op_sel:[0,1,0]
	v_pk_fma_f32 v[40:41], s[40:41], v[52:53], v[40:41] op_sel_hi:[0,1,1]
	v_cvt_scalef32_pk_f32_fp4 v[52:53], v160, 1.0 op_sel:[1,1,0]
	v_pk_fma_f32 v[42:43], s[40:41], v[52:53], v[42:43] op_sel_hi:[0,1,1]
	v_cvt_scalef32_pk_f32_fp4 v[52:53], v161, 1.0
	v_pk_fma_f32 v[44:45], s[40:41], v[52:53], v[44:45] op_sel_hi:[0,1,1]
	v_cvt_scalef32_pk_f32_fp4 v[52:53], v161, 1.0 op_sel:[1,0,0]
	v_pk_fma_f32 v[46:47], s[40:41], v[52:53], v[46:47] op_sel_hi:[0,1,1]
	v_cvt_scalef32_pk_f32_fp4 v[52:53], v161, 1.0 op_sel:[0,1,0]
	v_pk_fma_f32 v[48:49], s[40:41], v[52:53], v[48:49] op_sel_hi:[0,1,1]
	v_cvt_scalef32_pk_f32_fp4 v[52:53], v161, 1.0 op_sel:[1,1,0]
	v_pk_fma_f32 v[50:51], s[40:41], v[52:53], v[50:51] op_sel_hi:[0,1,1]
	v_cvt_scalef32_pk_f32_fp4 v[52:53], v158, 1.0
	v_pk_fma_f32 v[36:37], s[38:39], v[52:53], v[36:37] op_sel_hi:[0,1,1]
	v_cvt_scalef32_pk_f32_fp4 v[52:53], v158, 1.0 op_sel:[1,0,0]
	v_pk_fma_f32 v[38:39], s[38:39], v[52:53], v[38:39] op_sel_hi:[0,1,1]
	v_cvt_scalef32_pk_f32_fp4 v[52:53], v158, 1.0 op_sel:[0,1,0]
	v_pk_fma_f32 v[40:41], s[38:39], v[52:53], v[40:41] op_sel_hi:[0,1,1]
	v_cvt_scalef32_pk_f32_fp4 v[52:53], v158, 1.0 op_sel:[1,1,0]
	v_pk_fma_f32 v[42:43], s[38:39], v[52:53], v[42:43] op_sel_hi:[0,1,1]
	v_cvt_scalef32_pk_f32_fp4 v[52:53], v159, 1.0
	v_pk_fma_f32 v[44:45], s[38:39], v[52:53], v[44:45] op_sel_hi:[0,1,1]
	v_cvt_scalef32_pk_f32_fp4 v[52:53], v159, 1.0 op_sel:[1,0,0]
	v_pk_fma_f32 v[46:47], s[38:39], v[52:53], v[46:47] op_sel_hi:[0,1,1]
	v_cvt_scalef32_pk_f32_fp4 v[52:53], v159, 1.0 op_sel:[0,1,0]
	v_pk_fma_f32 v[48:49], s[38:39], v[52:53], v[48:49] op_sel_hi:[0,1,1]
	v_cvt_scalef32_pk_f32_fp4 v[52:53], v159, 1.0 op_sel:[1,1,0]
	v_pk_fma_f32 v[50:51], s[38:39], v[52:53], v[50:51] op_sel_hi:[0,1,1]
	v_cvt_scalef32_pk_f32_fp4 v[52:53], v156, 1.0
	v_pk_fma_f32 v[36:37], s[36:37], v[52:53], v[36:37] op_sel_hi:[0,1,1]
	v_cvt_scalef32_pk_f32_fp4 v[52:53], v156, 1.0 op_sel:[1,0,0]
	v_pk_fma_f32 v[38:39], s[36:37], v[52:53], v[38:39] op_sel_hi:[0,1,1]
	v_cvt_scalef32_pk_f32_fp4 v[52:53], v156, 1.0 op_sel:[0,1,0]
	v_pk_fma_f32 v[40:41], s[36:37], v[52:53], v[40:41] op_sel_hi:[0,1,1]
	v_cvt_scalef32_pk_f32_fp4 v[52:53], v156, 1.0 op_sel:[1,1,0]
	v_pk_fma_f32 v[42:43], s[36:37], v[52:53], v[42:43] op_sel_hi:[0,1,1]
	v_cvt_scalef32_pk_f32_fp4 v[52:53], v157, 1.0
	v_pk_fma_f32 v[44:45], s[36:37], v[52:53], v[44:45] op_sel_hi:[0,1,1]
	v_cvt_scalef32_pk_f32_fp4 v[52:53], v157, 1.0 op_sel:[1,0,0]
	v_pk_fma_f32 v[46:47], s[36:37], v[52:53], v[46:47] op_sel_hi:[0,1,1]
	v_cvt_scalef32_pk_f32_fp4 v[52:53], v157, 1.0 op_sel:[0,1,0]
	v_pk_fma_f32 v[48:49], s[36:37], v[52:53], v[48:49] op_sel_hi:[0,1,1]
	v_cvt_scalef32_pk_f32_fp4 v[52:53], v157, 1.0 op_sel:[1,1,0]
	v_pk_fma_f32 v[50:51], s[36:37], v[52:53], v[50:51] op_sel_hi:[0,1,1]
	v_cvt_scalef32_pk_f32_fp4 v[52:53], v154, 1.0
	v_pk_fma_f32 v[36:37], s[34:35], v[52:53], v[36:37] op_sel_hi:[0,1,1]
	v_cvt_scalef32_pk_f32_fp4 v[52:53], v154, 1.0 op_sel:[1,0,0]
	v_pk_fma_f32 v[38:39], s[34:35], v[52:53], v[38:39] op_sel_hi:[0,1,1]
	v_cvt_scalef32_pk_f32_fp4 v[52:53], v154, 1.0 op_sel:[0,1,0]
	v_pk_fma_f32 v[40:41], s[34:35], v[52:53], v[40:41] op_sel_hi:[0,1,1]
	v_cvt_scalef32_pk_f32_fp4 v[52:53], v154, 1.0 op_sel:[1,1,0]
	v_pk_fma_f32 v[42:43], s[34:35], v[52:53], v[42:43] op_sel_hi:[0,1,1]
	v_cvt_scalef32_pk_f32_fp4 v[52:53], v155, 1.0
	v_pk_fma_f32 v[44:45], s[34:35], v[52:53], v[44:45] op_sel_hi:[0,1,1]
	v_cvt_scalef32_pk_f32_fp4 v[52:53], v155, 1.0 op_sel:[1,0,0]
	v_pk_fma_f32 v[46:47], s[34:35], v[52:53], v[46:47] op_sel_hi:[0,1,1]
	v_cvt_scalef32_pk_f32_fp4 v[52:53], v155, 1.0 op_sel:[0,1,0]
	v_pk_fma_f32 v[48:49], s[34:35], v[52:53], v[48:49] op_sel_hi:[0,1,1]
	v_cvt_scalef32_pk_f32_fp4 v[52:53], v155, 1.0 op_sel:[1,1,0]
	v_pk_fma_f32 v[50:51], s[34:35], v[52:53], v[50:51] op_sel_hi:[0,1,1]
	v_mov_b32_e32 v35, s49
	v_mov_b32_e32 v52, s25
	v_cndmask_b32_e64 v35, v35, v52, s[4:5]
	v_mov_b32_e32 v52, s35
	v_bfi_b32 v33, s47, v34, v33
	v_cndmask_b32_e64 v35, v35, v52, s[2:3]
	v_mov_b32_e32 v52, s7
	v_mul_f32_e32 v32, 0.5, v32
	v_add_f32_e32 v33, 1.0, v33
	v_cndmask_b32_e64 v35, v35, v52, s[0:1]
	v_mul_f32_e32 v32, v32, v33
	v_mul_f32_e32 v32, v35, v32
	v_cvt_scalef32_pk_f32_fp4 v[34:35], v152, 1.0 op_sel:[1,0,0]
	v_readlane_b32 s6, v32, 0
	v_readlane_b32 s18, v32, 32
	v_readlane_b32 s20, v32, 16
	v_readlane_b32 s22, v32, 48
	v_cvt_scalef32_pk_f32_fp4 v[32:33], v152, 1.0
	v_pk_fma_f32 v[32:33], s[6:7], v[32:33], v[36:37] op_sel_hi:[0,1,1]
	v_cvt_scalef32_pk_f32_fp4 v[36:37], v152, 1.0 op_sel:[0,1,0]
	v_pk_fma_f32 v[36:37], s[6:7], v[36:37], v[40:41] op_sel_hi:[0,1,1]
	v_cvt_scalef32_pk_f32_fp4 v[40:41], v153, 1.0
	v_pk_fma_f32 v[40:41], s[6:7], v[40:41], v[44:45] op_sel_hi:[0,1,1]
	v_cvt_scalef32_pk_f32_fp4 v[44:45], v153, 1.0 op_sel:[0,1,0]
	v_pk_fma_f32 v[44:45], s[6:7], v[44:45], v[48:49] op_sel_hi:[0,1,1]
	v_cvt_scalef32_pk_f32_fp4 v[48:49], v150, 1.0
	v_pk_fma_f32 v[34:35], s[6:7], v[34:35], v[38:39] op_sel_hi:[0,1,1]
	v_pk_fma_f32 v[32:33], s[18:19], v[48:49], v[32:33] op_sel_hi:[0,1,1]
	v_cvt_scalef32_pk_f32_fp4 v[48:49], v150, 1.0 op_sel:[1,0,0]
	v_cvt_scalef32_pk_f32_fp4 v[38:39], v152, 1.0 op_sel:[1,1,0]
	v_pk_fma_f32 v[34:35], s[18:19], v[48:49], v[34:35] op_sel_hi:[0,1,1]
	v_cvt_scalef32_pk_f32_fp4 v[48:49], v150, 1.0 op_sel:[0,1,0]
	v_pk_fma_f32 v[38:39], s[6:7], v[38:39], v[42:43] op_sel_hi:[0,1,1]
	v_pk_fma_f32 v[36:37], s[18:19], v[48:49], v[36:37] op_sel_hi:[0,1,1]
	v_cvt_scalef32_pk_f32_fp4 v[48:49], v150, 1.0 op_sel:[1,1,0]
	v_cvt_scalef32_pk_f32_fp4 v[42:43], v153, 1.0 op_sel:[1,0,0]
	v_pk_fma_f32 v[38:39], s[18:19], v[48:49], v[38:39] op_sel_hi:[0,1,1]
	v_cvt_scalef32_pk_f32_fp4 v[48:49], v151, 1.0
	v_pk_fma_f32 v[42:43], s[6:7], v[42:43], v[46:47] op_sel_hi:[0,1,1]
	v_pk_fma_f32 v[40:41], s[18:19], v[48:49], v[40:41] op_sel_hi:[0,1,1]
	v_cvt_scalef32_pk_f32_fp4 v[48:49], v151, 1.0 op_sel:[1,0,0]
	v_cvt_scalef32_pk_f32_fp4 v[46:47], v153, 1.0 op_sel:[1,1,0]
	v_pk_fma_f32 v[42:43], s[18:19], v[48:49], v[42:43] op_sel_hi:[0,1,1]
	v_cvt_scalef32_pk_f32_fp4 v[48:49], v151, 1.0 op_sel:[0,1,0]
	v_pk_fma_f32 v[46:47], s[6:7], v[46:47], v[50:51] op_sel_hi:[0,1,1]
	v_pk_fma_f32 v[44:45], s[18:19], v[48:49], v[44:45] op_sel_hi:[0,1,1]
	v_cvt_scalef32_pk_f32_fp4 v[48:49], v151, 1.0 op_sel:[1,1,0]
	v_pk_fma_f32 v[46:47], s[18:19], v[48:49], v[46:47] op_sel_hi:[0,1,1]
	v_cvt_scalef32_pk_f32_fp4 v[48:49], v148, 1.0
	v_pk_fma_f32 v[32:33], s[20:21], v[48:49], v[32:33] op_sel_hi:[0,1,1]
	v_cvt_scalef32_pk_f32_fp4 v[48:49], v148, 1.0 op_sel:[1,0,0]
	v_pk_fma_f32 v[34:35], s[20:21], v[48:49], v[34:35] op_sel_hi:[0,1,1]
	v_cvt_scalef32_pk_f32_fp4 v[48:49], v148, 1.0 op_sel:[0,1,0]
	v_pk_fma_f32 v[36:37], s[20:21], v[48:49], v[36:37] op_sel_hi:[0,1,1]
	v_cvt_scalef32_pk_f32_fp4 v[48:49], v148, 1.0 op_sel:[1,1,0]
	v_pk_fma_f32 v[38:39], s[20:21], v[48:49], v[38:39] op_sel_hi:[0,1,1]
	v_cvt_scalef32_pk_f32_fp4 v[48:49], v149, 1.0
	v_pk_fma_f32 v[40:41], s[20:21], v[48:49], v[40:41] op_sel_hi:[0,1,1]
	v_cvt_scalef32_pk_f32_fp4 v[48:49], v149, 1.0 op_sel:[1,0,0]
	v_pk_fma_f32 v[42:43], s[20:21], v[48:49], v[42:43] op_sel_hi:[0,1,1]
	v_cvt_scalef32_pk_f32_fp4 v[48:49], v149, 1.0 op_sel:[0,1,0]
	v_pk_fma_f32 v[44:45], s[20:21], v[48:49], v[44:45] op_sel_hi:[0,1,1]
	v_cvt_scalef32_pk_f32_fp4 v[48:49], v149, 1.0 op_sel:[1,1,0]
	v_pk_fma_f32 v[46:47], s[20:21], v[48:49], v[46:47] op_sel_hi:[0,1,1]
	v_cvt_scalef32_pk_f32_fp4 v[48:49], v146, 1.0
	v_pk_fma_f32 v[174:175], s[22:23], v[48:49], v[32:33] op_sel_hi:[0,1,1]
	v_cvt_scalef32_pk_f32_fp4 v[32:33], v146, 1.0 op_sel:[1,0,0]
	v_pk_fma_f32 v[192:193], s[22:23], v[32:33], v[34:35] op_sel_hi:[0,1,1]
	v_cvt_scalef32_pk_f32_fp4 v[32:33], v146, 1.0 op_sel:[0,1,0]
	v_pk_fma_f32 v[188:189], s[22:23], v[32:33], v[36:37] op_sel_hi:[0,1,1]
	v_cvt_scalef32_pk_f32_fp4 v[32:33], v146, 1.0 op_sel:[1,1,0]
	v_pk_fma_f32 v[190:191], s[22:23], v[32:33], v[38:39] op_sel_hi:[0,1,1]
	v_cvt_scalef32_pk_f32_fp4 v[32:33], v147, 1.0
	v_pk_fma_f32 v[184:185], s[22:23], v[32:33], v[40:41] op_sel_hi:[0,1,1]
	v_cvt_scalef32_pk_f32_fp4 v[32:33], v147, 1.0 op_sel:[1,0,0]
	v_pk_fma_f32 v[186:187], s[22:23], v[32:33], v[42:43] op_sel_hi:[0,1,1]
	v_cvt_scalef32_pk_f32_fp4 v[32:33], v147, 1.0 op_sel:[0,1,0]
	v_pk_fma_f32 v[178:179], s[22:23], v[32:33], v[44:45] op_sel_hi:[0,1,1]
	v_cvt_scalef32_pk_f32_fp4 v[32:33], v147, 1.0 op_sel:[1,1,0]
	v_pk_fma_f32 v[180:181], s[22:23], v[32:33], v[46:47] op_sel_hi:[0,1,1]
	s_and_b64 vcc, exec, s[8:9]
	s_cbranch_vccnz .LBB0_2569
	s_mov_b32 s18, s48
	s_add_i32 s48, s18, 16
	s_cmpk_gt_u32 s18, 0x6f
	s_cselect_b64 s[8:9], -1, 0
	s_cmpk_lt_u32 s18, 0x70
	s_cselect_b64 vcc, -1, 0
	s_bitcmp0_b32 s48, 6
	s_cselect_b64 s[6:7], -1, 0
	v_cndmask_b32_e64 v104, v102, v100, s[6:7]
	v_cndmask_b32_e32 v104, v114, v104, vcc
	s_nop 0
	s_waitcnt vmcnt(24)
	v_accvgpr_read_b32 v183, a29
	v_accvgpr_read_b32 v177, a31
	v_accvgpr_read_b32 v173, a33
	v_accvgpr_read_b32 v171, a35
	v_accvgpr_read_b32 v95, a11
	v_mov_b64_e32 v[88:89], v[250:251]
	v_accvgpr_read_b32 v87, a3
	v_accvgpr_read_b32 v83, a7
	v_accvgpr_read_b32 v182, a28
	v_accvgpr_read_b32 v176, a30
	v_accvgpr_read_b32 v172, a32
	v_accvgpr_read_b32 v170, a34
	v_accvgpr_read_b32 v94, a10
	v_accvgpr_read_b32 v93, a9
	v_accvgpr_read_b32 v92, a8
	v_mov_b64_e32 v[90:91], v[252:253]
	v_accvgpr_read_b32 v86, a2
	v_accvgpr_read_b32 v85, a1
	v_accvgpr_read_b32 v84, a0
	v_accvgpr_read_b32 v82, a6
	v_accvgpr_read_b32 v81, a5
	v_accvgpr_read_b32 v80, a4
	s_add_i32 s22, s18, 16
	v_readlane_b32 s20, v104, s22
	s_nop 1
	v_mad_i64_i32 v[108:109], s[6:7], s20, v194, v[96:97]
	global_load_dwordx4 a[8:11], v[108:109], off
	v_mad_i64_i32 v[108:109], s[6:7], s20, v194, v[98:99]
	global_load_dwordx2 a[28:29], v[108:109], off
	s_add_i32 s22, s18, 17
	v_readlane_b32 s20, v104, s22
	s_nop 1
	v_mad_i64_i32 v[108:109], s[6:7], s20, v194, v[96:97]
	global_load_dwordx4 v[250:253], v[108:109], off
	v_mad_i64_i32 v[108:109], s[6:7], s20, v194, v[98:99]
	global_load_dwordx2 a[30:31], v[108:109], off
	s_add_i32 s22, s18, 18
	v_readlane_b32 s20, v104, s22
	s_nop 1
	v_mad_i64_i32 v[108:109], s[6:7], s20, v194, v[96:97]
	global_load_dwordx4 a[0:3], v[108:109], off
	v_mad_i64_i32 v[108:109], s[6:7], s20, v194, v[98:99]
	global_load_dwordx2 a[32:33], v[108:109], off
	s_add_i32 s22, s18, 19
	v_readlane_b32 s20, v104, s22
	s_nop 1
	v_mad_i64_i32 v[108:109], s[6:7], s20, v194, v[96:97]
	global_load_dwordx4 a[4:7], v[108:109], off
	v_mad_i64_i32 v[108:109], s[6:7], s20, v194, v[98:99]
	global_load_dwordx2 a[34:35], v[108:109], off
	s_waitcnt vmcnt(24)
	v_accvgpr_read_b32 v169, a37
	v_accvgpr_read_b32 v167, a39
	v_accvgpr_read_b32 v165, a41
	v_accvgpr_read_b32 v163, a43
	v_mov_b64_e32 v[76:77], v[214:215]
	v_mov_b64_e32 v[72:73], v[218:219]
	v_mov_b64_e32 v[68:69], v[222:223]
	v_mov_b64_e32 v[64:65], v[226:227]
	v_accvgpr_read_b32 v168, a36
	v_accvgpr_read_b32 v166, a38
	v_accvgpr_read_b32 v164, a40
	v_accvgpr_read_b32 v162, a42
	v_mov_b64_e32 v[78:79], v[216:217]
	v_mov_b64_e32 v[74:75], v[220:221]
	v_mov_b64_e32 v[70:71], v[224:225]
	v_mov_b64_e32 v[66:67], v[228:229]
	s_add_i32 s22, s18, 20
	v_readlane_b32 s20, v104, s22
	s_nop 1
	v_mad_i64_i32 v[108:109], s[6:7], s20, v194, v[96:97]
	global_load_dwordx4 v[214:217], v[108:109], off
	v_mad_i64_i32 v[108:109], s[6:7], s20, v194, v[98:99]
	global_load_dwordx2 a[36:37], v[108:109], off
	s_add_i32 s22, s18, 21
	v_readlane_b32 s20, v104, s22
	s_nop 1
	v_mad_i64_i32 v[108:109], s[6:7], s20, v194, v[96:97]
	global_load_dwordx4 v[218:221], v[108:109], off
	v_mad_i64_i32 v[108:109], s[6:7], s20, v194, v[98:99]
	global_load_dwordx2 a[38:39], v[108:109], off
	s_add_i32 s22, s18, 22
	v_readlane_b32 s20, v104, s22
	s_nop 1
	v_mad_i64_i32 v[108:109], s[6:7], s20, v194, v[96:97]
	global_load_dwordx4 v[222:225], v[108:109], off
	v_mad_i64_i32 v[108:109], s[6:7], s20, v194, v[98:99]
	global_load_dwordx2 a[40:41], v[108:109], off
	s_add_i32 s22, s18, 23
	v_readlane_b32 s20, v104, s22
	s_nop 1
	v_mad_i64_i32 v[108:109], s[6:7], s20, v194, v[96:97]
	global_load_dwordx4 v[226:229], v[108:109], off
	v_mad_i64_i32 v[108:109], s[6:7], s20, v194, v[98:99]
	global_load_dwordx2 a[42:43], v[108:109], off
	s_waitcnt vmcnt(24)
	v_accvgpr_read_b32 v161, a45
	v_accvgpr_read_b32 v159, a47
	v_accvgpr_read_b32 v157, a49
	v_accvgpr_read_b32 v155, a51
	v_mov_b64_e32 v[60:61], v[230:231]
	v_mov_b64_e32 v[56:57], v[234:235]
	v_mov_b64_e32 v[52:53], v[238:239]
	v_mov_b64_e32 v[48:49], v[242:243]
	v_accvgpr_read_b32 v160, a44
	v_accvgpr_read_b32 v158, a46
	v_accvgpr_read_b32 v156, a48
	v_accvgpr_read_b32 v154, a50
	v_mov_b64_e32 v[62:63], v[232:233]
	v_mov_b64_e32 v[58:59], v[236:237]
	v_mov_b64_e32 v[54:55], v[240:241]
	v_mov_b64_e32 v[50:51], v[244:245]
	s_add_i32 s22, s18, 24
	v_readlane_b32 s20, v104, s22
	s_nop 1
	v_mad_i64_i32 v[108:109], s[6:7], s20, v194, v[96:97]
	global_load_dwordx4 v[230:233], v[108:109], off
	v_mad_i64_i32 v[108:109], s[6:7], s20, v194, v[98:99]
	global_load_dwordx2 a[44:45], v[108:109], off
	s_add_i32 s22, s18, 25
	v_readlane_b32 s20, v104, s22
	s_nop 1
	v_mad_i64_i32 v[108:109], s[6:7], s20, v194, v[96:97]
	global_load_dwordx4 v[234:237], v[108:109], off
	v_mad_i64_i32 v[108:109], s[6:7], s20, v194, v[98:99]
	global_load_dwordx2 a[46:47], v[108:109], off
	s_add_i32 s22, s18, 26
	v_readlane_b32 s20, v104, s22
	s_nop 1
	v_mad_i64_i32 v[108:109], s[6:7], s20, v194, v[96:97]
	global_load_dwordx4 v[238:241], v[108:109], off
	v_mad_i64_i32 v[108:109], s[6:7], s20, v194, v[98:99]
	global_load_dwordx2 a[48:49], v[108:109], off
	s_add_i32 s22, s18, 27
	v_readlane_b32 s20, v104, s22
	s_nop 1
	v_mad_i64_i32 v[108:109], s[6:7], s20, v194, v[96:97]
	global_load_dwordx4 v[242:245], v[108:109], off
	v_mad_i64_i32 v[108:109], s[6:7], s20, v194, v[98:99]
	global_load_dwordx2 a[50:51], v[108:109], off
	s_waitcnt vmcnt(24)
	v_accvgpr_read_b32 v153, a25
	v_accvgpr_read_b32 v151, a23
	v_accvgpr_read_b32 v149, a21
	v_accvgpr_read_b32 v147, a27
	v_mov_b64_e32 v[44:45], v[246:247]
	v_mov_b64_e32 v[40:41], v[210:211]
	v_mov_b64_e32 v[36:37], v[206:207]
	v_mov_b64_e32 v[32:33], v[202:203]
	v_accvgpr_read_b32 v152, a24
	v_accvgpr_read_b32 v150, a22
	v_accvgpr_read_b32 v148, a20
	v_accvgpr_read_b32 v146, a26
	v_mov_b64_e32 v[46:47], v[248:249]
	v_mov_b64_e32 v[42:43], v[212:213]
	v_mov_b64_e32 v[38:39], v[208:209]
	v_mov_b64_e32 v[34:35], v[204:205]
	s_add_i32 s22, s18, 28
	v_readlane_b32 s20, v104, s22
	s_nop 1
	v_mad_i64_i32 v[108:109], s[6:7], s20, v194, v[96:97]
	global_load_dwordx4 v[246:249], v[108:109], off
	v_mad_i64_i32 v[108:109], s[6:7], s20, v194, v[98:99]
	global_load_dwordx2 a[24:25], v[108:109], off
	s_add_i32 s22, s18, 29
	v_readlane_b32 s20, v104, s22
	s_nop 1
	v_mad_i64_i32 v[108:109], s[6:7], s20, v194, v[96:97]
	global_load_dwordx4 v[210:213], v[108:109], off
	v_mad_i64_i32 v[108:109], s[6:7], s20, v194, v[98:99]
	global_load_dwordx2 a[22:23], v[108:109], off
	s_add_i32 s22, s18, 30
	v_readlane_b32 s20, v104, s22
	s_nop 1
	v_mad_i64_i32 v[108:109], s[6:7], s20, v194, v[96:97]
	global_load_dwordx4 v[206:209], v[108:109], off
	v_mad_i64_i32 v[108:109], s[6:7], s20, v194, v[98:99]
	global_load_dwordx2 a[20:21], v[108:109], off
	s_add_i32 s22, s18, 31
	v_readlane_b32 s20, v104, s22
	s_nop 1
	v_mad_i64_i32 v[108:109], s[6:7], s20, v194, v[96:97]
	global_load_dwordx4 v[202:205], v[108:109], off
	v_mad_i64_i32 v[108:109], s[6:7], s20, v194, v[98:99]
	global_load_dwordx2 a[26:27], v[108:109], off
	s_cmp_lg_u32 s18, 64
	s_cbranch_scc1 .LBB0_2573
	global_load_dword a53, v[144:145], off
	global_load_dword a54, v[142:143], off
	global_load_dword v103, v[140:141], off
	global_load_dword v101, v[138:139], off
	s_branch .LBB0_2573
